# trailing half's re-offset barrier deferred from before the unit header to the K-loop entry (headers of both halves overlap); plus v1 EpiResid epilogues
# speedup vs baseline: 1.0001x; 1.0001x over previous
; #define LAS __attribute__((address_space(3)))
; __global__ void __launch_bounds__(NWAVES * 64, 2) mk_fwd(Args args) {
;     extern __shared__ __attribute__((aligned(16))) unsigned char lds[];
;     cg::grid_group grid = cg::this_grid();
;     LAS unsigned char* L = (LAS unsigned char*)lds;
;     const int wave = __builtin_amdgcn_readfirstlane((int)threadIdx.x >> 6);
;     ...
;     const int G = gridDim.x, bx = blockIdx.x, vcu = (G % 8 == 0) ? (bx % 8) * (G / 8) + bx / 8 : bx;
_Z6mk_fwd4Args:
	s_load_dwordx2 s[24:25], s[0:1], 0xc8
	s_add_u32 s6, s0, 0xc8
	s_addc_u32 s7, s1, 0
	v_and_b32_e32 v1, 0x3ff, v0
	s_mov_b32 s83, s2
	s_waitcnt lgkmcnt(0)
	s_and_b32 s3, s24, 7
	v_readfirstlane_b32 s72, v1
	s_mov_b32 s98, 0
	s_cmp_lg_u32 s3, 0
	s_cbranch_scc1 .LBB0_2
	s_ashr_i32 s4, s2, 31
	s_lshr_b32 s4, s4, 29
	s_add_i32 s4, s2, s4
	s_and_b32 s5, s4, -8
	s_ashr_i32 s3, s24, 3
	s_sub_i32 s5, s2, s5
	s_mul_i32 s3, s3, s5
	s_ashr_i32 s4, s4, 3
	s_add_i32 s83, s3, s4

; #define PG8_STAGE(bufoff, gbase, voff) do { _Pragma("unroll") for (int _i = 0; _i < 2; ++_i) \
;         __builtin_amdgcn_global_load_lds((const unsigned*)((const char*)(gbase) + (voff)[_i]), (PG8_LAS unsigned*)(lds + (bufoff) + ldsw + _i * 8192), 16, 0, 0); } while (0)
; #define PG8_LDA(dst, b, h) do { _Pragma("unroll") for (int m = 0; m < 4; ++m) _Pragma("unroll") for (int k = 0; k < 2; ++k) dst[m][k] = *(const PG8_LAS bf16x8*)(lds + PG8_SA(b, h) + aoff + m * 2048 + k * 1024); } while (0)
; #define PG8_LDB(dst, b, h) do { _Pragma("unroll") for (int n = 0; n < 2; ++n) _Pragma("unroll") for (int k = 0; k < 2; ++k) dst[n][k] = *(const PG8_LAS bf16x8*)(lds + PG8_SB(b, h) + boff + n * 2048 + k * 1024); } while (0)
; #define PG8_BAR __builtin_amdgcn_s_barrier()
; #define PG8_SCHED __builtin_amdgcn_sched_barrier(0)
; template <class Epi, class Sched, bool ALIGN_EPI = false, bool SP2 = false>
; __device__ __forceinline__ void gemm_phase(PG8_LAS unsigned char* lds, const Gemm g, const Sched& S, const Epi& E, int tid_in) {
;     ...
;         const bool has_next = S.next(ui + 1, nxt);
;         const char* nA = has_next ? (const char*)g.A + (size_t)nxt.pm * tstep : cA; const char* nB = has_next ? (const char*)g.Bt + (size_t)nxt.pn * tstepB : cB;
;         for (int t = 0; t < nt; t += 2) {
;             const bool last = (t == nt - 2);
;             const char* a1 = cA + (size_t)(t + 1) * kstep;
;             const char* a2 = last ? nA : cA + (size_t)(t + 2) * kstep; const char* b2 = last ? nB : cB + (size_t)(t + 2) * kstep;
;             const char* a3 = a2 + kstep; const char* b3 = b2 + kstep;
;             if (last && has_next) S.a_ready(nxt);
;             if constexpr (SP2) {
;             PG8_LDB(B0, 0, 0); PG8_LDB(B1, 0, 1); PG8_SCHED; PG8_LDA(At, 0, 0); PG8_STAGE(PG8_SA(1, 1), a1 + hstep, voffA);
;     ...
; #pragma unroll
;         for (int a = 0; a < 2; ++a)
; #pragma unroll
;             for (int b = 0; b < 2; ++b)
; #pragma unroll
;                 for (int m = 0; m < 4; ++m)
; #pragma unroll
;                     for (int n = 0; n < 2; ++n) acc[a][b][m][n] = (f32x4){0.f, 0.f, 0.f, 0.f};
;         cur = nxt; cA = nA; cB = nB; ++ui;
;         if constexpr (ALIGN_EPI) { if (wr == 1) PG8_BAR; }
.LBB0_79:
	s_ashr_i32 s41, s40, 31
	s_lshl_b64 s[26:27], s[40:41], 20
	s_add_u32 s42, s28, s26
	s_addc_u32 s43, s29, s27
	s_and_b64 s[26:27], s[6:7], exec
	s_cselect_b32 s41, s43, s49
	s_cselect_b32 s70, s42, s48
	s_ashr_i32 s39, s38, 31
	s_lshl_b64 s[26:27], s[38:39], 20
	s_add_u32 s44, s36, s26
	s_addc_u32 s45, s37, s27
	s_and_b64 s[26:27], s[6:7], exec
	s_cselect_b32 s39, s45, s51
	s_cselect_b32 s71, s44, s50
	s_add_u32 s48, s48, 0x80080
	s_addc_u32 s49, s49, 0
	s_add_u32 s74, s50, 0x100
	v_mov_b32_e32 v0, 0
	s_addc_u32 s75, s51, 0
	s_mov_b32 s76, -2
	v_mov_b32_e32 v1, v0
	v_mov_b32_e32 v2, v0
	v_mov_b32_e32 v3, v0
	v_mov_b32_e32 v4, v0
	v_mov_b32_e32 v5, v0
	v_mov_b32_e32 v6, v0
	v_mov_b32_e32 v7, v0
	v_mov_b32_e32 v16, v0
	v_mov_b32_e32 v17, v0
	v_mov_b32_e32 v18, v0
	v_mov_b32_e32 v19, v0
	v_mov_b32_e32 v20, v0
	v_mov_b32_e32 v21, v0
	v_mov_b32_e32 v22, v0
	v_mov_b32_e32 v23, v0
	v_mov_b32_e32 v32, v0
	v_mov_b32_e32 v33, v0
	v_mov_b32_e32 v34, v0
	v_mov_b32_e32 v35, v0
	v_mov_b32_e32 v36, v0
	v_mov_b32_e32 v37, v0
	v_mov_b32_e32 v38, v0
	v_mov_b32_e32 v39, v0
	v_mov_b32_e32 v48, v0
	v_mov_b32_e32 v49, v0
	v_mov_b32_e32 v50, v0
	v_mov_b32_e32 v51, v0
	v_mov_b32_e32 v52, v0
	v_mov_b32_e32 v53, v0
	v_mov_b32_e32 v54, v0
	v_mov_b32_e32 v55, v0
	v_mov_b32_e32 v8, v0
	v_mov_b32_e32 v9, v0
	v_mov_b32_e32 v10, v0
	v_mov_b32_e32 v11, v0
	v_mov_b32_e32 v12, v0
	v_mov_b32_e32 v13, v0
	v_mov_b32_e32 v14, v0
	v_mov_b32_e32 v15, v0
	v_mov_b32_e32 v24, v0
	v_mov_b32_e32 v25, v0
	v_mov_b32_e32 v26, v0
	v_mov_b32_e32 v27, v0
	v_mov_b32_e32 v28, v0
	v_mov_b32_e32 v29, v0
	v_mov_b32_e32 v30, v0
	v_mov_b32_e32 v31, v0
	v_mov_b32_e32 v40, v0
	v_mov_b32_e32 v41, v0
	v_mov_b32_e32 v42, v0
	v_mov_b32_e32 v43, v0
	v_mov_b32_e32 v44, v0
	v_mov_b32_e32 v45, v0
	v_mov_b32_e32 v46, v0
	v_mov_b32_e32 v47, v0
	v_mov_b32_e32 v56, v0
	v_mov_b32_e32 v57, v0
	v_mov_b32_e32 v58, v0
	v_mov_b32_e32 v59, v0
	v_mov_b32_e32 v60, v0
	v_mov_b32_e32 v61, v0
	v_mov_b32_e32 v62, v0
	v_mov_b32_e32 v63, v0
	v_mov_b32_e32 v64, v0
	v_mov_b32_e32 v65, v0
	v_mov_b32_e32 v66, v0
	v_mov_b32_e32 v67, v0
	v_mov_b32_e32 v68, v0
	v_mov_b32_e32 v69, v0
	v_mov_b32_e32 v70, v0
	v_mov_b32_e32 v71, v0
	v_mov_b32_e32 v80, v0
	v_mov_b32_e32 v81, v0
	v_mov_b32_e32 v82, v0
	v_mov_b32_e32 v83, v0
	v_mov_b32_e32 v84, v0
	v_mov_b32_e32 v85, v0
	v_mov_b32_e32 v86, v0
	v_mov_b32_e32 v87, v0
	v_mov_b32_e32 v96, v0
	v_mov_b32_e32 v97, v0
	v_mov_b32_e32 v98, v0
	v_mov_b32_e32 v99, v0
	v_mov_b32_e32 v100, v0
	v_mov_b32_e32 v101, v0
	v_mov_b32_e32 v102, v0
	v_mov_b32_e32 v103, v0
	v_mov_b32_e32 v112, v0
	v_mov_b32_e32 v113, v0
	v_mov_b32_e32 v114, v0
	v_mov_b32_e32 v115, v0
	v_mov_b32_e32 v116, v0
	v_mov_b32_e32 v117, v0
	v_mov_b32_e32 v118, v0
	v_mov_b32_e32 v119, v0
	v_mov_b32_e32 v72, v0
	v_mov_b32_e32 v73, v0
	v_mov_b32_e32 v74, v0
	v_mov_b32_e32 v75, v0
	v_mov_b32_e32 v76, v0
	v_mov_b32_e32 v77, v0
	v_mov_b32_e32 v78, v0
	v_mov_b32_e32 v79, v0
	v_mov_b32_e32 v88, v0
	v_mov_b32_e32 v89, v0
	v_mov_b32_e32 v90, v0
	v_mov_b32_e32 v91, v0
	v_mov_b32_e32 v92, v0
	v_mov_b32_e32 v93, v0
	v_mov_b32_e32 v94, v0
	v_mov_b32_e32 v95, v0
	v_mov_b32_e32 v104, v0
	v_mov_b32_e32 v105, v0
	v_mov_b32_e32 v106, v0
	v_mov_b32_e32 v107, v0
	v_mov_b32_e32 v108, v0
	v_mov_b32_e32 v109, v0
	v_mov_b32_e32 v110, v0
	v_mov_b32_e32 v111, v0
	v_mov_b32_e32 v120, v0
	v_mov_b32_e32 v121, v0
	v_mov_b32_e32 v122, v0
	v_mov_b32_e32 v123, v0
	v_mov_b32_e32 v124, v0
	v_mov_b32_e32 v125, v0
	v_mov_b32_e32 v126, v0
	v_mov_b32_e32 v127, v0
	s_cmp_eq_u32 s98, 1
	s_cbranch_scc0 .Lkb_skip_0
	s_mov_b32 s98, 0
	s_barrier
.Lkb_skip_0:
.LBB0_80:
	ds_read_b128 v[156:159], v150
	ds_read_b128 v[160:163], v150 offset:1024
	ds_read_b128 v[164:167], v150 offset:2048
	ds_read_b128 v[168:171], v150 offset:3072
	ds_read_b128 v[172:175], v151
	ds_read_b128 v[176:179], v151 offset:1024
	ds_read_b128 v[180:183], v151 offset:2048
	ds_read_b128 v[184:187], v151 offset:3072
	s_add_u32 s26, s48, 0xfff80080
	s_addc_u32 s27, s49, -1
	s_cmp_eq_u32 s76, 28
	s_cselect_b32 s53, s41, s27
	s_cselect_b32 s52, s70, s26
	s_cselect_b32 s51, s39, s75
	s_cselect_b32 s50, s71, s74
	v_lshl_add_u64 v[204:205], s[48:49], 0, v[138:139]
	s_add_i32 m0, s47, 0xc000
	ds_read_b128 v[188:191], v152
	ds_read_b128 v[192:195], v152 offset:1024
	ds_read_b128 v[196:199], v152 offset:2048
	ds_read_b128 v[200:203], v152 offset:3072
	ds_read_b128 v[212:215], v152 offset:4096
	ds_read_b128 v[216:219], v152 offset:5120
	ds_read_b128 v[220:223], v152 offset:6144
	ds_read_b128 v[224:227], v152 offset:7168
	global_load_lds_dwordx4 v[204:205], off
	v_lshl_add_u64 v[204:205], s[48:49], 0, v[140:141]
	s_add_i32 m0, s47, 0xe000
	s_nop 0
	global_load_lds_dwordx4 v[204:205], off
	s_waitcnt vmcnt(8)
	s_waitcnt lgkmcnt(0)
	s_barrier
; #define PG8_STAGE(bufoff, gbase, voff) do { _Pragma("unroll") for (int _i = 0; _i < 2; ++_i) \
;         __builtin_amdgcn_global_load_lds((const unsigned*)((const char*)(gbase) + (voff)[_i]), (PG8_LAS unsigned*)(lds + (bufoff) + ldsw + _i * 8192), 16, 0, 0); } while (0)
; #define PG8_LDA(dst, b, h) do { _Pragma("unroll") for (int m = 0; m < 4; ++m) _Pragma("unroll") for (int k = 0; k < 2; ++k) dst[m][k] = *(const PG8_LAS bf16x8*)(lds + PG8_SA(b, h) + aoff + m * 2048 + k * 1024); } while (0)
; #define PG8_LDB(dst, b, h) do { _Pragma("unroll") for (int n = 0; n < 2; ++n) _Pragma("unroll") for (int k = 0; k < 2; ++k) dst[n][k] = *(const PG8_LAS bf16x8*)(lds + PG8_SB(b, h) + boff + n * 2048 + k * 1024); } while (0)
; #define PG8_MMA(ai, bj, At, Bt) do { __builtin_amdgcn_s_setprio(1); _Pragma("unroll") for (int m = 0; m < 4; ++m) _Pragma("unroll") for (int n = 0; n < 2; ++n) _Pragma("unroll") for (int k = 0; k < 2; ++k) \
;         acc[ai][bj][m][n] = __builtin_amdgcn_mfma_f32_16x16x32_bf16(Bt[n][k], At[m][k], acc[ai][bj][m][n], 0, 0, 0); __builtin_amdgcn_s_setprio(0); } while (0)
; #define PG8_WAIT_V(n) asm volatile("s_waitcnt vmcnt(" #n ")" ::: "memory")
; #define PG8_WAIT_L(n) asm volatile("s_waitcnt lgkmcnt(" #n ")" ::: "memory")
; #define PG8_BAR __builtin_amdgcn_s_barrier()
; #define PG8_SCHED __builtin_amdgcn_sched_barrier(0)
; template <class Epi, class Sched, bool ALIGN_EPI = false, bool SP2 = false>
; __device__ __forceinline__ void gemm_phase(PG8_LAS unsigned char* lds, const Gemm g, const Sched& S, const Epi& E, int tid_in) {
;     ...
;             PG8_LDB(B0, 0, 0); PG8_LDB(B1, 0, 1); PG8_SCHED; PG8_LDA(At, 0, 0); PG8_STAGE(PG8_SA(1, 1), a1 + hstep, voffA);
;             PG8_WAIT_V(8); PG8_WAIT_L(0); PG8_BAR; PG8_MMA(0, 0, At, B0); PG8_MMA(0, 1, At, B1); PG8_BAR; PG8_SCHED;
;             PG8_LDA(At, 0, 1); PG8_STAGE(PG8_SB(0, 0), b2, voffB); PG8_STAGE(PG8_SB(0, 1), b2 + hstepB, voffB); PG8_STAGE(PG8_SA(0, 0), a2, voffA);
;             PG8_WAIT_V(8); PG8_WAIT_L(0); PG8_BAR; PG8_MMA(1, 0, At, B0); PG8_MMA(1, 1, At, B1); PG8_BAR; PG8_SCHED;
	s_setprio 1
	s_waitcnt lgkmcnt(0)
	v_mfma_f32_16x16x32_bf16 v[124:127], v[156:159], v[188:191], v[124:127]
	v_mfma_f32_16x16x32_bf16 v[120:123], v[164:167], v[188:191], v[120:123]
	v_mfma_f32_16x16x32_bf16 v[108:111], v[156:159], v[196:199], v[108:111]
	v_mfma_f32_16x16x32_bf16 v[104:107], v[164:167], v[196:199], v[104:107]
	v_mfma_f32_16x16x32_bf16 v[92:95], v[156:159], v[212:215], v[92:95]
	v_mfma_f32_16x16x32_bf16 v[88:91], v[164:167], v[212:215], v[88:91]
	v_mfma_f32_16x16x32_bf16 v[76:79], v[156:159], v[220:223], v[76:79]
	v_mfma_f32_16x16x32_bf16 v[72:75], v[164:167], v[220:223], v[72:75]
	v_mfma_f32_16x16x32_bf16 v[124:127], v[160:163], v[192:195], v[124:127]
	v_mfma_f32_16x16x32_bf16 v[120:123], v[168:171], v[192:195], v[120:123]
	v_mfma_f32_16x16x32_bf16 v[108:111], v[160:163], v[200:203], v[108:111]
	v_mfma_f32_16x16x32_bf16 v[104:107], v[168:171], v[200:203], v[104:107]
	v_mfma_f32_16x16x32_bf16 v[92:95], v[160:163], v[216:219], v[92:95]
	v_mfma_f32_16x16x32_bf16 v[88:91], v[168:171], v[216:219], v[88:91]
	v_mfma_f32_16x16x32_bf16 v[76:79], v[160:163], v[224:227], v[76:79]
	v_mfma_f32_16x16x32_bf16 v[72:75], v[168:171], v[224:227], v[72:75]
	s_setprio 0
	s_setprio 1
	v_mfma_f32_16x16x32_bf16 v[116:119], v[172:175], v[188:191], v[116:119]
	v_mfma_f32_16x16x32_bf16 v[112:115], v[180:183], v[188:191], v[112:115]
	v_mfma_f32_16x16x32_bf16 v[100:103], v[172:175], v[196:199], v[100:103]
	v_mfma_f32_16x16x32_bf16 v[96:99], v[180:183], v[196:199], v[96:99]
	v_mfma_f32_16x16x32_bf16 v[84:87], v[172:175], v[212:215], v[84:87]
	v_mfma_f32_16x16x32_bf16 v[80:83], v[180:183], v[212:215], v[80:83]
	v_mfma_f32_16x16x32_bf16 v[68:71], v[172:175], v[220:223], v[68:71]
	v_mfma_f32_16x16x32_bf16 v[64:67], v[180:183], v[220:223], v[64:67]
	v_mfma_f32_16x16x32_bf16 v[116:119], v[176:179], v[192:195], v[116:119]
	v_mfma_f32_16x16x32_bf16 v[112:115], v[184:187], v[192:195], v[112:115]
	v_mfma_f32_16x16x32_bf16 v[100:103], v[176:179], v[200:203], v[100:103]
	v_mfma_f32_16x16x32_bf16 v[96:99], v[184:187], v[200:203], v[96:99]
	v_mfma_f32_16x16x32_bf16 v[84:87], v[176:179], v[216:219], v[84:87]
	v_mfma_f32_16x16x32_bf16 v[80:83], v[184:187], v[216:219], v[80:83]
	v_mfma_f32_16x16x32_bf16 v[68:71], v[176:179], v[224:227], v[68:71]
	v_mfma_f32_16x16x32_bf16 v[64:67], v[184:187], v[224:227], v[64:67]
	s_setprio 0
	s_barrier
	s_add_i32 s26, s67, s54
	v_lshl_add_u64 v[204:205], s[50:51], 0, v[132:133]
	s_mov_b32 m0, s26
	ds_read_b128 v[188:191], v152 offset:16384
	ds_read_b128 v[192:195], v152 offset:17408
	ds_read_b128 v[196:199], v152 offset:18432
	ds_read_b128 v[200:203], v152 offset:19456
	ds_read_b128 v[212:215], v152 offset:20480
	ds_read_b128 v[216:219], v152 offset:21504
	ds_read_b128 v[220:223], v152 offset:22528
	ds_read_b128 v[224:227], v152 offset:23552
	global_load_lds_dwordx4 v[204:205], off
	s_add_i32 m0, s26, 0x2000
	s_add_u32 s26, s50, 0x20000
	v_lshl_add_u64 v[206:207], s[50:51], 0, v[128:129]
	s_addc_u32 s27, s51, 0
	s_add_i32 s33, s68, s54
	global_load_lds_dwordx4 v[206:207], off
	v_lshl_add_u64 v[208:209], s[26:27], 0, v[132:133]
	s_mov_b32 m0, s33
	v_lshl_add_u64 v[228:229], s[52:53], 0, v[130:131]
	global_load_lds_dwordx4 v[208:209], off
	v_lshl_add_u64 v[208:209], s[26:27], 0, v[128:129]
	s_add_i32 m0, s33, 0x2000
	s_nop 0
	global_load_lds_dwordx4 v[208:209], off
	v_lshl_add_u64 v[208:209], s[52:53], 0, v[134:135]
	s_mov_b32 m0, s47
	s_nop 0
	global_load_lds_dwordx4 v[208:209], off
	s_mov_b32 m0, s56
	s_nop 0
	global_load_lds_dwordx4 v[228:229], off
	s_waitcnt vmcnt(8)
	s_waitcnt lgkmcnt(0)
	s_barrier
	s_setprio 1
	s_waitcnt lgkmcnt(0)
	v_mfma_f32_16x16x32_bf16 v[60:63], v[156:159], v[188:191], v[60:63]
	v_mfma_f32_16x16x32_bf16 v[56:59], v[164:167], v[188:191], v[56:59]
	v_mfma_f32_16x16x32_bf16 v[44:47], v[156:159], v[196:199], v[44:47]
	v_mfma_f32_16x16x32_bf16 v[40:43], v[164:167], v[196:199], v[40:43]
	v_mfma_f32_16x16x32_bf16 v[28:31], v[156:159], v[212:215], v[28:31]
	v_mfma_f32_16x16x32_bf16 v[24:27], v[164:167], v[212:215], v[24:27]
	v_mfma_f32_16x16x32_bf16 v[12:15], v[156:159], v[220:223], v[12:15]
	v_mfma_f32_16x16x32_bf16 v[8:11], v[164:167], v[220:223], v[8:11]
	v_mfma_f32_16x16x32_bf16 v[60:63], v[160:163], v[192:195], v[60:63]
	v_mfma_f32_16x16x32_bf16 v[56:59], v[168:171], v[192:195], v[56:59]
	v_mfma_f32_16x16x32_bf16 v[44:47], v[160:163], v[200:203], v[44:47]
	v_mfma_f32_16x16x32_bf16 v[40:43], v[168:171], v[200:203], v[40:43]
	v_mfma_f32_16x16x32_bf16 v[28:31], v[160:163], v[216:219], v[28:31]
	v_mfma_f32_16x16x32_bf16 v[24:27], v[168:171], v[216:219], v[24:27]
	v_mfma_f32_16x16x32_bf16 v[12:15], v[160:163], v[224:227], v[12:15]
	v_mfma_f32_16x16x32_bf16 v[8:11], v[168:171], v[224:227], v[8:11]
	s_setprio 0
	s_setprio 1
	v_mfma_f32_16x16x32_bf16 v[52:55], v[172:175], v[188:191], v[52:55]
	v_mfma_f32_16x16x32_bf16 v[48:51], v[180:183], v[188:191], v[48:51]
	v_mfma_f32_16x16x32_bf16 v[36:39], v[172:175], v[196:199], v[36:39]
	v_mfma_f32_16x16x32_bf16 v[32:35], v[180:183], v[196:199], v[32:35]
	v_mfma_f32_16x16x32_bf16 v[20:23], v[172:175], v[212:215], v[20:23]
	v_mfma_f32_16x16x32_bf16 v[16:19], v[180:183], v[212:215], v[16:19]
	v_mfma_f32_16x16x32_bf16 v[4:7], v[172:175], v[220:223], v[4:7]
	v_mfma_f32_16x16x32_bf16 v[0:3], v[180:183], v[220:223], v[0:3]
	v_mfma_f32_16x16x32_bf16 v[52:55], v[176:179], v[192:195], v[52:55]
	v_mfma_f32_16x16x32_bf16 v[48:51], v[184:187], v[192:195], v[48:51]
	v_mfma_f32_16x16x32_bf16 v[36:39], v[176:179], v[200:203], v[36:39]
	v_mfma_f32_16x16x32_bf16 v[32:35], v[184:187], v[200:203], v[32:35]
	v_mfma_f32_16x16x32_bf16 v[20:23], v[176:179], v[216:219], v[20:23]
	v_mfma_f32_16x16x32_bf16 v[16:19], v[184:187], v[216:219], v[16:19]
	v_mfma_f32_16x16x32_bf16 v[4:7], v[176:179], v[224:227], v[4:7]
	v_mfma_f32_16x16x32_bf16 v[0:3], v[184:187], v[224:227], v[0:3]
	s_setprio 0
	s_barrier
; #define PG8_STAGE(bufoff, gbase, voff) do { _Pragma("unroll") for (int _i = 0; _i < 2; ++_i) \
;         __builtin_amdgcn_global_load_lds((const unsigned*)((const char*)(gbase) + (voff)[_i]), (PG8_LAS unsigned*)(lds + (bufoff) + ldsw + _i * 8192), 16, 0, 0); } while (0)
; #define PG8_LDA(dst, b, h) do { _Pragma("unroll") for (int m = 0; m < 4; ++m) _Pragma("unroll") for (int k = 0; k < 2; ++k) dst[m][k] = *(const PG8_LAS bf16x8*)(lds + PG8_SA(b, h) + aoff + m * 2048 + k * 1024); } while (0)
; #define PG8_LDB(dst, b, h) do { _Pragma("unroll") for (int n = 0; n < 2; ++n) _Pragma("unroll") for (int k = 0; k < 2; ++k) dst[n][k] = *(const PG8_LAS bf16x8*)(lds + PG8_SB(b, h) + boff + n * 2048 + k * 1024); } while (0)
; #define PG8_MMA(ai, bj, At, Bt) do { __builtin_amdgcn_s_setprio(1); _Pragma("unroll") for (int m = 0; m < 4; ++m) _Pragma("unroll") for (int n = 0; n < 2; ++n) _Pragma("unroll") for (int k = 0; k < 2; ++k) \
;         acc[ai][bj][m][n] = __builtin_amdgcn_mfma_f32_16x16x32_bf16(Bt[n][k], At[m][k], acc[ai][bj][m][n], 0, 0, 0); __builtin_amdgcn_s_setprio(0); } while (0)
; #define PG8_WAIT_V(n) asm volatile("s_waitcnt vmcnt(" #n ")" ::: "memory")
; #define PG8_WAIT_L(n) asm volatile("s_waitcnt lgkmcnt(" #n ")" ::: "memory")
; #define PG8_BAR __builtin_amdgcn_s_barrier()
; #define PG8_SCHED __builtin_amdgcn_sched_barrier(0)
; template <class Epi, class Sched, bool ALIGN_EPI = false, bool SP2 = false>
; __device__ __forceinline__ void gemm_phase(PG8_LAS unsigned char* lds, const Gemm g, const Sched& S, const Epi& E, int tid_in) {
;     ...
;             PG8_LDB(B0, 1, 0); PG8_LDB(B1, 1, 1); PG8_SCHED; PG8_LDA(At, 1, 0); PG8_STAGE(PG8_SA(0, 1), a2 + hstep, voffA);
;             PG8_WAIT_V(8); PG8_WAIT_L(0); PG8_BAR; PG8_MMA(0, 0, At, B0); PG8_MMA(0, 1, At, B1); PG8_BAR; PG8_SCHED;
;             PG8_LDA(At, 1, 1); PG8_STAGE(PG8_SB(1, 0), b3, voffB); PG8_STAGE(PG8_SB(1, 1), b3 + hstepB, voffB); PG8_STAGE(PG8_SA(1, 0), a3, voffA);
;             PG8_WAIT_V(8); PG8_WAIT_L(0); PG8_BAR; PG8_MMA(1, 0, At, B0); PG8_MMA(1, 1, At, B1); PG8_BAR; PG8_SCHED;
	s_add_i32 s33, 0, 0x18000
	v_add_u32_e32 v155, s33, v146
	s_add_i32 s77, 0, 0x1c000
	ds_read_b128 v[156:159], v155
	ds_read_b128 v[160:163], v155 offset:1024
	ds_read_b128 v[164:167], v155 offset:2048
	ds_read_b128 v[168:171], v155 offset:3072
	v_add_u32_e32 v155, s77, v146
	ds_read_b128 v[172:175], v155
	ds_read_b128 v[176:179], v155 offset:1024
	ds_read_b128 v[180:183], v155 offset:2048
	ds_read_b128 v[184:187], v155 offset:3072
	s_add_u32 s26, s52, 0x80000
	s_addc_u32 s27, s53, 0
	s_mov_b32 m0, s57
	v_lshl_add_u64 v[230:231], s[26:27], 0, v[134:135]
	ds_read_b128 v[188:191], v152 offset:32768
	ds_read_b128 v[192:195], v152 offset:33792
	ds_read_b128 v[196:199], v152 offset:34816
	ds_read_b128 v[200:203], v152 offset:35840
	ds_read_b128 v[212:215], v152 offset:36864
	ds_read_b128 v[216:219], v152 offset:37888
	ds_read_b128 v[220:223], v152 offset:38912
	ds_read_b128 v[224:227], v152 offset:39936
	global_load_lds_dwordx4 v[230:231], off
	v_lshl_add_u64 v[230:231], s[26:27], 0, v[130:131]
	s_mov_b32 m0, s58
	s_nop 0
	global_load_lds_dwordx4 v[230:231], off
	s_waitcnt vmcnt(8)
	s_waitcnt lgkmcnt(0)
	s_barrier
	s_setprio 1
	s_waitcnt lgkmcnt(0)
	v_mfma_f32_16x16x32_bf16 v[124:127], v[156:159], v[188:191], v[124:127]
	v_mfma_f32_16x16x32_bf16 v[120:123], v[164:167], v[188:191], v[120:123]
	v_mfma_f32_16x16x32_bf16 v[108:111], v[156:159], v[196:199], v[108:111]
	v_mfma_f32_16x16x32_bf16 v[104:107], v[164:167], v[196:199], v[104:107]
	v_mfma_f32_16x16x32_bf16 v[92:95], v[156:159], v[212:215], v[92:95]
	v_mfma_f32_16x16x32_bf16 v[88:91], v[164:167], v[212:215], v[88:91]
	v_mfma_f32_16x16x32_bf16 v[76:79], v[156:159], v[220:223], v[76:79]
	v_mfma_f32_16x16x32_bf16 v[72:75], v[164:167], v[220:223], v[72:75]
	v_mfma_f32_16x16x32_bf16 v[124:127], v[160:163], v[192:195], v[124:127]
	v_mfma_f32_16x16x32_bf16 v[120:123], v[168:171], v[192:195], v[120:123]
	v_mfma_f32_16x16x32_bf16 v[108:111], v[160:163], v[200:203], v[108:111]
	v_mfma_f32_16x16x32_bf16 v[104:107], v[168:171], v[200:203], v[104:107]
	v_mfma_f32_16x16x32_bf16 v[92:95], v[160:163], v[216:219], v[92:95]
	v_mfma_f32_16x16x32_bf16 v[88:91], v[168:171], v[216:219], v[88:91]
	v_mfma_f32_16x16x32_bf16 v[76:79], v[160:163], v[224:227], v[76:79]
	v_mfma_f32_16x16x32_bf16 v[72:75], v[168:171], v[224:227], v[72:75]
	s_setprio 0
	s_setprio 1
	v_mfma_f32_16x16x32_bf16 v[116:119], v[172:175], v[188:191], v[116:119]
	v_mfma_f32_16x16x32_bf16 v[112:115], v[180:183], v[188:191], v[112:115]
	v_mfma_f32_16x16x32_bf16 v[100:103], v[172:175], v[196:199], v[100:103]
	v_mfma_f32_16x16x32_bf16 v[96:99], v[180:183], v[196:199], v[96:99]
	v_mfma_f32_16x16x32_bf16 v[84:87], v[172:175], v[212:215], v[84:87]
	v_mfma_f32_16x16x32_bf16 v[80:83], v[180:183], v[212:215], v[80:83]
	v_mfma_f32_16x16x32_bf16 v[68:71], v[172:175], v[220:223], v[68:71]
	v_mfma_f32_16x16x32_bf16 v[64:67], v[180:183], v[220:223], v[64:67]
	v_mfma_f32_16x16x32_bf16 v[116:119], v[176:179], v[192:195], v[116:119]
	v_mfma_f32_16x16x32_bf16 v[112:115], v[184:187], v[192:195], v[112:115]
	v_mfma_f32_16x16x32_bf16 v[100:103], v[176:179], v[200:203], v[100:103]
	v_mfma_f32_16x16x32_bf16 v[96:99], v[184:187], v[200:203], v[96:99]
	v_mfma_f32_16x16x32_bf16 v[84:87], v[176:179], v[216:219], v[84:87]
	v_mfma_f32_16x16x32_bf16 v[80:83], v[184:187], v[216:219], v[80:83]
	v_mfma_f32_16x16x32_bf16 v[68:71], v[176:179], v[224:227], v[68:71]
	v_mfma_f32_16x16x32_bf16 v[64:67], v[184:187], v[224:227], v[64:67]
	s_setprio 0
	s_barrier
	s_add_i32 s26, s33, s54
	v_lshl_add_u64 v[204:205], v[204:205], 0, s[10:11]
	s_mov_b32 m0, s26
	ds_read_b128 v[188:191], v152 offset:49152
	ds_read_b128 v[192:195], v152 offset:50176
	ds_read_b128 v[196:199], v152 offset:51200
	ds_read_b128 v[200:203], v152 offset:52224
	ds_read_b128 v[212:215], v152 offset:53248
	ds_read_b128 v[216:219], v152 offset:54272
	ds_read_b128 v[220:223], v152 offset:55296
	ds_read_b128 v[224:227], v152 offset:56320
	global_load_lds_dwordx4 v[204:205], off
	s_add_i32 m0, s26, 0x2000
	s_add_u32 s26, s50, 0x20080
	v_lshl_add_u64 v[204:205], v[206:207], 0, s[10:11]
	s_addc_u32 s27, s51, 0
	s_add_i32 s33, s77, s54
	global_load_lds_dwordx4 v[204:205], off
	v_lshl_add_u64 v[204:205], s[26:27], 0, v[132:133]
	s_mov_b32 m0, s33
	s_nop 0
	global_load_lds_dwordx4 v[204:205], off
	v_lshl_add_u64 v[204:205], s[26:27], 0, v[128:129]
	s_add_i32 m0, s33, 0x2000
	s_nop 0
	global_load_lds_dwordx4 v[204:205], off
	v_lshl_add_u64 v[204:205], v[208:209], 0, s[10:11]
	s_mov_b32 m0, s61
	s_nop 0
	global_load_lds_dwordx4 v[204:205], off
	v_lshl_add_u64 v[204:205], v[228:229], 0, s[10:11]
	s_mov_b32 m0, s62
	s_nop 0
	global_load_lds_dwordx4 v[204:205], off
	s_waitcnt vmcnt(8)
	s_waitcnt lgkmcnt(0)
	s_barrier
; template <class Epi, class Sched, bool ALIGN_EPI = false, bool SP2 = false>
; __device__ __forceinline__ void gemm_phase(PG8_LAS unsigned char* lds, const Gemm g, const Sched& S, const Epi& E, int tid_in) {
;     ...
;             PG8_WAIT_V(8); PG8_WAIT_L(0); PG8_BAR; PG8_MMA(1, 0, At, B0); PG8_MMA(1, 1, At, B1); PG8_BAR; PG8_SCHED;
;             } else {
;             PG8_LDB(B0, 0, 0); PG8_SCHED; PG8_LDA(At, 0, 0); PG8_STAGE(PG8_SA(1, 1), a1 + hstep, voffA);
;             PG8_WAIT_L(8); PG8_BAR; PG8_WAIT_L(0); PG8_MMA(0, 0, At, B0); PG8_BAR; PG8_SCHED;
;             PG8_LDB(B1, 0, 1); PG8_STAGE(PG8_SB(0, 0), b2, voffB);
;             PG8_BAR; PG8_WAIT_L(0); PG8_MMA(0, 1, At, B1); PG8_BAR;
;             PG8_LDA(At, 0, 1); PG8_STAGE(PG8_SA(0, 0), a2, voffA);
;             PG8_BAR; PG8_WAIT_L(0); PG8_MMA(1, 0, At, B0); PG8_BAR; PG8_SCHED;
;             PG8_STAGE(PG8_SB(0, 1), b2 + hstepB, voffB);
;             PG8_WAIT_V(6); PG8_BAR; PG8_MMA(1, 1, At, B1); PG8_BAR;
;             PG8_LDB(B0, 1, 0); PG8_SCHED; PG8_LDA(At, 1, 0); PG8_STAGE(PG8_SA(0, 1), a2 + hstep, voffA);
;             PG8_WAIT_L(8); PG8_BAR; PG8_WAIT_L(0); PG8_MMA(0, 0, At, B0); PG8_BAR; PG8_SCHED;
;             PG8_LDB(B1, 1, 1); PG8_STAGE(PG8_SB(1, 0), b3, voffB);
;             PG8_BAR; PG8_WAIT_L(0); PG8_MMA(0, 1, At, B1); PG8_BAR;
;             PG8_LDA(At, 1, 1); PG8_STAGE(PG8_SA(1, 0), a3, voffA);
;             PG8_BAR; PG8_WAIT_L(0); PG8_MMA(1, 0, At, B0); PG8_BAR; PG8_SCHED;
;             PG8_STAGE(PG8_SB(1, 1), b3 + hstepB, voffB);
;             PG8_WAIT_V(6); PG8_BAR; PG8_MMA(1, 1, At, B1); PG8_BAR;
;             }
;         }
;         if constexpr (ALIGN_EPI) { if (wr == 0) PG8_BAR; }
;     __device__ __forceinline__ void operator()(const f32x4 (&acc)[2][2][4][2], const Unit& u, int wr, int wc, int fr, int fq) const {
;         const int lane = fr + 16 * fq; PG8_LAS unsigned char* stg = lds + STG_OFF + (wr * 4 + wc) * STG_WAVE;
;         const PG8_LAS float* rtab = (const PG8_LAS float*)(lds + RSTD_OFF) + ((u.pm >> 3) & 3) * 256;
; #pragma unroll
;         for (int ai = 0; ai < 2; ++ai)
; #pragma unroll
;             for (int m = 0; m < 4; ++m) {
;                 const int rowg0 = u.pm * BM + ai * HALF + wr * 64 + m * 16; const float rs = rtab[ai * HALF + wr * 64 + m * 16 + fr];
; #pragma unroll
;                 for (int bj = 0; bj < 2; ++bj) {
	s_setprio 1
	s_waitcnt lgkmcnt(0)
	v_mfma_f32_16x16x32_bf16 v[60:63], v[156:159], v[188:191], v[60:63]
	v_mfma_f32_16x16x32_bf16 v[56:59], v[164:167], v[188:191], v[56:59]
	v_mfma_f32_16x16x32_bf16 v[44:47], v[156:159], v[196:199], v[44:47]
	v_mfma_f32_16x16x32_bf16 v[40:43], v[164:167], v[196:199], v[40:43]
	v_mfma_f32_16x16x32_bf16 v[28:31], v[156:159], v[212:215], v[28:31]
	v_mfma_f32_16x16x32_bf16 v[24:27], v[164:167], v[212:215], v[24:27]
	v_mfma_f32_16x16x32_bf16 v[12:15], v[156:159], v[220:223], v[12:15]
	v_mfma_f32_16x16x32_bf16 v[8:11], v[164:167], v[220:223], v[8:11]
	v_mfma_f32_16x16x32_bf16 v[60:63], v[160:163], v[192:195], v[60:63]
	v_mfma_f32_16x16x32_bf16 v[56:59], v[168:171], v[192:195], v[56:59]
	v_mfma_f32_16x16x32_bf16 v[44:47], v[160:163], v[200:203], v[44:47]
	v_mfma_f32_16x16x32_bf16 v[40:43], v[168:171], v[200:203], v[40:43]
	v_mfma_f32_16x16x32_bf16 v[28:31], v[160:163], v[216:219], v[28:31]
	v_mfma_f32_16x16x32_bf16 v[24:27], v[168:171], v[216:219], v[24:27]
	v_mfma_f32_16x16x32_bf16 v[12:15], v[160:163], v[224:227], v[12:15]
	v_mfma_f32_16x16x32_bf16 v[8:11], v[168:171], v[224:227], v[8:11]
	s_setprio 0
	s_setprio 1
	v_mfma_f32_16x16x32_bf16 v[52:55], v[172:175], v[188:191], v[52:55]
	v_mfma_f32_16x16x32_bf16 v[48:51], v[180:183], v[188:191], v[48:51]
	v_mfma_f32_16x16x32_bf16 v[36:39], v[172:175], v[196:199], v[36:39]
	v_mfma_f32_16x16x32_bf16 v[32:35], v[180:183], v[196:199], v[32:35]
	v_mfma_f32_16x16x32_bf16 v[20:23], v[172:175], v[212:215], v[20:23]
	v_mfma_f32_16x16x32_bf16 v[16:19], v[180:183], v[212:215], v[16:19]
	v_mfma_f32_16x16x32_bf16 v[4:7], v[172:175], v[220:223], v[4:7]
	v_mfma_f32_16x16x32_bf16 v[0:3], v[180:183], v[220:223], v[0:3]
	v_mfma_f32_16x16x32_bf16 v[52:55], v[176:179], v[192:195], v[52:55]
	v_mfma_f32_16x16x32_bf16 v[48:51], v[184:187], v[192:195], v[48:51]
	v_mfma_f32_16x16x32_bf16 v[36:39], v[176:179], v[200:203], v[36:39]
	v_mfma_f32_16x16x32_bf16 v[32:35], v[184:187], v[200:203], v[32:35]
	v_mfma_f32_16x16x32_bf16 v[20:23], v[176:179], v[216:219], v[20:23]
	v_mfma_f32_16x16x32_bf16 v[16:19], v[184:187], v[216:219], v[16:19]
	v_mfma_f32_16x16x32_bf16 v[4:7], v[176:179], v[224:227], v[4:7]
	v_mfma_f32_16x16x32_bf16 v[0:3], v[184:187], v[224:227], v[0:3]
	s_setprio 0
	s_barrier
	s_add_i32 s76, s76, 2
	s_add_u32 s48, s48, 0x100
	s_addc_u32 s49, s49, 0
	s_add_u32 s74, s74, 0x100
	s_addc_u32 s75, s75, 0
	s_cmp_gt_u32 s76, 29
	s_cbranch_scc0 .LBB0_80
	s_and_b64 vcc, exec, s[14:15]
	s_cbranch_vccz .LBB0_83
	s_barrier
.LBB0_83:
	s_lshl_b32 s26, s46, 7
	s_and_b32 s26, s26, 0xc00
	v_add_u32_e32 v155, s26, v147
	ds_read_b32 v156, v155
	s_lshl_b32 s41, s46, 8
	s_lshl_b32 s26, s69, 1
	s_add_i32 s39, s41, s60
	s_or_b32 s26, s26, s63
	s_waitcnt lgkmcnt(0)
	v_pk_mul_f32 v[126:127], v[126:127], v[156:157] op_sel_hi:[1,0]
	v_pk_mul_f32 v[124:125], v[124:125], v[156:157] op_sel_hi:[1,0]
	v_pk_mul_f32 v[158:159], v[122:123], v[156:157] op_sel_hi:[1,0]
	v_pk_mul_f32 v[122:123], v[120:121], v[156:157] op_sel_hi:[1,0]
	v_cvt_pk_bf16_f32 v120, v124, v125
	v_cvt_pk_bf16_f32 v121, v126, v127
	v_pk_mul_f32 v[118:119], v[118:119], v[156:157] op_sel_hi:[1,0]
	v_cvt_pk_bf16_f32 v122, v122, v123
	v_cvt_pk_bf16_f32 v123, v158, v159
	ds_write_b128 v153, v[120:123]
	v_pk_mul_f32 v[120:121], v[114:115], v[156:157] op_sel_hi:[1,0]
	v_pk_mul_f32 v[114:115], v[112:113], v[156:157] op_sel_hi:[1,0]
	v_pk_mul_f32 v[116:117], v[116:117], v[156:157] op_sel_hi:[1,0]
	s_ashr_i32 s27, s26, 31
	v_cvt_pk_bf16_f32 v112, v116, v117
	v_cvt_pk_bf16_f32 v113, v118, v119
	v_cvt_pk_bf16_f32 v114, v114, v115
	v_cvt_pk_bf16_f32 v115, v120, v121
	ds_write_b128 v153, v[112:115] offset:64
	ds_read_b128 v[114:117], v154
	ds_read_b32 v120, v155 offset:64
	v_or_b32_e32 v118, s39, v148
	s_lshl_b64 s[26:27], s[26:27], 23
	v_ashrrev_i32_e32 v119, 31, v118
	v_lshl_add_u64 v[112:113], v[136:137], 0, s[26:27]
	v_lshlrev_b64 v[118:119], 8, v[118:119]
	v_lshl_add_u64 v[118:119], v[112:113], 0, v[118:119]
	s_waitcnt lgkmcnt(0)
	global_store_dwordx4 v[118:119], v[114:117], off nt
	ds_read_b128 v[114:117], v154 offset:1152
	v_or_b32_e32 v118, s39, v149
	v_ashrrev_i32_e32 v119, 31, v118
	v_lshlrev_b64 v[118:119], 8, v[118:119]
	v_lshl_add_u64 v[118:119], v[112:113], 0, v[118:119]
	s_waitcnt lgkmcnt(0)
	global_store_dwordx4 v[118:119], v[114:117], off nt
	v_pk_mul_f32 v[110:111], v[110:111], v[120:121] op_sel_hi:[1,0]
	v_pk_mul_f32 v[108:109], v[108:109], v[120:121] op_sel_hi:[1,0]
	v_pk_mul_f32 v[114:115], v[106:107], v[120:121] op_sel_hi:[1,0]
	v_pk_mul_f32 v[106:107], v[104:105], v[120:121] op_sel_hi:[1,0]
	v_cvt_pk_bf16_f32 v104, v108, v109
	v_cvt_pk_bf16_f32 v105, v110, v111
	v_pk_mul_f32 v[102:103], v[102:103], v[120:121] op_sel_hi:[1,0]
	v_cvt_pk_bf16_f32 v106, v106, v107
	v_cvt_pk_bf16_f32 v107, v114, v115
	ds_write_b128 v153, v[104:107]
	v_pk_mul_f32 v[104:105], v[98:99], v[120:121] op_sel_hi:[1,0]
	v_pk_mul_f32 v[98:99], v[96:97], v[120:121] op_sel_hi:[1,0]
	v_pk_mul_f32 v[100:101], v[100:101], v[120:121] op_sel_hi:[1,0]
	s_add_i32 s26, s41, s64
	v_cvt_pk_bf16_f32 v96, v100, v101
	v_cvt_pk_bf16_f32 v97, v102, v103
	v_cvt_pk_bf16_f32 v98, v98, v99
	v_cvt_pk_bf16_f32 v99, v104, v105
	ds_write_b128 v153, v[96:99] offset:64
	ds_read_b128 v[96:99], v154
	ds_read_b32 v102, v155 offset:128
	v_or_b32_e32 v100, s26, v148
	v_ashrrev_i32_e32 v101, 31, v100
	v_lshlrev_b64 v[100:101], 8, v[100:101]
	v_lshl_add_u64 v[100:101], v[112:113], 0, v[100:101]
	s_waitcnt lgkmcnt(0)
	global_store_dwordx4 v[100:101], v[96:99], off nt
	ds_read_b128 v[96:99], v154 offset:1152
	v_or_b32_e32 v100, s26, v149
	v_ashrrev_i32_e32 v101, 31, v100
	v_lshlrev_b64 v[100:101], 8, v[100:101]
	v_lshl_add_u64 v[100:101], v[112:113], 0, v[100:101]
	s_waitcnt lgkmcnt(0)
; #define PG8_LAS __attribute__((address_space(3)))
; __device__ __forceinline__ unsigned cvt_pk_bf16(float lo, float hi) { unsigned r; asm volatile("v_cvt_pk_bf16_f32 %0, %1, %2" : "=v"(r) : "v"(lo), "v"(hi)); return r; }
; template <int LAYOUT> __device__ __forceinline__ void staged_store_bf16(PG8_LAS unsigned char* stg, bf16_t* O, size_t ldc, int rowg0, int pn, int wc, int lane) {
;     const int p = lane & 7;
; #pragma unroll
;     for (int hr = 0; hr < 2; ++hr) { const int r = 8 * hr + (lane >> 3), rowg = rowg0 + r; const u32x4 w = *(const PG8_LAS u32x4*)(stg + r * STG_ROW + p * 16);
;         if (LAYOUT == 0) __builtin_nontemporal_store(w, (u32x4*)(O + (size_t)rowg * ldc + pn * BM + wc * 64 + p * 8));
;         else { const int P = 2 * pn + (wc >> 1); int drow = rowg;
;             if (LAYOUT == 2) { const int sh = 2 * (P / 24), t = rowg & 16383; drow = (rowg & ~16383) + ((t & ((1 << sh) - 1)) << (14 - sh)) + (t >> sh); }
;             __builtin_nontemporal_store(w, (u32x4*)(O + (size_t)P * PLANE + (size_t)drow * 128 + (wc & 1) * 64 + p * 8)); } }
; }
;     __device__ __forceinline__ void operator()(const f32x4 (&acc)[2][2][4][2], const Unit& u, int wr, int wc, int fr, int fq) const {
;         const int lane = fr + 16 * fq; PG8_LAS unsigned char* stg = lds + STG_OFF + (wr * 4 + wc) * STG_WAVE;
;         const PG8_LAS float* rtab = (const PG8_LAS float*)(lds + RSTD_OFF) + ((u.pm >> 3) & 3) * 256;
; #pragma unroll
;         for (int ai = 0; ai < 2; ++ai)
; #pragma unroll
;             for (int m = 0; m < 4; ++m) {
;                 const int rowg0 = u.pm * BM + ai * HALF + wr * 64 + m * 16; const float rs = rtab[ai * HALF + wr * 64 + m * 16 + fr];
; #pragma unroll
;                 for (int bj = 0; bj < 2; ++bj) {
;                     f32x4 v0 = acc[ai][bj][m][0] * rs, v1 = acc[ai][bj][m][1] * rs;
;                     if (ACT == 1) { const f32x4 z = {0.f, 0.f, 0.f, 0.f}; v0 = __builtin_elementwise_max(v0, z); v1 = __builtin_elementwise_max(v1, z); v0 = v0 * v0; v1 = v1 * v1; }
;                     u32x4 w; w.x = cvt_pk_bf16(v0[0], v0[1]); w.y = cvt_pk_bf16(v0[2], v0[3]); w.z = cvt_pk_bf16(v1[0], v1[1]); w.w = cvt_pk_bf16(v1[2], v1[3]);
;                     *(PG8_LAS u32x4*)(stg + fr * STG_ROW + bj * 64 + fq * 16) = w; }
;                 staged_store_bf16<LAYOUT>(stg, O, (size_t)ldc, rowg0, u.pn, wc, lane);
	global_store_dwordx4 v[100:101], v[96:99], off nt
	v_pk_mul_f32 v[94:95], v[94:95], v[102:103] op_sel_hi:[1,0]
	v_pk_mul_f32 v[92:93], v[92:93], v[102:103] op_sel_hi:[1,0]
	v_pk_mul_f32 v[96:97], v[90:91], v[102:103] op_sel_hi:[1,0]
	v_pk_mul_f32 v[90:91], v[88:89], v[102:103] op_sel_hi:[1,0]
	v_cvt_pk_bf16_f32 v88, v92, v93
	v_cvt_pk_bf16_f32 v89, v94, v95
	v_pk_mul_f32 v[86:87], v[86:87], v[102:103] op_sel_hi:[1,0]
	v_cvt_pk_bf16_f32 v90, v90, v91
	v_cvt_pk_bf16_f32 v91, v96, v97
	ds_write_b128 v153, v[88:91]
	v_pk_mul_f32 v[88:89], v[82:83], v[102:103] op_sel_hi:[1,0]
	v_pk_mul_f32 v[82:83], v[80:81], v[102:103] op_sel_hi:[1,0]
	v_pk_mul_f32 v[84:85], v[84:85], v[102:103] op_sel_hi:[1,0]
	s_add_i32 s26, s41, s65
	v_cvt_pk_bf16_f32 v80, v84, v85
	v_cvt_pk_bf16_f32 v81, v86, v87
	v_cvt_pk_bf16_f32 v82, v82, v83
	v_cvt_pk_bf16_f32 v83, v88, v89
	ds_write_b128 v153, v[80:83] offset:64
	ds_read_b128 v[80:83], v154
	ds_read_b32 v86, v155 offset:192
	v_or_b32_e32 v84, s26, v148
	v_ashrrev_i32_e32 v85, 31, v84
	v_lshlrev_b64 v[84:85], 8, v[84:85]
	v_lshl_add_u64 v[84:85], v[112:113], 0, v[84:85]
	s_waitcnt lgkmcnt(0)
	global_store_dwordx4 v[84:85], v[80:83], off nt
	ds_read_b128 v[80:83], v154 offset:1152
	v_or_b32_e32 v84, s26, v149
	v_ashrrev_i32_e32 v85, 31, v84
	v_lshlrev_b64 v[84:85], 8, v[84:85]
	v_lshl_add_u64 v[84:85], v[112:113], 0, v[84:85]
	s_waitcnt lgkmcnt(0)
	global_store_dwordx4 v[84:85], v[80:83], off nt
	v_pk_mul_f32 v[78:79], v[78:79], v[86:87] op_sel_hi:[1,0]
	v_pk_mul_f32 v[76:77], v[76:77], v[86:87] op_sel_hi:[1,0]
	v_pk_mul_f32 v[80:81], v[74:75], v[86:87] op_sel_hi:[1,0]
	v_pk_mul_f32 v[74:75], v[72:73], v[86:87] op_sel_hi:[1,0]
	v_cvt_pk_bf16_f32 v72, v76, v77
	v_cvt_pk_bf16_f32 v73, v78, v79
	v_pk_mul_f32 v[70:71], v[70:71], v[86:87] op_sel_hi:[1,0]
	v_cvt_pk_bf16_f32 v74, v74, v75
	v_cvt_pk_bf16_f32 v75, v80, v81
	ds_write_b128 v153, v[72:75]
	v_pk_mul_f32 v[72:73], v[66:67], v[86:87] op_sel_hi:[1,0]
	v_pk_mul_f32 v[66:67], v[64:65], v[86:87] op_sel_hi:[1,0]
	v_pk_mul_f32 v[68:69], v[68:69], v[86:87] op_sel_hi:[1,0]
	s_add_i32 s41, s41, s66
	v_cvt_pk_bf16_f32 v64, v68, v69
	v_cvt_pk_bf16_f32 v65, v70, v71
	v_cvt_pk_bf16_f32 v66, v66, v67
	v_cvt_pk_bf16_f32 v67, v72, v73
	ds_write_b128 v153, v[64:67] offset:64
	ds_read_b128 v[64:67], v154
	ds_read_b32 v70, v155 offset:512
	v_or_b32_e32 v68, s41, v148
	v_ashrrev_i32_e32 v69, 31, v68
	v_lshlrev_b64 v[68:69], 8, v[68:69]
	v_lshl_add_u64 v[68:69], v[112:113], 0, v[68:69]
	s_waitcnt lgkmcnt(0)
	global_store_dwordx4 v[68:69], v[64:67], off nt
	ds_read_b128 v[64:67], v154 offset:1152
	v_or_b32_e32 v68, s41, v149
	v_ashrrev_i32_e32 v69, 31, v68
	v_lshlrev_b64 v[68:69], 8, v[68:69]
	v_lshl_add_u64 v[68:69], v[112:113], 0, v[68:69]
	s_waitcnt lgkmcnt(0)
	global_store_dwordx4 v[68:69], v[64:67], off nt
	v_pk_mul_f32 v[62:63], v[62:63], v[70:71] op_sel_hi:[1,0]
	v_pk_mul_f32 v[60:61], v[60:61], v[70:71] op_sel_hi:[1,0]
	v_pk_mul_f32 v[64:65], v[58:59], v[70:71] op_sel_hi:[1,0]
	v_pk_mul_f32 v[58:59], v[56:57], v[70:71] op_sel_hi:[1,0]
	v_cvt_pk_bf16_f32 v56, v60, v61
	v_cvt_pk_bf16_f32 v57, v62, v63
	v_pk_mul_f32 v[54:55], v[54:55], v[70:71] op_sel_hi:[1,0]
	v_cvt_pk_bf16_f32 v58, v58, v59
	v_cvt_pk_bf16_f32 v59, v64, v65
	ds_write_b128 v153, v[56:59]
	v_pk_mul_f32 v[56:57], v[50:51], v[70:71] op_sel_hi:[1,0]
	v_pk_mul_f32 v[50:51], v[48:49], v[70:71] op_sel_hi:[1,0]
	v_pk_mul_f32 v[52:53], v[52:53], v[70:71] op_sel_hi:[1,0]
	s_add_i32 s26, s39, 0x80
	v_cvt_pk_bf16_f32 v48, v52, v53
	v_cvt_pk_bf16_f32 v49, v54, v55
	v_cvt_pk_bf16_f32 v50, v50, v51
	v_cvt_pk_bf16_f32 v51, v56, v57
	ds_write_b128 v153, v[48:51] offset:64
	ds_read_b128 v[48:51], v154
	ds_read_b32 v54, v155 offset:576
	v_or_b32_e32 v52, s26, v148
	v_ashrrev_i32_e32 v53, 31, v52
	v_lshlrev_b64 v[52:53], 8, v[52:53]
	v_lshl_add_u64 v[52:53], v[112:113], 0, v[52:53]
	s_waitcnt lgkmcnt(0)
	global_store_dwordx4 v[52:53], v[48:51], off nt
	ds_read_b128 v[48:51], v154 offset:1152
	v_or_b32_e32 v52, s26, v149
	v_ashrrev_i32_e32 v53, 31, v52
	v_lshlrev_b64 v[52:53], 8, v[52:53]
	v_lshl_add_u64 v[52:53], v[112:113], 0, v[52:53]
	s_waitcnt lgkmcnt(0)
; #define PG8_LAS __attribute__((address_space(3)))
; __device__ __forceinline__ unsigned cvt_pk_bf16(float lo, float hi) { unsigned r; asm volatile("v_cvt_pk_bf16_f32 %0, %1, %2" : "=v"(r) : "v"(lo), "v"(hi)); return r; }
; template <int LAYOUT> __device__ __forceinline__ void staged_store_bf16(PG8_LAS unsigned char* stg, bf16_t* O, size_t ldc, int rowg0, int pn, int wc, int lane) {
;     const int p = lane & 7;
; #pragma unroll
;     for (int hr = 0; hr < 2; ++hr) { const int r = 8 * hr + (lane >> 3), rowg = rowg0 + r; const u32x4 w = *(const PG8_LAS u32x4*)(stg + r * STG_ROW + p * 16);
;         if (LAYOUT == 0) __builtin_nontemporal_store(w, (u32x4*)(O + (size_t)rowg * ldc + pn * BM + wc * 64 + p * 8));
;         else { const int P = 2 * pn + (wc >> 1); int drow = rowg;
;             if (LAYOUT == 2) { const int sh = 2 * (P / 24), t = rowg & 16383; drow = (rowg & ~16383) + ((t & ((1 << sh) - 1)) << (14 - sh)) + (t >> sh); }
;             __builtin_nontemporal_store(w, (u32x4*)(O + (size_t)P * PLANE + (size_t)drow * 128 + (wc & 1) * 64 + p * 8)); } }
; }
;     __device__ __forceinline__ void operator()(const f32x4 (&acc)[2][2][4][2], const Unit& u, int wr, int wc, int fr, int fq) const {
;         const int lane = fr + 16 * fq; PG8_LAS unsigned char* stg = lds + STG_OFF + (wr * 4 + wc) * STG_WAVE;
;         const PG8_LAS float* rtab = (const PG8_LAS float*)(lds + RSTD_OFF) + ((u.pm >> 3) & 3) * 256;
; #pragma unroll
;         for (int ai = 0; ai < 2; ++ai)
; #pragma unroll
;             for (int m = 0; m < 4; ++m) {
;                 const int rowg0 = u.pm * BM + ai * HALF + wr * 64 + m * 16; const float rs = rtab[ai * HALF + wr * 64 + m * 16 + fr];
; #pragma unroll
;                 for (int bj = 0; bj < 2; ++bj) {
;                     f32x4 v0 = acc[ai][bj][m][0] * rs, v1 = acc[ai][bj][m][1] * rs;
;                     if (ACT == 1) { const f32x4 z = {0.f, 0.f, 0.f, 0.f}; v0 = __builtin_elementwise_max(v0, z); v1 = __builtin_elementwise_max(v1, z); v0 = v0 * v0; v1 = v1 * v1; }
;                     u32x4 w; w.x = cvt_pk_bf16(v0[0], v0[1]); w.y = cvt_pk_bf16(v0[2], v0[3]); w.z = cvt_pk_bf16(v1[0], v1[1]); w.w = cvt_pk_bf16(v1[2], v1[3]);
;                     *(PG8_LAS u32x4*)(stg + fr * STG_ROW + bj * 64 + fq * 16) = w; }
;                 staged_store_bf16<LAYOUT>(stg, O, (size_t)ldc, rowg0, u.pn, wc, lane);
	global_store_dwordx4 v[52:53], v[48:51], off nt
	v_pk_mul_f32 v[46:47], v[46:47], v[54:55] op_sel_hi:[1,0]
	v_pk_mul_f32 v[44:45], v[44:45], v[54:55] op_sel_hi:[1,0]
	v_pk_mul_f32 v[48:49], v[42:43], v[54:55] op_sel_hi:[1,0]
	v_pk_mul_f32 v[42:43], v[40:41], v[54:55] op_sel_hi:[1,0]
	v_cvt_pk_bf16_f32 v40, v44, v45
	v_cvt_pk_bf16_f32 v41, v46, v47
	v_pk_mul_f32 v[38:39], v[38:39], v[54:55] op_sel_hi:[1,0]
	v_cvt_pk_bf16_f32 v42, v42, v43
	v_cvt_pk_bf16_f32 v43, v48, v49
	ds_write_b128 v153, v[40:43]
	v_pk_mul_f32 v[40:41], v[34:35], v[54:55] op_sel_hi:[1,0]
	v_pk_mul_f32 v[34:35], v[32:33], v[54:55] op_sel_hi:[1,0]
	v_pk_mul_f32 v[36:37], v[36:37], v[54:55] op_sel_hi:[1,0]
	s_add_i32 s26, s39, 0x90
	v_cvt_pk_bf16_f32 v32, v36, v37
	v_cvt_pk_bf16_f32 v33, v38, v39
	v_cvt_pk_bf16_f32 v34, v34, v35
	v_cvt_pk_bf16_f32 v35, v40, v41
	ds_write_b128 v153, v[32:35] offset:64
	ds_read_b128 v[32:35], v154
	ds_read_b32 v38, v155 offset:640
	v_or_b32_e32 v36, s26, v148
	v_ashrrev_i32_e32 v37, 31, v36
	v_lshlrev_b64 v[36:37], 8, v[36:37]
	v_lshl_add_u64 v[36:37], v[112:113], 0, v[36:37]
	s_waitcnt lgkmcnt(0)
	global_store_dwordx4 v[36:37], v[32:35], off nt
	ds_read_b128 v[32:35], v154 offset:1152
	v_or_b32_e32 v36, s26, v149
	v_ashrrev_i32_e32 v37, 31, v36
	v_lshlrev_b64 v[36:37], 8, v[36:37]
	v_lshl_add_u64 v[36:37], v[112:113], 0, v[36:37]
	s_waitcnt lgkmcnt(0)
	global_store_dwordx4 v[36:37], v[32:35], off nt
	v_pk_mul_f32 v[30:31], v[30:31], v[38:39] op_sel_hi:[1,0]
	v_pk_mul_f32 v[28:29], v[28:29], v[38:39] op_sel_hi:[1,0]
	v_pk_mul_f32 v[32:33], v[26:27], v[38:39] op_sel_hi:[1,0]
	v_pk_mul_f32 v[26:27], v[24:25], v[38:39] op_sel_hi:[1,0]
	v_cvt_pk_bf16_f32 v24, v28, v29
	v_cvt_pk_bf16_f32 v25, v30, v31
	v_pk_mul_f32 v[22:23], v[22:23], v[38:39] op_sel_hi:[1,0]
	v_cvt_pk_bf16_f32 v26, v26, v27
	v_cvt_pk_bf16_f32 v27, v32, v33
	ds_write_b128 v153, v[24:27]
	v_pk_mul_f32 v[24:25], v[18:19], v[38:39] op_sel_hi:[1,0]
	v_pk_mul_f32 v[18:19], v[16:17], v[38:39] op_sel_hi:[1,0]
	v_pk_mul_f32 v[20:21], v[20:21], v[38:39] op_sel_hi:[1,0]
	s_add_i32 s26, s39, 0xa0
	v_cvt_pk_bf16_f32 v16, v20, v21
	v_cvt_pk_bf16_f32 v17, v22, v23
	v_cvt_pk_bf16_f32 v18, v18, v19
	v_cvt_pk_bf16_f32 v19, v24, v25
	ds_write_b128 v153, v[16:19] offset:64
	ds_read_b128 v[16:19], v154
	ds_read_b32 v22, v155 offset:704
	v_or_b32_e32 v20, s26, v148
	v_ashrrev_i32_e32 v21, 31, v20
	v_lshlrev_b64 v[20:21], 8, v[20:21]
	v_lshl_add_u64 v[20:21], v[112:113], 0, v[20:21]
	s_waitcnt lgkmcnt(0)
	global_store_dwordx4 v[20:21], v[16:19], off nt
	ds_read_b128 v[16:19], v154 offset:1152
	v_or_b32_e32 v20, s26, v149
	v_ashrrev_i32_e32 v21, 31, v20
	v_lshlrev_b64 v[20:21], 8, v[20:21]
	v_lshl_add_u64 v[20:21], v[112:113], 0, v[20:21]
	s_waitcnt lgkmcnt(0)
	global_store_dwordx4 v[20:21], v[16:19], off nt
	v_pk_mul_f32 v[14:15], v[14:15], v[22:23] op_sel_hi:[1,0]
	v_pk_mul_f32 v[12:13], v[12:13], v[22:23] op_sel_hi:[1,0]
	v_pk_mul_f32 v[16:17], v[10:11], v[22:23] op_sel_hi:[1,0]
	v_pk_mul_f32 v[10:11], v[8:9], v[22:23] op_sel_hi:[1,0]
	v_cvt_pk_bf16_f32 v8, v12, v13
	v_cvt_pk_bf16_f32 v9, v14, v15
	v_pk_mul_f32 v[6:7], v[6:7], v[22:23] op_sel_hi:[1,0]
	v_cvt_pk_bf16_f32 v10, v10, v11
	v_cvt_pk_bf16_f32 v11, v16, v17
	ds_write_b128 v153, v[8:11]
	v_pk_mul_f32 v[8:9], v[2:3], v[22:23] op_sel_hi:[1,0]
	v_pk_mul_f32 v[2:3], v[0:1], v[22:23] op_sel_hi:[1,0]
	v_pk_mul_f32 v[4:5], v[4:5], v[22:23] op_sel_hi:[1,0]
	s_addk_i32 s39, 0xb0
	v_cvt_pk_bf16_f32 v0, v4, v5
	v_cvt_pk_bf16_f32 v1, v6, v7
	v_cvt_pk_bf16_f32 v2, v2, v3
	v_cvt_pk_bf16_f32 v3, v8, v9
	ds_write_b128 v153, v[0:3] offset:64
	ds_read_b128 v[0:3], v154
	v_or_b32_e32 v4, s39, v148
	v_ashrrev_i32_e32 v5, 31, v4
	v_lshlrev_b64 v[4:5], 8, v[4:5]
	v_lshl_add_u64 v[8:9], v[112:113], 0, v[4:5]
	ds_read_b128 v[4:7], v154 offset:1152
	s_waitcnt lgkmcnt(0)
	global_store_dwordx4 v[8:9], v[0:3], off nt
	s_andn2_b64 vcc, exec, s[6:7]
	s_mov_b64 s[6:7], -1
	v_or_b32_e32 v0, s39, v149
	v_ashrrev_i32_e32 v1, 31, v0
	v_lshlrev_b64 v[0:1], 8, v[0:1]
	v_lshl_add_u64 v[0:1], v[112:113], 0, v[0:1]
	global_store_dwordx4 v[0:1], v[4:7], off nt
	s_cbranch_vccnz .LBB0_76
	s_andn2_b64 vcc, exec, s[8:9]
	s_cbranch_vccnz .LBB0_75
	s_mov_b32 s98, 1
	s_branch .LBB0_75

; #define PG8_STAGE(bufoff, gbase, voff) do { _Pragma("unroll") for (int _i = 0; _i < 2; ++_i) \
;         __builtin_amdgcn_global_load_lds((const unsigned*)((const char*)(gbase) + (voff)[_i]), (PG8_LAS unsigned*)(lds + (bufoff) + ldsw + _i * 8192), 16, 0, 0); } while (0)
; #define PG8_LDA(dst, b, h) do { _Pragma("unroll") for (int m = 0; m < 4; ++m) _Pragma("unroll") for (int k = 0; k < 2; ++k) dst[m][k] = *(const PG8_LAS bf16x8*)(lds + PG8_SA(b, h) + aoff + m * 2048 + k * 1024); } while (0)
; #define PG8_LDB(dst, b, h) do { _Pragma("unroll") for (int n = 0; n < 2; ++n) _Pragma("unroll") for (int k = 0; k < 2; ++k) dst[n][k] = *(const PG8_LAS bf16x8*)(lds + PG8_SB(b, h) + boff + n * 2048 + k * 1024); } while (0)
; #define PG8_BAR __builtin_amdgcn_s_barrier()
; #define PG8_SCHED __builtin_amdgcn_sched_barrier(0)
; template <class Epi, class Sched, bool ALIGN_EPI = false, bool SP2 = false>
; __device__ __forceinline__ void gemm_phase(PG8_LAS unsigned char* lds, const Gemm g, const Sched& S, const Epi& E, int tid_in) {
;     ...
;         const bool has_next = S.next(ui + 1, nxt);
;         const char* nA = has_next ? (const char*)g.A + (size_t)nxt.pm * tstep : cA; const char* nB = has_next ? (const char*)g.Bt + (size_t)nxt.pn * tstepB : cB;
;         for (int t = 0; t < nt; t += 2) {
;             const bool last = (t == nt - 2);
;             const char* a1 = cA + (size_t)(t + 1) * kstep;
;             const char* a2 = last ? nA : cA + (size_t)(t + 2) * kstep; const char* b2 = last ? nB : cB + (size_t)(t + 2) * kstep;
;             const char* a3 = a2 + kstep; const char* b3 = b2 + kstep;
;             if (last && has_next) S.a_ready(nxt);
;             if constexpr (SP2) {
;             PG8_LDB(B0, 0, 0); PG8_LDB(B1, 0, 1); PG8_SCHED; PG8_LDA(At, 0, 0); PG8_STAGE(PG8_SA(1, 1), a1 + hstep, voffA);
;     ...
; #pragma unroll
;         for (int a = 0; a < 2; ++a)
; #pragma unroll
;             for (int b = 0; b < 2; ++b)
; #pragma unroll
;                 for (int m = 0; m < 4; ++m)
; #pragma unroll
;                     for (int n = 0; n < 2; ++n) acc[a][b][m][n] = (f32x4){0.f, 0.f, 0.f, 0.f};
;         cur = nxt; cA = nA; cB = nB; ++ui;
;         if constexpr (ALIGN_EPI) { if (wr == 1) PG8_BAR; }
.LBB0_291:
	s_ashr_i32 s49, s48, 31
	s_lshl_b64 s[26:27], s[48:49], 20
	s_add_u32 s50, s28, s26
	s_addc_u32 s51, s29, s27
	s_and_b64 s[26:27], s[10:11], exec
	s_cselect_b32 s49, s51, s59
	s_cselect_b32 s55, s50, s58
	s_ashr_i32 s47, s46, 31
	s_lshl_b64 s[26:27], s[46:47], 20
	s_add_u32 s52, s64, s26
	s_addc_u32 s53, s65, s27
	s_and_b64 s[26:27], s[10:11], exec
	s_cselect_b32 s47, s53, s61
	s_cselect_b32 s75, s52, s60
	s_add_u32 s58, s58, 0x80080
	s_addc_u32 s59, s59, 0
	s_add_u32 s76, s60, 0x100
	v_mov_b32_e32 v0, 0
	s_addc_u32 s77, s61, 0
	s_mov_b32 s79, -2
	s_waitcnt lgkmcnt(0)
	v_mov_b32_e32 v1, v0
	v_mov_b32_e32 v2, v0
	v_mov_b32_e32 v3, v0
	v_mov_b32_e32 v4, v0
	v_mov_b32_e32 v5, v0
	v_mov_b32_e32 v6, v0
	v_mov_b32_e32 v7, v0
	v_mov_b32_e32 v16, v0
	v_mov_b32_e32 v17, v0
	v_mov_b32_e32 v18, v0
	v_mov_b32_e32 v19, v0
	v_mov_b32_e32 v20, v0
	v_mov_b32_e32 v21, v0
	v_mov_b32_e32 v22, v0
	v_mov_b32_e32 v23, v0
	v_mov_b32_e32 v32, v0
	v_mov_b32_e32 v33, v0
	v_mov_b32_e32 v34, v0
	v_mov_b32_e32 v35, v0
	v_mov_b32_e32 v36, v0
	v_mov_b32_e32 v37, v0
	v_mov_b32_e32 v38, v0
	v_mov_b32_e32 v39, v0
	v_mov_b32_e32 v48, v0
	v_mov_b32_e32 v49, v0
	v_mov_b32_e32 v50, v0
	v_mov_b32_e32 v51, v0
	v_mov_b32_e32 v52, v0
	v_mov_b32_e32 v53, v0
	v_mov_b32_e32 v54, v0
	v_mov_b32_e32 v55, v0
	v_mov_b32_e32 v8, v0
	v_mov_b32_e32 v9, v0
	v_mov_b32_e32 v10, v0
	v_mov_b32_e32 v11, v0
	v_mov_b32_e32 v12, v0
	v_mov_b32_e32 v13, v0
	v_mov_b32_e32 v14, v0
	v_mov_b32_e32 v15, v0
	v_mov_b32_e32 v24, v0
	v_mov_b32_e32 v25, v0
	v_mov_b32_e32 v26, v0
	v_mov_b32_e32 v27, v0
	v_mov_b32_e32 v28, v0
	v_mov_b32_e32 v29, v0
	v_mov_b32_e32 v30, v0
	v_mov_b32_e32 v31, v0
	v_mov_b32_e32 v40, v0
	v_mov_b32_e32 v41, v0
	v_mov_b32_e32 v42, v0
	v_mov_b32_e32 v43, v0
	v_mov_b32_e32 v44, v0
	v_mov_b32_e32 v45, v0
	v_mov_b32_e32 v46, v0
	v_mov_b32_e32 v47, v0
	v_mov_b32_e32 v56, v0
	v_mov_b32_e32 v57, v0
	v_mov_b32_e32 v58, v0
	v_mov_b32_e32 v59, v0
	v_mov_b32_e32 v60, v0
	v_mov_b32_e32 v61, v0
	v_mov_b32_e32 v62, v0
	v_mov_b32_e32 v63, v0
	v_mov_b32_e32 v64, v0
	v_mov_b32_e32 v65, v0
	v_mov_b32_e32 v66, v0
	v_mov_b32_e32 v67, v0
	v_mov_b32_e32 v68, v0
	v_mov_b32_e32 v69, v0
	v_mov_b32_e32 v70, v0
	v_mov_b32_e32 v71, v0
	v_mov_b32_e32 v80, v0
	v_mov_b32_e32 v81, v0
	v_mov_b32_e32 v82, v0
	v_mov_b32_e32 v83, v0
	v_mov_b32_e32 v84, v0
	v_mov_b32_e32 v85, v0
	v_mov_b32_e32 v86, v0
	v_mov_b32_e32 v87, v0
	v_mov_b32_e32 v96, v0
	v_mov_b32_e32 v97, v0
	v_mov_b32_e32 v98, v0
	v_mov_b32_e32 v99, v0
	v_mov_b32_e32 v100, v0
	v_mov_b32_e32 v101, v0
	v_mov_b32_e32 v102, v0
	v_mov_b32_e32 v103, v0
	v_mov_b32_e32 v112, v0
	v_mov_b32_e32 v113, v0
	v_mov_b32_e32 v114, v0
	v_mov_b32_e32 v115, v0
	v_mov_b32_e32 v116, v0
	v_mov_b32_e32 v117, v0
	v_mov_b32_e32 v118, v0
	v_mov_b32_e32 v119, v0
	v_mov_b32_e32 v72, v0
	v_mov_b32_e32 v73, v0
	v_mov_b32_e32 v74, v0
	v_mov_b32_e32 v75, v0
	v_mov_b32_e32 v76, v0
	v_mov_b32_e32 v77, v0
	v_mov_b32_e32 v78, v0
	v_mov_b32_e32 v79, v0
	v_mov_b32_e32 v88, v0
	v_mov_b32_e32 v89, v0
	v_mov_b32_e32 v90, v0
	v_mov_b32_e32 v91, v0
	v_mov_b32_e32 v92, v0
	v_mov_b32_e32 v93, v0
	v_mov_b32_e32 v94, v0
	v_mov_b32_e32 v95, v0
	v_mov_b32_e32 v104, v0
	v_mov_b32_e32 v105, v0
	v_mov_b32_e32 v106, v0
	v_mov_b32_e32 v107, v0
	v_mov_b32_e32 v108, v0
	v_mov_b32_e32 v109, v0
	v_mov_b32_e32 v110, v0
	v_mov_b32_e32 v111, v0
	v_mov_b32_e32 v120, v0
	v_mov_b32_e32 v121, v0
	v_mov_b32_e32 v122, v0
	v_mov_b32_e32 v123, v0
	v_mov_b32_e32 v124, v0
	v_mov_b32_e32 v125, v0
	v_mov_b32_e32 v126, v0
	v_mov_b32_e32 v127, v0
	s_cmp_eq_u32 s98, 1
	s_cbranch_scc0 .Lkb_skip_1
	s_mov_b32 s98, 0
	s_barrier
.Lkb_skip_1:
.LBB0_292:
	ds_read_b128 v[146:149], v153
	ds_read_b128 v[158:161], v153 offset:1024
	ds_read_b128 v[162:165], v153 offset:2048
	ds_read_b128 v[166:169], v153 offset:3072
	ds_read_b128 v[170:173], v154
	ds_read_b128 v[174:177], v154 offset:1024
	ds_read_b128 v[178:181], v154 offset:2048
	ds_read_b128 v[182:185], v154 offset:3072
	s_add_u32 s26, s58, 0xfff80080
	s_addc_u32 s27, s59, -1
	s_cmp_eq_u32 s79, 28
	s_cselect_b32 s63, s49, s27
	s_cselect_b32 s62, s55, s26
	s_cselect_b32 s61, s47, s77
	s_cselect_b32 s60, s75, s76
	v_lshl_add_u64 v[220:221], s[58:59], 0, v[138:139]
	s_add_i32 m0, s57, 0xc000
	ds_read_b128 v[186:189], v155
	ds_read_b128 v[190:193], v155 offset:1024
	ds_read_b128 v[194:197], v155 offset:2048
	ds_read_b128 v[198:201], v155 offset:3072
	ds_read_b128 v[202:205], v155 offset:4096
	ds_read_b128 v[206:209], v155 offset:5120
	ds_read_b128 v[212:215], v155 offset:6144
	ds_read_b128 v[216:219], v155 offset:7168
	global_load_lds_dwordx4 v[220:221], off
	v_lshl_add_u64 v[220:221], s[58:59], 0, v[140:141]
	s_add_i32 m0, s57, 0xe000
	s_nop 0
	global_load_lds_dwordx4 v[220:221], off
	s_waitcnt vmcnt(8)
	s_waitcnt lgkmcnt(0)
	s_barrier
; #define PG8_STAGE(bufoff, gbase, voff) do { _Pragma("unroll") for (int _i = 0; _i < 2; ++_i) \
;         __builtin_amdgcn_global_load_lds((const unsigned*)((const char*)(gbase) + (voff)[_i]), (PG8_LAS unsigned*)(lds + (bufoff) + ldsw + _i * 8192), 16, 0, 0); } while (0)
; #define PG8_LDA(dst, b, h) do { _Pragma("unroll") for (int m = 0; m < 4; ++m) _Pragma("unroll") for (int k = 0; k < 2; ++k) dst[m][k] = *(const PG8_LAS bf16x8*)(lds + PG8_SA(b, h) + aoff + m * 2048 + k * 1024); } while (0)
; #define PG8_LDB(dst, b, h) do { _Pragma("unroll") for (int n = 0; n < 2; ++n) _Pragma("unroll") for (int k = 0; k < 2; ++k) dst[n][k] = *(const PG8_LAS bf16x8*)(lds + PG8_SB(b, h) + boff + n * 2048 + k * 1024); } while (0)
; #define PG8_MMA(ai, bj, At, Bt) do { __builtin_amdgcn_s_setprio(1); _Pragma("unroll") for (int m = 0; m < 4; ++m) _Pragma("unroll") for (int n = 0; n < 2; ++n) _Pragma("unroll") for (int k = 0; k < 2; ++k) \
;         acc[ai][bj][m][n] = __builtin_amdgcn_mfma_f32_16x16x32_bf16(Bt[n][k], At[m][k], acc[ai][bj][m][n], 0, 0, 0); __builtin_amdgcn_s_setprio(0); } while (0)
; #define PG8_WAIT_V(n) asm volatile("s_waitcnt vmcnt(" #n ")" ::: "memory")
; #define PG8_WAIT_L(n) asm volatile("s_waitcnt lgkmcnt(" #n ")" ::: "memory")
; #define PG8_BAR __builtin_amdgcn_s_barrier()
; #define PG8_SCHED __builtin_amdgcn_sched_barrier(0)
; template <class Epi, class Sched, bool ALIGN_EPI = false, bool SP2 = false>
; __device__ __forceinline__ void gemm_phase(PG8_LAS unsigned char* lds, const Gemm g, const Sched& S, const Epi& E, int tid_in) {
;     ...
;             PG8_LDB(B0, 0, 0); PG8_LDB(B1, 0, 1); PG8_SCHED; PG8_LDA(At, 0, 0); PG8_STAGE(PG8_SA(1, 1), a1 + hstep, voffA);
;             PG8_WAIT_V(8); PG8_WAIT_L(0); PG8_BAR; PG8_MMA(0, 0, At, B0); PG8_MMA(0, 1, At, B1); PG8_BAR; PG8_SCHED;
;             PG8_LDA(At, 0, 1); PG8_STAGE(PG8_SB(0, 0), b2, voffB); PG8_STAGE(PG8_SB(0, 1), b2 + hstepB, voffB); PG8_STAGE(PG8_SA(0, 0), a2, voffA);
;             PG8_WAIT_V(8); PG8_WAIT_L(0); PG8_BAR; PG8_MMA(1, 0, At, B0); PG8_MMA(1, 1, At, B1); PG8_BAR; PG8_SCHED;
	s_setprio 1
	s_waitcnt lgkmcnt(0)
	v_mfma_f32_16x16x32_bf16 v[124:127], v[146:149], v[186:189], v[124:127]
	v_mfma_f32_16x16x32_bf16 v[120:123], v[162:165], v[186:189], v[120:123]
	v_mfma_f32_16x16x32_bf16 v[108:111], v[146:149], v[194:197], v[108:111]
	v_mfma_f32_16x16x32_bf16 v[104:107], v[162:165], v[194:197], v[104:107]
	v_mfma_f32_16x16x32_bf16 v[92:95], v[146:149], v[202:205], v[92:95]
	v_mfma_f32_16x16x32_bf16 v[88:91], v[162:165], v[202:205], v[88:91]
	v_mfma_f32_16x16x32_bf16 v[76:79], v[146:149], v[212:215], v[76:79]
	v_mfma_f32_16x16x32_bf16 v[72:75], v[162:165], v[212:215], v[72:75]
	v_mfma_f32_16x16x32_bf16 v[124:127], v[158:161], v[190:193], v[124:127]
	v_mfma_f32_16x16x32_bf16 v[120:123], v[166:169], v[190:193], v[120:123]
	v_mfma_f32_16x16x32_bf16 v[108:111], v[158:161], v[198:201], v[108:111]
	v_mfma_f32_16x16x32_bf16 v[104:107], v[166:169], v[198:201], v[104:107]
	v_mfma_f32_16x16x32_bf16 v[92:95], v[158:161], v[206:209], v[92:95]
	v_mfma_f32_16x16x32_bf16 v[88:91], v[166:169], v[206:209], v[88:91]
	v_mfma_f32_16x16x32_bf16 v[76:79], v[158:161], v[216:219], v[76:79]
	v_mfma_f32_16x16x32_bf16 v[72:75], v[166:169], v[216:219], v[72:75]
	s_setprio 0
	s_setprio 1
	v_mfma_f32_16x16x32_bf16 v[116:119], v[170:173], v[186:189], v[116:119]
	v_mfma_f32_16x16x32_bf16 v[112:115], v[178:181], v[186:189], v[112:115]
	v_mfma_f32_16x16x32_bf16 v[100:103], v[170:173], v[194:197], v[100:103]
	v_mfma_f32_16x16x32_bf16 v[96:99], v[178:181], v[194:197], v[96:99]
	v_mfma_f32_16x16x32_bf16 v[84:87], v[170:173], v[202:205], v[84:87]
	v_mfma_f32_16x16x32_bf16 v[80:83], v[178:181], v[202:205], v[80:83]
	v_mfma_f32_16x16x32_bf16 v[68:71], v[170:173], v[212:215], v[68:71]
	v_mfma_f32_16x16x32_bf16 v[64:67], v[178:181], v[212:215], v[64:67]
	v_mfma_f32_16x16x32_bf16 v[116:119], v[174:177], v[190:193], v[116:119]
	v_mfma_f32_16x16x32_bf16 v[112:115], v[182:185], v[190:193], v[112:115]
	v_mfma_f32_16x16x32_bf16 v[100:103], v[174:177], v[198:201], v[100:103]
	v_mfma_f32_16x16x32_bf16 v[96:99], v[182:185], v[198:201], v[96:99]
	v_mfma_f32_16x16x32_bf16 v[84:87], v[174:177], v[206:209], v[84:87]
	v_mfma_f32_16x16x32_bf16 v[80:83], v[182:185], v[206:209], v[80:83]
	v_mfma_f32_16x16x32_bf16 v[68:71], v[174:177], v[216:219], v[68:71]
	v_mfma_f32_16x16x32_bf16 v[64:67], v[182:185], v[216:219], v[64:67]
	s_setprio 0
	s_barrier
	s_add_i32 s26, s73, s66
	v_lshl_add_u64 v[220:221], s[60:61], 0, v[130:131]
	s_mov_b32 m0, s26
	ds_read_b128 v[186:189], v155 offset:16384
	ds_read_b128 v[190:193], v155 offset:17408
	ds_read_b128 v[194:197], v155 offset:18432
	ds_read_b128 v[198:201], v155 offset:19456
	ds_read_b128 v[202:205], v155 offset:20480
	ds_read_b128 v[206:209], v155 offset:21504
	ds_read_b128 v[212:215], v155 offset:22528
	ds_read_b128 v[216:219], v155 offset:23552
	global_load_lds_dwordx4 v[220:221], off
	s_add_i32 m0, s26, 0x2000
	s_add_u32 s26, s60, 0x20000
	v_lshl_add_u64 v[222:223], s[60:61], 0, v[134:135]
	s_addc_u32 s27, s61, 0
	s_add_i32 s33, s74, s66
	global_load_lds_dwordx4 v[222:223], off
	v_lshl_add_u64 v[224:225], s[26:27], 0, v[130:131]
	s_mov_b32 m0, s33
	v_lshl_add_u64 v[226:227], s[62:63], 0, v[132:133]
	global_load_lds_dwordx4 v[224:225], off
	v_lshl_add_u64 v[224:225], s[26:27], 0, v[134:135]
	s_add_i32 m0, s33, 0x2000
	s_nop 0
	global_load_lds_dwordx4 v[224:225], off
	v_lshl_add_u64 v[224:225], s[62:63], 0, v[128:129]
	s_mov_b32 m0, s57
	s_nop 0
	global_load_lds_dwordx4 v[224:225], off
	s_mov_b32 m0, s67
	s_nop 0
	global_load_lds_dwordx4 v[226:227], off
	s_waitcnt vmcnt(8)
	s_waitcnt lgkmcnt(0)
	s_barrier
	s_setprio 1
	s_waitcnt lgkmcnt(0)
	v_mfma_f32_16x16x32_bf16 v[60:63], v[146:149], v[186:189], v[60:63]
	v_mfma_f32_16x16x32_bf16 v[56:59], v[162:165], v[186:189], v[56:59]
	v_mfma_f32_16x16x32_bf16 v[44:47], v[146:149], v[194:197], v[44:47]
	v_mfma_f32_16x16x32_bf16 v[40:43], v[162:165], v[194:197], v[40:43]
	v_mfma_f32_16x16x32_bf16 v[28:31], v[146:149], v[202:205], v[28:31]
	v_mfma_f32_16x16x32_bf16 v[24:27], v[162:165], v[202:205], v[24:27]
	v_mfma_f32_16x16x32_bf16 v[12:15], v[146:149], v[212:215], v[12:15]
	v_mfma_f32_16x16x32_bf16 v[8:11], v[162:165], v[212:215], v[8:11]
	v_mfma_f32_16x16x32_bf16 v[60:63], v[158:161], v[190:193], v[60:63]
	v_mfma_f32_16x16x32_bf16 v[56:59], v[166:169], v[190:193], v[56:59]
	v_mfma_f32_16x16x32_bf16 v[44:47], v[158:161], v[198:201], v[44:47]
	v_mfma_f32_16x16x32_bf16 v[40:43], v[166:169], v[198:201], v[40:43]
	v_mfma_f32_16x16x32_bf16 v[28:31], v[158:161], v[206:209], v[28:31]
	v_mfma_f32_16x16x32_bf16 v[24:27], v[166:169], v[206:209], v[24:27]
	v_mfma_f32_16x16x32_bf16 v[12:15], v[158:161], v[216:219], v[12:15]
	v_mfma_f32_16x16x32_bf16 v[8:11], v[166:169], v[216:219], v[8:11]
	s_setprio 0
	s_setprio 1
	v_mfma_f32_16x16x32_bf16 v[52:55], v[170:173], v[186:189], v[52:55]
	v_mfma_f32_16x16x32_bf16 v[48:51], v[178:181], v[186:189], v[48:51]
	v_mfma_f32_16x16x32_bf16 v[36:39], v[170:173], v[194:197], v[36:39]
	v_mfma_f32_16x16x32_bf16 v[32:35], v[178:181], v[194:197], v[32:35]
	v_mfma_f32_16x16x32_bf16 v[20:23], v[170:173], v[202:205], v[20:23]
	v_mfma_f32_16x16x32_bf16 v[16:19], v[178:181], v[202:205], v[16:19]
	v_mfma_f32_16x16x32_bf16 v[4:7], v[170:173], v[212:215], v[4:7]
	v_mfma_f32_16x16x32_bf16 v[0:3], v[178:181], v[212:215], v[0:3]
	v_mfma_f32_16x16x32_bf16 v[52:55], v[174:177], v[190:193], v[52:55]
	v_mfma_f32_16x16x32_bf16 v[48:51], v[182:185], v[190:193], v[48:51]
	v_mfma_f32_16x16x32_bf16 v[36:39], v[174:177], v[198:201], v[36:39]
	v_mfma_f32_16x16x32_bf16 v[32:35], v[182:185], v[198:201], v[32:35]
	v_mfma_f32_16x16x32_bf16 v[20:23], v[174:177], v[206:209], v[20:23]
	v_mfma_f32_16x16x32_bf16 v[16:19], v[182:185], v[206:209], v[16:19]
	v_mfma_f32_16x16x32_bf16 v[4:7], v[174:177], v[216:219], v[4:7]
	v_mfma_f32_16x16x32_bf16 v[0:3], v[182:185], v[216:219], v[0:3]
	s_setprio 0
	s_barrier
; #define PG8_STAGE(bufoff, gbase, voff) do { _Pragma("unroll") for (int _i = 0; _i < 2; ++_i) \
;         __builtin_amdgcn_global_load_lds((const unsigned*)((const char*)(gbase) + (voff)[_i]), (PG8_LAS unsigned*)(lds + (bufoff) + ldsw + _i * 8192), 16, 0, 0); } while (0)
; #define PG8_LDA(dst, b, h) do { _Pragma("unroll") for (int m = 0; m < 4; ++m) _Pragma("unroll") for (int k = 0; k < 2; ++k) dst[m][k] = *(const PG8_LAS bf16x8*)(lds + PG8_SA(b, h) + aoff + m * 2048 + k * 1024); } while (0)
; #define PG8_LDB(dst, b, h) do { _Pragma("unroll") for (int n = 0; n < 2; ++n) _Pragma("unroll") for (int k = 0; k < 2; ++k) dst[n][k] = *(const PG8_LAS bf16x8*)(lds + PG8_SB(b, h) + boff + n * 2048 + k * 1024); } while (0)
; #define PG8_MMA(ai, bj, At, Bt) do { __builtin_amdgcn_s_setprio(1); _Pragma("unroll") for (int m = 0; m < 4; ++m) _Pragma("unroll") for (int n = 0; n < 2; ++n) _Pragma("unroll") for (int k = 0; k < 2; ++k) \
;         acc[ai][bj][m][n] = __builtin_amdgcn_mfma_f32_16x16x32_bf16(Bt[n][k], At[m][k], acc[ai][bj][m][n], 0, 0, 0); __builtin_amdgcn_s_setprio(0); } while (0)
; #define PG8_WAIT_V(n) asm volatile("s_waitcnt vmcnt(" #n ")" ::: "memory")
; #define PG8_WAIT_L(n) asm volatile("s_waitcnt lgkmcnt(" #n ")" ::: "memory")
; #define PG8_BAR __builtin_amdgcn_s_barrier()
; #define PG8_SCHED __builtin_amdgcn_sched_barrier(0)
; template <class Epi, class Sched, bool ALIGN_EPI = false, bool SP2 = false>
; __device__ __forceinline__ void gemm_phase(PG8_LAS unsigned char* lds, const Gemm g, const Sched& S, const Epi& E, int tid_in) {
;     ...
;             PG8_LDB(B0, 1, 0); PG8_LDB(B1, 1, 1); PG8_SCHED; PG8_LDA(At, 1, 0); PG8_STAGE(PG8_SA(0, 1), a2 + hstep, voffA);
;             PG8_WAIT_V(8); PG8_WAIT_L(0); PG8_BAR; PG8_MMA(0, 0, At, B0); PG8_MMA(0, 1, At, B1); PG8_BAR; PG8_SCHED;
;             PG8_LDA(At, 1, 1); PG8_STAGE(PG8_SB(1, 0), b3, voffB); PG8_STAGE(PG8_SB(1, 1), b3 + hstepB, voffB); PG8_STAGE(PG8_SA(1, 0), a3, voffA);
;             PG8_WAIT_V(8); PG8_WAIT_L(0); PG8_BAR; PG8_MMA(1, 0, At, B0); PG8_MMA(1, 1, At, B1); PG8_BAR; PG8_SCHED;
	s_add_i32 s33, 0, 0x18000
	s_add_i32 s84, 0, 0x1c000
	v_add_u32_e32 v166, s33, v137
	v_add_u32_e32 v182, s84, v137
	ds_read_b128 v[146:149], v166
	ds_read_b128 v[158:161], v166 offset:1024
	ds_read_b128 v[162:165], v166 offset:2048
	ds_read_b128 v[166:169], v166 offset:3072
	ds_read_b128 v[170:173], v182
	ds_read_b128 v[174:177], v182 offset:1024
	ds_read_b128 v[178:181], v182 offset:2048
	ds_read_b128 v[182:185], v182 offset:3072
	s_add_u32 s26, s62, 0x80000
	s_addc_u32 s27, s63, 0
	s_mov_b32 m0, s68
	v_lshl_add_u64 v[228:229], s[26:27], 0, v[128:129]
	ds_read_b128 v[186:189], v155 offset:32768
	ds_read_b128 v[190:193], v155 offset:33792
	ds_read_b128 v[194:197], v155 offset:34816
	ds_read_b128 v[198:201], v155 offset:35840
	ds_read_b128 v[202:205], v155 offset:36864
	ds_read_b128 v[206:209], v155 offset:37888
	ds_read_b128 v[212:215], v155 offset:38912
	ds_read_b128 v[216:219], v155 offset:39936
	global_load_lds_dwordx4 v[228:229], off
	v_lshl_add_u64 v[228:229], s[26:27], 0, v[132:133]
	s_mov_b32 m0, s69
	s_nop 0
	global_load_lds_dwordx4 v[228:229], off
	s_waitcnt vmcnt(8)
	s_waitcnt lgkmcnt(0)
	s_barrier
	s_setprio 1
	s_waitcnt lgkmcnt(0)
	v_mfma_f32_16x16x32_bf16 v[124:127], v[146:149], v[186:189], v[124:127]
	v_mfma_f32_16x16x32_bf16 v[120:123], v[162:165], v[186:189], v[120:123]
	v_mfma_f32_16x16x32_bf16 v[108:111], v[146:149], v[194:197], v[108:111]
	v_mfma_f32_16x16x32_bf16 v[104:107], v[162:165], v[194:197], v[104:107]
	v_mfma_f32_16x16x32_bf16 v[92:95], v[146:149], v[202:205], v[92:95]
	v_mfma_f32_16x16x32_bf16 v[88:91], v[162:165], v[202:205], v[88:91]
	v_mfma_f32_16x16x32_bf16 v[76:79], v[146:149], v[212:215], v[76:79]
	v_mfma_f32_16x16x32_bf16 v[72:75], v[162:165], v[212:215], v[72:75]
	v_mfma_f32_16x16x32_bf16 v[124:127], v[158:161], v[190:193], v[124:127]
	v_mfma_f32_16x16x32_bf16 v[120:123], v[166:169], v[190:193], v[120:123]
	v_mfma_f32_16x16x32_bf16 v[108:111], v[158:161], v[198:201], v[108:111]
	v_mfma_f32_16x16x32_bf16 v[104:107], v[166:169], v[198:201], v[104:107]
	v_mfma_f32_16x16x32_bf16 v[92:95], v[158:161], v[206:209], v[92:95]
	v_mfma_f32_16x16x32_bf16 v[88:91], v[166:169], v[206:209], v[88:91]
	v_mfma_f32_16x16x32_bf16 v[76:79], v[158:161], v[216:219], v[76:79]
	v_mfma_f32_16x16x32_bf16 v[72:75], v[166:169], v[216:219], v[72:75]
	s_setprio 0
	s_setprio 1
	v_mfma_f32_16x16x32_bf16 v[116:119], v[170:173], v[186:189], v[116:119]
	v_mfma_f32_16x16x32_bf16 v[112:115], v[178:181], v[186:189], v[112:115]
	v_mfma_f32_16x16x32_bf16 v[100:103], v[170:173], v[194:197], v[100:103]
	v_mfma_f32_16x16x32_bf16 v[96:99], v[178:181], v[194:197], v[96:99]
	v_mfma_f32_16x16x32_bf16 v[84:87], v[170:173], v[202:205], v[84:87]
	v_mfma_f32_16x16x32_bf16 v[80:83], v[178:181], v[202:205], v[80:83]
	v_mfma_f32_16x16x32_bf16 v[68:71], v[170:173], v[212:215], v[68:71]
	v_mfma_f32_16x16x32_bf16 v[64:67], v[178:181], v[212:215], v[64:67]
	v_mfma_f32_16x16x32_bf16 v[116:119], v[174:177], v[190:193], v[116:119]
	v_mfma_f32_16x16x32_bf16 v[112:115], v[182:185], v[190:193], v[112:115]
	v_mfma_f32_16x16x32_bf16 v[100:103], v[174:177], v[198:201], v[100:103]
	v_mfma_f32_16x16x32_bf16 v[96:99], v[182:185], v[198:201], v[96:99]
	v_mfma_f32_16x16x32_bf16 v[84:87], v[174:177], v[206:209], v[84:87]
	v_mfma_f32_16x16x32_bf16 v[80:83], v[182:185], v[206:209], v[80:83]
	v_mfma_f32_16x16x32_bf16 v[68:71], v[174:177], v[216:219], v[68:71]
	v_mfma_f32_16x16x32_bf16 v[64:67], v[182:185], v[216:219], v[64:67]
	s_setprio 0
	s_barrier
	s_add_i32 s26, s33, s66
	v_lshl_add_u64 v[220:221], v[220:221], 0, s[42:43]
	s_mov_b32 m0, s26
	ds_read_b128 v[186:189], v155 offset:49152
	ds_read_b128 v[190:193], v155 offset:50176
	ds_read_b128 v[194:197], v155 offset:51200
	ds_read_b128 v[198:201], v155 offset:52224
	ds_read_b128 v[202:205], v155 offset:53248
	ds_read_b128 v[206:209], v155 offset:54272
	ds_read_b128 v[212:215], v155 offset:55296
	ds_read_b128 v[216:219], v155 offset:56320
	global_load_lds_dwordx4 v[220:221], off
	s_add_i32 m0, s26, 0x2000
	s_add_u32 s26, s60, 0x20080
	v_lshl_add_u64 v[220:221], v[222:223], 0, s[42:43]
	s_addc_u32 s27, s61, 0
	s_add_i32 s33, s84, s66
	global_load_lds_dwordx4 v[220:221], off
	v_lshl_add_u64 v[220:221], s[26:27], 0, v[130:131]
	s_mov_b32 m0, s33
	s_nop 0
	global_load_lds_dwordx4 v[220:221], off
	v_lshl_add_u64 v[220:221], s[26:27], 0, v[134:135]
	s_add_i32 m0, s33, 0x2000
	s_nop 0
	global_load_lds_dwordx4 v[220:221], off
	v_lshl_add_u64 v[220:221], v[224:225], 0, s[42:43]
	s_mov_b32 m0, s71
	s_nop 0
	global_load_lds_dwordx4 v[220:221], off
	v_lshl_add_u64 v[220:221], v[226:227], 0, s[42:43]
	s_mov_b32 m0, s72
	s_nop 0
	global_load_lds_dwordx4 v[220:221], off
	s_waitcnt vmcnt(8)
	s_waitcnt lgkmcnt(0)
	s_barrier
; template <class Epi, class Sched, bool ALIGN_EPI = false, bool SP2 = false>
; __device__ __forceinline__ void gemm_phase(PG8_LAS unsigned char* lds, const Gemm g, const Sched& S, const Epi& E, int tid_in) {
;     ...
;             PG8_WAIT_V(8); PG8_WAIT_L(0); PG8_BAR; PG8_MMA(1, 0, At, B0); PG8_MMA(1, 1, At, B1); PG8_BAR; PG8_SCHED;
;             } else {
;             PG8_LDB(B0, 0, 0); PG8_SCHED; PG8_LDA(At, 0, 0); PG8_STAGE(PG8_SA(1, 1), a1 + hstep, voffA);
;             PG8_WAIT_L(8); PG8_BAR; PG8_WAIT_L(0); PG8_MMA(0, 0, At, B0); PG8_BAR; PG8_SCHED;
;             PG8_LDB(B1, 0, 1); PG8_STAGE(PG8_SB(0, 0), b2, voffB);
;             PG8_BAR; PG8_WAIT_L(0); PG8_MMA(0, 1, At, B1); PG8_BAR;
;             PG8_LDA(At, 0, 1); PG8_STAGE(PG8_SA(0, 0), a2, voffA);
;             PG8_BAR; PG8_WAIT_L(0); PG8_MMA(1, 0, At, B0); PG8_BAR; PG8_SCHED;
;             PG8_STAGE(PG8_SB(0, 1), b2 + hstepB, voffB);
;             PG8_WAIT_V(6); PG8_BAR; PG8_MMA(1, 1, At, B1); PG8_BAR;
;             PG8_LDB(B0, 1, 0); PG8_SCHED; PG8_LDA(At, 1, 0); PG8_STAGE(PG8_SA(0, 1), a2 + hstep, voffA);
;             PG8_WAIT_L(8); PG8_BAR; PG8_WAIT_L(0); PG8_MMA(0, 0, At, B0); PG8_BAR; PG8_SCHED;
;             PG8_LDB(B1, 1, 1); PG8_STAGE(PG8_SB(1, 0), b3, voffB);
;             PG8_BAR; PG8_WAIT_L(0); PG8_MMA(0, 1, At, B1); PG8_BAR;
;             PG8_LDA(At, 1, 1); PG8_STAGE(PG8_SA(1, 0), a3, voffA);
;             PG8_BAR; PG8_WAIT_L(0); PG8_MMA(1, 0, At, B0); PG8_BAR; PG8_SCHED;
;             PG8_STAGE(PG8_SB(1, 1), b3 + hstepB, voffB);
;             PG8_WAIT_V(6); PG8_BAR; PG8_MMA(1, 1, At, B1); PG8_BAR;
;             }
;         }
;         if constexpr (ALIGN_EPI) { if (wr == 0) PG8_BAR; }
;     __device__ __forceinline__ void operator()(const f32x4 (&acc)[2][2][4][2], const Unit& u, int wr, int wc, int fr, int fq) const {
;         const int lane = fr + 16 * fq, r = lane >> 2, p = lane & 3; PG8_LAS unsigned char* stg = lds + STG_OFF + (wr * 4 + wc) * STG_WAVE;
; #pragma unroll
;         for (int ai = 0; ai < 2; ++ai)
; #pragma unroll
;             for (int m = 0; m < 4; ++m) {
;                 const int row = u.pm * BM + ai * HALF + wr * 64 + m * 16 + r; float q = 0.f;
; #pragma unroll
;                 for (int bj = 0; bj < 2; ++bj) {
;                     const size_t off = (size_t)row * 2048 + u.pn * BM + wc * 64 + bj * 32 + 8 * p;
;                     f32x4 b0, b1;
	s_setprio 1
	s_waitcnt lgkmcnt(0)
	v_mfma_f32_16x16x32_bf16 v[60:63], v[146:149], v[186:189], v[60:63]
	v_mfma_f32_16x16x32_bf16 v[56:59], v[162:165], v[186:189], v[56:59]
	v_mfma_f32_16x16x32_bf16 v[44:47], v[146:149], v[194:197], v[44:47]
	v_mfma_f32_16x16x32_bf16 v[40:43], v[162:165], v[194:197], v[40:43]
	v_mfma_f32_16x16x32_bf16 v[28:31], v[146:149], v[202:205], v[28:31]
	v_mfma_f32_16x16x32_bf16 v[24:27], v[162:165], v[202:205], v[24:27]
	v_mfma_f32_16x16x32_bf16 v[12:15], v[146:149], v[212:215], v[12:15]
	v_mfma_f32_16x16x32_bf16 v[8:11], v[162:165], v[212:215], v[8:11]
	v_mfma_f32_16x16x32_bf16 v[60:63], v[158:161], v[190:193], v[60:63]
	v_mfma_f32_16x16x32_bf16 v[56:59], v[166:169], v[190:193], v[56:59]
	v_mfma_f32_16x16x32_bf16 v[44:47], v[158:161], v[198:201], v[44:47]
	v_mfma_f32_16x16x32_bf16 v[40:43], v[166:169], v[198:201], v[40:43]
	v_mfma_f32_16x16x32_bf16 v[28:31], v[158:161], v[206:209], v[28:31]
	v_mfma_f32_16x16x32_bf16 v[24:27], v[166:169], v[206:209], v[24:27]
	v_mfma_f32_16x16x32_bf16 v[12:15], v[158:161], v[216:219], v[12:15]
	v_mfma_f32_16x16x32_bf16 v[8:11], v[166:169], v[216:219], v[8:11]
	s_setprio 0
	s_setprio 1
	v_mfma_f32_16x16x32_bf16 v[52:55], v[170:173], v[186:189], v[52:55]
	v_mfma_f32_16x16x32_bf16 v[48:51], v[178:181], v[186:189], v[48:51]
	v_mfma_f32_16x16x32_bf16 v[36:39], v[170:173], v[194:197], v[36:39]
	v_mfma_f32_16x16x32_bf16 v[32:35], v[178:181], v[194:197], v[32:35]
	v_mfma_f32_16x16x32_bf16 v[20:23], v[170:173], v[202:205], v[20:23]
	v_mfma_f32_16x16x32_bf16 v[16:19], v[178:181], v[202:205], v[16:19]
	v_mfma_f32_16x16x32_bf16 v[4:7], v[170:173], v[212:215], v[4:7]
	v_mfma_f32_16x16x32_bf16 v[0:3], v[178:181], v[212:215], v[0:3]
	v_mfma_f32_16x16x32_bf16 v[52:55], v[174:177], v[190:193], v[52:55]
	v_mfma_f32_16x16x32_bf16 v[48:51], v[182:185], v[190:193], v[48:51]
	v_mfma_f32_16x16x32_bf16 v[36:39], v[174:177], v[198:201], v[36:39]
	v_mfma_f32_16x16x32_bf16 v[32:35], v[182:185], v[198:201], v[32:35]
	v_mfma_f32_16x16x32_bf16 v[20:23], v[174:177], v[206:209], v[20:23]
	v_mfma_f32_16x16x32_bf16 v[16:19], v[182:185], v[206:209], v[16:19]
	v_mfma_f32_16x16x32_bf16 v[4:7], v[174:177], v[216:219], v[4:7]
	v_mfma_f32_16x16x32_bf16 v[0:3], v[182:185], v[216:219], v[0:3]
	s_setprio 0
	s_barrier
	s_add_i32 s79, s79, 2
	s_add_u32 s58, s58, 0x100
	s_addc_u32 s59, s59, 0
	s_add_u32 s76, s76, 0x100
	s_addc_u32 s77, s77, 0
	s_cmp_gt_u32 s79, 29
	s_cbranch_scc0 .LBB0_292
	v_lshl_add_u32 v148, s54, 8, v150
	v_lshl_or_b32 v146, s56, 8, v136
	v_lshl_add_u32 v147, v148, 11, v146
	v_lshlrev_b32_e32 v159, 1, v147
	v_lshlrev_b32_e32 v158, 2, v147
	v_lshlrev_b32_e32 v208, 3, v148
	global_load_dwordx4 v[160:163], v158, s[12:13]
	global_load_dwordx4 v[164:167], v158, s[12:13] offset:16
	global_load_dwordx4 v[168:171], v158, s[12:13] offset:128
	global_load_dwordx4 v[172:175], v158, s[12:13] offset:144
	v_add_u32_e32 v149, 0x20000, v158
	global_load_dwordx4 v[176:179], v149, s[12:13]
	global_load_dwordx4 v[180:183], v149, s[12:13] offset:16
	global_load_dwordx4 v[184:187], v149, s[12:13] offset:128
	global_load_dwordx4 v[188:191], v149, s[12:13] offset:144
	v_add_u32_e32 v209, 0x40000, v158
	global_load_dwordx4 v[192:195], v209, s[12:13]
	global_load_dwordx4 v[196:199], v209, s[12:13] offset:16
	global_load_dwordx4 v[200:203], v209, s[12:13] offset:128
	global_load_dwordx4 v[204:207], v209, s[12:13] offset:144
	v_add_u32_e32 v149, 0x60000, v158
	global_load_dwordx4 v[212:215], v149, s[12:13]
	global_load_dwordx4 v[216:219], v149, s[12:13] offset:16
	global_load_dwordx4 v[220:223], v149, s[12:13] offset:128
	global_load_dwordx4 v[224:227], v149, s[12:13] offset:144
	v_add_u32_e32 v209, 0x100000, v158
	global_load_dwordx4 v[228:231], v209, s[12:13]
	global_load_dwordx4 v[232:235], v209, s[12:13] offset:16
	global_load_dwordx4 v[236:239], v209, s[12:13] offset:128
	global_load_dwordx4 v[240:243], v209, s[12:13] offset:144
	s_and_b64 vcc, exec, s[44:45]
	s_cbranch_vccz .LBB0_295
	s_barrier
.LBB0_295:
	ds_write_b128 v156, v[124:127]
	ds_write_b128 v156, v[120:123] offset:64
	ds_read_b128 v[120:123], v157
	ds_read_b128 v[124:127], v157 offset:16
	ds_write_b128 v156, v[116:119]
	ds_write_b128 v156, v[112:115] offset:64
	ds_read_b128 v[112:115], v157
	ds_read_b128 v[116:119], v157 offset:16
	s_waitcnt vmcnt(18) lgkmcnt(4)
	v_pk_add_f32 v[120:121], v[160:161], v[120:121]
	v_pk_add_f32 v[122:123], v[162:163], v[122:123]
	v_pk_add_f32 v[124:125], v[164:165], v[124:125]
	v_pk_add_f32 v[126:127], v[166:167], v[126:127]
	v_add_u32_e32 v149, 0x120000, v158
	global_load_dwordx4 v[160:163], v149, s[12:13]
	global_load_dwordx4 v[164:167], v149, s[12:13] offset:16
	v_mul_f32_e32 v244, v121, v121
	v_mul_f32_e32 v245, v123, v123
	v_mul_f32_e32 v246, v125, v125
	v_mul_f32_e32 v247, v127, v127
	v_fmac_f32_e32 v244, v120, v120
	v_fmac_f32_e32 v245, v122, v122
	v_fmac_f32_e32 v246, v124, v124
	v_fmac_f32_e32 v247, v126, v126
	v_cvt_pk_bf16_f32 v120, v120, v121
	v_cvt_pk_bf16_f32 v121, v122, v123
	v_cvt_pk_bf16_f32 v122, v124, v125
	v_cvt_pk_bf16_f32 v123, v126, v127
	v_add_f32_e32 v244, v244, v245
	v_add_f32_e32 v245, v246, v247
	v_add_f32_e32 v124, v244, v245
	global_store_dwordx4 v159, v[120:123], s[38:39]
	ds_write_b128 v156, v[108:111]
	ds_write_b128 v156, v[104:107] offset:64
	ds_read_b128 v[104:107], v157
	ds_read_b128 v[108:111], v157 offset:16
	s_waitcnt vmcnt(19) lgkmcnt(4)
; #define PG8_LAS __attribute__((address_space(3)))
; __device__ __forceinline__ unsigned cvt_pk_bf16(float lo, float hi) { unsigned r; asm volatile("v_cvt_pk_bf16_f32 %0, %1, %2" : "=v"(r) : "v"(lo), "v"(hi)); return r; }
;     __device__ __forceinline__ void operator()(const f32x4 (&acc)[2][2][4][2], const Unit& u, int wr, int wc, int fr, int fq) const {
;         const int lane = fr + 16 * fq, r = lane >> 2, p = lane & 3; PG8_LAS unsigned char* stg = lds + STG_OFF + (wr * 4 + wc) * STG_WAVE;
; #pragma unroll
;         for (int ai = 0; ai < 2; ++ai)
; #pragma unroll
;             for (int m = 0; m < 4; ++m) {
;                 const int row = u.pm * BM + ai * HALF + wr * 64 + m * 16 + r; float q = 0.f;
; #pragma unroll
;                 for (int bj = 0; bj < 2; ++bj) {
;                     const size_t off = (size_t)row * 2048 + u.pn * BM + wc * 64 + bj * 32 + 8 * p;
;                     f32x4 b0, b1;
;                     if (BASE_F32) { b0 = *(const f32x4*)((const float*)base + off); b1 = *(const f32x4*)((const float*)base + off + 4); }
;                     else { const u32x4 bb = *(const u32x4*)((const bf16_t*)base + off);
;                         b0 = (f32x4){__uint_as_float(bb.x << 16), __uint_as_float(bb.x & 0xffff0000u), __uint_as_float(bb.y << 16), __uint_as_float(bb.y & 0xffff0000u)};
;                         b1 = (f32x4){__uint_as_float(bb.z << 16), __uint_as_float(bb.z & 0xffff0000u), __uint_as_float(bb.w << 16), __uint_as_float(bb.w & 0xffff0000u)}; }
; #pragma unroll
;                     for (int n = 0; n < 2; ++n) *(PG8_LAS f32x4*)(stg + fr * STG_ROW + n * 64 + fq * 16) = acc[ai][bj][m][n];
;                     const f32x4 v0 = *(const PG8_LAS f32x4*)(stg + r * STG_ROW + p * 32) + b0, v1 = *(const PG8_LAS f32x4*)(stg + r * STG_ROW + p * 32 + 16) + b1;
;                     q += ((v0[0] * v0[0] + v0[1] * v0[1]) + (v0[2] * v0[2] + v0[3] * v0[3])) + ((v1[0] * v1[0] + v1[1] * v1[1]) + (v1[2] * v1[2] + v1[3] * v1[3]));
;                     u32x4 w; w.x = cvt_pk_bf16(v0[0], v0[1]); w.y = cvt_pk_bf16(v0[2], v0[3]); w.z = cvt_pk_bf16(v1[0], v1[1]); w.w = cvt_pk_bf16(v1[2], v1[3]);
;                     *(u32x4*)(out + off) = w;
;                 }
;                 q += __shfl_xor(q, 1); q += __shfl_xor(q, 2);
;                 if (p == 0) atomicAdd(ssn + row, (u64)(q * SS_SCALE));
	v_pk_add_f32 v[112:113], v[168:169], v[112:113]
	v_pk_add_f32 v[114:115], v[170:171], v[114:115]
	v_pk_add_f32 v[116:117], v[172:173], v[116:117]
	v_pk_add_f32 v[118:119], v[174:175], v[118:119]
	global_load_dwordx4 v[168:171], v149, s[12:13] offset:128
	global_load_dwordx4 v[172:175], v149, s[12:13] offset:144
	v_mul_f32_e32 v244, v113, v113
	v_mul_f32_e32 v245, v115, v115
	v_mul_f32_e32 v246, v117, v117
	v_mul_f32_e32 v247, v119, v119
	v_fmac_f32_e32 v244, v112, v112
	v_fmac_f32_e32 v245, v114, v114
	v_fmac_f32_e32 v246, v116, v116
	v_fmac_f32_e32 v247, v118, v118
	v_cvt_pk_bf16_f32 v112, v112, v113
	v_cvt_pk_bf16_f32 v113, v114, v115
	v_cvt_pk_bf16_f32 v114, v116, v117
	v_cvt_pk_bf16_f32 v115, v118, v119
	v_add_f32_e32 v244, v244, v245
	v_add_f32_e32 v245, v246, v247
	v_add_f32_e32 v116, v244, v245
	global_store_dwordx4 v159, v[112:115], s[38:39] offset:64
	v_add_f32_e32 v117, v124, v116
	s_nop 1
	v_add_f32_dpp v118, v117, v117 quad_perm:[1,0,3,2] row_mask:0xf bank_mask:0xf
	s_nop 1
	v_add_f32_dpp v119, v118, v118 quad_perm:[2,3,0,1] row_mask:0xf bank_mask:0xf
	v_mul_f32_e32 v126, 0x49800000, v119
	v_trunc_f32_e32 v126, v126
	v_mul_f32_e32 v127, 0x2f800000, v126
	v_floor_f32_e32 v127, v127
	v_fmac_f32_e32 v126, 0xcf800000, v127
	v_cvt_u32_f32_e32 v126, v126
	v_cvt_u32_f32_e32 v127, v127
	s_mov_b64 exec, s[8:9]
	global_atomic_add_x2 v208, v[126:127], s[14:15]
	s_mov_b64 exec, -1
	ds_write_b128 v156, v[100:103]
	ds_write_b128 v156, v[96:99] offset:64
	ds_read_b128 v[96:99], v157
	ds_read_b128 v[100:103], v157 offset:16
	s_waitcnt vmcnt(21) lgkmcnt(4)
	v_pk_add_f32 v[104:105], v[176:177], v[104:105]
	v_pk_add_f32 v[106:107], v[178:179], v[106:107]
	v_pk_add_f32 v[108:109], v[180:181], v[108:109]
	v_pk_add_f32 v[110:111], v[182:183], v[110:111]
	v_add_u32_e32 v209, 0x140000, v158
	global_load_dwordx4 v[176:179], v209, s[12:13]
	global_load_dwordx4 v[180:183], v209, s[12:13] offset:16
	v_mul_f32_e32 v244, v105, v105
	v_mul_f32_e32 v245, v107, v107
	v_mul_f32_e32 v246, v109, v109
	v_mul_f32_e32 v247, v111, v111
	v_fmac_f32_e32 v244, v104, v104
	v_fmac_f32_e32 v245, v106, v106
	v_fmac_f32_e32 v246, v108, v108
	v_fmac_f32_e32 v247, v110, v110
	v_cvt_pk_bf16_f32 v104, v104, v105
	v_cvt_pk_bf16_f32 v105, v106, v107
	v_cvt_pk_bf16_f32 v106, v108, v109
	v_cvt_pk_bf16_f32 v107, v110, v111
	v_add_f32_e32 v244, v244, v245
	v_add_f32_e32 v245, v246, v247
	v_add_f32_e32 v108, v244, v245
	v_add_u32_e32 v147, 0x10000, v159
	global_store_dwordx4 v147, v[104:107], s[38:39]
	ds_write_b128 v156, v[92:95]
	ds_write_b128 v156, v[88:91] offset:64
	ds_read_b128 v[88:91], v157
	ds_read_b128 v[92:95], v157 offset:16
	s_waitcnt vmcnt(22) lgkmcnt(4)
	v_pk_add_f32 v[96:97], v[184:185], v[96:97]
	v_pk_add_f32 v[98:99], v[186:187], v[98:99]
	v_pk_add_f32 v[100:101], v[188:189], v[100:101]
	v_pk_add_f32 v[102:103], v[190:191], v[102:103]
	global_load_dwordx4 v[184:187], v209, s[12:13] offset:128
	global_load_dwordx4 v[188:191], v209, s[12:13] offset:144
	v_mul_f32_e32 v244, v97, v97
	v_mul_f32_e32 v245, v99, v99
	v_mul_f32_e32 v246, v101, v101
	v_mul_f32_e32 v247, v103, v103
	v_fmac_f32_e32 v244, v96, v96
	v_fmac_f32_e32 v245, v98, v98
	v_fmac_f32_e32 v246, v100, v100
	v_fmac_f32_e32 v247, v102, v102
	v_cvt_pk_bf16_f32 v96, v96, v97
	v_cvt_pk_bf16_f32 v97, v98, v99
	v_cvt_pk_bf16_f32 v98, v100, v101
	v_cvt_pk_bf16_f32 v99, v102, v103
	v_add_f32_e32 v244, v244, v245
	v_add_f32_e32 v245, v246, v247
	v_add_f32_e32 v100, v244, v245
	global_store_dwordx4 v147, v[96:99], s[38:39] offset:64
	v_add_f32_e32 v101, v108, v100
	s_nop 1
	v_add_f32_dpp v102, v101, v101 quad_perm:[1,0,3,2] row_mask:0xf bank_mask:0xf
	s_nop 1
	v_add_f32_dpp v103, v102, v102 quad_perm:[2,3,0,1] row_mask:0xf bank_mask:0xf
	v_mul_f32_e32 v110, 0x49800000, v103
	v_trunc_f32_e32 v110, v110
	v_mul_f32_e32 v111, 0x2f800000, v110
	v_floor_f32_e32 v111, v111
	v_fmac_f32_e32 v110, 0xcf800000, v111
	v_cvt_u32_f32_e32 v110, v110
	v_cvt_u32_f32_e32 v111, v111
	s_mov_b64 exec, s[8:9]
	global_atomic_add_x2 v208, v[110:111], s[14:15] offset:128
	s_mov_b64 exec, -1
	ds_write_b128 v156, v[84:87]
	ds_write_b128 v156, v[80:83] offset:64
	ds_read_b128 v[80:83], v157
	ds_read_b128 v[84:87], v157 offset:16
	s_waitcnt vmcnt(24) lgkmcnt(4)
	v_pk_add_f32 v[88:89], v[192:193], v[88:89]
	v_pk_add_f32 v[90:91], v[194:195], v[90:91]
	v_pk_add_f32 v[92:93], v[196:197], v[92:93]
	v_pk_add_f32 v[94:95], v[198:199], v[94:95]
	v_add_u32_e32 v149, 0x160000, v158
	global_load_dwordx4 v[192:195], v149, s[12:13]
	global_load_dwordx4 v[196:199], v149, s[12:13] offset:16
	v_mul_f32_e32 v244, v89, v89
	v_mul_f32_e32 v245, v91, v91
	v_mul_f32_e32 v246, v93, v93
	v_mul_f32_e32 v247, v95, v95
	v_fmac_f32_e32 v244, v88, v88
	v_fmac_f32_e32 v245, v90, v90
	v_fmac_f32_e32 v246, v92, v92
	v_fmac_f32_e32 v247, v94, v94
	v_cvt_pk_bf16_f32 v88, v88, v89
	v_cvt_pk_bf16_f32 v89, v90, v91
	v_cvt_pk_bf16_f32 v90, v92, v93
	v_cvt_pk_bf16_f32 v91, v94, v95
	v_add_f32_e32 v244, v244, v245
	v_add_f32_e32 v245, v246, v247
	v_add_f32_e32 v92, v244, v245
	v_add_u32_e32 v146, 0x20000, v159
	global_store_dwordx4 v146, v[88:91], s[38:39]
	ds_write_b128 v156, v[76:79]
	ds_write_b128 v156, v[72:75] offset:64
	ds_read_b128 v[72:75], v157
	ds_read_b128 v[76:79], v157 offset:16
	s_waitcnt vmcnt(25) lgkmcnt(4)
; #define PG8_LAS __attribute__((address_space(3)))
; __device__ __forceinline__ unsigned cvt_pk_bf16(float lo, float hi) { unsigned r; asm volatile("v_cvt_pk_bf16_f32 %0, %1, %2" : "=v"(r) : "v"(lo), "v"(hi)); return r; }
;     __device__ __forceinline__ void operator()(const f32x4 (&acc)[2][2][4][2], const Unit& u, int wr, int wc, int fr, int fq) const {
;         const int lane = fr + 16 * fq, r = lane >> 2, p = lane & 3; PG8_LAS unsigned char* stg = lds + STG_OFF + (wr * 4 + wc) * STG_WAVE;
; #pragma unroll
;         for (int ai = 0; ai < 2; ++ai)
; #pragma unroll
;             for (int m = 0; m < 4; ++m) {
;                 const int row = u.pm * BM + ai * HALF + wr * 64 + m * 16 + r; float q = 0.f;
; #pragma unroll
;                 for (int bj = 0; bj < 2; ++bj) {
;                     const size_t off = (size_t)row * 2048 + u.pn * BM + wc * 64 + bj * 32 + 8 * p;
;                     f32x4 b0, b1;
;                     if (BASE_F32) { b0 = *(const f32x4*)((const float*)base + off); b1 = *(const f32x4*)((const float*)base + off + 4); }
;                     else { const u32x4 bb = *(const u32x4*)((const bf16_t*)base + off);
;                         b0 = (f32x4){__uint_as_float(bb.x << 16), __uint_as_float(bb.x & 0xffff0000u), __uint_as_float(bb.y << 16), __uint_as_float(bb.y & 0xffff0000u)};
;                         b1 = (f32x4){__uint_as_float(bb.z << 16), __uint_as_float(bb.z & 0xffff0000u), __uint_as_float(bb.w << 16), __uint_as_float(bb.w & 0xffff0000u)}; }
; #pragma unroll
;                     for (int n = 0; n < 2; ++n) *(PG8_LAS f32x4*)(stg + fr * STG_ROW + n * 64 + fq * 16) = acc[ai][bj][m][n];
;                     const f32x4 v0 = *(const PG8_LAS f32x4*)(stg + r * STG_ROW + p * 32) + b0, v1 = *(const PG8_LAS f32x4*)(stg + r * STG_ROW + p * 32 + 16) + b1;
;                     q += ((v0[0] * v0[0] + v0[1] * v0[1]) + (v0[2] * v0[2] + v0[3] * v0[3])) + ((v1[0] * v1[0] + v1[1] * v1[1]) + (v1[2] * v1[2] + v1[3] * v1[3]));
;                     u32x4 w; w.x = cvt_pk_bf16(v0[0], v0[1]); w.y = cvt_pk_bf16(v0[2], v0[3]); w.z = cvt_pk_bf16(v1[0], v1[1]); w.w = cvt_pk_bf16(v1[2], v1[3]);
;                     *(u32x4*)(out + off) = w;
;                 }
;                 q += __shfl_xor(q, 1); q += __shfl_xor(q, 2);
;                 if (p == 0) atomicAdd(ssn + row, (u64)(q * SS_SCALE));
	v_pk_add_f32 v[80:81], v[200:201], v[80:81]
	v_pk_add_f32 v[82:83], v[202:203], v[82:83]
	v_pk_add_f32 v[84:85], v[204:205], v[84:85]
	v_pk_add_f32 v[86:87], v[206:207], v[86:87]
	global_load_dwordx4 v[200:203], v149, s[12:13] offset:128
	global_load_dwordx4 v[204:207], v149, s[12:13] offset:144
	v_mul_f32_e32 v244, v81, v81
	v_mul_f32_e32 v245, v83, v83
	v_mul_f32_e32 v246, v85, v85
	v_mul_f32_e32 v247, v87, v87
	v_fmac_f32_e32 v244, v80, v80
	v_fmac_f32_e32 v245, v82, v82
	v_fmac_f32_e32 v246, v84, v84
	v_fmac_f32_e32 v247, v86, v86
	v_cvt_pk_bf16_f32 v80, v80, v81
	v_cvt_pk_bf16_f32 v81, v82, v83
	v_cvt_pk_bf16_f32 v82, v84, v85
	v_cvt_pk_bf16_f32 v83, v86, v87
	v_add_f32_e32 v244, v244, v245
	v_add_f32_e32 v245, v246, v247
	v_add_f32_e32 v84, v244, v245
	global_store_dwordx4 v146, v[80:83], s[38:39] offset:64
	v_add_f32_e32 v85, v92, v84
	s_nop 1
	v_add_f32_dpp v86, v85, v85 quad_perm:[1,0,3,2] row_mask:0xf bank_mask:0xf
	s_nop 1
	v_add_f32_dpp v87, v86, v86 quad_perm:[2,3,0,1] row_mask:0xf bank_mask:0xf
	v_mul_f32_e32 v94, 0x49800000, v87
	v_trunc_f32_e32 v94, v94
	v_mul_f32_e32 v95, 0x2f800000, v94
	v_floor_f32_e32 v95, v95
	v_fmac_f32_e32 v94, 0xcf800000, v95
	v_cvt_u32_f32_e32 v94, v94
	v_cvt_u32_f32_e32 v95, v95
	s_mov_b64 exec, s[8:9]
	global_atomic_add_x2 v208, v[94:95], s[14:15] offset:256
	s_mov_b64 exec, -1
	ds_write_b128 v156, v[68:71]
	ds_write_b128 v156, v[64:67] offset:64
	ds_read_b128 v[64:67], v157
	ds_read_b128 v[68:71], v157 offset:16
	s_waitcnt vmcnt(27) lgkmcnt(4)
	v_pk_add_f32 v[72:73], v[212:213], v[72:73]
	v_pk_add_f32 v[74:75], v[214:215], v[74:75]
	v_pk_add_f32 v[76:77], v[216:217], v[76:77]
	v_pk_add_f32 v[78:79], v[218:219], v[78:79]
	v_mul_f32_e32 v244, v73, v73
	v_mul_f32_e32 v245, v75, v75
	v_mul_f32_e32 v246, v77, v77
	v_mul_f32_e32 v247, v79, v79
	v_fmac_f32_e32 v244, v72, v72
	v_fmac_f32_e32 v245, v74, v74
	v_fmac_f32_e32 v246, v76, v76
	v_fmac_f32_e32 v247, v78, v78
	v_cvt_pk_bf16_f32 v72, v72, v73
	v_cvt_pk_bf16_f32 v73, v74, v75
	v_cvt_pk_bf16_f32 v74, v76, v77
	v_cvt_pk_bf16_f32 v75, v78, v79
	v_add_f32_e32 v244, v244, v245
	v_add_f32_e32 v245, v246, v247
	v_add_f32_e32 v76, v244, v245
	v_add_u32_e32 v147, 0x30000, v159
	global_store_dwordx4 v147, v[72:75], s[38:39]
	ds_write_b128 v156, v[60:63]
	ds_write_b128 v156, v[56:59] offset:64
	ds_read_b128 v[56:59], v157
	ds_read_b128 v[60:63], v157 offset:16
	s_waitcnt vmcnt(26) lgkmcnt(4)
	v_pk_add_f32 v[64:65], v[220:221], v[64:65]
	v_pk_add_f32 v[66:67], v[222:223], v[66:67]
	v_pk_add_f32 v[68:69], v[224:225], v[68:69]
	v_pk_add_f32 v[70:71], v[226:227], v[70:71]
	v_mul_f32_e32 v244, v65, v65
	v_mul_f32_e32 v245, v67, v67
	v_mul_f32_e32 v246, v69, v69
	v_mul_f32_e32 v247, v71, v71
	v_fmac_f32_e32 v244, v64, v64
	v_fmac_f32_e32 v245, v66, v66
	v_fmac_f32_e32 v246, v68, v68
	v_fmac_f32_e32 v247, v70, v70
	v_cvt_pk_bf16_f32 v64, v64, v65
	v_cvt_pk_bf16_f32 v65, v66, v67
	v_cvt_pk_bf16_f32 v66, v68, v69
	v_cvt_pk_bf16_f32 v67, v70, v71
	v_add_f32_e32 v244, v244, v245
	v_add_f32_e32 v245, v246, v247
	v_add_f32_e32 v68, v244, v245
	global_store_dwordx4 v147, v[64:67], s[38:39] offset:64
	v_add_f32_e32 v69, v76, v68
	s_nop 1
	v_add_f32_dpp v70, v69, v69 quad_perm:[1,0,3,2] row_mask:0xf bank_mask:0xf
	s_nop 1
	v_add_f32_dpp v71, v70, v70 quad_perm:[2,3,0,1] row_mask:0xf bank_mask:0xf
	v_mul_f32_e32 v78, 0x49800000, v71
	v_trunc_f32_e32 v78, v78
	v_mul_f32_e32 v79, 0x2f800000, v78
	v_floor_f32_e32 v79, v79
	v_fmac_f32_e32 v78, 0xcf800000, v79
	v_cvt_u32_f32_e32 v78, v78
	v_cvt_u32_f32_e32 v79, v79
	s_mov_b64 exec, s[8:9]
	global_atomic_add_x2 v208, v[78:79], s[14:15] offset:384
	s_mov_b64 exec, -1
	ds_write_b128 v156, v[52:55]
	ds_write_b128 v156, v[48:51] offset:64
	ds_read_b128 v[48:51], v157
	ds_read_b128 v[52:55], v157 offset:16
	s_waitcnt vmcnt(26) lgkmcnt(4)
	v_pk_add_f32 v[56:57], v[228:229], v[56:57]
	v_pk_add_f32 v[58:59], v[230:231], v[58:59]
	v_pk_add_f32 v[60:61], v[232:233], v[60:61]
	v_pk_add_f32 v[62:63], v[234:235], v[62:63]
	v_mul_f32_e32 v244, v57, v57
	v_mul_f32_e32 v245, v59, v59
	v_mul_f32_e32 v246, v61, v61
	v_mul_f32_e32 v247, v63, v63
	v_fmac_f32_e32 v244, v56, v56
	v_fmac_f32_e32 v245, v58, v58
	v_fmac_f32_e32 v246, v60, v60
	v_fmac_f32_e32 v247, v62, v62
	v_cvt_pk_bf16_f32 v56, v56, v57
	v_cvt_pk_bf16_f32 v57, v58, v59
	v_cvt_pk_bf16_f32 v58, v60, v61
	v_cvt_pk_bf16_f32 v59, v62, v63
	v_add_f32_e32 v244, v244, v245
	v_add_f32_e32 v245, v246, v247
	v_add_f32_e32 v60, v244, v245
	v_add_u32_e32 v146, 0x80000, v159
	global_store_dwordx4 v146, v[56:59], s[38:39]
	ds_write_b128 v156, v[44:47]
	ds_write_b128 v156, v[40:43] offset:64
	ds_read_b128 v[40:43], v157
	ds_read_b128 v[44:47], v157 offset:16
	s_waitcnt vmcnt(25) lgkmcnt(4)
	v_pk_add_f32 v[48:49], v[236:237], v[48:49]
	v_pk_add_f32 v[50:51], v[238:239], v[50:51]
	v_pk_add_f32 v[52:53], v[240:241], v[52:53]
	v_pk_add_f32 v[54:55], v[242:243], v[54:55]
	v_mul_f32_e32 v244, v49, v49
	v_mul_f32_e32 v245, v51, v51
	v_mul_f32_e32 v246, v53, v53
	v_mul_f32_e32 v247, v55, v55
	v_fmac_f32_e32 v244, v48, v48
	v_fmac_f32_e32 v245, v50, v50
	v_fmac_f32_e32 v246, v52, v52
	v_fmac_f32_e32 v247, v54, v54
	v_cvt_pk_bf16_f32 v48, v48, v49
	v_cvt_pk_bf16_f32 v49, v50, v51
	v_cvt_pk_bf16_f32 v50, v52, v53
	v_cvt_pk_bf16_f32 v51, v54, v55
	v_add_f32_e32 v244, v244, v245
	v_add_f32_e32 v245, v246, v247
	v_add_f32_e32 v52, v244, v245
	global_store_dwordx4 v146, v[48:51], s[38:39] offset:64
	v_add_f32_e32 v53, v60, v52
	s_nop 1
	v_add_f32_dpp v54, v53, v53 quad_perm:[1,0,3,2] row_mask:0xf bank_mask:0xf
	s_nop 1
	v_add_f32_dpp v55, v54, v54 quad_perm:[2,3,0,1] row_mask:0xf bank_mask:0xf
	v_mul_f32_e32 v62, 0x49800000, v55
	v_trunc_f32_e32 v62, v62
	v_mul_f32_e32 v63, 0x2f800000, v62
	v_floor_f32_e32 v63, v63
	v_fmac_f32_e32 v62, 0xcf800000, v63
	v_cvt_u32_f32_e32 v62, v62
	v_cvt_u32_f32_e32 v63, v63
	s_mov_b64 exec, s[8:9]
	global_atomic_add_x2 v208, v[62:63], s[14:15] offset:1024
	s_mov_b64 exec, -1
	ds_write_b128 v156, v[36:39]
	ds_write_b128 v156, v[32:35] offset:64
	ds_read_b128 v[32:35], v157
	ds_read_b128 v[36:39], v157 offset:16
	s_waitcnt vmcnt(25) lgkmcnt(4)
; #define PG8_LAS __attribute__((address_space(3)))
; __device__ __forceinline__ unsigned cvt_pk_bf16(float lo, float hi) { unsigned r; asm volatile("v_cvt_pk_bf16_f32 %0, %1, %2" : "=v"(r) : "v"(lo), "v"(hi)); return r; }
;     __device__ __forceinline__ void operator()(const f32x4 (&acc)[2][2][4][2], const Unit& u, int wr, int wc, int fr, int fq) const {
;         const int lane = fr + 16 * fq, r = lane >> 2, p = lane & 3; PG8_LAS unsigned char* stg = lds + STG_OFF + (wr * 4 + wc) * STG_WAVE;
; #pragma unroll
;         for (int ai = 0; ai < 2; ++ai)
; #pragma unroll
;             for (int m = 0; m < 4; ++m) {
;                 const int row = u.pm * BM + ai * HALF + wr * 64 + m * 16 + r; float q = 0.f;
; #pragma unroll
;                 for (int bj = 0; bj < 2; ++bj) {
;                     const size_t off = (size_t)row * 2048 + u.pn * BM + wc * 64 + bj * 32 + 8 * p;
;                     f32x4 b0, b1;
;                     if (BASE_F32) { b0 = *(const f32x4*)((const float*)base + off); b1 = *(const f32x4*)((const float*)base + off + 4); }
;                     else { const u32x4 bb = *(const u32x4*)((const bf16_t*)base + off);
;                         b0 = (f32x4){__uint_as_float(bb.x << 16), __uint_as_float(bb.x & 0xffff0000u), __uint_as_float(bb.y << 16), __uint_as_float(bb.y & 0xffff0000u)};
;                         b1 = (f32x4){__uint_as_float(bb.z << 16), __uint_as_float(bb.z & 0xffff0000u), __uint_as_float(bb.w << 16), __uint_as_float(bb.w & 0xffff0000u)}; }
; #pragma unroll
;                     for (int n = 0; n < 2; ++n) *(PG8_LAS f32x4*)(stg + fr * STG_ROW + n * 64 + fq * 16) = acc[ai][bj][m][n];
;                     const f32x4 v0 = *(const PG8_LAS f32x4*)(stg + r * STG_ROW + p * 32) + b0, v1 = *(const PG8_LAS f32x4*)(stg + r * STG_ROW + p * 32 + 16) + b1;
;                     q += ((v0[0] * v0[0] + v0[1] * v0[1]) + (v0[2] * v0[2] + v0[3] * v0[3])) + ((v1[0] * v1[0] + v1[1] * v1[1]) + (v1[2] * v1[2] + v1[3] * v1[3]));
;                     u32x4 w; w.x = cvt_pk_bf16(v0[0], v0[1]); w.y = cvt_pk_bf16(v0[2], v0[3]); w.z = cvt_pk_bf16(v1[0], v1[1]); w.w = cvt_pk_bf16(v1[2], v1[3]);
;                     *(u32x4*)(out + off) = w;
;                 }
;                 q += __shfl_xor(q, 1); q += __shfl_xor(q, 2);
;                 if (p == 0) atomicAdd(ssn + row, (u64)(q * SS_SCALE));
	v_pk_add_f32 v[40:41], v[160:161], v[40:41]
	v_pk_add_f32 v[42:43], v[162:163], v[42:43]
	v_pk_add_f32 v[44:45], v[164:165], v[44:45]
	v_pk_add_f32 v[46:47], v[166:167], v[46:47]
	v_mul_f32_e32 v244, v41, v41
	v_mul_f32_e32 v245, v43, v43
	v_mul_f32_e32 v246, v45, v45
	v_mul_f32_e32 v247, v47, v47
	v_fmac_f32_e32 v244, v40, v40
	v_fmac_f32_e32 v245, v42, v42
	v_fmac_f32_e32 v246, v44, v44
	v_fmac_f32_e32 v247, v46, v46
	v_cvt_pk_bf16_f32 v40, v40, v41
	v_cvt_pk_bf16_f32 v41, v42, v43
	v_cvt_pk_bf16_f32 v42, v44, v45
	v_cvt_pk_bf16_f32 v43, v46, v47
	v_add_f32_e32 v244, v244, v245
	v_add_f32_e32 v245, v246, v247
	v_add_f32_e32 v44, v244, v245
	v_add_u32_e32 v147, 0x90000, v159
	global_store_dwordx4 v147, v[40:43], s[38:39]
	ds_write_b128 v156, v[28:31]
	ds_write_b128 v156, v[24:27] offset:64
	ds_read_b128 v[24:27], v157
	ds_read_b128 v[28:31], v157 offset:16
	s_waitcnt vmcnt(23) lgkmcnt(4)
	v_pk_add_f32 v[32:33], v[168:169], v[32:33]
	v_pk_add_f32 v[34:35], v[170:171], v[34:35]
	v_pk_add_f32 v[36:37], v[172:173], v[36:37]
	v_pk_add_f32 v[38:39], v[174:175], v[38:39]
	v_mul_f32_e32 v244, v33, v33
	v_mul_f32_e32 v245, v35, v35
	v_mul_f32_e32 v246, v37, v37
	v_mul_f32_e32 v247, v39, v39
	v_fmac_f32_e32 v244, v32, v32
	v_fmac_f32_e32 v245, v34, v34
	v_fmac_f32_e32 v246, v36, v36
	v_fmac_f32_e32 v247, v38, v38
	v_cvt_pk_bf16_f32 v32, v32, v33
	v_cvt_pk_bf16_f32 v33, v34, v35
	v_cvt_pk_bf16_f32 v34, v36, v37
	v_cvt_pk_bf16_f32 v35, v38, v39
	v_add_f32_e32 v244, v244, v245
	v_add_f32_e32 v245, v246, v247
	v_add_f32_e32 v36, v244, v245
	global_store_dwordx4 v147, v[32:35], s[38:39] offset:64
	v_add_f32_e32 v37, v44, v36
	s_nop 1
	v_add_f32_dpp v38, v37, v37 quad_perm:[1,0,3,2] row_mask:0xf bank_mask:0xf
	s_nop 1
	v_add_f32_dpp v39, v38, v38 quad_perm:[2,3,0,1] row_mask:0xf bank_mask:0xf
	v_mul_f32_e32 v46, 0x49800000, v39
	v_trunc_f32_e32 v46, v46
	v_mul_f32_e32 v47, 0x2f800000, v46
	v_floor_f32_e32 v47, v47
	v_fmac_f32_e32 v46, 0xcf800000, v47
	v_cvt_u32_f32_e32 v46, v46
	v_cvt_u32_f32_e32 v47, v47
	s_mov_b64 exec, s[8:9]
	global_atomic_add_x2 v208, v[46:47], s[14:15] offset:1152
	s_mov_b64 exec, -1
	ds_write_b128 v156, v[20:23]
	ds_write_b128 v156, v[16:19] offset:64
	ds_read_b128 v[16:19], v157
	ds_read_b128 v[20:23], v157 offset:16
	s_waitcnt vmcnt(21) lgkmcnt(4)
	v_pk_add_f32 v[24:25], v[176:177], v[24:25]
	v_pk_add_f32 v[26:27], v[178:179], v[26:27]
	v_pk_add_f32 v[28:29], v[180:181], v[28:29]
	v_pk_add_f32 v[30:31], v[182:183], v[30:31]
	v_mul_f32_e32 v244, v25, v25
	v_mul_f32_e32 v245, v27, v27
	v_mul_f32_e32 v246, v29, v29
	v_mul_f32_e32 v247, v31, v31
	v_fmac_f32_e32 v244, v24, v24
	v_fmac_f32_e32 v245, v26, v26
	v_fmac_f32_e32 v246, v28, v28
	v_fmac_f32_e32 v247, v30, v30
	v_cvt_pk_bf16_f32 v24, v24, v25
	v_cvt_pk_bf16_f32 v25, v26, v27
	v_cvt_pk_bf16_f32 v26, v28, v29
	v_cvt_pk_bf16_f32 v27, v30, v31
	v_add_f32_e32 v244, v244, v245
	v_add_f32_e32 v245, v246, v247
	v_add_f32_e32 v28, v244, v245
	v_add_u32_e32 v146, 0xa0000, v159
	global_store_dwordx4 v146, v[24:27], s[38:39]
	ds_write_b128 v156, v[12:15]
	ds_write_b128 v156, v[8:11] offset:64
	ds_read_b128 v[8:11], v157
	ds_read_b128 v[12:15], v157 offset:16
	s_waitcnt vmcnt(19) lgkmcnt(4)
	v_pk_add_f32 v[16:17], v[184:185], v[16:17]
	v_pk_add_f32 v[18:19], v[186:187], v[18:19]
	v_pk_add_f32 v[20:21], v[188:189], v[20:21]
	v_pk_add_f32 v[22:23], v[190:191], v[22:23]
	v_mul_f32_e32 v244, v17, v17
	v_mul_f32_e32 v245, v19, v19
	v_mul_f32_e32 v246, v21, v21
	v_mul_f32_e32 v247, v23, v23
	v_fmac_f32_e32 v244, v16, v16
	v_fmac_f32_e32 v245, v18, v18
	v_fmac_f32_e32 v246, v20, v20
	v_fmac_f32_e32 v247, v22, v22
	v_cvt_pk_bf16_f32 v16, v16, v17
	v_cvt_pk_bf16_f32 v17, v18, v19
	v_cvt_pk_bf16_f32 v18, v20, v21
	v_cvt_pk_bf16_f32 v19, v22, v23
	v_add_f32_e32 v244, v244, v245
	v_add_f32_e32 v245, v246, v247
	v_add_f32_e32 v20, v244, v245
	global_store_dwordx4 v146, v[16:19], s[38:39] offset:64
	v_add_f32_e32 v21, v28, v20
	s_nop 1
	v_add_f32_dpp v22, v21, v21 quad_perm:[1,0,3,2] row_mask:0xf bank_mask:0xf
	s_nop 1
	v_add_f32_dpp v23, v22, v22 quad_perm:[2,3,0,1] row_mask:0xf bank_mask:0xf
	v_mul_f32_e32 v30, 0x49800000, v23
	v_trunc_f32_e32 v30, v30
	v_mul_f32_e32 v31, 0x2f800000, v30
	v_floor_f32_e32 v31, v31
	v_fmac_f32_e32 v30, 0xcf800000, v31
	v_cvt_u32_f32_e32 v30, v30
	v_cvt_u32_f32_e32 v31, v31
	s_mov_b64 exec, s[8:9]
	global_atomic_add_x2 v208, v[30:31], s[14:15] offset:1280
	s_mov_b64 exec, -1
	ds_write_b128 v156, v[4:7]
	ds_write_b128 v156, v[0:3] offset:64
	ds_read_b128 v[0:3], v157
	ds_read_b128 v[4:7], v157 offset:16
	s_waitcnt vmcnt(17) lgkmcnt(4)
	v_pk_add_f32 v[8:9], v[192:193], v[8:9]
	v_pk_add_f32 v[10:11], v[194:195], v[10:11]
	v_pk_add_f32 v[12:13], v[196:197], v[12:13]
	v_pk_add_f32 v[14:15], v[198:199], v[14:15]
	v_mul_f32_e32 v244, v9, v9
	v_mul_f32_e32 v245, v11, v11
	v_mul_f32_e32 v246, v13, v13
	v_mul_f32_e32 v247, v15, v15
	v_fmac_f32_e32 v244, v8, v8
	v_fmac_f32_e32 v245, v10, v10
	v_fmac_f32_e32 v246, v12, v12
	v_fmac_f32_e32 v247, v14, v14
	v_cvt_pk_bf16_f32 v8, v8, v9
	v_cvt_pk_bf16_f32 v9, v10, v11
	v_cvt_pk_bf16_f32 v10, v12, v13
	v_cvt_pk_bf16_f32 v11, v14, v15
	v_add_f32_e32 v244, v244, v245
	v_add_f32_e32 v245, v246, v247
	v_add_f32_e32 v12, v244, v245
	v_add_u32_e32 v147, 0xb0000, v159
	global_store_dwordx4 v147, v[8:11], s[38:39]
	s_waitcnt vmcnt(15) lgkmcnt(0)
	v_pk_add_f32 v[0:1], v[200:201], v[0:1]
	v_pk_add_f32 v[2:3], v[202:203], v[2:3]
	v_pk_add_f32 v[4:5], v[204:205], v[4:5]
	v_pk_add_f32 v[6:7], v[206:207], v[6:7]
	v_mul_f32_e32 v244, v1, v1
	v_mul_f32_e32 v245, v3, v3
	v_mul_f32_e32 v246, v5, v5
	v_mul_f32_e32 v247, v7, v7
	v_fmac_f32_e32 v244, v0, v0
	v_fmac_f32_e32 v245, v2, v2
	v_fmac_f32_e32 v246, v4, v4
	v_fmac_f32_e32 v247, v6, v6
	v_cvt_pk_bf16_f32 v0, v0, v1
	v_cvt_pk_bf16_f32 v1, v2, v3
	v_cvt_pk_bf16_f32 v2, v4, v5
	v_cvt_pk_bf16_f32 v3, v6, v7
	v_add_f32_e32 v244, v244, v245
	v_add_f32_e32 v245, v246, v247
	v_add_f32_e32 v4, v244, v245
	global_store_dwordx4 v147, v[0:3], s[38:39] offset:64
	v_add_f32_e32 v5, v12, v4
	s_nop 1
	v_add_f32_dpp v6, v5, v5 quad_perm:[1,0,3,2] row_mask:0xf bank_mask:0xf
	s_nop 1
	v_add_f32_dpp v7, v6, v6 quad_perm:[2,3,0,1] row_mask:0xf bank_mask:0xf
	v_mul_f32_e32 v14, 0x49800000, v7
	v_trunc_f32_e32 v14, v14
	v_mul_f32_e32 v15, 0x2f800000, v14
	v_floor_f32_e32 v15, v15
	v_fmac_f32_e32 v14, 0xcf800000, v15
	v_cvt_u32_f32_e32 v14, v14
	v_cvt_u32_f32_e32 v15, v15
	s_mov_b64 exec, s[8:9]
	global_atomic_add_x2 v208, v[14:15], s[14:15] offset:1408
	s_mov_b64 exec, -1
	s_andn2_b64 vcc, exec, s[10:11]
	s_mov_b64 s[10:11], -1
	s_cbranch_vccnz .LBB0_284
	s_andn2_b64 vcc, exec, s[40:41]
	s_cbranch_vccnz .LBB0_283
	s_mov_b32 s98, 1
	s_branch .LBB0_283

; #define PG8_STAGE(bufoff, gbase, voff) do { _Pragma("unroll") for (int _i = 0; _i < 2; ++_i) \
;         __builtin_amdgcn_global_load_lds((const unsigned*)((const char*)(gbase) + (voff)[_i]), (PG8_LAS unsigned*)(lds + (bufoff) + ldsw + _i * 8192), 16, 0, 0); } while (0)
; #define PG8_LDA(dst, b, h) do { _Pragma("unroll") for (int m = 0; m < 4; ++m) _Pragma("unroll") for (int k = 0; k < 2; ++k) dst[m][k] = *(const PG8_LAS bf16x8*)(lds + PG8_SA(b, h) + aoff + m * 2048 + k * 1024); } while (0)
; #define PG8_LDB(dst, b, h) do { _Pragma("unroll") for (int n = 0; n < 2; ++n) _Pragma("unroll") for (int k = 0; k < 2; ++k) dst[n][k] = *(const PG8_LAS bf16x8*)(lds + PG8_SB(b, h) + boff + n * 2048 + k * 1024); } while (0)
; #define PG8_BAR __builtin_amdgcn_s_barrier()
; #define PG8_SCHED __builtin_amdgcn_sched_barrier(0)
; template <class Epi, class Sched, bool ALIGN_EPI = false, bool SP2 = false>
; __device__ __forceinline__ void gemm_phase(PG8_LAS unsigned char* lds, const Gemm g, const Sched& S, const Epi& E, int tid_in) {
;     ...
;         const bool has_next = S.next(ui + 1, nxt);
;         const char* nA = has_next ? (const char*)g.A + (size_t)nxt.pm * tstep : cA; const char* nB = has_next ? (const char*)g.Bt + (size_t)nxt.pn * tstepB : cB;
;         for (int t = 0; t < nt; t += 2) {
;             const bool last = (t == nt - 2);
;             const char* a1 = cA + (size_t)(t + 1) * kstep;
;             const char* a2 = last ? nA : cA + (size_t)(t + 2) * kstep; const char* b2 = last ? nB : cB + (size_t)(t + 2) * kstep;
;             const char* a3 = a2 + kstep; const char* b3 = b2 + kstep;
;             if (last && has_next) S.a_ready(nxt);
;             if constexpr (SP2) {
;             PG8_LDB(B0, 0, 0); PG8_LDB(B1, 0, 1); PG8_SCHED; PG8_LDA(At, 0, 0); PG8_STAGE(PG8_SA(1, 1), a1 + hstep, voffA);
;     ...
; #pragma unroll
;         for (int a = 0; a < 2; ++a)
; #pragma unroll
;             for (int b = 0; b < 2; ++b)
; #pragma unroll
;                 for (int m = 0; m < 4; ++m)
; #pragma unroll
;                     for (int n = 0; n < 2; ++n) acc[a][b][m][n] = (f32x4){0.f, 0.f, 0.f, 0.f};
;         cur = nxt; cA = nA; cB = nB; ++ui;
;         if constexpr (ALIGN_EPI) { if (wr == 1) PG8_BAR; }
.LBB0_393:
	s_ashr_i32 s45, s44, 31
	s_lshl_b64 s[26:27], s[44:45], 20
	s_add_u32 s46, s38, s26
	s_addc_u32 s47, s39, s27
	s_and_b64 s[26:27], s[8:9], exec
	s_cselect_b32 s45, s47, s53
	s_cselect_b32 s72, s46, s52
	s_ashr_i32 s43, s42, 31
	s_lshl_b64 s[26:27], s[42:43], 20
	s_add_u32 s48, s58, s26
	s_addc_u32 s49, s59, s27
	s_and_b64 s[26:27], s[8:9], exec
	s_cselect_b32 s43, s49, s55
	s_cselect_b32 s73, s48, s54
	s_add_u32 s52, s52, 0x80080
	s_addc_u32 s53, s53, 0
	s_add_u32 s74, s54, 0x100
	v_mov_b32_e32 v0, 0
	s_addc_u32 s75, s55, 0
	s_mov_b32 s76, -2
	v_mov_b32_e32 v1, v0
	v_mov_b32_e32 v2, v0
	v_mov_b32_e32 v3, v0
	v_mov_b32_e32 v4, v0
	v_mov_b32_e32 v5, v0
	v_mov_b32_e32 v6, v0
	v_mov_b32_e32 v7, v0
	v_mov_b32_e32 v16, v0
	v_mov_b32_e32 v17, v0
	v_mov_b32_e32 v18, v0
	v_mov_b32_e32 v19, v0
	v_mov_b32_e32 v20, v0
	v_mov_b32_e32 v21, v0
	v_mov_b32_e32 v22, v0
	v_mov_b32_e32 v23, v0
	v_mov_b32_e32 v32, v0
	v_mov_b32_e32 v33, v0
	v_mov_b32_e32 v34, v0
	v_mov_b32_e32 v35, v0
	v_mov_b32_e32 v36, v0
	v_mov_b32_e32 v37, v0
	v_mov_b32_e32 v38, v0
	v_mov_b32_e32 v39, v0
	v_mov_b32_e32 v48, v0
	v_mov_b32_e32 v49, v0
	v_mov_b32_e32 v50, v0
	v_mov_b32_e32 v51, v0
	v_mov_b32_e32 v52, v0
	v_mov_b32_e32 v53, v0
	v_mov_b32_e32 v54, v0
	v_mov_b32_e32 v55, v0
	v_mov_b32_e32 v8, v0
	v_mov_b32_e32 v9, v0
	v_mov_b32_e32 v10, v0
	v_mov_b32_e32 v11, v0
	v_mov_b32_e32 v12, v0
	v_mov_b32_e32 v13, v0
	v_mov_b32_e32 v14, v0
	v_mov_b32_e32 v15, v0
	v_mov_b32_e32 v24, v0
	v_mov_b32_e32 v25, v0
	v_mov_b32_e32 v26, v0
	v_mov_b32_e32 v27, v0
	v_mov_b32_e32 v28, v0
	v_mov_b32_e32 v29, v0
	v_mov_b32_e32 v30, v0
	v_mov_b32_e32 v31, v0
	v_mov_b32_e32 v40, v0
	v_mov_b32_e32 v41, v0
	v_mov_b32_e32 v42, v0
	v_mov_b32_e32 v43, v0
	v_mov_b32_e32 v44, v0
	v_mov_b32_e32 v45, v0
	v_mov_b32_e32 v46, v0
	v_mov_b32_e32 v47, v0
	v_mov_b32_e32 v56, v0
	v_mov_b32_e32 v57, v0
	v_mov_b32_e32 v58, v0
	v_mov_b32_e32 v59, v0
	v_mov_b32_e32 v60, v0
	v_mov_b32_e32 v61, v0
	v_mov_b32_e32 v62, v0
	v_mov_b32_e32 v63, v0
	v_mov_b32_e32 v64, v0
	v_mov_b32_e32 v65, v0
	v_mov_b32_e32 v66, v0
	v_mov_b32_e32 v67, v0
	v_mov_b32_e32 v68, v0
	v_mov_b32_e32 v69, v0
	v_mov_b32_e32 v70, v0
	v_mov_b32_e32 v71, v0
	v_mov_b32_e32 v80, v0
	v_mov_b32_e32 v81, v0
	v_mov_b32_e32 v82, v0
	v_mov_b32_e32 v83, v0
	v_mov_b32_e32 v84, v0
	v_mov_b32_e32 v85, v0
	v_mov_b32_e32 v86, v0
	v_mov_b32_e32 v87, v0
	v_mov_b32_e32 v96, v0
	v_mov_b32_e32 v97, v0
	v_mov_b32_e32 v98, v0
	v_mov_b32_e32 v99, v0
	v_mov_b32_e32 v100, v0
	v_mov_b32_e32 v101, v0
	v_mov_b32_e32 v102, v0
	v_mov_b32_e32 v103, v0
	v_mov_b32_e32 v112, v0
	v_mov_b32_e32 v113, v0
	v_mov_b32_e32 v114, v0
	v_mov_b32_e32 v115, v0
	v_mov_b32_e32 v116, v0
	v_mov_b32_e32 v117, v0
	v_mov_b32_e32 v118, v0
	v_mov_b32_e32 v119, v0
	v_mov_b32_e32 v72, v0
	v_mov_b32_e32 v73, v0
	v_mov_b32_e32 v74, v0
	v_mov_b32_e32 v75, v0
	v_mov_b32_e32 v76, v0
	v_mov_b32_e32 v77, v0
	v_mov_b32_e32 v78, v0
	v_mov_b32_e32 v79, v0
	v_mov_b32_e32 v88, v0
	v_mov_b32_e32 v89, v0
	v_mov_b32_e32 v90, v0
	v_mov_b32_e32 v91, v0
	v_mov_b32_e32 v92, v0
	v_mov_b32_e32 v93, v0
	v_mov_b32_e32 v94, v0
	v_mov_b32_e32 v95, v0
	v_mov_b32_e32 v104, v0
	v_mov_b32_e32 v105, v0
	v_mov_b32_e32 v106, v0
	v_mov_b32_e32 v107, v0
	v_mov_b32_e32 v108, v0
	v_mov_b32_e32 v109, v0
	v_mov_b32_e32 v110, v0
	v_mov_b32_e32 v111, v0
	v_mov_b32_e32 v120, v0
	v_mov_b32_e32 v121, v0
	v_mov_b32_e32 v122, v0
	v_mov_b32_e32 v123, v0
	v_mov_b32_e32 v124, v0
	v_mov_b32_e32 v125, v0
	v_mov_b32_e32 v126, v0
	v_mov_b32_e32 v127, v0
	s_cmp_eq_u32 s98, 1
	s_cbranch_scc0 .Lkb_skip_2
	s_mov_b32 s98, 0
	s_barrier
.Lkb_skip_2:
.LBB0_394:
	ds_read_b128 v[156:159], v150
	ds_read_b128 v[160:163], v150 offset:1024
	ds_read_b128 v[164:167], v150 offset:2048
	ds_read_b128 v[168:171], v150 offset:3072
	ds_read_b128 v[172:175], v151
	ds_read_b128 v[176:179], v151 offset:1024
	ds_read_b128 v[180:183], v151 offset:2048
	ds_read_b128 v[184:187], v151 offset:3072
	s_add_u32 s26, s52, 0xfff80080
	s_addc_u32 s27, s53, -1
	s_cmp_eq_u32 s76, 28
	s_cselect_b32 s57, s45, s27
	s_cselect_b32 s56, s72, s26
	s_cselect_b32 s55, s43, s75
	s_cselect_b32 s54, s73, s74
	v_lshl_add_u64 v[208:209], s[52:53], 0, v[138:139]
	s_add_i32 m0, s51, 0xc000
	ds_read_b128 v[188:191], v152
	ds_read_b128 v[192:195], v152 offset:1024
	ds_read_b128 v[196:199], v152 offset:2048
	ds_read_b128 v[200:203], v152 offset:3072
	ds_read_b128 v[204:207], v152 offset:4096
	ds_read_b128 v[212:215], v152 offset:5120
	ds_read_b128 v[216:219], v152 offset:6144
	ds_read_b128 v[220:223], v152 offset:7168
	global_load_lds_dwordx4 v[208:209], off
	v_lshl_add_u64 v[208:209], s[52:53], 0, v[140:141]
	s_add_i32 m0, s51, 0xe000
	s_nop 0
	global_load_lds_dwordx4 v[208:209], off
	s_waitcnt vmcnt(8)
	s_waitcnt lgkmcnt(0)
	s_barrier
; #define PG8_STAGE(bufoff, gbase, voff) do { _Pragma("unroll") for (int _i = 0; _i < 2; ++_i) \
;         __builtin_amdgcn_global_load_lds((const unsigned*)((const char*)(gbase) + (voff)[_i]), (PG8_LAS unsigned*)(lds + (bufoff) + ldsw + _i * 8192), 16, 0, 0); } while (0)
; #define PG8_LDA(dst, b, h) do { _Pragma("unroll") for (int m = 0; m < 4; ++m) _Pragma("unroll") for (int k = 0; k < 2; ++k) dst[m][k] = *(const PG8_LAS bf16x8*)(lds + PG8_SA(b, h) + aoff + m * 2048 + k * 1024); } while (0)
; #define PG8_LDB(dst, b, h) do { _Pragma("unroll") for (int n = 0; n < 2; ++n) _Pragma("unroll") for (int k = 0; k < 2; ++k) dst[n][k] = *(const PG8_LAS bf16x8*)(lds + PG8_SB(b, h) + boff + n * 2048 + k * 1024); } while (0)
; #define PG8_MMA(ai, bj, At, Bt) do { __builtin_amdgcn_s_setprio(1); _Pragma("unroll") for (int m = 0; m < 4; ++m) _Pragma("unroll") for (int n = 0; n < 2; ++n) _Pragma("unroll") for (int k = 0; k < 2; ++k) \
;         acc[ai][bj][m][n] = __builtin_amdgcn_mfma_f32_16x16x32_bf16(Bt[n][k], At[m][k], acc[ai][bj][m][n], 0, 0, 0); __builtin_amdgcn_s_setprio(0); } while (0)
; #define PG8_WAIT_V(n) asm volatile("s_waitcnt vmcnt(" #n ")" ::: "memory")
; #define PG8_WAIT_L(n) asm volatile("s_waitcnt lgkmcnt(" #n ")" ::: "memory")
; #define PG8_BAR __builtin_amdgcn_s_barrier()
; #define PG8_SCHED __builtin_amdgcn_sched_barrier(0)
; template <class Epi, class Sched, bool ALIGN_EPI = false, bool SP2 = false>
; __device__ __forceinline__ void gemm_phase(PG8_LAS unsigned char* lds, const Gemm g, const Sched& S, const Epi& E, int tid_in) {
;     ...
;             PG8_LDB(B0, 0, 0); PG8_LDB(B1, 0, 1); PG8_SCHED; PG8_LDA(At, 0, 0); PG8_STAGE(PG8_SA(1, 1), a1 + hstep, voffA);
;             PG8_WAIT_V(8); PG8_WAIT_L(0); PG8_BAR; PG8_MMA(0, 0, At, B0); PG8_MMA(0, 1, At, B1); PG8_BAR; PG8_SCHED;
;             PG8_LDA(At, 0, 1); PG8_STAGE(PG8_SB(0, 0), b2, voffB); PG8_STAGE(PG8_SB(0, 1), b2 + hstepB, voffB); PG8_STAGE(PG8_SA(0, 0), a2, voffA);
;             PG8_WAIT_V(8); PG8_WAIT_L(0); PG8_BAR; PG8_MMA(1, 0, At, B0); PG8_MMA(1, 1, At, B1); PG8_BAR; PG8_SCHED;
	s_setprio 1
	s_waitcnt lgkmcnt(0)
	v_mfma_f32_16x16x32_bf16 v[124:127], v[156:159], v[188:191], v[124:127]
	v_mfma_f32_16x16x32_bf16 v[120:123], v[164:167], v[188:191], v[120:123]
	v_mfma_f32_16x16x32_bf16 v[108:111], v[156:159], v[196:199], v[108:111]
	v_mfma_f32_16x16x32_bf16 v[104:107], v[164:167], v[196:199], v[104:107]
	v_mfma_f32_16x16x32_bf16 v[92:95], v[156:159], v[204:207], v[92:95]
	v_mfma_f32_16x16x32_bf16 v[88:91], v[164:167], v[204:207], v[88:91]
	v_mfma_f32_16x16x32_bf16 v[76:79], v[156:159], v[216:219], v[76:79]
	v_mfma_f32_16x16x32_bf16 v[72:75], v[164:167], v[216:219], v[72:75]
	v_mfma_f32_16x16x32_bf16 v[124:127], v[160:163], v[192:195], v[124:127]
	v_mfma_f32_16x16x32_bf16 v[120:123], v[168:171], v[192:195], v[120:123]
	v_mfma_f32_16x16x32_bf16 v[108:111], v[160:163], v[200:203], v[108:111]
	v_mfma_f32_16x16x32_bf16 v[104:107], v[168:171], v[200:203], v[104:107]
	v_mfma_f32_16x16x32_bf16 v[92:95], v[160:163], v[212:215], v[92:95]
	v_mfma_f32_16x16x32_bf16 v[88:91], v[168:171], v[212:215], v[88:91]
	v_mfma_f32_16x16x32_bf16 v[76:79], v[160:163], v[220:223], v[76:79]
	v_mfma_f32_16x16x32_bf16 v[72:75], v[168:171], v[220:223], v[72:75]
	s_setprio 0
	s_setprio 1
	v_mfma_f32_16x16x32_bf16 v[116:119], v[172:175], v[188:191], v[116:119]
	v_mfma_f32_16x16x32_bf16 v[112:115], v[180:183], v[188:191], v[112:115]
	v_mfma_f32_16x16x32_bf16 v[100:103], v[172:175], v[196:199], v[100:103]
	v_mfma_f32_16x16x32_bf16 v[96:99], v[180:183], v[196:199], v[96:99]
	v_mfma_f32_16x16x32_bf16 v[84:87], v[172:175], v[204:207], v[84:87]
	v_mfma_f32_16x16x32_bf16 v[80:83], v[180:183], v[204:207], v[80:83]
	v_mfma_f32_16x16x32_bf16 v[68:71], v[172:175], v[216:219], v[68:71]
	v_mfma_f32_16x16x32_bf16 v[64:67], v[180:183], v[216:219], v[64:67]
	v_mfma_f32_16x16x32_bf16 v[116:119], v[176:179], v[192:195], v[116:119]
	v_mfma_f32_16x16x32_bf16 v[112:115], v[184:187], v[192:195], v[112:115]
	v_mfma_f32_16x16x32_bf16 v[100:103], v[176:179], v[200:203], v[100:103]
	v_mfma_f32_16x16x32_bf16 v[96:99], v[184:187], v[200:203], v[96:99]
	v_mfma_f32_16x16x32_bf16 v[84:87], v[176:179], v[212:215], v[84:87]
	v_mfma_f32_16x16x32_bf16 v[80:83], v[184:187], v[212:215], v[80:83]
	v_mfma_f32_16x16x32_bf16 v[68:71], v[176:179], v[220:223], v[68:71]
	v_mfma_f32_16x16x32_bf16 v[64:67], v[184:187], v[220:223], v[64:67]
	s_setprio 0
	s_barrier
	s_add_i32 s26, s68, s60
	v_lshl_add_u64 v[208:209], s[54:55], 0, v[130:131]
	s_mov_b32 m0, s26
	ds_read_b128 v[188:191], v152 offset:16384
	ds_read_b128 v[192:195], v152 offset:17408
	ds_read_b128 v[196:199], v152 offset:18432
	ds_read_b128 v[200:203], v152 offset:19456
	ds_read_b128 v[204:207], v152 offset:20480
	ds_read_b128 v[212:215], v152 offset:21504
	ds_read_b128 v[216:219], v152 offset:22528
	ds_read_b128 v[220:223], v152 offset:23552
	global_load_lds_dwordx4 v[208:209], off
	s_add_i32 m0, s26, 0x2000
	s_add_u32 s26, s54, 0x20000
	v_lshl_add_u64 v[224:225], s[54:55], 0, v[134:135]
	s_addc_u32 s27, s55, 0
	s_add_i32 s33, s69, s60
	global_load_lds_dwordx4 v[224:225], off
	v_lshl_add_u64 v[226:227], s[26:27], 0, v[130:131]
	s_mov_b32 m0, s33
	v_lshl_add_u64 v[228:229], s[56:57], 0, v[132:133]
	global_load_lds_dwordx4 v[226:227], off
	v_lshl_add_u64 v[226:227], s[26:27], 0, v[134:135]
	s_add_i32 m0, s33, 0x2000
	s_nop 0
	global_load_lds_dwordx4 v[226:227], off
	v_lshl_add_u64 v[226:227], s[56:57], 0, v[128:129]
	s_mov_b32 m0, s51
	s_nop 0
	global_load_lds_dwordx4 v[226:227], off
	s_mov_b32 m0, s61
	s_nop 0
	global_load_lds_dwordx4 v[228:229], off
	s_waitcnt vmcnt(8)
	s_waitcnt lgkmcnt(0)
	s_barrier
	s_setprio 1
	s_waitcnt lgkmcnt(0)
	v_mfma_f32_16x16x32_bf16 v[60:63], v[156:159], v[188:191], v[60:63]
	v_mfma_f32_16x16x32_bf16 v[56:59], v[164:167], v[188:191], v[56:59]
	v_mfma_f32_16x16x32_bf16 v[44:47], v[156:159], v[196:199], v[44:47]
	v_mfma_f32_16x16x32_bf16 v[40:43], v[164:167], v[196:199], v[40:43]
	v_mfma_f32_16x16x32_bf16 v[28:31], v[156:159], v[204:207], v[28:31]
	v_mfma_f32_16x16x32_bf16 v[24:27], v[164:167], v[204:207], v[24:27]
	v_mfma_f32_16x16x32_bf16 v[12:15], v[156:159], v[216:219], v[12:15]
	v_mfma_f32_16x16x32_bf16 v[8:11], v[164:167], v[216:219], v[8:11]
	v_mfma_f32_16x16x32_bf16 v[60:63], v[160:163], v[192:195], v[60:63]
	v_mfma_f32_16x16x32_bf16 v[56:59], v[168:171], v[192:195], v[56:59]
	v_mfma_f32_16x16x32_bf16 v[44:47], v[160:163], v[200:203], v[44:47]
	v_mfma_f32_16x16x32_bf16 v[40:43], v[168:171], v[200:203], v[40:43]
	v_mfma_f32_16x16x32_bf16 v[28:31], v[160:163], v[212:215], v[28:31]
	v_mfma_f32_16x16x32_bf16 v[24:27], v[168:171], v[212:215], v[24:27]
	v_mfma_f32_16x16x32_bf16 v[12:15], v[160:163], v[220:223], v[12:15]
	v_mfma_f32_16x16x32_bf16 v[8:11], v[168:171], v[220:223], v[8:11]
	s_setprio 0
	s_setprio 1
	v_mfma_f32_16x16x32_bf16 v[52:55], v[172:175], v[188:191], v[52:55]
	v_mfma_f32_16x16x32_bf16 v[48:51], v[180:183], v[188:191], v[48:51]
	v_mfma_f32_16x16x32_bf16 v[36:39], v[172:175], v[196:199], v[36:39]
	v_mfma_f32_16x16x32_bf16 v[32:35], v[180:183], v[196:199], v[32:35]
	v_mfma_f32_16x16x32_bf16 v[20:23], v[172:175], v[204:207], v[20:23]
	v_mfma_f32_16x16x32_bf16 v[16:19], v[180:183], v[204:207], v[16:19]
	v_mfma_f32_16x16x32_bf16 v[4:7], v[172:175], v[216:219], v[4:7]
	v_mfma_f32_16x16x32_bf16 v[0:3], v[180:183], v[216:219], v[0:3]
	v_mfma_f32_16x16x32_bf16 v[52:55], v[176:179], v[192:195], v[52:55]
	v_mfma_f32_16x16x32_bf16 v[48:51], v[184:187], v[192:195], v[48:51]
	v_mfma_f32_16x16x32_bf16 v[36:39], v[176:179], v[200:203], v[36:39]
	v_mfma_f32_16x16x32_bf16 v[32:35], v[184:187], v[200:203], v[32:35]
	v_mfma_f32_16x16x32_bf16 v[20:23], v[176:179], v[212:215], v[20:23]
	v_mfma_f32_16x16x32_bf16 v[16:19], v[184:187], v[212:215], v[16:19]
	v_mfma_f32_16x16x32_bf16 v[4:7], v[176:179], v[220:223], v[4:7]
	v_mfma_f32_16x16x32_bf16 v[0:3], v[184:187], v[220:223], v[0:3]
	s_setprio 0
	s_barrier
; #define PG8_STAGE(bufoff, gbase, voff) do { _Pragma("unroll") for (int _i = 0; _i < 2; ++_i) \
;         __builtin_amdgcn_global_load_lds((const unsigned*)((const char*)(gbase) + (voff)[_i]), (PG8_LAS unsigned*)(lds + (bufoff) + ldsw + _i * 8192), 16, 0, 0); } while (0)
; #define PG8_LDA(dst, b, h) do { _Pragma("unroll") for (int m = 0; m < 4; ++m) _Pragma("unroll") for (int k = 0; k < 2; ++k) dst[m][k] = *(const PG8_LAS bf16x8*)(lds + PG8_SA(b, h) + aoff + m * 2048 + k * 1024); } while (0)
; #define PG8_LDB(dst, b, h) do { _Pragma("unroll") for (int n = 0; n < 2; ++n) _Pragma("unroll") for (int k = 0; k < 2; ++k) dst[n][k] = *(const PG8_LAS bf16x8*)(lds + PG8_SB(b, h) + boff + n * 2048 + k * 1024); } while (0)
; #define PG8_MMA(ai, bj, At, Bt) do { __builtin_amdgcn_s_setprio(1); _Pragma("unroll") for (int m = 0; m < 4; ++m) _Pragma("unroll") for (int n = 0; n < 2; ++n) _Pragma("unroll") for (int k = 0; k < 2; ++k) \
;         acc[ai][bj][m][n] = __builtin_amdgcn_mfma_f32_16x16x32_bf16(Bt[n][k], At[m][k], acc[ai][bj][m][n], 0, 0, 0); __builtin_amdgcn_s_setprio(0); } while (0)
; #define PG8_WAIT_V(n) asm volatile("s_waitcnt vmcnt(" #n ")" ::: "memory")
; #define PG8_WAIT_L(n) asm volatile("s_waitcnt lgkmcnt(" #n ")" ::: "memory")
; #define PG8_BAR __builtin_amdgcn_s_barrier()
; #define PG8_SCHED __builtin_amdgcn_sched_barrier(0)
; template <class Epi, class Sched, bool ALIGN_EPI = false, bool SP2 = false>
; __device__ __forceinline__ void gemm_phase(PG8_LAS unsigned char* lds, const Gemm g, const Sched& S, const Epi& E, int tid_in) {
;     ...
;             PG8_LDB(B0, 1, 0); PG8_LDB(B1, 1, 1); PG8_SCHED; PG8_LDA(At, 1, 0); PG8_STAGE(PG8_SA(0, 1), a2 + hstep, voffA);
;             PG8_WAIT_V(8); PG8_WAIT_L(0); PG8_BAR; PG8_MMA(0, 0, At, B0); PG8_MMA(0, 1, At, B1); PG8_BAR; PG8_SCHED;
;             PG8_LDA(At, 1, 1); PG8_STAGE(PG8_SB(1, 0), b3, voffB); PG8_STAGE(PG8_SB(1, 1), b3 + hstepB, voffB); PG8_STAGE(PG8_SA(1, 0), a3, voffA);
;             PG8_WAIT_V(8); PG8_WAIT_L(0); PG8_BAR; PG8_MMA(1, 0, At, B0); PG8_MMA(1, 1, At, B1); PG8_BAR; PG8_SCHED;
	s_add_i32 s33, 0, 0x18000
	v_add_u32_e32 v155, s33, v146
	s_add_i32 s77, 0, 0x1c000
	ds_read_b128 v[156:159], v155
	ds_read_b128 v[160:163], v155 offset:1024
	ds_read_b128 v[164:167], v155 offset:2048
	ds_read_b128 v[168:171], v155 offset:3072
	v_add_u32_e32 v155, s77, v146
	ds_read_b128 v[172:175], v155
	ds_read_b128 v[176:179], v155 offset:1024
	ds_read_b128 v[180:183], v155 offset:2048
	ds_read_b128 v[184:187], v155 offset:3072
	s_add_u32 s26, s56, 0x80000
	s_addc_u32 s27, s57, 0
	s_mov_b32 m0, s62
	v_lshl_add_u64 v[230:231], s[26:27], 0, v[128:129]
	ds_read_b128 v[188:191], v152 offset:32768
	ds_read_b128 v[192:195], v152 offset:33792
	ds_read_b128 v[196:199], v152 offset:34816
	ds_read_b128 v[200:203], v152 offset:35840
	ds_read_b128 v[204:207], v152 offset:36864
	ds_read_b128 v[212:215], v152 offset:37888
	ds_read_b128 v[216:219], v152 offset:38912
	ds_read_b128 v[220:223], v152 offset:39936
	global_load_lds_dwordx4 v[230:231], off
	v_lshl_add_u64 v[230:231], s[26:27], 0, v[132:133]
	s_mov_b32 m0, s63
	s_nop 0
	global_load_lds_dwordx4 v[230:231], off
	s_waitcnt vmcnt(8)
	s_waitcnt lgkmcnt(0)
	s_barrier
	s_setprio 1
	s_waitcnt lgkmcnt(0)
	v_mfma_f32_16x16x32_bf16 v[124:127], v[156:159], v[188:191], v[124:127]
	v_mfma_f32_16x16x32_bf16 v[120:123], v[164:167], v[188:191], v[120:123]
	v_mfma_f32_16x16x32_bf16 v[108:111], v[156:159], v[196:199], v[108:111]
	v_mfma_f32_16x16x32_bf16 v[104:107], v[164:167], v[196:199], v[104:107]
	v_mfma_f32_16x16x32_bf16 v[92:95], v[156:159], v[204:207], v[92:95]
	v_mfma_f32_16x16x32_bf16 v[88:91], v[164:167], v[204:207], v[88:91]
	v_mfma_f32_16x16x32_bf16 v[76:79], v[156:159], v[216:219], v[76:79]
	v_mfma_f32_16x16x32_bf16 v[72:75], v[164:167], v[216:219], v[72:75]
	v_mfma_f32_16x16x32_bf16 v[124:127], v[160:163], v[192:195], v[124:127]
	v_mfma_f32_16x16x32_bf16 v[120:123], v[168:171], v[192:195], v[120:123]
	v_mfma_f32_16x16x32_bf16 v[108:111], v[160:163], v[200:203], v[108:111]
	v_mfma_f32_16x16x32_bf16 v[104:107], v[168:171], v[200:203], v[104:107]
	v_mfma_f32_16x16x32_bf16 v[92:95], v[160:163], v[212:215], v[92:95]
	v_mfma_f32_16x16x32_bf16 v[88:91], v[168:171], v[212:215], v[88:91]
	v_mfma_f32_16x16x32_bf16 v[76:79], v[160:163], v[220:223], v[76:79]
	v_mfma_f32_16x16x32_bf16 v[72:75], v[168:171], v[220:223], v[72:75]
	s_setprio 0
	s_setprio 1
	v_mfma_f32_16x16x32_bf16 v[116:119], v[172:175], v[188:191], v[116:119]
	v_mfma_f32_16x16x32_bf16 v[112:115], v[180:183], v[188:191], v[112:115]
	v_mfma_f32_16x16x32_bf16 v[100:103], v[172:175], v[196:199], v[100:103]
	v_mfma_f32_16x16x32_bf16 v[96:99], v[180:183], v[196:199], v[96:99]
	v_mfma_f32_16x16x32_bf16 v[84:87], v[172:175], v[204:207], v[84:87]
	v_mfma_f32_16x16x32_bf16 v[80:83], v[180:183], v[204:207], v[80:83]
	v_mfma_f32_16x16x32_bf16 v[68:71], v[172:175], v[216:219], v[68:71]
	v_mfma_f32_16x16x32_bf16 v[64:67], v[180:183], v[216:219], v[64:67]
	v_mfma_f32_16x16x32_bf16 v[116:119], v[176:179], v[192:195], v[116:119]
	v_mfma_f32_16x16x32_bf16 v[112:115], v[184:187], v[192:195], v[112:115]
	v_mfma_f32_16x16x32_bf16 v[100:103], v[176:179], v[200:203], v[100:103]
	v_mfma_f32_16x16x32_bf16 v[96:99], v[184:187], v[200:203], v[96:99]
	v_mfma_f32_16x16x32_bf16 v[84:87], v[176:179], v[212:215], v[84:87]
	v_mfma_f32_16x16x32_bf16 v[80:83], v[184:187], v[212:215], v[80:83]
	v_mfma_f32_16x16x32_bf16 v[68:71], v[176:179], v[220:223], v[68:71]
	v_mfma_f32_16x16x32_bf16 v[64:67], v[184:187], v[220:223], v[64:67]
	s_setprio 0
	s_barrier
	s_add_i32 s26, s33, s60
	v_lshl_add_u64 v[208:209], v[208:209], 0, s[12:13]
	s_mov_b32 m0, s26
	ds_read_b128 v[188:191], v152 offset:49152
	ds_read_b128 v[192:195], v152 offset:50176
	ds_read_b128 v[196:199], v152 offset:51200
	ds_read_b128 v[200:203], v152 offset:52224
	ds_read_b128 v[204:207], v152 offset:53248
	ds_read_b128 v[212:215], v152 offset:54272
	ds_read_b128 v[216:219], v152 offset:55296
	ds_read_b128 v[220:223], v152 offset:56320
	global_load_lds_dwordx4 v[208:209], off
	s_add_i32 m0, s26, 0x2000
	s_add_u32 s26, s54, 0x20080
	v_lshl_add_u64 v[208:209], v[224:225], 0, s[12:13]
	s_addc_u32 s27, s55, 0
	s_add_i32 s33, s77, s60
	global_load_lds_dwordx4 v[208:209], off
	v_lshl_add_u64 v[208:209], s[26:27], 0, v[130:131]
	s_mov_b32 m0, s33
	s_nop 0
	global_load_lds_dwordx4 v[208:209], off
	v_lshl_add_u64 v[208:209], s[26:27], 0, v[134:135]
	s_add_i32 m0, s33, 0x2000
	s_nop 0
	global_load_lds_dwordx4 v[208:209], off
	v_lshl_add_u64 v[208:209], v[226:227], 0, s[12:13]
	s_mov_b32 m0, s66
	s_nop 0
	global_load_lds_dwordx4 v[208:209], off
	v_lshl_add_u64 v[208:209], v[228:229], 0, s[12:13]
	s_mov_b32 m0, s67
	s_nop 0
	global_load_lds_dwordx4 v[208:209], off
	s_waitcnt vmcnt(8)
	s_waitcnt lgkmcnt(0)
	s_barrier
; template <class Epi, class Sched, bool ALIGN_EPI = false, bool SP2 = false>
; __device__ __forceinline__ void gemm_phase(PG8_LAS unsigned char* lds, const Gemm g, const Sched& S, const Epi& E, int tid_in) {
;     ...
;             PG8_WAIT_V(8); PG8_WAIT_L(0); PG8_BAR; PG8_MMA(1, 0, At, B0); PG8_MMA(1, 1, At, B1); PG8_BAR; PG8_SCHED;
;             } else {
;             PG8_LDB(B0, 0, 0); PG8_SCHED; PG8_LDA(At, 0, 0); PG8_STAGE(PG8_SA(1, 1), a1 + hstep, voffA);
;             PG8_WAIT_L(8); PG8_BAR; PG8_WAIT_L(0); PG8_MMA(0, 0, At, B0); PG8_BAR; PG8_SCHED;
;             PG8_LDB(B1, 0, 1); PG8_STAGE(PG8_SB(0, 0), b2, voffB);
;             PG8_BAR; PG8_WAIT_L(0); PG8_MMA(0, 1, At, B1); PG8_BAR;
;             PG8_LDA(At, 0, 1); PG8_STAGE(PG8_SA(0, 0), a2, voffA);
;             PG8_BAR; PG8_WAIT_L(0); PG8_MMA(1, 0, At, B0); PG8_BAR; PG8_SCHED;
;             PG8_STAGE(PG8_SB(0, 1), b2 + hstepB, voffB);
;             PG8_WAIT_V(6); PG8_BAR; PG8_MMA(1, 1, At, B1); PG8_BAR;
;             PG8_LDB(B0, 1, 0); PG8_SCHED; PG8_LDA(At, 1, 0); PG8_STAGE(PG8_SA(0, 1), a2 + hstep, voffA);
;             PG8_WAIT_L(8); PG8_BAR; PG8_WAIT_L(0); PG8_MMA(0, 0, At, B0); PG8_BAR; PG8_SCHED;
;             PG8_LDB(B1, 1, 1); PG8_STAGE(PG8_SB(1, 0), b3, voffB);
;             PG8_BAR; PG8_WAIT_L(0); PG8_MMA(0, 1, At, B1); PG8_BAR;
;             PG8_LDA(At, 1, 1); PG8_STAGE(PG8_SA(1, 0), a3, voffA);
;             PG8_BAR; PG8_WAIT_L(0); PG8_MMA(1, 0, At, B0); PG8_BAR; PG8_SCHED;
;             PG8_STAGE(PG8_SB(1, 1), b3 + hstepB, voffB);
;             PG8_WAIT_V(6); PG8_BAR; PG8_MMA(1, 1, At, B1); PG8_BAR;
;             }
;         }
;         if constexpr (ALIGN_EPI) { if (wr == 0) PG8_BAR; }
;     __device__ __forceinline__ void operator()(const f32x4 (&acc)[2][2][4][2], const Unit& u, int wr, int wc, int fr, int fq) const {
;         const int lane = fr + 16 * fq; PG8_LAS unsigned char* stg = lds + STG_OFF + (wr * 4 + wc) * STG_WAVE;
;         const PG8_LAS float* rtab = (const PG8_LAS float*)(lds + RSTD_OFF) + ((u.pm >> 3) & 3) * 256;
; #pragma unroll
;         for (int ai = 0; ai < 2; ++ai)
; #pragma unroll
;             for (int m = 0; m < 4; ++m) {
;                 const int rowg0 = u.pm * BM + ai * HALF + wr * 64 + m * 16; const float rs = rtab[ai * HALF + wr * 64 + m * 16 + fr];
; #pragma unroll
;                 for (int bj = 0; bj < 2; ++bj) {
	s_setprio 1
	s_waitcnt lgkmcnt(0)
	v_mfma_f32_16x16x32_bf16 v[60:63], v[156:159], v[188:191], v[60:63]
	v_mfma_f32_16x16x32_bf16 v[56:59], v[164:167], v[188:191], v[56:59]
	v_mfma_f32_16x16x32_bf16 v[44:47], v[156:159], v[196:199], v[44:47]
	v_mfma_f32_16x16x32_bf16 v[40:43], v[164:167], v[196:199], v[40:43]
	v_mfma_f32_16x16x32_bf16 v[28:31], v[156:159], v[204:207], v[28:31]
	v_mfma_f32_16x16x32_bf16 v[24:27], v[164:167], v[204:207], v[24:27]
	v_mfma_f32_16x16x32_bf16 v[12:15], v[156:159], v[216:219], v[12:15]
	v_mfma_f32_16x16x32_bf16 v[8:11], v[164:167], v[216:219], v[8:11]
	v_mfma_f32_16x16x32_bf16 v[60:63], v[160:163], v[192:195], v[60:63]
	v_mfma_f32_16x16x32_bf16 v[56:59], v[168:171], v[192:195], v[56:59]
	v_mfma_f32_16x16x32_bf16 v[44:47], v[160:163], v[200:203], v[44:47]
	v_mfma_f32_16x16x32_bf16 v[40:43], v[168:171], v[200:203], v[40:43]
	v_mfma_f32_16x16x32_bf16 v[28:31], v[160:163], v[212:215], v[28:31]
	v_mfma_f32_16x16x32_bf16 v[24:27], v[168:171], v[212:215], v[24:27]
	v_mfma_f32_16x16x32_bf16 v[12:15], v[160:163], v[220:223], v[12:15]
	v_mfma_f32_16x16x32_bf16 v[8:11], v[168:171], v[220:223], v[8:11]
	s_setprio 0
	s_setprio 1
	v_mfma_f32_16x16x32_bf16 v[52:55], v[172:175], v[188:191], v[52:55]
	v_mfma_f32_16x16x32_bf16 v[48:51], v[180:183], v[188:191], v[48:51]
	v_mfma_f32_16x16x32_bf16 v[36:39], v[172:175], v[196:199], v[36:39]
	v_mfma_f32_16x16x32_bf16 v[32:35], v[180:183], v[196:199], v[32:35]
	v_mfma_f32_16x16x32_bf16 v[20:23], v[172:175], v[204:207], v[20:23]
	v_mfma_f32_16x16x32_bf16 v[16:19], v[180:183], v[204:207], v[16:19]
	v_mfma_f32_16x16x32_bf16 v[4:7], v[172:175], v[216:219], v[4:7]
	v_mfma_f32_16x16x32_bf16 v[0:3], v[180:183], v[216:219], v[0:3]
	v_mfma_f32_16x16x32_bf16 v[52:55], v[176:179], v[192:195], v[52:55]
	v_mfma_f32_16x16x32_bf16 v[48:51], v[184:187], v[192:195], v[48:51]
	v_mfma_f32_16x16x32_bf16 v[36:39], v[176:179], v[200:203], v[36:39]
	v_mfma_f32_16x16x32_bf16 v[32:35], v[184:187], v[200:203], v[32:35]
	v_mfma_f32_16x16x32_bf16 v[20:23], v[176:179], v[212:215], v[20:23]
	v_mfma_f32_16x16x32_bf16 v[16:19], v[184:187], v[212:215], v[16:19]
	v_mfma_f32_16x16x32_bf16 v[4:7], v[176:179], v[220:223], v[4:7]
	v_mfma_f32_16x16x32_bf16 v[0:3], v[184:187], v[220:223], v[0:3]
	s_setprio 0
	s_barrier
	s_add_i32 s76, s76, 2
	s_add_u32 s52, s52, 0x100
	s_addc_u32 s53, s53, 0
	s_add_u32 s74, s74, 0x100
	s_addc_u32 s75, s75, 0
	s_cmp_gt_u32 s76, 29
	s_cbranch_scc0 .LBB0_394
	s_and_b64 vcc, exec, s[14:15]
	s_cbranch_vccz .LBB0_397
	s_barrier
.LBB0_397:
	s_lshl_b32 s26, s50, 7
	s_and_b32 s26, s26, 0xc00
	v_add_u32_e32 v155, s26, v149
	ds_read_b32 v156, v155
	s_lshl_b32 s43, s50, 8
	s_lshl_b32 s26, s71, 8
	s_add_i32 s43, s43, s65
	s_ashr_i32 s27, s26, 31
	s_waitcnt lgkmcnt(0)
	v_pk_mul_f32 v[126:127], v[126:127], v[156:157] op_sel_hi:[1,0]
	v_pk_mul_f32 v[124:125], v[124:125], v[156:157] op_sel_hi:[1,0]
	v_pk_mul_f32 v[122:123], v[122:123], v[156:157] op_sel_hi:[1,0]
	v_pk_mul_f32 v[120:121], v[120:121], v[156:157] op_sel_hi:[1,0]
	v_max_f32_e32 v127, 0, v127
	v_max_f32_e32 v126, 0, v126
	v_max_f32_e32 v125, 0, v125
	v_max_f32_e32 v124, 0, v124
	v_max_f32_e32 v123, 0, v123
	v_max_f32_e32 v122, 0, v122
	v_max_f32_e32 v121, 0, v121
	v_max_f32_e32 v120, 0, v120
	v_pk_mul_f32 v[118:119], v[118:119], v[156:157] op_sel_hi:[1,0]
	v_pk_mul_f32 v[116:117], v[116:117], v[156:157] op_sel_hi:[1,0]
	v_pk_mul_f32 v[114:115], v[114:115], v[156:157] op_sel_hi:[1,0]
	v_pk_mul_f32 v[112:113], v[112:113], v[156:157] op_sel_hi:[1,0]
	v_pk_mul_f32 v[126:127], v[126:127], v[126:127]
	v_pk_mul_f32 v[124:125], v[124:125], v[124:125]
	v_pk_mul_f32 v[158:159], v[122:123], v[122:123]
	v_pk_mul_f32 v[122:123], v[120:121], v[120:121]
	v_cvt_pk_bf16_f32 v120, v124, v125
	v_cvt_pk_bf16_f32 v121, v126, v127
	v_max_f32_e32 v119, 0, v119
	v_max_f32_e32 v118, 0, v118
	v_max_f32_e32 v117, 0, v117
	v_max_f32_e32 v116, 0, v116
	v_max_f32_e32 v115, 0, v115
	v_max_f32_e32 v114, 0, v114
	v_max_f32_e32 v113, 0, v113
	v_max_f32_e32 v112, 0, v112
	v_cvt_pk_bf16_f32 v122, v122, v123
	v_cvt_pk_bf16_f32 v123, v158, v159
	ds_write_b128 v153, v[120:123]
	v_pk_mul_f32 v[118:119], v[118:119], v[118:119]
	v_pk_mul_f32 v[116:117], v[116:117], v[116:117]
	v_pk_mul_f32 v[120:121], v[114:115], v[114:115]
	v_pk_mul_f32 v[114:115], v[112:113], v[112:113]
	v_cvt_pk_bf16_f32 v112, v116, v117
	v_cvt_pk_bf16_f32 v113, v118, v119
	v_or_b32_e32 v118, s43, v147
	v_cvt_pk_bf16_f32 v114, v114, v115
	v_cvt_pk_bf16_f32 v115, v120, v121
	ds_write_b128 v153, v[112:115] offset:64
	v_lshl_add_u64 v[112:113], s[26:27], 1, v[136:137]
	ds_read_b128 v[114:117], v154
	v_mad_i64_i32 v[122:123], s[26:27], v118, s70, v[112:113]
	ds_read_b128 v[118:121], v154 offset:1152
	ds_read_b32 v124, v155 offset:64
	s_or_b32 s33, s43, 16
	s_waitcnt lgkmcnt(0)
; #define PG8_LAS __attribute__((address_space(3)))
; __device__ __forceinline__ unsigned cvt_pk_bf16(float lo, float hi) { unsigned r; asm volatile("v_cvt_pk_bf16_f32 %0, %1, %2" : "=v"(r) : "v"(lo), "v"(hi)); return r; }
;     __device__ __forceinline__ void operator()(const f32x4 (&acc)[2][2][4][2], const Unit& u, int wr, int wc, int fr, int fq) const {
;         const int lane = fr + 16 * fq; PG8_LAS unsigned char* stg = lds + STG_OFF + (wr * 4 + wc) * STG_WAVE;
;         const PG8_LAS float* rtab = (const PG8_LAS float*)(lds + RSTD_OFF) + ((u.pm >> 3) & 3) * 256;
; #pragma unroll
;         for (int ai = 0; ai < 2; ++ai)
; #pragma unroll
;             for (int m = 0; m < 4; ++m) {
;                 const int rowg0 = u.pm * BM + ai * HALF + wr * 64 + m * 16; const float rs = rtab[ai * HALF + wr * 64 + m * 16 + fr];
; #pragma unroll
;                 for (int bj = 0; bj < 2; ++bj) {
;                     f32x4 v0 = acc[ai][bj][m][0] * rs, v1 = acc[ai][bj][m][1] * rs;
;                     if (ACT == 1) { const f32x4 z = {0.f, 0.f, 0.f, 0.f}; v0 = __builtin_elementwise_max(v0, z); v1 = __builtin_elementwise_max(v1, z); v0 = v0 * v0; v1 = v1 * v1; }
;                     u32x4 w; w.x = cvt_pk_bf16(v0[0], v0[1]); w.y = cvt_pk_bf16(v0[2], v0[3]); w.z = cvt_pk_bf16(v1[0], v1[1]); w.w = cvt_pk_bf16(v1[2], v1[3]);
;                     *(PG8_LAS u32x4*)(stg + fr * STG_ROW + bj * 64 + fq * 16) = w; }
;                 staged_store_bf16<LAYOUT>(stg, O, (size_t)ldc, rowg0, u.pn, wc, lane);
	global_store_dwordx4 v[122:123], v[114:117], off nt
	s_andn2_b64 vcc, exec, s[8:9]
	s_mov_b64 s[8:9], -1
	v_or_b32_e32 v114, s43, v148
	v_pk_mul_f32 v[110:111], v[110:111], v[124:125] op_sel_hi:[1,0]
	v_pk_mul_f32 v[108:109], v[108:109], v[124:125] op_sel_hi:[1,0]
	v_pk_mul_f32 v[106:107], v[106:107], v[124:125] op_sel_hi:[1,0]
	v_pk_mul_f32 v[104:105], v[104:105], v[124:125] op_sel_hi:[1,0]
	v_mad_i64_i32 v[114:115], s[26:27], v114, s70, v[112:113]
	v_max_f32_e32 v111, 0, v111
	v_max_f32_e32 v110, 0, v110
	v_max_f32_e32 v109, 0, v109
	v_max_f32_e32 v108, 0, v108
	v_max_f32_e32 v107, 0, v107
	v_max_f32_e32 v106, 0, v106
	v_max_f32_e32 v105, 0, v105
	v_max_f32_e32 v104, 0, v104
	v_pk_mul_f32 v[100:101], v[100:101], v[124:125] op_sel_hi:[1,0]
	v_pk_mul_f32 v[98:99], v[98:99], v[124:125] op_sel_hi:[1,0]
	v_pk_mul_f32 v[96:97], v[96:97], v[124:125] op_sel_hi:[1,0]
	global_store_dwordx4 v[114:115], v[118:121], off nt
	v_pk_mul_f32 v[110:111], v[110:111], v[110:111]
	v_pk_mul_f32 v[108:109], v[108:109], v[108:109]
	v_pk_mul_f32 v[114:115], v[106:107], v[106:107]
	v_pk_mul_f32 v[106:107], v[104:105], v[104:105]
	v_cvt_pk_bf16_f32 v104, v108, v109
	v_cvt_pk_bf16_f32 v105, v110, v111
	v_pk_mul_f32 v[102:103], v[102:103], v[124:125] op_sel_hi:[1,0]
	v_max_f32_e32 v101, 0, v101
	v_max_f32_e32 v100, 0, v100
	v_max_f32_e32 v99, 0, v99
	v_max_f32_e32 v98, 0, v98
	v_max_f32_e32 v97, 0, v97
	v_max_f32_e32 v96, 0, v96
	v_cvt_pk_bf16_f32 v106, v106, v107
	v_cvt_pk_bf16_f32 v107, v114, v115
	ds_write_b128 v153, v[104:107]
	v_max_f32_e32 v103, 0, v103
	v_max_f32_e32 v102, 0, v102
	v_pk_mul_f32 v[100:101], v[100:101], v[100:101]
	v_pk_mul_f32 v[104:105], v[98:99], v[98:99]
	v_pk_mul_f32 v[98:99], v[96:97], v[96:97]
	v_pk_mul_f32 v[102:103], v[102:103], v[102:103]
	v_cvt_pk_bf16_f32 v96, v100, v101
	v_or_b32_e32 v100, s33, v147
	v_cvt_pk_bf16_f32 v97, v102, v103
	v_cvt_pk_bf16_f32 v98, v98, v99
	v_cvt_pk_bf16_f32 v99, v104, v105
	ds_write_b128 v153, v[96:99] offset:64
	ds_read_b128 v[96:99], v154
	v_mad_i64_i32 v[104:105], s[26:27], v100, s70, v[112:113]
	ds_read_b128 v[100:103], v154 offset:1152
	ds_read_b32 v106, v155 offset:128
	s_waitcnt lgkmcnt(0)
	global_store_dwordx4 v[104:105], v[96:99], off nt
	v_pk_mul_f32 v[94:95], v[94:95], v[106:107] op_sel_hi:[1,0]
	s_nop 0
	v_or_b32_e32 v96, s33, v148
	v_pk_mul_f32 v[92:93], v[92:93], v[106:107] op_sel_hi:[1,0]
	v_pk_mul_f32 v[90:91], v[90:91], v[106:107] op_sel_hi:[1,0]
	v_pk_mul_f32 v[88:89], v[88:89], v[106:107] op_sel_hi:[1,0]
	v_mad_i64_i32 v[96:97], s[26:27], v96, s70, v[112:113]
	v_max_f32_e32 v95, 0, v95
	v_max_f32_e32 v94, 0, v94
	v_max_f32_e32 v93, 0, v93
	v_max_f32_e32 v92, 0, v92
	v_max_f32_e32 v91, 0, v91
	v_max_f32_e32 v90, 0, v90
	v_max_f32_e32 v89, 0, v89
	v_max_f32_e32 v88, 0, v88
	v_pk_mul_f32 v[84:85], v[84:85], v[106:107] op_sel_hi:[1,0]
	v_pk_mul_f32 v[82:83], v[82:83], v[106:107] op_sel_hi:[1,0]
	v_pk_mul_f32 v[80:81], v[80:81], v[106:107] op_sel_hi:[1,0]
	global_store_dwordx4 v[96:97], v[100:103], off nt
	v_pk_mul_f32 v[94:95], v[94:95], v[94:95]
	v_pk_mul_f32 v[92:93], v[92:93], v[92:93]
	v_pk_mul_f32 v[96:97], v[90:91], v[90:91]
	v_pk_mul_f32 v[90:91], v[88:89], v[88:89]
	v_cvt_pk_bf16_f32 v88, v92, v93
	v_cvt_pk_bf16_f32 v89, v94, v95
	v_pk_mul_f32 v[86:87], v[86:87], v[106:107] op_sel_hi:[1,0]
	v_max_f32_e32 v85, 0, v85
	v_max_f32_e32 v84, 0, v84
	v_max_f32_e32 v83, 0, v83
	v_max_f32_e32 v82, 0, v82
	v_max_f32_e32 v81, 0, v81
	v_max_f32_e32 v80, 0, v80
	v_cvt_pk_bf16_f32 v90, v90, v91
	v_cvt_pk_bf16_f32 v91, v96, v97
	ds_write_b128 v153, v[88:91]
	v_max_f32_e32 v87, 0, v87
	v_max_f32_e32 v86, 0, v86
	v_pk_mul_f32 v[84:85], v[84:85], v[84:85]
	v_pk_mul_f32 v[88:89], v[82:83], v[82:83]
	v_pk_mul_f32 v[82:83], v[80:81], v[80:81]
	s_or_b32 s33, s43, 32
	v_pk_mul_f32 v[86:87], v[86:87], v[86:87]
	v_cvt_pk_bf16_f32 v80, v84, v85
	v_or_b32_e32 v84, s33, v147
	v_cvt_pk_bf16_f32 v81, v86, v87
	v_cvt_pk_bf16_f32 v82, v82, v83
	v_cvt_pk_bf16_f32 v83, v88, v89
	ds_write_b128 v153, v[80:83] offset:64
	ds_read_b128 v[80:83], v154
	v_mad_i64_i32 v[88:89], s[26:27], v84, s70, v[112:113]
	ds_read_b128 v[84:87], v154 offset:1152
	ds_read_b32 v90, v155 offset:192
	s_waitcnt lgkmcnt(0)
	global_store_dwordx4 v[88:89], v[80:83], off nt
	v_pk_mul_f32 v[78:79], v[78:79], v[90:91] op_sel_hi:[1,0]
	s_nop 0
	v_or_b32_e32 v80, s33, v148
	v_pk_mul_f32 v[76:77], v[76:77], v[90:91] op_sel_hi:[1,0]
	v_pk_mul_f32 v[74:75], v[74:75], v[90:91] op_sel_hi:[1,0]
	v_pk_mul_f32 v[72:73], v[72:73], v[90:91] op_sel_hi:[1,0]
	v_mad_i64_i32 v[80:81], s[26:27], v80, s70, v[112:113]
	v_max_f32_e32 v79, 0, v79
	v_max_f32_e32 v78, 0, v78
	v_max_f32_e32 v77, 0, v77
	v_max_f32_e32 v76, 0, v76
	v_max_f32_e32 v75, 0, v75
	v_max_f32_e32 v74, 0, v74
	v_max_f32_e32 v73, 0, v73
	v_max_f32_e32 v72, 0, v72
	v_pk_mul_f32 v[68:69], v[68:69], v[90:91] op_sel_hi:[1,0]
	v_pk_mul_f32 v[66:67], v[66:67], v[90:91] op_sel_hi:[1,0]
	v_pk_mul_f32 v[64:65], v[64:65], v[90:91] op_sel_hi:[1,0]
	global_store_dwordx4 v[80:81], v[84:87], off nt
	v_pk_mul_f32 v[78:79], v[78:79], v[78:79]
	v_pk_mul_f32 v[76:77], v[76:77], v[76:77]
	v_pk_mul_f32 v[80:81], v[74:75], v[74:75]
	v_pk_mul_f32 v[74:75], v[72:73], v[72:73]
	v_cvt_pk_bf16_f32 v72, v76, v77
	v_cvt_pk_bf16_f32 v73, v78, v79
	v_pk_mul_f32 v[70:71], v[70:71], v[90:91] op_sel_hi:[1,0]
	v_max_f32_e32 v69, 0, v69
	v_max_f32_e32 v68, 0, v68
	v_max_f32_e32 v67, 0, v67
	v_max_f32_e32 v66, 0, v66
	v_max_f32_e32 v65, 0, v65
	v_max_f32_e32 v64, 0, v64
	v_cvt_pk_bf16_f32 v74, v74, v75
	v_cvt_pk_bf16_f32 v75, v80, v81
	ds_write_b128 v153, v[72:75]
	v_max_f32_e32 v71, 0, v71
	v_max_f32_e32 v70, 0, v70
	v_pk_mul_f32 v[68:69], v[68:69], v[68:69]
	v_pk_mul_f32 v[72:73], v[66:67], v[66:67]
	v_pk_mul_f32 v[66:67], v[64:65], v[64:65]
	s_or_b32 s33, s43, 48
	v_pk_mul_f32 v[70:71], v[70:71], v[70:71]
	v_cvt_pk_bf16_f32 v64, v68, v69
	v_or_b32_e32 v68, s33, v147
	v_cvt_pk_bf16_f32 v65, v70, v71
	v_cvt_pk_bf16_f32 v66, v66, v67
	v_cvt_pk_bf16_f32 v67, v72, v73
	ds_write_b128 v153, v[64:67] offset:64
	ds_read_b128 v[64:67], v154
	v_mad_i64_i32 v[72:73], s[26:27], v68, s70, v[112:113]
	ds_read_b128 v[68:71], v154 offset:1152
	ds_read_b32 v74, v155 offset:512
	s_waitcnt lgkmcnt(0)
; #define PG8_LAS __attribute__((address_space(3)))
; __device__ __forceinline__ unsigned cvt_pk_bf16(float lo, float hi) { unsigned r; asm volatile("v_cvt_pk_bf16_f32 %0, %1, %2" : "=v"(r) : "v"(lo), "v"(hi)); return r; }
; template <int LAYOUT> __device__ __forceinline__ void staged_store_bf16(PG8_LAS unsigned char* stg, bf16_t* O, size_t ldc, int rowg0, int pn, int wc, int lane) {
;     const int p = lane & 7;
; #pragma unroll
;     for (int hr = 0; hr < 2; ++hr) { const int r = 8 * hr + (lane >> 3), rowg = rowg0 + r; const u32x4 w = *(const PG8_LAS u32x4*)(stg + r * STG_ROW + p * 16);
;         if (LAYOUT == 0) __builtin_nontemporal_store(w, (u32x4*)(O + (size_t)rowg * ldc + pn * BM + wc * 64 + p * 8));
;         else { const int P = 2 * pn + (wc >> 1); int drow = rowg;
;             if (LAYOUT == 2) { const int sh = 2 * (P / 24), t = rowg & 16383; drow = (rowg & ~16383) + ((t & ((1 << sh) - 1)) << (14 - sh)) + (t >> sh); }
;             __builtin_nontemporal_store(w, (u32x4*)(O + (size_t)P * PLANE + (size_t)drow * 128 + (wc & 1) * 64 + p * 8)); } }
; }
;     __device__ __forceinline__ void operator()(const f32x4 (&acc)[2][2][4][2], const Unit& u, int wr, int wc, int fr, int fq) const {
;         const int lane = fr + 16 * fq; PG8_LAS unsigned char* stg = lds + STG_OFF + (wr * 4 + wc) * STG_WAVE;
;         const PG8_LAS float* rtab = (const PG8_LAS float*)(lds + RSTD_OFF) + ((u.pm >> 3) & 3) * 256;
; #pragma unroll
;         for (int ai = 0; ai < 2; ++ai)
; #pragma unroll
;             for (int m = 0; m < 4; ++m) {
;                 const int rowg0 = u.pm * BM + ai * HALF + wr * 64 + m * 16; const float rs = rtab[ai * HALF + wr * 64 + m * 16 + fr];
; #pragma unroll
;                 for (int bj = 0; bj < 2; ++bj) {
;                     f32x4 v0 = acc[ai][bj][m][0] * rs, v1 = acc[ai][bj][m][1] * rs;
;                     if (ACT == 1) { const f32x4 z = {0.f, 0.f, 0.f, 0.f}; v0 = __builtin_elementwise_max(v0, z); v1 = __builtin_elementwise_max(v1, z); v0 = v0 * v0; v1 = v1 * v1; }
;                     u32x4 w; w.x = cvt_pk_bf16(v0[0], v0[1]); w.y = cvt_pk_bf16(v0[2], v0[3]); w.z = cvt_pk_bf16(v1[0], v1[1]); w.w = cvt_pk_bf16(v1[2], v1[3]);
;                     *(PG8_LAS u32x4*)(stg + fr * STG_ROW + bj * 64 + fq * 16) = w; }
;                 staged_store_bf16<LAYOUT>(stg, O, (size_t)ldc, rowg0, u.pn, wc, lane);
	global_store_dwordx4 v[72:73], v[64:67], off nt
	v_pk_mul_f32 v[62:63], v[62:63], v[74:75] op_sel_hi:[1,0]
	s_nop 0
	v_or_b32_e32 v64, s33, v148
	v_pk_mul_f32 v[60:61], v[60:61], v[74:75] op_sel_hi:[1,0]
	v_pk_mul_f32 v[58:59], v[58:59], v[74:75] op_sel_hi:[1,0]
	v_pk_mul_f32 v[56:57], v[56:57], v[74:75] op_sel_hi:[1,0]
	v_mad_i64_i32 v[64:65], s[26:27], v64, s70, v[112:113]
	v_max_f32_e32 v63, 0, v63
	v_max_f32_e32 v62, 0, v62
	v_max_f32_e32 v61, 0, v61
	v_max_f32_e32 v60, 0, v60
	v_max_f32_e32 v59, 0, v59
	v_max_f32_e32 v58, 0, v58
	v_max_f32_e32 v57, 0, v57
	v_max_f32_e32 v56, 0, v56
	v_pk_mul_f32 v[52:53], v[52:53], v[74:75] op_sel_hi:[1,0]
	v_pk_mul_f32 v[50:51], v[50:51], v[74:75] op_sel_hi:[1,0]
	v_pk_mul_f32 v[48:49], v[48:49], v[74:75] op_sel_hi:[1,0]
	global_store_dwordx4 v[64:65], v[68:71], off nt
	v_pk_mul_f32 v[62:63], v[62:63], v[62:63]
	v_pk_mul_f32 v[60:61], v[60:61], v[60:61]
	v_pk_mul_f32 v[64:65], v[58:59], v[58:59]
	v_pk_mul_f32 v[58:59], v[56:57], v[56:57]
	v_cvt_pk_bf16_f32 v56, v60, v61
	v_cvt_pk_bf16_f32 v57, v62, v63
	v_pk_mul_f32 v[54:55], v[54:55], v[74:75] op_sel_hi:[1,0]
	v_max_f32_e32 v53, 0, v53
	v_max_f32_e32 v52, 0, v52
	v_max_f32_e32 v51, 0, v51
	v_max_f32_e32 v50, 0, v50
	v_max_f32_e32 v49, 0, v49
	v_max_f32_e32 v48, 0, v48
	s_add_i32 s33, s43, 0x80
	v_cvt_pk_bf16_f32 v58, v58, v59
	v_cvt_pk_bf16_f32 v59, v64, v65
	ds_write_b128 v153, v[56:59]
	v_max_f32_e32 v55, 0, v55
	v_max_f32_e32 v54, 0, v54
	v_pk_mul_f32 v[52:53], v[52:53], v[52:53]
	v_pk_mul_f32 v[56:57], v[50:51], v[50:51]
	v_pk_mul_f32 v[50:51], v[48:49], v[48:49]
	v_pk_mul_f32 v[54:55], v[54:55], v[54:55]
	v_cvt_pk_bf16_f32 v48, v52, v53
	v_or_b32_e32 v52, s33, v147
	v_cvt_pk_bf16_f32 v49, v54, v55
	v_cvt_pk_bf16_f32 v50, v50, v51
	v_cvt_pk_bf16_f32 v51, v56, v57
	ds_write_b128 v153, v[48:51] offset:64
	ds_read_b128 v[48:51], v154
	v_mad_i64_i32 v[56:57], s[26:27], v52, s70, v[112:113]
	ds_read_b128 v[52:55], v154 offset:1152
	ds_read_b32 v58, v155 offset:576
	s_waitcnt lgkmcnt(0)
	global_store_dwordx4 v[56:57], v[48:51], off nt
	v_pk_mul_f32 v[46:47], v[46:47], v[58:59] op_sel_hi:[1,0]
	s_nop 0
	v_or_b32_e32 v48, s33, v148
	v_pk_mul_f32 v[44:45], v[44:45], v[58:59] op_sel_hi:[1,0]
	v_pk_mul_f32 v[42:43], v[42:43], v[58:59] op_sel_hi:[1,0]
	v_pk_mul_f32 v[40:41], v[40:41], v[58:59] op_sel_hi:[1,0]
	v_mad_i64_i32 v[48:49], s[26:27], v48, s70, v[112:113]
	v_max_f32_e32 v47, 0, v47
	v_max_f32_e32 v46, 0, v46
	v_max_f32_e32 v45, 0, v45
	v_max_f32_e32 v44, 0, v44
	v_max_f32_e32 v43, 0, v43
	v_max_f32_e32 v42, 0, v42
	v_max_f32_e32 v41, 0, v41
	v_max_f32_e32 v40, 0, v40
	v_pk_mul_f32 v[36:37], v[36:37], v[58:59] op_sel_hi:[1,0]
	v_pk_mul_f32 v[34:35], v[34:35], v[58:59] op_sel_hi:[1,0]
	v_pk_mul_f32 v[32:33], v[32:33], v[58:59] op_sel_hi:[1,0]
	global_store_dwordx4 v[48:49], v[52:55], off nt
	v_pk_mul_f32 v[46:47], v[46:47], v[46:47]
	v_pk_mul_f32 v[44:45], v[44:45], v[44:45]
	v_pk_mul_f32 v[48:49], v[42:43], v[42:43]
	v_pk_mul_f32 v[42:43], v[40:41], v[40:41]
	v_cvt_pk_bf16_f32 v40, v44, v45
	v_cvt_pk_bf16_f32 v41, v46, v47
	v_pk_mul_f32 v[38:39], v[38:39], v[58:59] op_sel_hi:[1,0]
	v_max_f32_e32 v37, 0, v37
	v_max_f32_e32 v36, 0, v36
	v_max_f32_e32 v35, 0, v35
	v_max_f32_e32 v34, 0, v34
	v_max_f32_e32 v33, 0, v33
	v_max_f32_e32 v32, 0, v32
	v_cvt_pk_bf16_f32 v42, v42, v43
	v_cvt_pk_bf16_f32 v43, v48, v49
	ds_write_b128 v153, v[40:43]
	v_max_f32_e32 v39, 0, v39
	v_max_f32_e32 v38, 0, v38
	v_pk_mul_f32 v[36:37], v[36:37], v[36:37]
	v_pk_mul_f32 v[40:41], v[34:35], v[34:35]
	v_pk_mul_f32 v[34:35], v[32:33], v[32:33]
	s_add_i32 s33, s43, 0x90
	v_pk_mul_f32 v[38:39], v[38:39], v[38:39]
	v_cvt_pk_bf16_f32 v32, v36, v37
	v_or_b32_e32 v36, s33, v147
	v_cvt_pk_bf16_f32 v33, v38, v39
	v_cvt_pk_bf16_f32 v34, v34, v35
	v_cvt_pk_bf16_f32 v35, v40, v41
	ds_write_b128 v153, v[32:35] offset:64
	ds_read_b128 v[32:35], v154
	v_mad_i64_i32 v[40:41], s[26:27], v36, s70, v[112:113]
	ds_read_b128 v[36:39], v154 offset:1152
	ds_read_b32 v42, v155 offset:640
	s_waitcnt lgkmcnt(0)
; #define PG8_LAS __attribute__((address_space(3)))
; __device__ __forceinline__ unsigned cvt_pk_bf16(float lo, float hi) { unsigned r; asm volatile("v_cvt_pk_bf16_f32 %0, %1, %2" : "=v"(r) : "v"(lo), "v"(hi)); return r; }
; template <int LAYOUT> __device__ __forceinline__ void staged_store_bf16(PG8_LAS unsigned char* stg, bf16_t* O, size_t ldc, int rowg0, int pn, int wc, int lane) {
;     const int p = lane & 7;
; #pragma unroll
;     for (int hr = 0; hr < 2; ++hr) { const int r = 8 * hr + (lane >> 3), rowg = rowg0 + r; const u32x4 w = *(const PG8_LAS u32x4*)(stg + r * STG_ROW + p * 16);
;         if (LAYOUT == 0) __builtin_nontemporal_store(w, (u32x4*)(O + (size_t)rowg * ldc + pn * BM + wc * 64 + p * 8));
;         else { const int P = 2 * pn + (wc >> 1); int drow = rowg;
;             if (LAYOUT == 2) { const int sh = 2 * (P / 24), t = rowg & 16383; drow = (rowg & ~16383) + ((t & ((1 << sh) - 1)) << (14 - sh)) + (t >> sh); }
;             __builtin_nontemporal_store(w, (u32x4*)(O + (size_t)P * PLANE + (size_t)drow * 128 + (wc & 1) * 64 + p * 8)); } }
; }
;     __device__ __forceinline__ void operator()(const f32x4 (&acc)[2][2][4][2], const Unit& u, int wr, int wc, int fr, int fq) const {
;         const int lane = fr + 16 * fq; PG8_LAS unsigned char* stg = lds + STG_OFF + (wr * 4 + wc) * STG_WAVE;
;         const PG8_LAS float* rtab = (const PG8_LAS float*)(lds + RSTD_OFF) + ((u.pm >> 3) & 3) * 256;
; #pragma unroll
;         for (int ai = 0; ai < 2; ++ai)
; #pragma unroll
;             for (int m = 0; m < 4; ++m) {
;                 const int rowg0 = u.pm * BM + ai * HALF + wr * 64 + m * 16; const float rs = rtab[ai * HALF + wr * 64 + m * 16 + fr];
; #pragma unroll
;                 for (int bj = 0; bj < 2; ++bj) {
;                     f32x4 v0 = acc[ai][bj][m][0] * rs, v1 = acc[ai][bj][m][1] * rs;
;                     if (ACT == 1) { const f32x4 z = {0.f, 0.f, 0.f, 0.f}; v0 = __builtin_elementwise_max(v0, z); v1 = __builtin_elementwise_max(v1, z); v0 = v0 * v0; v1 = v1 * v1; }
;                     u32x4 w; w.x = cvt_pk_bf16(v0[0], v0[1]); w.y = cvt_pk_bf16(v0[2], v0[3]); w.z = cvt_pk_bf16(v1[0], v1[1]); w.w = cvt_pk_bf16(v1[2], v1[3]);
;                     *(PG8_LAS u32x4*)(stg + fr * STG_ROW + bj * 64 + fq * 16) = w; }
;                 staged_store_bf16<LAYOUT>(stg, O, (size_t)ldc, rowg0, u.pn, wc, lane);
	global_store_dwordx4 v[40:41], v[32:35], off nt
	v_pk_mul_f32 v[30:31], v[30:31], v[42:43] op_sel_hi:[1,0]
	s_nop 0
	v_or_b32_e32 v32, s33, v148
	v_pk_mul_f32 v[28:29], v[28:29], v[42:43] op_sel_hi:[1,0]
	v_pk_mul_f32 v[26:27], v[26:27], v[42:43] op_sel_hi:[1,0]
	v_pk_mul_f32 v[24:25], v[24:25], v[42:43] op_sel_hi:[1,0]
	v_mad_i64_i32 v[32:33], s[26:27], v32, s70, v[112:113]
	v_max_f32_e32 v31, 0, v31
	v_max_f32_e32 v30, 0, v30
	v_max_f32_e32 v29, 0, v29
	v_max_f32_e32 v28, 0, v28
	v_max_f32_e32 v27, 0, v27
	v_max_f32_e32 v26, 0, v26
	v_max_f32_e32 v25, 0, v25
	v_max_f32_e32 v24, 0, v24
	v_pk_mul_f32 v[20:21], v[20:21], v[42:43] op_sel_hi:[1,0]
	v_pk_mul_f32 v[18:19], v[18:19], v[42:43] op_sel_hi:[1,0]
	v_pk_mul_f32 v[16:17], v[16:17], v[42:43] op_sel_hi:[1,0]
	global_store_dwordx4 v[32:33], v[36:39], off nt
	v_pk_mul_f32 v[30:31], v[30:31], v[30:31]
	v_pk_mul_f32 v[28:29], v[28:29], v[28:29]
	v_pk_mul_f32 v[32:33], v[26:27], v[26:27]
	v_pk_mul_f32 v[26:27], v[24:25], v[24:25]
	v_cvt_pk_bf16_f32 v24, v28, v29
	v_cvt_pk_bf16_f32 v25, v30, v31
	v_pk_mul_f32 v[22:23], v[22:23], v[42:43] op_sel_hi:[1,0]
	v_max_f32_e32 v21, 0, v21
	v_max_f32_e32 v20, 0, v20
	v_max_f32_e32 v19, 0, v19
	v_max_f32_e32 v18, 0, v18
	v_max_f32_e32 v17, 0, v17
	v_max_f32_e32 v16, 0, v16
	v_cvt_pk_bf16_f32 v26, v26, v27
	v_cvt_pk_bf16_f32 v27, v32, v33
	ds_write_b128 v153, v[24:27]
	v_max_f32_e32 v23, 0, v23
	v_max_f32_e32 v22, 0, v22
	v_pk_mul_f32 v[20:21], v[20:21], v[20:21]
	v_pk_mul_f32 v[24:25], v[18:19], v[18:19]
	v_pk_mul_f32 v[18:19], v[16:17], v[16:17]
	s_add_i32 s33, s43, 0xa0
	v_pk_mul_f32 v[22:23], v[22:23], v[22:23]
	v_cvt_pk_bf16_f32 v16, v20, v21
	v_or_b32_e32 v20, s33, v147
	v_cvt_pk_bf16_f32 v17, v22, v23
	v_cvt_pk_bf16_f32 v18, v18, v19
	v_cvt_pk_bf16_f32 v19, v24, v25
	ds_write_b128 v153, v[16:19] offset:64
	ds_read_b128 v[16:19], v154
	v_mad_i64_i32 v[24:25], s[26:27], v20, s70, v[112:113]
	ds_read_b128 v[20:23], v154 offset:1152
	ds_read_b32 v26, v155 offset:704
	s_addk_i32 s43, 0xb0
	s_waitcnt lgkmcnt(0)
	global_store_dwordx4 v[24:25], v[16:19], off nt
	v_pk_mul_f32 v[14:15], v[14:15], v[26:27] op_sel_hi:[1,0]
	s_nop 0
	v_or_b32_e32 v16, s33, v148
	v_pk_mul_f32 v[12:13], v[12:13], v[26:27] op_sel_hi:[1,0]
	v_pk_mul_f32 v[10:11], v[10:11], v[26:27] op_sel_hi:[1,0]
	v_pk_mul_f32 v[8:9], v[8:9], v[26:27] op_sel_hi:[1,0]
	v_mad_i64_i32 v[16:17], s[26:27], v16, s70, v[112:113]
	v_max_f32_e32 v15, 0, v15
	v_max_f32_e32 v14, 0, v14
	v_max_f32_e32 v13, 0, v13
	v_max_f32_e32 v12, 0, v12
	v_max_f32_e32 v11, 0, v11
	v_max_f32_e32 v10, 0, v10
	v_max_f32_e32 v9, 0, v9
	v_max_f32_e32 v8, 0, v8
	v_pk_mul_f32 v[2:3], v[2:3], v[26:27] op_sel_hi:[1,0]
	v_pk_mul_f32 v[0:1], v[0:1], v[26:27] op_sel_hi:[1,0]
	global_store_dwordx4 v[16:17], v[20:23], off nt
	v_pk_mul_f32 v[14:15], v[14:15], v[14:15]
	v_pk_mul_f32 v[12:13], v[12:13], v[12:13]
	v_pk_mul_f32 v[16:17], v[10:11], v[10:11]
	v_pk_mul_f32 v[10:11], v[8:9], v[8:9]
	v_cvt_pk_bf16_f32 v8, v12, v13
	v_cvt_pk_bf16_f32 v9, v14, v15
	v_pk_mul_f32 v[6:7], v[6:7], v[26:27] op_sel_hi:[1,0]
	v_pk_mul_f32 v[4:5], v[4:5], v[26:27] op_sel_hi:[1,0]
	v_max_f32_e32 v3, 0, v3
	v_max_f32_e32 v2, 0, v2
	v_max_f32_e32 v1, 0, v1
	v_max_f32_e32 v0, 0, v0
	v_cvt_pk_bf16_f32 v10, v10, v11
	v_cvt_pk_bf16_f32 v11, v16, v17
	ds_write_b128 v153, v[8:11]
	v_max_f32_e32 v7, 0, v7
	v_max_f32_e32 v6, 0, v6
	v_max_f32_e32 v5, 0, v5
	v_max_f32_e32 v4, 0, v4
	v_pk_mul_f32 v[8:9], v[2:3], v[2:3]
	v_pk_mul_f32 v[2:3], v[0:1], v[0:1]
	v_pk_mul_f32 v[6:7], v[6:7], v[6:7]
	v_pk_mul_f32 v[4:5], v[4:5], v[4:5]
	s_nop 0
	v_cvt_pk_bf16_f32 v0, v4, v5
	v_cvt_pk_bf16_f32 v1, v6, v7
	v_cvt_pk_bf16_f32 v2, v2, v3
	v_cvt_pk_bf16_f32 v3, v8, v9
	ds_write_b128 v153, v[0:3] offset:64
	ds_read_b128 v[0:3], v154
	v_or_b32_e32 v4, s43, v147
	v_mad_i64_i32 v[8:9], s[26:27], v4, s70, v[112:113]
	ds_read_b128 v[4:7], v154 offset:1152
	s_waitcnt lgkmcnt(0)
	global_store_dwordx4 v[8:9], v[0:3], off nt
	s_nop 1
	v_or_b32_e32 v0, s43, v148
	v_mad_i64_i32 v[0:1], s[26:27], v0, s70, v[112:113]
	global_store_dwordx4 v[0:1], v[4:7], off nt
	s_cbranch_vccnz .LBB0_386
	s_andn2_b64 vcc, exec, s[10:11]
	s_cbranch_vccnz .LBB0_385
	s_mov_b32 s98, 1
	s_branch .LBB0_385

; #define PG8_STAGE(bufoff, gbase, voff) do { _Pragma("unroll") for (int _i = 0; _i < 2; ++_i) \
;         __builtin_amdgcn_global_load_lds((const unsigned*)((const char*)(gbase) + (voff)[_i]), (PG8_LAS unsigned*)(lds + (bufoff) + ldsw + _i * 8192), 16, 0, 0); } while (0)
; #define PG8_LDA(dst, b, h) do { _Pragma("unroll") for (int m = 0; m < 4; ++m) _Pragma("unroll") for (int k = 0; k < 2; ++k) dst[m][k] = *(const PG8_LAS bf16x8*)(lds + PG8_SA(b, h) + aoff + m * 2048 + k * 1024); } while (0)
; #define PG8_LDB(dst, b, h) do { _Pragma("unroll") for (int n = 0; n < 2; ++n) _Pragma("unroll") for (int k = 0; k < 2; ++k) dst[n][k] = *(const PG8_LAS bf16x8*)(lds + PG8_SB(b, h) + boff + n * 2048 + k * 1024); } while (0)
; #define PG8_BAR __builtin_amdgcn_s_barrier()
; #define PG8_SCHED __builtin_amdgcn_sched_barrier(0)
; template <class Epi, class Sched, bool ALIGN_EPI = false, bool SP2 = false>
; __device__ __forceinline__ void gemm_phase(PG8_LAS unsigned char* lds, const Gemm g, const Sched& S, const Epi& E, int tid_in) {
;     ...
;         const bool has_next = S.next(ui + 1, nxt);
;         const char* nA = has_next ? (const char*)g.A + (size_t)nxt.pm * tstep : cA; const char* nB = has_next ? (const char*)g.Bt + (size_t)nxt.pn * tstepB : cB;
;         for (int t = 0; t < nt; t += 2) {
;             const bool last = (t == nt - 2);
;             const char* a1 = cA + (size_t)(t + 1) * kstep;
;             const char* a2 = last ? nA : cA + (size_t)(t + 2) * kstep; const char* b2 = last ? nB : cB + (size_t)(t + 2) * kstep;
;             const char* a3 = a2 + kstep; const char* b3 = b2 + kstep;
;             if (last && has_next) S.a_ready(nxt);
;             if constexpr (SP2) {
;             PG8_LDB(B0, 0, 0); PG8_LDB(B1, 0, 1); PG8_SCHED; PG8_LDA(At, 0, 0); PG8_STAGE(PG8_SA(1, 1), a1 + hstep, voffA);
;     ...
; #pragma unroll
;         for (int a = 0; a < 2; ++a)
; #pragma unroll
;             for (int b = 0; b < 2; ++b)
; #pragma unroll
;                 for (int m = 0; m < 4; ++m)
; #pragma unroll
;                     for (int n = 0; n < 2; ++n) acc[a][b][m][n] = (f32x4){0.f, 0.f, 0.f, 0.f};
;         cur = nxt; cA = nA; cB = nB; ++ui;
;         if constexpr (ALIGN_EPI) { if (wr == 1) PG8_BAR; }
.LBB0_473:
	s_ashr_i32 s49, s48, 31
	s_lshl_b64 s[26:27], s[48:49], 22
	s_add_u32 s52, s62, s26
	s_addc_u32 s53, s63, s27
	s_and_b64 s[12:13], s[12:13], exec
	s_cselect_b32 s49, s53, s59
	s_cselect_b32 s75, s52, s58
	s_add_u32 s76, s58, 0x100
	v_mov_b32_e32 v0, 0
	s_addc_u32 s77, s59, 0
	s_mov_b32 s79, -2
	s_waitcnt lgkmcnt(0)
	v_mov_b32_e32 v1, v0
	v_mov_b32_e32 v2, v0
	v_mov_b32_e32 v3, v0
	v_mov_b32_e32 v4, v0
	v_mov_b32_e32 v5, v0
	v_mov_b32_e32 v6, v0
	v_mov_b32_e32 v7, v0
	v_mov_b32_e32 v16, v0
	v_mov_b32_e32 v17, v0
	v_mov_b32_e32 v18, v0
	v_mov_b32_e32 v19, v0
	v_mov_b32_e32 v20, v0
	v_mov_b32_e32 v21, v0
	v_mov_b32_e32 v22, v0
	v_mov_b32_e32 v23, v0
	v_mov_b32_e32 v32, v0
	v_mov_b32_e32 v33, v0
	v_mov_b32_e32 v34, v0
	v_mov_b32_e32 v35, v0
	v_mov_b32_e32 v36, v0
	v_mov_b32_e32 v37, v0
	v_mov_b32_e32 v38, v0
	v_mov_b32_e32 v39, v0
	v_mov_b32_e32 v48, v0
	v_mov_b32_e32 v49, v0
	v_mov_b32_e32 v50, v0
	v_mov_b32_e32 v51, v0
	v_mov_b32_e32 v52, v0
	v_mov_b32_e32 v53, v0
	v_mov_b32_e32 v54, v0
	v_mov_b32_e32 v55, v0
	v_mov_b32_e32 v8, v0
	v_mov_b32_e32 v9, v0
	v_mov_b32_e32 v10, v0
	v_mov_b32_e32 v11, v0
	v_mov_b32_e32 v12, v0
	v_mov_b32_e32 v13, v0
	v_mov_b32_e32 v14, v0
	v_mov_b32_e32 v15, v0
	v_mov_b32_e32 v24, v0
	v_mov_b32_e32 v25, v0
	v_mov_b32_e32 v26, v0
	v_mov_b32_e32 v27, v0
	v_mov_b32_e32 v28, v0
	v_mov_b32_e32 v29, v0
	v_mov_b32_e32 v30, v0
	v_mov_b32_e32 v31, v0
	v_mov_b32_e32 v40, v0
	v_mov_b32_e32 v41, v0
	v_mov_b32_e32 v42, v0
	v_mov_b32_e32 v43, v0
	v_mov_b32_e32 v44, v0
	v_mov_b32_e32 v45, v0
	v_mov_b32_e32 v46, v0
	v_mov_b32_e32 v47, v0
	v_mov_b32_e32 v56, v0
	v_mov_b32_e32 v57, v0
	v_mov_b32_e32 v58, v0
	v_mov_b32_e32 v59, v0
	v_mov_b32_e32 v60, v0
	v_mov_b32_e32 v61, v0
	v_mov_b32_e32 v62, v0
	v_mov_b32_e32 v63, v0
	v_mov_b32_e32 v64, v0
	v_mov_b32_e32 v65, v0
	v_mov_b32_e32 v66, v0
	v_mov_b32_e32 v67, v0
	v_mov_b32_e32 v68, v0
	v_mov_b32_e32 v69, v0
	v_mov_b32_e32 v70, v0
	v_mov_b32_e32 v71, v0
	v_mov_b32_e32 v80, v0
	v_mov_b32_e32 v81, v0
	v_mov_b32_e32 v82, v0
	v_mov_b32_e32 v83, v0
	v_mov_b32_e32 v84, v0
	v_mov_b32_e32 v85, v0
	v_mov_b32_e32 v86, v0
	v_mov_b32_e32 v87, v0
	v_mov_b32_e32 v96, v0
	v_mov_b32_e32 v97, v0
	v_mov_b32_e32 v98, v0
	v_mov_b32_e32 v99, v0
	v_mov_b32_e32 v100, v0
	v_mov_b32_e32 v101, v0
	v_mov_b32_e32 v102, v0
	v_mov_b32_e32 v103, v0
	v_mov_b32_e32 v112, v0
	v_mov_b32_e32 v113, v0
	v_mov_b32_e32 v114, v0
	v_mov_b32_e32 v115, v0
	v_mov_b32_e32 v116, v0
	v_mov_b32_e32 v117, v0
	v_mov_b32_e32 v118, v0
	v_mov_b32_e32 v119, v0
	v_mov_b32_e32 v72, v0
	v_mov_b32_e32 v73, v0
	v_mov_b32_e32 v74, v0
	v_mov_b32_e32 v75, v0
	v_mov_b32_e32 v76, v0
	v_mov_b32_e32 v77, v0
	v_mov_b32_e32 v78, v0
	v_mov_b32_e32 v79, v0
	v_mov_b32_e32 v88, v0
	v_mov_b32_e32 v89, v0
	v_mov_b32_e32 v90, v0
	v_mov_b32_e32 v91, v0
	v_mov_b32_e32 v92, v0
	v_mov_b32_e32 v93, v0
	v_mov_b32_e32 v94, v0
	v_mov_b32_e32 v95, v0
	v_mov_b32_e32 v104, v0
	v_mov_b32_e32 v105, v0
	v_mov_b32_e32 v106, v0
	v_mov_b32_e32 v107, v0
	v_mov_b32_e32 v108, v0
	v_mov_b32_e32 v109, v0
	v_mov_b32_e32 v110, v0
	v_mov_b32_e32 v111, v0
	v_mov_b32_e32 v120, v0
	v_mov_b32_e32 v121, v0
	v_mov_b32_e32 v122, v0
	v_mov_b32_e32 v123, v0
	v_mov_b32_e32 v124, v0
	v_mov_b32_e32 v125, v0
	v_mov_b32_e32 v126, v0
	v_mov_b32_e32 v127, v0
	s_cmp_eq_u32 s98, 1
	s_cbranch_scc0 .Lkb_skip_3
	s_mov_b32 s98, 0
	s_barrier
.Lkb_skip_3:
.LBB0_474:
	ds_read_b128 v[146:149], v153
	ds_read_b128 v[158:161], v153 offset:1024
	ds_read_b128 v[162:165], v153 offset:2048
	ds_read_b128 v[166:169], v153 offset:3072
	ds_read_b128 v[170:173], v154
	ds_read_b128 v[174:177], v154 offset:1024
	ds_read_b128 v[178:181], v154 offset:2048
	ds_read_b128 v[182:185], v154 offset:3072
	s_add_u32 s12, s56, 0x100
	s_addc_u32 s13, s57, 0
	s_cmpk_eq_i32 s79, 0x7c
	s_cselect_b32 s61, s51, s13
	s_cselect_b32 s60, s50, s12
	s_cselect_b32 s59, s49, s77
	s_cselect_b32 s58, s75, s76
	v_lshl_add_u64 v[220:221], s[56:57], 0, v[138:139]
	s_add_i32 m0, s55, 0xc000
	ds_read_b128 v[186:189], v155
	ds_read_b128 v[190:193], v155 offset:1024
	ds_read_b128 v[194:197], v155 offset:2048
	ds_read_b128 v[198:201], v155 offset:3072
	ds_read_b128 v[202:205], v155 offset:4096
	ds_read_b128 v[206:209], v155 offset:5120
	ds_read_b128 v[212:215], v155 offset:6144
	ds_read_b128 v[216:219], v155 offset:7168
	global_load_lds_dwordx4 v[220:221], off
	v_lshl_add_u64 v[220:221], s[56:57], 0, v[140:141]
	s_add_i32 m0, s55, 0xe000
	s_nop 0
	global_load_lds_dwordx4 v[220:221], off
	s_waitcnt vmcnt(8)
	s_waitcnt lgkmcnt(0)
	s_barrier
; #define PG8_STAGE(bufoff, gbase, voff) do { _Pragma("unroll") for (int _i = 0; _i < 2; ++_i) \
;         __builtin_amdgcn_global_load_lds((const unsigned*)((const char*)(gbase) + (voff)[_i]), (PG8_LAS unsigned*)(lds + (bufoff) + ldsw + _i * 8192), 16, 0, 0); } while (0)
; #define PG8_LDA(dst, b, h) do { _Pragma("unroll") for (int m = 0; m < 4; ++m) _Pragma("unroll") for (int k = 0; k < 2; ++k) dst[m][k] = *(const PG8_LAS bf16x8*)(lds + PG8_SA(b, h) + aoff + m * 2048 + k * 1024); } while (0)
; #define PG8_LDB(dst, b, h) do { _Pragma("unroll") for (int n = 0; n < 2; ++n) _Pragma("unroll") for (int k = 0; k < 2; ++k) dst[n][k] = *(const PG8_LAS bf16x8*)(lds + PG8_SB(b, h) + boff + n * 2048 + k * 1024); } while (0)
; #define PG8_MMA(ai, bj, At, Bt) do { __builtin_amdgcn_s_setprio(1); _Pragma("unroll") for (int m = 0; m < 4; ++m) _Pragma("unroll") for (int n = 0; n < 2; ++n) _Pragma("unroll") for (int k = 0; k < 2; ++k) \
;         acc[ai][bj][m][n] = __builtin_amdgcn_mfma_f32_16x16x32_bf16(Bt[n][k], At[m][k], acc[ai][bj][m][n], 0, 0, 0); __builtin_amdgcn_s_setprio(0); } while (0)
; #define PG8_WAIT_V(n) asm volatile("s_waitcnt vmcnt(" #n ")" ::: "memory")
; #define PG8_WAIT_L(n) asm volatile("s_waitcnt lgkmcnt(" #n ")" ::: "memory")
; #define PG8_BAR __builtin_amdgcn_s_barrier()
; #define PG8_SCHED __builtin_amdgcn_sched_barrier(0)
; template <class Epi, class Sched, bool ALIGN_EPI = false, bool SP2 = false>
; __device__ __forceinline__ void gemm_phase(PG8_LAS unsigned char* lds, const Gemm g, const Sched& S, const Epi& E, int tid_in) {
;     ...
;             PG8_LDB(B0, 0, 0); PG8_LDB(B1, 0, 1); PG8_SCHED; PG8_LDA(At, 0, 0); PG8_STAGE(PG8_SA(1, 1), a1 + hstep, voffA);
;             PG8_WAIT_V(8); PG8_WAIT_L(0); PG8_BAR; PG8_MMA(0, 0, At, B0); PG8_MMA(0, 1, At, B1); PG8_BAR; PG8_SCHED;
;             PG8_LDA(At, 0, 1); PG8_STAGE(PG8_SB(0, 0), b2, voffB); PG8_STAGE(PG8_SB(0, 1), b2 + hstepB, voffB); PG8_STAGE(PG8_SA(0, 0), a2, voffA);
;             PG8_WAIT_V(8); PG8_WAIT_L(0); PG8_BAR; PG8_MMA(1, 0, At, B0); PG8_MMA(1, 1, At, B1); PG8_BAR; PG8_SCHED;
	s_setprio 1
	s_waitcnt lgkmcnt(0)
	v_mfma_f32_16x16x32_bf16 v[124:127], v[146:149], v[186:189], v[124:127]
	v_mfma_f32_16x16x32_bf16 v[120:123], v[162:165], v[186:189], v[120:123]
	v_mfma_f32_16x16x32_bf16 v[108:111], v[146:149], v[194:197], v[108:111]
	v_mfma_f32_16x16x32_bf16 v[104:107], v[162:165], v[194:197], v[104:107]
	v_mfma_f32_16x16x32_bf16 v[92:95], v[146:149], v[202:205], v[92:95]
	v_mfma_f32_16x16x32_bf16 v[88:91], v[162:165], v[202:205], v[88:91]
	v_mfma_f32_16x16x32_bf16 v[76:79], v[146:149], v[212:215], v[76:79]
	v_mfma_f32_16x16x32_bf16 v[72:75], v[162:165], v[212:215], v[72:75]
	v_mfma_f32_16x16x32_bf16 v[124:127], v[158:161], v[190:193], v[124:127]
	v_mfma_f32_16x16x32_bf16 v[120:123], v[166:169], v[190:193], v[120:123]
	v_mfma_f32_16x16x32_bf16 v[108:111], v[158:161], v[198:201], v[108:111]
	v_mfma_f32_16x16x32_bf16 v[104:107], v[166:169], v[198:201], v[104:107]
	v_mfma_f32_16x16x32_bf16 v[92:95], v[158:161], v[206:209], v[92:95]
	v_mfma_f32_16x16x32_bf16 v[88:91], v[166:169], v[206:209], v[88:91]
	v_mfma_f32_16x16x32_bf16 v[76:79], v[158:161], v[216:219], v[76:79]
	v_mfma_f32_16x16x32_bf16 v[72:75], v[166:169], v[216:219], v[72:75]
	s_setprio 0
	s_setprio 1
	v_mfma_f32_16x16x32_bf16 v[116:119], v[170:173], v[186:189], v[116:119]
	v_mfma_f32_16x16x32_bf16 v[112:115], v[178:181], v[186:189], v[112:115]
	v_mfma_f32_16x16x32_bf16 v[100:103], v[170:173], v[194:197], v[100:103]
	v_mfma_f32_16x16x32_bf16 v[96:99], v[178:181], v[194:197], v[96:99]
	v_mfma_f32_16x16x32_bf16 v[84:87], v[170:173], v[202:205], v[84:87]
	v_mfma_f32_16x16x32_bf16 v[80:83], v[178:181], v[202:205], v[80:83]
	v_mfma_f32_16x16x32_bf16 v[68:71], v[170:173], v[212:215], v[68:71]
	v_mfma_f32_16x16x32_bf16 v[64:67], v[178:181], v[212:215], v[64:67]
	v_mfma_f32_16x16x32_bf16 v[116:119], v[174:177], v[190:193], v[116:119]
	v_mfma_f32_16x16x32_bf16 v[112:115], v[182:185], v[190:193], v[112:115]
	v_mfma_f32_16x16x32_bf16 v[100:103], v[174:177], v[198:201], v[100:103]
	v_mfma_f32_16x16x32_bf16 v[96:99], v[182:185], v[198:201], v[96:99]
	v_mfma_f32_16x16x32_bf16 v[84:87], v[174:177], v[206:209], v[84:87]
	v_mfma_f32_16x16x32_bf16 v[80:83], v[182:185], v[206:209], v[80:83]
	v_mfma_f32_16x16x32_bf16 v[68:71], v[174:177], v[216:219], v[68:71]
	v_mfma_f32_16x16x32_bf16 v[64:67], v[182:185], v[216:219], v[64:67]
	s_setprio 0
	s_barrier
	s_add_i32 s26, s71, s64
	v_lshl_add_u64 v[220:221], s[58:59], 0, v[130:131]
	s_mov_b32 m0, s26
	ds_read_b128 v[186:189], v155 offset:16384
	ds_read_b128 v[190:193], v155 offset:17408
	ds_read_b128 v[194:197], v155 offset:18432
	ds_read_b128 v[198:201], v155 offset:19456
	ds_read_b128 v[202:205], v155 offset:20480
	ds_read_b128 v[206:209], v155 offset:21504
	ds_read_b128 v[212:215], v155 offset:22528
	ds_read_b128 v[216:219], v155 offset:23552
	global_load_lds_dwordx4 v[220:221], off
	s_add_i32 m0, s26, 0x2000
	s_add_u32 s26, s58, 0x80000
	v_lshl_add_u64 v[222:223], s[58:59], 0, v[134:135]
	s_addc_u32 s27, s59, 0
	s_add_i32 s33, s72, s64
	global_load_lds_dwordx4 v[222:223], off
	v_lshl_add_u64 v[224:225], s[26:27], 0, v[130:131]
	s_mov_b32 m0, s33
	v_lshl_add_u64 v[226:227], s[60:61], 0, v[132:133]
	global_load_lds_dwordx4 v[224:225], off
	v_lshl_add_u64 v[224:225], s[26:27], 0, v[134:135]
	s_add_i32 m0, s33, 0x2000
	s_nop 0
	global_load_lds_dwordx4 v[224:225], off
	v_lshl_add_u64 v[224:225], s[60:61], 0, v[128:129]
	s_mov_b32 m0, s55
	s_nop 0
	global_load_lds_dwordx4 v[224:225], off
	s_mov_b32 m0, s65
	s_nop 0
	global_load_lds_dwordx4 v[226:227], off
	s_waitcnt vmcnt(8)
	s_waitcnt lgkmcnt(0)
	s_barrier
	s_setprio 1
	s_waitcnt lgkmcnt(0)
	v_mfma_f32_16x16x32_bf16 v[60:63], v[146:149], v[186:189], v[60:63]
	v_mfma_f32_16x16x32_bf16 v[56:59], v[162:165], v[186:189], v[56:59]
	v_mfma_f32_16x16x32_bf16 v[44:47], v[146:149], v[194:197], v[44:47]
	v_mfma_f32_16x16x32_bf16 v[40:43], v[162:165], v[194:197], v[40:43]
	v_mfma_f32_16x16x32_bf16 v[28:31], v[146:149], v[202:205], v[28:31]
	v_mfma_f32_16x16x32_bf16 v[24:27], v[162:165], v[202:205], v[24:27]
	v_mfma_f32_16x16x32_bf16 v[12:15], v[146:149], v[212:215], v[12:15]
	v_mfma_f32_16x16x32_bf16 v[8:11], v[162:165], v[212:215], v[8:11]
	v_mfma_f32_16x16x32_bf16 v[60:63], v[158:161], v[190:193], v[60:63]
	v_mfma_f32_16x16x32_bf16 v[56:59], v[166:169], v[190:193], v[56:59]
	v_mfma_f32_16x16x32_bf16 v[44:47], v[158:161], v[198:201], v[44:47]
	v_mfma_f32_16x16x32_bf16 v[40:43], v[166:169], v[198:201], v[40:43]
	v_mfma_f32_16x16x32_bf16 v[28:31], v[158:161], v[206:209], v[28:31]
	v_mfma_f32_16x16x32_bf16 v[24:27], v[166:169], v[206:209], v[24:27]
	v_mfma_f32_16x16x32_bf16 v[12:15], v[158:161], v[216:219], v[12:15]
	v_mfma_f32_16x16x32_bf16 v[8:11], v[166:169], v[216:219], v[8:11]
	s_setprio 0
	s_setprio 1
	v_mfma_f32_16x16x32_bf16 v[52:55], v[170:173], v[186:189], v[52:55]
	v_mfma_f32_16x16x32_bf16 v[48:51], v[178:181], v[186:189], v[48:51]
	v_mfma_f32_16x16x32_bf16 v[36:39], v[170:173], v[194:197], v[36:39]
	v_mfma_f32_16x16x32_bf16 v[32:35], v[178:181], v[194:197], v[32:35]
	v_mfma_f32_16x16x32_bf16 v[20:23], v[170:173], v[202:205], v[20:23]
	v_mfma_f32_16x16x32_bf16 v[16:19], v[178:181], v[202:205], v[16:19]
	v_mfma_f32_16x16x32_bf16 v[4:7], v[170:173], v[212:215], v[4:7]
	v_mfma_f32_16x16x32_bf16 v[0:3], v[178:181], v[212:215], v[0:3]
	v_mfma_f32_16x16x32_bf16 v[52:55], v[174:177], v[190:193], v[52:55]
	v_mfma_f32_16x16x32_bf16 v[48:51], v[182:185], v[190:193], v[48:51]
	v_mfma_f32_16x16x32_bf16 v[36:39], v[174:177], v[198:201], v[36:39]
	v_mfma_f32_16x16x32_bf16 v[32:35], v[182:185], v[198:201], v[32:35]
	v_mfma_f32_16x16x32_bf16 v[20:23], v[174:177], v[206:209], v[20:23]
	v_mfma_f32_16x16x32_bf16 v[16:19], v[182:185], v[206:209], v[16:19]
	v_mfma_f32_16x16x32_bf16 v[4:7], v[174:177], v[216:219], v[4:7]
	v_mfma_f32_16x16x32_bf16 v[0:3], v[182:185], v[216:219], v[0:3]
	s_setprio 0
	s_barrier
; #define PG8_STAGE(bufoff, gbase, voff) do { _Pragma("unroll") for (int _i = 0; _i < 2; ++_i) \
;         __builtin_amdgcn_global_load_lds((const unsigned*)((const char*)(gbase) + (voff)[_i]), (PG8_LAS unsigned*)(lds + (bufoff) + ldsw + _i * 8192), 16, 0, 0); } while (0)
; #define PG8_LDA(dst, b, h) do { _Pragma("unroll") for (int m = 0; m < 4; ++m) _Pragma("unroll") for (int k = 0; k < 2; ++k) dst[m][k] = *(const PG8_LAS bf16x8*)(lds + PG8_SA(b, h) + aoff + m * 2048 + k * 1024); } while (0)
; #define PG8_LDB(dst, b, h) do { _Pragma("unroll") for (int n = 0; n < 2; ++n) _Pragma("unroll") for (int k = 0; k < 2; ++k) dst[n][k] = *(const PG8_LAS bf16x8*)(lds + PG8_SB(b, h) + boff + n * 2048 + k * 1024); } while (0)
; #define PG8_MMA(ai, bj, At, Bt) do { __builtin_amdgcn_s_setprio(1); _Pragma("unroll") for (int m = 0; m < 4; ++m) _Pragma("unroll") for (int n = 0; n < 2; ++n) _Pragma("unroll") for (int k = 0; k < 2; ++k) \
;         acc[ai][bj][m][n] = __builtin_amdgcn_mfma_f32_16x16x32_bf16(Bt[n][k], At[m][k], acc[ai][bj][m][n], 0, 0, 0); __builtin_amdgcn_s_setprio(0); } while (0)
; #define PG8_WAIT_V(n) asm volatile("s_waitcnt vmcnt(" #n ")" ::: "memory")
; #define PG8_WAIT_L(n) asm volatile("s_waitcnt lgkmcnt(" #n ")" ::: "memory")
; #define PG8_BAR __builtin_amdgcn_s_barrier()
; #define PG8_SCHED __builtin_amdgcn_sched_barrier(0)
; template <class Epi, class Sched, bool ALIGN_EPI = false, bool SP2 = false>
; __device__ __forceinline__ void gemm_phase(PG8_LAS unsigned char* lds, const Gemm g, const Sched& S, const Epi& E, int tid_in) {
;     ...
;             PG8_LDB(B0, 1, 0); PG8_LDB(B1, 1, 1); PG8_SCHED; PG8_LDA(At, 1, 0); PG8_STAGE(PG8_SA(0, 1), a2 + hstep, voffA);
;             PG8_WAIT_V(8); PG8_WAIT_L(0); PG8_BAR; PG8_MMA(0, 0, At, B0); PG8_MMA(0, 1, At, B1); PG8_BAR; PG8_SCHED;
;             PG8_LDA(At, 1, 1); PG8_STAGE(PG8_SB(1, 0), b3, voffB); PG8_STAGE(PG8_SB(1, 1), b3 + hstepB, voffB); PG8_STAGE(PG8_SA(1, 0), a3, voffA);
;             PG8_WAIT_V(8); PG8_WAIT_L(0); PG8_BAR; PG8_MMA(1, 0, At, B0); PG8_MMA(1, 1, At, B1); PG8_BAR; PG8_SCHED;
	s_add_i32 s33, 0, 0x18000
	s_add_i32 s56, 0, 0x1c000
	v_add_u32_e32 v166, s33, v137
	v_add_u32_e32 v182, s56, v137
	ds_read_b128 v[146:149], v166
	ds_read_b128 v[158:161], v166 offset:1024
	ds_read_b128 v[162:165], v166 offset:2048
	ds_read_b128 v[166:169], v166 offset:3072
	ds_read_b128 v[170:173], v182
	ds_read_b128 v[174:177], v182 offset:1024
	ds_read_b128 v[178:181], v182 offset:2048
	ds_read_b128 v[182:185], v182 offset:3072
	s_add_u32 s26, s60, 0x204000
	s_addc_u32 s27, s61, 0
	s_mov_b32 m0, s66
	v_lshl_add_u64 v[228:229], s[26:27], 0, v[128:129]
	ds_read_b128 v[186:189], v155 offset:32768
	ds_read_b128 v[190:193], v155 offset:33792
	ds_read_b128 v[194:197], v155 offset:34816
	ds_read_b128 v[198:201], v155 offset:35840
	ds_read_b128 v[202:205], v155 offset:36864
	ds_read_b128 v[206:209], v155 offset:37888
	ds_read_b128 v[212:215], v155 offset:38912
	ds_read_b128 v[216:219], v155 offset:39936
	global_load_lds_dwordx4 v[228:229], off
	v_lshl_add_u64 v[228:229], s[26:27], 0, v[132:133]
	s_mov_b32 m0, s67
	s_nop 0
	global_load_lds_dwordx4 v[228:229], off
	s_waitcnt vmcnt(8)
	s_waitcnt lgkmcnt(0)
	s_barrier
	s_setprio 1
	s_waitcnt lgkmcnt(0)
	v_mfma_f32_16x16x32_bf16 v[124:127], v[146:149], v[186:189], v[124:127]
	v_mfma_f32_16x16x32_bf16 v[120:123], v[162:165], v[186:189], v[120:123]
	v_mfma_f32_16x16x32_bf16 v[108:111], v[146:149], v[194:197], v[108:111]
	v_mfma_f32_16x16x32_bf16 v[104:107], v[162:165], v[194:197], v[104:107]
	v_mfma_f32_16x16x32_bf16 v[92:95], v[146:149], v[202:205], v[92:95]
	v_mfma_f32_16x16x32_bf16 v[88:91], v[162:165], v[202:205], v[88:91]
	v_mfma_f32_16x16x32_bf16 v[76:79], v[146:149], v[212:215], v[76:79]
	v_mfma_f32_16x16x32_bf16 v[72:75], v[162:165], v[212:215], v[72:75]
	v_mfma_f32_16x16x32_bf16 v[124:127], v[158:161], v[190:193], v[124:127]
	v_mfma_f32_16x16x32_bf16 v[120:123], v[166:169], v[190:193], v[120:123]
	v_mfma_f32_16x16x32_bf16 v[108:111], v[158:161], v[198:201], v[108:111]
	v_mfma_f32_16x16x32_bf16 v[104:107], v[166:169], v[198:201], v[104:107]
	v_mfma_f32_16x16x32_bf16 v[92:95], v[158:161], v[206:209], v[92:95]
	v_mfma_f32_16x16x32_bf16 v[88:91], v[166:169], v[206:209], v[88:91]
	v_mfma_f32_16x16x32_bf16 v[76:79], v[158:161], v[216:219], v[76:79]
	v_mfma_f32_16x16x32_bf16 v[72:75], v[166:169], v[216:219], v[72:75]
	s_setprio 0
	s_setprio 1
	v_mfma_f32_16x16x32_bf16 v[116:119], v[170:173], v[186:189], v[116:119]
	v_mfma_f32_16x16x32_bf16 v[112:115], v[178:181], v[186:189], v[112:115]
	v_mfma_f32_16x16x32_bf16 v[100:103], v[170:173], v[194:197], v[100:103]
	v_mfma_f32_16x16x32_bf16 v[96:99], v[178:181], v[194:197], v[96:99]
	v_mfma_f32_16x16x32_bf16 v[84:87], v[170:173], v[202:205], v[84:87]
	v_mfma_f32_16x16x32_bf16 v[80:83], v[178:181], v[202:205], v[80:83]
	v_mfma_f32_16x16x32_bf16 v[68:71], v[170:173], v[212:215], v[68:71]
	v_mfma_f32_16x16x32_bf16 v[64:67], v[178:181], v[212:215], v[64:67]
	v_mfma_f32_16x16x32_bf16 v[116:119], v[174:177], v[190:193], v[116:119]
	v_mfma_f32_16x16x32_bf16 v[112:115], v[182:185], v[190:193], v[112:115]
	v_mfma_f32_16x16x32_bf16 v[100:103], v[174:177], v[198:201], v[100:103]
	v_mfma_f32_16x16x32_bf16 v[96:99], v[182:185], v[198:201], v[96:99]
	v_mfma_f32_16x16x32_bf16 v[84:87], v[174:177], v[206:209], v[84:87]
	v_mfma_f32_16x16x32_bf16 v[80:83], v[182:185], v[206:209], v[80:83]
	v_mfma_f32_16x16x32_bf16 v[68:71], v[174:177], v[216:219], v[68:71]
	v_mfma_f32_16x16x32_bf16 v[64:67], v[182:185], v[216:219], v[64:67]
	s_setprio 0
	s_barrier
	s_add_i32 s26, s33, s64
	v_lshl_add_u64 v[220:221], v[220:221], 0, s[42:43]
	s_mov_b32 m0, s26
	ds_read_b128 v[186:189], v155 offset:49152
	ds_read_b128 v[190:193], v155 offset:50176
	ds_read_b128 v[194:197], v155 offset:51200
	ds_read_b128 v[198:201], v155 offset:52224
	ds_read_b128 v[202:205], v155 offset:53248
	ds_read_b128 v[206:209], v155 offset:54272
	ds_read_b128 v[212:215], v155 offset:55296
	ds_read_b128 v[216:219], v155 offset:56320
	global_load_lds_dwordx4 v[220:221], off
	s_add_i32 m0, s26, 0x2000
	s_add_u32 s26, s58, 0x80080
	v_lshl_add_u64 v[220:221], v[222:223], 0, s[42:43]
	s_addc_u32 s27, s59, 0
	s_add_i32 s33, s56, s64
	global_load_lds_dwordx4 v[220:221], off
	v_lshl_add_u64 v[220:221], s[26:27], 0, v[130:131]
	s_mov_b32 m0, s33
	s_nop 0
	global_load_lds_dwordx4 v[220:221], off
	v_lshl_add_u64 v[220:221], s[26:27], 0, v[134:135]
	s_add_i32 m0, s33, 0x2000
	s_nop 0
	global_load_lds_dwordx4 v[220:221], off
	v_lshl_add_u64 v[220:221], v[224:225], 0, s[42:43]
	s_mov_b32 m0, s69
	s_nop 0
	global_load_lds_dwordx4 v[220:221], off
	v_lshl_add_u64 v[220:221], v[226:227], 0, s[42:43]
	s_mov_b32 m0, s70
	s_nop 0
	global_load_lds_dwordx4 v[220:221], off
	s_waitcnt vmcnt(8)
	s_waitcnt lgkmcnt(0)
	s_barrier
; template <class Epi, class Sched, bool ALIGN_EPI = false, bool SP2 = false>
; __device__ __forceinline__ void gemm_phase(PG8_LAS unsigned char* lds, const Gemm g, const Sched& S, const Epi& E, int tid_in) {
;     ...
;             PG8_WAIT_V(8); PG8_WAIT_L(0); PG8_BAR; PG8_MMA(1, 0, At, B0); PG8_MMA(1, 1, At, B1); PG8_BAR; PG8_SCHED;
;             } else {
;             PG8_LDB(B0, 0, 0); PG8_SCHED; PG8_LDA(At, 0, 0); PG8_STAGE(PG8_SA(1, 1), a1 + hstep, voffA);
;             PG8_WAIT_L(8); PG8_BAR; PG8_WAIT_L(0); PG8_MMA(0, 0, At, B0); PG8_BAR; PG8_SCHED;
;             PG8_LDB(B1, 0, 1); PG8_STAGE(PG8_SB(0, 0), b2, voffB);
;             PG8_BAR; PG8_WAIT_L(0); PG8_MMA(0, 1, At, B1); PG8_BAR;
;             PG8_LDA(At, 0, 1); PG8_STAGE(PG8_SA(0, 0), a2, voffA);
;             PG8_BAR; PG8_WAIT_L(0); PG8_MMA(1, 0, At, B0); PG8_BAR; PG8_SCHED;
;             PG8_STAGE(PG8_SB(0, 1), b2 + hstepB, voffB);
;             PG8_WAIT_V(6); PG8_BAR; PG8_MMA(1, 1, At, B1); PG8_BAR;
;             PG8_LDB(B0, 1, 0); PG8_SCHED; PG8_LDA(At, 1, 0); PG8_STAGE(PG8_SA(0, 1), a2 + hstep, voffA);
;             PG8_WAIT_L(8); PG8_BAR; PG8_WAIT_L(0); PG8_MMA(0, 0, At, B0); PG8_BAR; PG8_SCHED;
;             PG8_LDB(B1, 1, 1); PG8_STAGE(PG8_SB(1, 0), b3, voffB);
;             PG8_BAR; PG8_WAIT_L(0); PG8_MMA(0, 1, At, B1); PG8_BAR;
;             PG8_LDA(At, 1, 1); PG8_STAGE(PG8_SA(1, 0), a3, voffA);
;             PG8_BAR; PG8_WAIT_L(0); PG8_MMA(1, 0, At, B0); PG8_BAR; PG8_SCHED;
;             PG8_STAGE(PG8_SB(1, 1), b3 + hstepB, voffB);
;             PG8_WAIT_V(6); PG8_BAR; PG8_MMA(1, 1, At, B1); PG8_BAR;
;             }
;         }
;         if constexpr (ALIGN_EPI) { if (wr == 0) PG8_BAR; }
;     __device__ __forceinline__ void operator()(const f32x4 (&acc)[2][2][4][2], const Unit& u, int wr, int wc, int fr, int fq) const {
;         const int lane = fr + 16 * fq, r = lane >> 2, p = lane & 3; PG8_LAS unsigned char* stg = lds + STG_OFF + (wr * 4 + wc) * STG_WAVE;
; #pragma unroll
;         for (int ai = 0; ai < 2; ++ai)
; #pragma unroll
;             for (int m = 0; m < 4; ++m) {
;                 const int row = u.pm * BM + ai * HALF + wr * 64 + m * 16 + r; float q = 0.f;
; #pragma unroll
;                 for (int bj = 0; bj < 2; ++bj) {
;                     const size_t off = (size_t)row * 2048 + u.pn * BM + wc * 64 + bj * 32 + 8 * p;
;                     f32x4 b0, b1;
	s_setprio 1
	s_waitcnt lgkmcnt(0)
	v_mfma_f32_16x16x32_bf16 v[60:63], v[146:149], v[186:189], v[60:63]
	v_mfma_f32_16x16x32_bf16 v[56:59], v[162:165], v[186:189], v[56:59]
	v_mfma_f32_16x16x32_bf16 v[44:47], v[146:149], v[194:197], v[44:47]
	v_mfma_f32_16x16x32_bf16 v[40:43], v[162:165], v[194:197], v[40:43]
	v_mfma_f32_16x16x32_bf16 v[28:31], v[146:149], v[202:205], v[28:31]
	v_mfma_f32_16x16x32_bf16 v[24:27], v[162:165], v[202:205], v[24:27]
	v_mfma_f32_16x16x32_bf16 v[12:15], v[146:149], v[212:215], v[12:15]
	v_mfma_f32_16x16x32_bf16 v[8:11], v[162:165], v[212:215], v[8:11]
	v_mfma_f32_16x16x32_bf16 v[60:63], v[158:161], v[190:193], v[60:63]
	v_mfma_f32_16x16x32_bf16 v[56:59], v[166:169], v[190:193], v[56:59]
	v_mfma_f32_16x16x32_bf16 v[44:47], v[158:161], v[198:201], v[44:47]
	v_mfma_f32_16x16x32_bf16 v[40:43], v[166:169], v[198:201], v[40:43]
	v_mfma_f32_16x16x32_bf16 v[28:31], v[158:161], v[206:209], v[28:31]
	v_mfma_f32_16x16x32_bf16 v[24:27], v[166:169], v[206:209], v[24:27]
	v_mfma_f32_16x16x32_bf16 v[12:15], v[158:161], v[216:219], v[12:15]
	v_mfma_f32_16x16x32_bf16 v[8:11], v[166:169], v[216:219], v[8:11]
	s_setprio 0
	s_setprio 1
	v_mfma_f32_16x16x32_bf16 v[52:55], v[170:173], v[186:189], v[52:55]
	v_mfma_f32_16x16x32_bf16 v[48:51], v[178:181], v[186:189], v[48:51]
	v_mfma_f32_16x16x32_bf16 v[36:39], v[170:173], v[194:197], v[36:39]
	v_mfma_f32_16x16x32_bf16 v[32:35], v[178:181], v[194:197], v[32:35]
	v_mfma_f32_16x16x32_bf16 v[20:23], v[170:173], v[202:205], v[20:23]
	v_mfma_f32_16x16x32_bf16 v[16:19], v[178:181], v[202:205], v[16:19]
	v_mfma_f32_16x16x32_bf16 v[4:7], v[170:173], v[212:215], v[4:7]
	v_mfma_f32_16x16x32_bf16 v[0:3], v[178:181], v[212:215], v[0:3]
	v_mfma_f32_16x16x32_bf16 v[52:55], v[174:177], v[190:193], v[52:55]
	v_mfma_f32_16x16x32_bf16 v[48:51], v[182:185], v[190:193], v[48:51]
	v_mfma_f32_16x16x32_bf16 v[36:39], v[174:177], v[198:201], v[36:39]
	v_mfma_f32_16x16x32_bf16 v[32:35], v[182:185], v[198:201], v[32:35]
	v_mfma_f32_16x16x32_bf16 v[20:23], v[174:177], v[206:209], v[20:23]
	v_mfma_f32_16x16x32_bf16 v[16:19], v[182:185], v[206:209], v[16:19]
	v_mfma_f32_16x16x32_bf16 v[4:7], v[174:177], v[216:219], v[4:7]
	v_mfma_f32_16x16x32_bf16 v[0:3], v[182:185], v[216:219], v[0:3]
	s_setprio 0
	s_barrier
	s_add_i32 s79, s79, 2
	s_add_u32 s76, s76, 0x100
	s_addc_u32 s77, s77, 0
	s_cmpk_gt_u32 s79, 0x7d
	s_mov_b64 s[56:57], s[12:13]
	s_cbranch_scc0 .LBB0_474
	v_lshl_add_u32 v148, s74, 8, v150
	v_lshl_or_b32 v146, s54, 8, v136
	v_lshl_add_u32 v147, v148, 11, v146
	v_lshlrev_b32_e32 v159, 1, v147
	v_lshlrev_b32_e32 v208, 3, v148
	global_load_dwordx4 v[160:163], v159, s[38:39]
	global_load_dwordx4 v[164:167], v159, s[38:39] offset:64
	v_add_u32_e32 v149, 0x10000, v159
	global_load_dwordx4 v[168:171], v149, s[38:39]
	global_load_dwordx4 v[172:175], v149, s[38:39] offset:64
	v_add_u32_e32 v209, 0x20000, v159
	global_load_dwordx4 v[176:179], v209, s[38:39]
	global_load_dwordx4 v[180:183], v209, s[38:39] offset:64
	v_add_u32_e32 v149, 0x30000, v159
	global_load_dwordx4 v[184:187], v149, s[38:39]
	global_load_dwordx4 v[188:191], v149, s[38:39] offset:64
	v_add_u32_e32 v209, 0x80000, v159
	global_load_dwordx4 v[192:195], v209, s[38:39]
	global_load_dwordx4 v[196:199], v209, s[38:39] offset:64
	v_add_u32_e32 v149, 0x90000, v159
	global_load_dwordx4 v[200:203], v149, s[38:39]
	global_load_dwordx4 v[204:207], v149, s[38:39] offset:64
	v_add_u32_e32 v209, 0xa0000, v159
	global_load_dwordx4 v[212:215], v209, s[38:39]
	global_load_dwordx4 v[216:219], v209, s[38:39] offset:64
	v_add_u32_e32 v149, 0xb0000, v159
	global_load_dwordx4 v[220:223], v149, s[38:39]
	global_load_dwordx4 v[224:227], v149, s[38:39] offset:64
	s_and_b64 vcc, exec, s[46:47]
	s_cbranch_vccz .LBB0_477
	s_barrier
.LBB0_477:
	ds_write_b128 v156, v[124:127]
	ds_write_b128 v156, v[120:123] offset:64
	ds_read_b128 v[120:123], v157
	ds_read_b128 v[124:127], v157 offset:16
	ds_write_b128 v156, v[116:119]
	ds_write_b128 v156, v[112:115] offset:64
	ds_read_b128 v[112:115], v157
	ds_read_b128 v[116:119], v157 offset:16
	s_waitcnt vmcnt(15) lgkmcnt(4)
	v_lshlrev_b32_e32 v236, 16, v160
	v_and_b32_e32 v237, 0xffff0000, v160
	v_lshlrev_b32_e32 v238, 16, v161
	v_and_b32_e32 v239, 0xffff0000, v161
	v_lshlrev_b32_e32 v240, 16, v162
	v_and_b32_e32 v241, 0xffff0000, v162
	v_lshlrev_b32_e32 v242, 16, v163
	v_and_b32_e32 v243, 0xffff0000, v163
	v_pk_add_f32 v[120:121], v[120:121], v[236:237]
	v_pk_add_f32 v[122:123], v[122:123], v[238:239]
	v_pk_add_f32 v[124:125], v[124:125], v[240:241]
	v_pk_add_f32 v[126:127], v[126:127], v[242:243]
	v_mul_f32_e32 v236, v121, v121
	v_mul_f32_e32 v237, v123, v123
	v_mul_f32_e32 v238, v125, v125
	v_mul_f32_e32 v239, v127, v127
	v_fmac_f32_e32 v236, v120, v120
	v_fmac_f32_e32 v237, v122, v122
	v_fmac_f32_e32 v238, v124, v124
	v_fmac_f32_e32 v239, v126, v126
	v_cvt_pk_bf16_f32 v120, v120, v121
	v_cvt_pk_bf16_f32 v121, v122, v123
	v_cvt_pk_bf16_f32 v122, v124, v125
	v_cvt_pk_bf16_f32 v123, v126, v127
	v_add_f32_e32 v236, v236, v237
	v_add_f32_e32 v237, v238, v239
	v_add_f32_e32 v124, v236, v237
	global_store_dwordx4 v159, v[120:123], s[28:29]
	ds_write_b128 v156, v[108:111]
	ds_write_b128 v156, v[104:107] offset:64
	ds_read_b128 v[104:107], v157
	ds_read_b128 v[108:111], v157 offset:16
	s_waitcnt vmcnt(15) lgkmcnt(4)
; #define PG8_LAS __attribute__((address_space(3)))
; __device__ __forceinline__ unsigned cvt_pk_bf16(float lo, float hi) { unsigned r; asm volatile("v_cvt_pk_bf16_f32 %0, %1, %2" : "=v"(r) : "v"(lo), "v"(hi)); return r; }
;     __device__ __forceinline__ void operator()(const f32x4 (&acc)[2][2][4][2], const Unit& u, int wr, int wc, int fr, int fq) const {
;     ...
;                 const int row = u.pm * BM + ai * HALF + wr * 64 + m * 16 + r; float q = 0.f;
; #pragma unroll
;                 for (int bj = 0; bj < 2; ++bj) {
;                     const size_t off = (size_t)row * 2048 + u.pn * BM + wc * 64 + bj * 32 + 8 * p;
;                     f32x4 b0, b1;
;                     if (BASE_F32) { b0 = *(const f32x4*)((const float*)base + off); b1 = *(const f32x4*)((const float*)base + off + 4); }
;                     else { const u32x4 bb = *(const u32x4*)((const bf16_t*)base + off);
;                         b0 = (f32x4){__uint_as_float(bb.x << 16), __uint_as_float(bb.x & 0xffff0000u), __uint_as_float(bb.y << 16), __uint_as_float(bb.y & 0xffff0000u)};
;                         b1 = (f32x4){__uint_as_float(bb.z << 16), __uint_as_float(bb.z & 0xffff0000u), __uint_as_float(bb.w << 16), __uint_as_float(bb.w & 0xffff0000u)}; }
; #pragma unroll
;                     for (int n = 0; n < 2; ++n) *(PG8_LAS f32x4*)(stg + fr * STG_ROW + n * 64 + fq * 16) = acc[ai][bj][m][n];
;                     const f32x4 v0 = *(const PG8_LAS f32x4*)(stg + r * STG_ROW + p * 32) + b0, v1 = *(const PG8_LAS f32x4*)(stg + r * STG_ROW + p * 32 + 16) + b1;
;                     q += ((v0[0] * v0[0] + v0[1] * v0[1]) + (v0[2] * v0[2] + v0[3] * v0[3])) + ((v1[0] * v1[0] + v1[1] * v1[1]) + (v1[2] * v1[2] + v1[3] * v1[3]));
;                     u32x4 w; w.x = cvt_pk_bf16(v0[0], v0[1]); w.y = cvt_pk_bf16(v0[2], v0[3]); w.z = cvt_pk_bf16(v1[0], v1[1]); w.w = cvt_pk_bf16(v1[2], v1[3]);
;                     *(u32x4*)(out + off) = w;
;                 }
;                 q += __shfl_xor(q, 1); q += __shfl_xor(q, 2);
;                 if (p == 0) atomicAdd(ssn + row, (u64)(q * SS_SCALE));
	v_lshlrev_b32_e32 v236, 16, v164
	v_and_b32_e32 v237, 0xffff0000, v164
	v_lshlrev_b32_e32 v238, 16, v165
	v_and_b32_e32 v239, 0xffff0000, v165
	v_lshlrev_b32_e32 v240, 16, v166
	v_and_b32_e32 v241, 0xffff0000, v166
	v_lshlrev_b32_e32 v242, 16, v167
	v_and_b32_e32 v243, 0xffff0000, v167
	v_pk_add_f32 v[112:113], v[112:113], v[236:237]
	v_pk_add_f32 v[114:115], v[114:115], v[238:239]
	v_pk_add_f32 v[116:117], v[116:117], v[240:241]
	v_pk_add_f32 v[118:119], v[118:119], v[242:243]
	v_mul_f32_e32 v236, v113, v113
	v_mul_f32_e32 v237, v115, v115
	v_mul_f32_e32 v238, v117, v117
	v_mul_f32_e32 v239, v119, v119
	v_fmac_f32_e32 v236, v112, v112
	v_fmac_f32_e32 v237, v114, v114
	v_fmac_f32_e32 v238, v116, v116
	v_fmac_f32_e32 v239, v118, v118
	v_cvt_pk_bf16_f32 v112, v112, v113
	v_cvt_pk_bf16_f32 v113, v114, v115
	v_cvt_pk_bf16_f32 v114, v116, v117
	v_cvt_pk_bf16_f32 v115, v118, v119
	v_add_f32_e32 v236, v236, v237
	v_add_f32_e32 v237, v238, v239
	v_add_f32_e32 v116, v236, v237
	global_store_dwordx4 v159, v[112:115], s[28:29] offset:64
	v_add_f32_e32 v117, v124, v116
	s_nop 1
	v_add_f32_dpp v118, v117, v117 quad_perm:[1,0,3,2] row_mask:0xf bank_mask:0xf
	s_nop 1
	v_add_f32_dpp v119, v118, v118 quad_perm:[2,3,0,1] row_mask:0xf bank_mask:0xf
	v_mul_f32_e32 v126, 0x49800000, v119
	v_trunc_f32_e32 v126, v126
	v_mul_f32_e32 v127, 0x2f800000, v126
	v_floor_f32_e32 v127, v127
	v_fmac_f32_e32 v126, 0xcf800000, v127
	v_cvt_u32_f32_e32 v126, v126
	v_cvt_u32_f32_e32 v127, v127
	s_mov_b64 exec, s[8:9]
	global_atomic_add_x2 v208, v[126:127], s[44:45]
	s_mov_b64 exec, -1
	ds_write_b128 v156, v[100:103]
	ds_write_b128 v156, v[96:99] offset:64
	ds_read_b128 v[96:99], v157
	ds_read_b128 v[100:103], v157 offset:16
	s_waitcnt vmcnt(16) lgkmcnt(4)
	v_lshlrev_b32_e32 v236, 16, v168
	v_and_b32_e32 v237, 0xffff0000, v168
	v_lshlrev_b32_e32 v238, 16, v169
	v_and_b32_e32 v239, 0xffff0000, v169
	v_lshlrev_b32_e32 v240, 16, v170
	v_and_b32_e32 v241, 0xffff0000, v170
	v_lshlrev_b32_e32 v242, 16, v171
	v_and_b32_e32 v243, 0xffff0000, v171
	v_pk_add_f32 v[104:105], v[104:105], v[236:237]
	v_pk_add_f32 v[106:107], v[106:107], v[238:239]
	v_pk_add_f32 v[108:109], v[108:109], v[240:241]
	v_pk_add_f32 v[110:111], v[110:111], v[242:243]
	v_mul_f32_e32 v236, v105, v105
	v_mul_f32_e32 v237, v107, v107
	v_mul_f32_e32 v238, v109, v109
	v_mul_f32_e32 v239, v111, v111
	v_fmac_f32_e32 v236, v104, v104
	v_fmac_f32_e32 v237, v106, v106
	v_fmac_f32_e32 v238, v108, v108
	v_fmac_f32_e32 v239, v110, v110
	v_cvt_pk_bf16_f32 v104, v104, v105
	v_cvt_pk_bf16_f32 v105, v106, v107
	v_cvt_pk_bf16_f32 v106, v108, v109
	v_cvt_pk_bf16_f32 v107, v110, v111
	v_add_f32_e32 v236, v236, v237
	v_add_f32_e32 v237, v238, v239
	v_add_f32_e32 v108, v236, v237
	v_add_u32_e32 v147, 0x10000, v159
	global_store_dwordx4 v147, v[104:107], s[28:29]
	ds_write_b128 v156, v[92:95]
	ds_write_b128 v156, v[88:91] offset:64
	ds_read_b128 v[88:91], v157
	ds_read_b128 v[92:95], v157 offset:16
	s_waitcnt vmcnt(16) lgkmcnt(4)
	v_lshlrev_b32_e32 v236, 16, v172
	v_and_b32_e32 v237, 0xffff0000, v172
	v_lshlrev_b32_e32 v238, 16, v173
	v_and_b32_e32 v239, 0xffff0000, v173
	v_lshlrev_b32_e32 v240, 16, v174
	v_and_b32_e32 v241, 0xffff0000, v174
	v_lshlrev_b32_e32 v242, 16, v175
	v_and_b32_e32 v243, 0xffff0000, v175
	v_pk_add_f32 v[96:97], v[96:97], v[236:237]
	v_pk_add_f32 v[98:99], v[98:99], v[238:239]
	v_pk_add_f32 v[100:101], v[100:101], v[240:241]
	v_pk_add_f32 v[102:103], v[102:103], v[242:243]
	v_mul_f32_e32 v236, v97, v97
	v_mul_f32_e32 v237, v99, v99
	v_mul_f32_e32 v238, v101, v101
	v_mul_f32_e32 v239, v103, v103
	v_fmac_f32_e32 v236, v96, v96
	v_fmac_f32_e32 v237, v98, v98
	v_fmac_f32_e32 v238, v100, v100
	v_fmac_f32_e32 v239, v102, v102
	v_cvt_pk_bf16_f32 v96, v96, v97
	v_cvt_pk_bf16_f32 v97, v98, v99
	v_cvt_pk_bf16_f32 v98, v100, v101
	v_cvt_pk_bf16_f32 v99, v102, v103
	v_add_f32_e32 v236, v236, v237
	v_add_f32_e32 v237, v238, v239
	v_add_f32_e32 v100, v236, v237
	global_store_dwordx4 v147, v[96:99], s[28:29] offset:64
	v_add_f32_e32 v101, v108, v100
	s_nop 1
	v_add_f32_dpp v102, v101, v101 quad_perm:[1,0,3,2] row_mask:0xf bank_mask:0xf
	s_nop 1
	v_add_f32_dpp v103, v102, v102 quad_perm:[2,3,0,1] row_mask:0xf bank_mask:0xf
	v_mul_f32_e32 v110, 0x49800000, v103
	v_trunc_f32_e32 v110, v110
	v_mul_f32_e32 v111, 0x2f800000, v110
	v_floor_f32_e32 v111, v111
	v_fmac_f32_e32 v110, 0xcf800000, v111
	v_cvt_u32_f32_e32 v110, v110
	v_cvt_u32_f32_e32 v111, v111
	s_mov_b64 exec, s[8:9]
	global_atomic_add_x2 v208, v[110:111], s[44:45] offset:128
	s_mov_b64 exec, -1
	ds_write_b128 v156, v[84:87]
	ds_write_b128 v156, v[80:83] offset:64
	ds_read_b128 v[80:83], v157
	ds_read_b128 v[84:87], v157 offset:16
	s_waitcnt vmcnt(17) lgkmcnt(4)
	v_lshlrev_b32_e32 v236, 16, v176
	v_and_b32_e32 v237, 0xffff0000, v176
	v_lshlrev_b32_e32 v238, 16, v177
	v_and_b32_e32 v239, 0xffff0000, v177
	v_lshlrev_b32_e32 v240, 16, v178
	v_and_b32_e32 v241, 0xffff0000, v178
	v_lshlrev_b32_e32 v242, 16, v179
	v_and_b32_e32 v243, 0xffff0000, v179
	v_pk_add_f32 v[88:89], v[88:89], v[236:237]
	v_pk_add_f32 v[90:91], v[90:91], v[238:239]
	v_pk_add_f32 v[92:93], v[92:93], v[240:241]
	v_pk_add_f32 v[94:95], v[94:95], v[242:243]
	v_mul_f32_e32 v236, v89, v89
	v_mul_f32_e32 v237, v91, v91
	v_mul_f32_e32 v238, v93, v93
	v_mul_f32_e32 v239, v95, v95
	v_fmac_f32_e32 v236, v88, v88
	v_fmac_f32_e32 v237, v90, v90
	v_fmac_f32_e32 v238, v92, v92
	v_fmac_f32_e32 v239, v94, v94
	v_cvt_pk_bf16_f32 v88, v88, v89
	v_cvt_pk_bf16_f32 v89, v90, v91
	v_cvt_pk_bf16_f32 v90, v92, v93
	v_cvt_pk_bf16_f32 v91, v94, v95
	v_add_f32_e32 v236, v236, v237
	v_add_f32_e32 v237, v238, v239
	v_add_f32_e32 v92, v236, v237
	v_add_u32_e32 v146, 0x20000, v159
	global_store_dwordx4 v146, v[88:91], s[28:29]
	ds_write_b128 v156, v[76:79]
	ds_write_b128 v156, v[72:75] offset:64
	ds_read_b128 v[72:75], v157
	ds_read_b128 v[76:79], v157 offset:16
	s_waitcnt vmcnt(17) lgkmcnt(4)
; #define PG8_LAS __attribute__((address_space(3)))
; __device__ __forceinline__ unsigned cvt_pk_bf16(float lo, float hi) { unsigned r; asm volatile("v_cvt_pk_bf16_f32 %0, %1, %2" : "=v"(r) : "v"(lo), "v"(hi)); return r; }
;     __device__ __forceinline__ void operator()(const f32x4 (&acc)[2][2][4][2], const Unit& u, int wr, int wc, int fr, int fq) const {
;     ...
;                 const int row = u.pm * BM + ai * HALF + wr * 64 + m * 16 + r; float q = 0.f;
; #pragma unroll
;                 for (int bj = 0; bj < 2; ++bj) {
;                     const size_t off = (size_t)row * 2048 + u.pn * BM + wc * 64 + bj * 32 + 8 * p;
;                     f32x4 b0, b1;
;                     if (BASE_F32) { b0 = *(const f32x4*)((const float*)base + off); b1 = *(const f32x4*)((const float*)base + off + 4); }
;                     else { const u32x4 bb = *(const u32x4*)((const bf16_t*)base + off);
;                         b0 = (f32x4){__uint_as_float(bb.x << 16), __uint_as_float(bb.x & 0xffff0000u), __uint_as_float(bb.y << 16), __uint_as_float(bb.y & 0xffff0000u)};
;                         b1 = (f32x4){__uint_as_float(bb.z << 16), __uint_as_float(bb.z & 0xffff0000u), __uint_as_float(bb.w << 16), __uint_as_float(bb.w & 0xffff0000u)}; }
; #pragma unroll
;                     for (int n = 0; n < 2; ++n) *(PG8_LAS f32x4*)(stg + fr * STG_ROW + n * 64 + fq * 16) = acc[ai][bj][m][n];
;                     const f32x4 v0 = *(const PG8_LAS f32x4*)(stg + r * STG_ROW + p * 32) + b0, v1 = *(const PG8_LAS f32x4*)(stg + r * STG_ROW + p * 32 + 16) + b1;
;                     q += ((v0[0] * v0[0] + v0[1] * v0[1]) + (v0[2] * v0[2] + v0[3] * v0[3])) + ((v1[0] * v1[0] + v1[1] * v1[1]) + (v1[2] * v1[2] + v1[3] * v1[3]));
;                     u32x4 w; w.x = cvt_pk_bf16(v0[0], v0[1]); w.y = cvt_pk_bf16(v0[2], v0[3]); w.z = cvt_pk_bf16(v1[0], v1[1]); w.w = cvt_pk_bf16(v1[2], v1[3]);
;                     *(u32x4*)(out + off) = w;
;                 }
;                 q += __shfl_xor(q, 1); q += __shfl_xor(q, 2);
;                 if (p == 0) atomicAdd(ssn + row, (u64)(q * SS_SCALE));
	v_lshlrev_b32_e32 v236, 16, v180
	v_and_b32_e32 v237, 0xffff0000, v180
	v_lshlrev_b32_e32 v238, 16, v181
	v_and_b32_e32 v239, 0xffff0000, v181
	v_lshlrev_b32_e32 v240, 16, v182
	v_and_b32_e32 v241, 0xffff0000, v182
	v_lshlrev_b32_e32 v242, 16, v183
	v_and_b32_e32 v243, 0xffff0000, v183
	v_pk_add_f32 v[80:81], v[80:81], v[236:237]
	v_pk_add_f32 v[82:83], v[82:83], v[238:239]
	v_pk_add_f32 v[84:85], v[84:85], v[240:241]
	v_pk_add_f32 v[86:87], v[86:87], v[242:243]
	v_mul_f32_e32 v236, v81, v81
	v_mul_f32_e32 v237, v83, v83
	v_mul_f32_e32 v238, v85, v85
	v_mul_f32_e32 v239, v87, v87
	v_fmac_f32_e32 v236, v80, v80
	v_fmac_f32_e32 v237, v82, v82
	v_fmac_f32_e32 v238, v84, v84
	v_fmac_f32_e32 v239, v86, v86
	v_cvt_pk_bf16_f32 v80, v80, v81
	v_cvt_pk_bf16_f32 v81, v82, v83
	v_cvt_pk_bf16_f32 v82, v84, v85
	v_cvt_pk_bf16_f32 v83, v86, v87
	v_add_f32_e32 v236, v236, v237
	v_add_f32_e32 v237, v238, v239
	v_add_f32_e32 v84, v236, v237
	global_store_dwordx4 v146, v[80:83], s[28:29] offset:64
	v_add_f32_e32 v85, v92, v84
	s_nop 1
	v_add_f32_dpp v86, v85, v85 quad_perm:[1,0,3,2] row_mask:0xf bank_mask:0xf
	s_nop 1
	v_add_f32_dpp v87, v86, v86 quad_perm:[2,3,0,1] row_mask:0xf bank_mask:0xf
	v_mul_f32_e32 v94, 0x49800000, v87
	v_trunc_f32_e32 v94, v94
	v_mul_f32_e32 v95, 0x2f800000, v94
	v_floor_f32_e32 v95, v95
	v_fmac_f32_e32 v94, 0xcf800000, v95
	v_cvt_u32_f32_e32 v94, v94
	v_cvt_u32_f32_e32 v95, v95
	s_mov_b64 exec, s[8:9]
	global_atomic_add_x2 v208, v[94:95], s[44:45] offset:256
	s_mov_b64 exec, -1
	ds_write_b128 v156, v[68:71]
	ds_write_b128 v156, v[64:67] offset:64
	ds_read_b128 v[64:67], v157
	ds_read_b128 v[68:71], v157 offset:16
	s_waitcnt vmcnt(18) lgkmcnt(4)
	v_lshlrev_b32_e32 v236, 16, v184
	v_and_b32_e32 v237, 0xffff0000, v184
	v_lshlrev_b32_e32 v238, 16, v185
	v_and_b32_e32 v239, 0xffff0000, v185
	v_lshlrev_b32_e32 v240, 16, v186
	v_and_b32_e32 v241, 0xffff0000, v186
	v_lshlrev_b32_e32 v242, 16, v187
	v_and_b32_e32 v243, 0xffff0000, v187
	v_pk_add_f32 v[72:73], v[72:73], v[236:237]
	v_pk_add_f32 v[74:75], v[74:75], v[238:239]
	v_pk_add_f32 v[76:77], v[76:77], v[240:241]
	v_pk_add_f32 v[78:79], v[78:79], v[242:243]
	v_mul_f32_e32 v236, v73, v73
	v_mul_f32_e32 v237, v75, v75
	v_mul_f32_e32 v238, v77, v77
	v_mul_f32_e32 v239, v79, v79
	v_fmac_f32_e32 v236, v72, v72
	v_fmac_f32_e32 v237, v74, v74
	v_fmac_f32_e32 v238, v76, v76
	v_fmac_f32_e32 v239, v78, v78
	v_cvt_pk_bf16_f32 v72, v72, v73
	v_cvt_pk_bf16_f32 v73, v74, v75
	v_cvt_pk_bf16_f32 v74, v76, v77
	v_cvt_pk_bf16_f32 v75, v78, v79
	v_add_f32_e32 v236, v236, v237
	v_add_f32_e32 v237, v238, v239
	v_add_f32_e32 v76, v236, v237
	v_add_u32_e32 v147, 0x30000, v159
	global_store_dwordx4 v147, v[72:75], s[28:29]
	ds_write_b128 v156, v[60:63]
	ds_write_b128 v156, v[56:59] offset:64
	ds_read_b128 v[56:59], v157
	ds_read_b128 v[60:63], v157 offset:16
	s_waitcnt vmcnt(18) lgkmcnt(4)
	v_lshlrev_b32_e32 v236, 16, v188
	v_and_b32_e32 v237, 0xffff0000, v188
	v_lshlrev_b32_e32 v238, 16, v189
	v_and_b32_e32 v239, 0xffff0000, v189
	v_lshlrev_b32_e32 v240, 16, v190
	v_and_b32_e32 v241, 0xffff0000, v190
	v_lshlrev_b32_e32 v242, 16, v191
	v_and_b32_e32 v243, 0xffff0000, v191
	v_pk_add_f32 v[64:65], v[64:65], v[236:237]
	v_pk_add_f32 v[66:67], v[66:67], v[238:239]
	v_pk_add_f32 v[68:69], v[68:69], v[240:241]
	v_pk_add_f32 v[70:71], v[70:71], v[242:243]
	v_mul_f32_e32 v236, v65, v65
	v_mul_f32_e32 v237, v67, v67
	v_mul_f32_e32 v238, v69, v69
	v_mul_f32_e32 v239, v71, v71
	v_fmac_f32_e32 v236, v64, v64
	v_fmac_f32_e32 v237, v66, v66
	v_fmac_f32_e32 v238, v68, v68
	v_fmac_f32_e32 v239, v70, v70
	v_cvt_pk_bf16_f32 v64, v64, v65
	v_cvt_pk_bf16_f32 v65, v66, v67
	v_cvt_pk_bf16_f32 v66, v68, v69
	v_cvt_pk_bf16_f32 v67, v70, v71
	v_add_f32_e32 v236, v236, v237
	v_add_f32_e32 v237, v238, v239
	v_add_f32_e32 v68, v236, v237
	global_store_dwordx4 v147, v[64:67], s[28:29] offset:64
	v_add_f32_e32 v69, v76, v68
	s_nop 1
	v_add_f32_dpp v70, v69, v69 quad_perm:[1,0,3,2] row_mask:0xf bank_mask:0xf
	s_nop 1
	v_add_f32_dpp v71, v70, v70 quad_perm:[2,3,0,1] row_mask:0xf bank_mask:0xf
	v_mul_f32_e32 v78, 0x49800000, v71
	v_trunc_f32_e32 v78, v78
	v_mul_f32_e32 v79, 0x2f800000, v78
	v_floor_f32_e32 v79, v79
	v_fmac_f32_e32 v78, 0xcf800000, v79
	v_cvt_u32_f32_e32 v78, v78
	v_cvt_u32_f32_e32 v79, v79
	s_mov_b64 exec, s[8:9]
	global_atomic_add_x2 v208, v[78:79], s[44:45] offset:384
	s_mov_b64 exec, -1
	ds_write_b128 v156, v[52:55]
	ds_write_b128 v156, v[48:51] offset:64
	ds_read_b128 v[48:51], v157
	ds_read_b128 v[52:55], v157 offset:16
	s_waitcnt vmcnt(19) lgkmcnt(4)
	v_lshlrev_b32_e32 v236, 16, v192
	v_and_b32_e32 v237, 0xffff0000, v192
	v_lshlrev_b32_e32 v238, 16, v193
	v_and_b32_e32 v239, 0xffff0000, v193
	v_lshlrev_b32_e32 v240, 16, v194
	v_and_b32_e32 v241, 0xffff0000, v194
	v_lshlrev_b32_e32 v242, 16, v195
	v_and_b32_e32 v243, 0xffff0000, v195
	v_pk_add_f32 v[56:57], v[56:57], v[236:237]
	v_pk_add_f32 v[58:59], v[58:59], v[238:239]
	v_pk_add_f32 v[60:61], v[60:61], v[240:241]
	v_pk_add_f32 v[62:63], v[62:63], v[242:243]
	v_mul_f32_e32 v236, v57, v57
	v_mul_f32_e32 v237, v59, v59
	v_mul_f32_e32 v238, v61, v61
	v_mul_f32_e32 v239, v63, v63
	v_fmac_f32_e32 v236, v56, v56
	v_fmac_f32_e32 v237, v58, v58
	v_fmac_f32_e32 v238, v60, v60
	v_fmac_f32_e32 v239, v62, v62
	v_cvt_pk_bf16_f32 v56, v56, v57
	v_cvt_pk_bf16_f32 v57, v58, v59
	v_cvt_pk_bf16_f32 v58, v60, v61
	v_cvt_pk_bf16_f32 v59, v62, v63
	v_add_f32_e32 v236, v236, v237
	v_add_f32_e32 v237, v238, v239
	v_add_f32_e32 v60, v236, v237
	v_add_u32_e32 v146, 0x80000, v159
	global_store_dwordx4 v146, v[56:59], s[28:29]
	ds_write_b128 v156, v[44:47]
	ds_write_b128 v156, v[40:43] offset:64
	ds_read_b128 v[40:43], v157
	ds_read_b128 v[44:47], v157 offset:16
	s_waitcnt vmcnt(19) lgkmcnt(4)
; #define PG8_LAS __attribute__((address_space(3)))
; __device__ __forceinline__ unsigned cvt_pk_bf16(float lo, float hi) { unsigned r; asm volatile("v_cvt_pk_bf16_f32 %0, %1, %2" : "=v"(r) : "v"(lo), "v"(hi)); return r; }
;     __device__ __forceinline__ void operator()(const f32x4 (&acc)[2][2][4][2], const Unit& u, int wr, int wc, int fr, int fq) const {
;     ...
;                 const int row = u.pm * BM + ai * HALF + wr * 64 + m * 16 + r; float q = 0.f;
; #pragma unroll
;                 for (int bj = 0; bj < 2; ++bj) {
;                     const size_t off = (size_t)row * 2048 + u.pn * BM + wc * 64 + bj * 32 + 8 * p;
;                     f32x4 b0, b1;
;                     if (BASE_F32) { b0 = *(const f32x4*)((const float*)base + off); b1 = *(const f32x4*)((const float*)base + off + 4); }
;                     else { const u32x4 bb = *(const u32x4*)((const bf16_t*)base + off);
;                         b0 = (f32x4){__uint_as_float(bb.x << 16), __uint_as_float(bb.x & 0xffff0000u), __uint_as_float(bb.y << 16), __uint_as_float(bb.y & 0xffff0000u)};
;                         b1 = (f32x4){__uint_as_float(bb.z << 16), __uint_as_float(bb.z & 0xffff0000u), __uint_as_float(bb.w << 16), __uint_as_float(bb.w & 0xffff0000u)}; }
; #pragma unroll
;                     for (int n = 0; n < 2; ++n) *(PG8_LAS f32x4*)(stg + fr * STG_ROW + n * 64 + fq * 16) = acc[ai][bj][m][n];
;                     const f32x4 v0 = *(const PG8_LAS f32x4*)(stg + r * STG_ROW + p * 32) + b0, v1 = *(const PG8_LAS f32x4*)(stg + r * STG_ROW + p * 32 + 16) + b1;
;                     q += ((v0[0] * v0[0] + v0[1] * v0[1]) + (v0[2] * v0[2] + v0[3] * v0[3])) + ((v1[0] * v1[0] + v1[1] * v1[1]) + (v1[2] * v1[2] + v1[3] * v1[3]));
;                     u32x4 w; w.x = cvt_pk_bf16(v0[0], v0[1]); w.y = cvt_pk_bf16(v0[2], v0[3]); w.z = cvt_pk_bf16(v1[0], v1[1]); w.w = cvt_pk_bf16(v1[2], v1[3]);
;                     *(u32x4*)(out + off) = w;
;                 }
;                 q += __shfl_xor(q, 1); q += __shfl_xor(q, 2);
;                 if (p == 0) atomicAdd(ssn + row, (u64)(q * SS_SCALE));
	v_lshlrev_b32_e32 v236, 16, v196
	v_and_b32_e32 v237, 0xffff0000, v196
	v_lshlrev_b32_e32 v238, 16, v197
	v_and_b32_e32 v239, 0xffff0000, v197
	v_lshlrev_b32_e32 v240, 16, v198
	v_and_b32_e32 v241, 0xffff0000, v198
	v_lshlrev_b32_e32 v242, 16, v199
	v_and_b32_e32 v243, 0xffff0000, v199
	v_pk_add_f32 v[48:49], v[48:49], v[236:237]
	v_pk_add_f32 v[50:51], v[50:51], v[238:239]
	v_pk_add_f32 v[52:53], v[52:53], v[240:241]
	v_pk_add_f32 v[54:55], v[54:55], v[242:243]
	v_mul_f32_e32 v236, v49, v49
	v_mul_f32_e32 v237, v51, v51
	v_mul_f32_e32 v238, v53, v53
	v_mul_f32_e32 v239, v55, v55
	v_fmac_f32_e32 v236, v48, v48
	v_fmac_f32_e32 v237, v50, v50
	v_fmac_f32_e32 v238, v52, v52
	v_fmac_f32_e32 v239, v54, v54
	v_cvt_pk_bf16_f32 v48, v48, v49
	v_cvt_pk_bf16_f32 v49, v50, v51
	v_cvt_pk_bf16_f32 v50, v52, v53
	v_cvt_pk_bf16_f32 v51, v54, v55
	v_add_f32_e32 v236, v236, v237
	v_add_f32_e32 v237, v238, v239
	v_add_f32_e32 v52, v236, v237
	global_store_dwordx4 v146, v[48:51], s[28:29] offset:64
	v_add_f32_e32 v53, v60, v52
	s_nop 1
	v_add_f32_dpp v54, v53, v53 quad_perm:[1,0,3,2] row_mask:0xf bank_mask:0xf
	s_nop 1
	v_add_f32_dpp v55, v54, v54 quad_perm:[2,3,0,1] row_mask:0xf bank_mask:0xf
	v_mul_f32_e32 v62, 0x49800000, v55
	v_trunc_f32_e32 v62, v62
	v_mul_f32_e32 v63, 0x2f800000, v62
	v_floor_f32_e32 v63, v63
	v_fmac_f32_e32 v62, 0xcf800000, v63
	v_cvt_u32_f32_e32 v62, v62
	v_cvt_u32_f32_e32 v63, v63
	s_mov_b64 exec, s[8:9]
	global_atomic_add_x2 v208, v[62:63], s[44:45] offset:1024
	s_mov_b64 exec, -1
	ds_write_b128 v156, v[36:39]
	ds_write_b128 v156, v[32:35] offset:64
	ds_read_b128 v[32:35], v157
	ds_read_b128 v[36:39], v157 offset:16
	s_waitcnt vmcnt(20) lgkmcnt(4)
	v_lshlrev_b32_e32 v236, 16, v200
	v_and_b32_e32 v237, 0xffff0000, v200
	v_lshlrev_b32_e32 v238, 16, v201
	v_and_b32_e32 v239, 0xffff0000, v201
	v_lshlrev_b32_e32 v240, 16, v202
	v_and_b32_e32 v241, 0xffff0000, v202
	v_lshlrev_b32_e32 v242, 16, v203
	v_and_b32_e32 v243, 0xffff0000, v203
	v_pk_add_f32 v[40:41], v[40:41], v[236:237]
	v_pk_add_f32 v[42:43], v[42:43], v[238:239]
	v_pk_add_f32 v[44:45], v[44:45], v[240:241]
	v_pk_add_f32 v[46:47], v[46:47], v[242:243]
	v_mul_f32_e32 v236, v41, v41
	v_mul_f32_e32 v237, v43, v43
	v_mul_f32_e32 v238, v45, v45
	v_mul_f32_e32 v239, v47, v47
	v_fmac_f32_e32 v236, v40, v40
	v_fmac_f32_e32 v237, v42, v42
	v_fmac_f32_e32 v238, v44, v44
	v_fmac_f32_e32 v239, v46, v46
	v_cvt_pk_bf16_f32 v40, v40, v41
	v_cvt_pk_bf16_f32 v41, v42, v43
	v_cvt_pk_bf16_f32 v42, v44, v45
	v_cvt_pk_bf16_f32 v43, v46, v47
	v_add_f32_e32 v236, v236, v237
	v_add_f32_e32 v237, v238, v239
	v_add_f32_e32 v44, v236, v237
	v_add_u32_e32 v147, 0x90000, v159
	global_store_dwordx4 v147, v[40:43], s[28:29]
	ds_write_b128 v156, v[28:31]
	ds_write_b128 v156, v[24:27] offset:64
	ds_read_b128 v[24:27], v157
	ds_read_b128 v[28:31], v157 offset:16
	s_waitcnt vmcnt(20) lgkmcnt(4)
	v_lshlrev_b32_e32 v236, 16, v204
	v_and_b32_e32 v237, 0xffff0000, v204
	v_lshlrev_b32_e32 v238, 16, v205
	v_and_b32_e32 v239, 0xffff0000, v205
	v_lshlrev_b32_e32 v240, 16, v206
	v_and_b32_e32 v241, 0xffff0000, v206
	v_lshlrev_b32_e32 v242, 16, v207
	v_and_b32_e32 v243, 0xffff0000, v207
	v_pk_add_f32 v[32:33], v[32:33], v[236:237]
	v_pk_add_f32 v[34:35], v[34:35], v[238:239]
	v_pk_add_f32 v[36:37], v[36:37], v[240:241]
	v_pk_add_f32 v[38:39], v[38:39], v[242:243]
	v_mul_f32_e32 v236, v33, v33
	v_mul_f32_e32 v237, v35, v35
	v_mul_f32_e32 v238, v37, v37
	v_mul_f32_e32 v239, v39, v39
	v_fmac_f32_e32 v236, v32, v32
	v_fmac_f32_e32 v237, v34, v34
	v_fmac_f32_e32 v238, v36, v36
	v_fmac_f32_e32 v239, v38, v38
	v_cvt_pk_bf16_f32 v32, v32, v33
	v_cvt_pk_bf16_f32 v33, v34, v35
	v_cvt_pk_bf16_f32 v34, v36, v37
	v_cvt_pk_bf16_f32 v35, v38, v39
	v_add_f32_e32 v236, v236, v237
	v_add_f32_e32 v237, v238, v239
	v_add_f32_e32 v36, v236, v237
	global_store_dwordx4 v147, v[32:35], s[28:29] offset:64
	v_add_f32_e32 v37, v44, v36
	s_nop 1
	v_add_f32_dpp v38, v37, v37 quad_perm:[1,0,3,2] row_mask:0xf bank_mask:0xf
	s_nop 1
	v_add_f32_dpp v39, v38, v38 quad_perm:[2,3,0,1] row_mask:0xf bank_mask:0xf
	v_mul_f32_e32 v46, 0x49800000, v39
	v_trunc_f32_e32 v46, v46
	v_mul_f32_e32 v47, 0x2f800000, v46
	v_floor_f32_e32 v47, v47
	v_fmac_f32_e32 v46, 0xcf800000, v47
	v_cvt_u32_f32_e32 v46, v46
	v_cvt_u32_f32_e32 v47, v47
	s_mov_b64 exec, s[8:9]
	global_atomic_add_x2 v208, v[46:47], s[44:45] offset:1152
	s_mov_b64 exec, -1
	ds_write_b128 v156, v[20:23]
	ds_write_b128 v156, v[16:19] offset:64
	ds_read_b128 v[16:19], v157
	ds_read_b128 v[20:23], v157 offset:16
	s_waitcnt vmcnt(21) lgkmcnt(4)
; template <class Epi, class Sched, bool ALIGN_EPI = false, bool SP2 = false>
; __device__ __forceinline__ void gemm_phase(PG8_LAS unsigned char* lds, const Gemm g, const Sched& S, const Epi& E, int tid_in) {
;     ...
;         if (!has_next) break;
; #pragma unroll
;         for (int a = 0; a < 2; ++a)
; #pragma unroll
;             for (int b = 0; b < 2; ++b)
; #pragma unroll
;                 for (int m = 0; m < 4; ++m)
; #pragma unroll
;                     for (int n = 0; n < 2; ++n) acc[a][b][m][n] = (f32x4){0.f, 0.f, 0.f, 0.f};
;     __device__ __forceinline__ void operator()(const f32x4 (&acc)[2][2][4][2], const Unit& u, int wr, int wc, int fr, int fq) const {
;     ...
;                 const int row = u.pm * BM + ai * HALF + wr * 64 + m * 16 + r; float q = 0.f;
; #pragma unroll
;                 for (int bj = 0; bj < 2; ++bj) {
;                     const size_t off = (size_t)row * 2048 + u.pn * BM + wc * 64 + bj * 32 + 8 * p;
;                     f32x4 b0, b1;
;                     if (BASE_F32) { b0 = *(const f32x4*)((const float*)base + off); b1 = *(const f32x4*)((const float*)base + off + 4); }
;                     else { const u32x4 bb = *(const u32x4*)((const bf16_t*)base + off);
;                         b0 = (f32x4){__uint_as_float(bb.x << 16), __uint_as_float(bb.x & 0xffff0000u), __uint_as_float(bb.y << 16), __uint_as_float(bb.y & 0xffff0000u)};
;                         b1 = (f32x4){__uint_as_float(bb.z << 16), __uint_as_float(bb.z & 0xffff0000u), __uint_as_float(bb.w << 16), __uint_as_float(bb.w & 0xffff0000u)}; }
; #pragma unroll
;                     for (int n = 0; n < 2; ++n) *(PG8_LAS f32x4*)(stg + fr * STG_ROW + n * 64 + fq * 16) = acc[ai][bj][m][n];
;                     const f32x4 v0 = *(const PG8_LAS f32x4*)(stg + r * STG_ROW + p * 32) + b0, v1 = *(const PG8_LAS f32x4*)(stg + r * STG_ROW + p * 32 + 16) + b1;
;                     q += ((v0[0] * v0[0] + v0[1] * v0[1]) + (v0[2] * v0[2] + v0[3] * v0[3])) + ((v1[0] * v1[0] + v1[1] * v1[1]) + (v1[2] * v1[2] + v1[3] * v1[3]));
;                     u32x4 w; w.x = cvt_pk_bf16(v0[0], v0[1]); w.y = cvt_pk_bf16(v0[2], v0[3]); w.z = cvt_pk_bf16(v1[0], v1[1]); w.w = cvt_pk_bf16(v1[2], v1[3]);
;                     *(u32x4*)(out + off) = w;
;                 }
;                 q += __shfl_xor(q, 1); q += __shfl_xor(q, 2);
;                 if (p == 0) atomicAdd(ssn + row, (u64)(q * SS_SCALE));
	v_lshlrev_b32_e32 v236, 16, v212
	v_and_b32_e32 v237, 0xffff0000, v212
	v_lshlrev_b32_e32 v238, 16, v213
	v_and_b32_e32 v239, 0xffff0000, v213
	v_lshlrev_b32_e32 v240, 16, v214
	v_and_b32_e32 v241, 0xffff0000, v214
	v_lshlrev_b32_e32 v242, 16, v215
	v_and_b32_e32 v243, 0xffff0000, v215
	v_pk_add_f32 v[24:25], v[24:25], v[236:237]
	v_pk_add_f32 v[26:27], v[26:27], v[238:239]
	v_pk_add_f32 v[28:29], v[28:29], v[240:241]
	v_pk_add_f32 v[30:31], v[30:31], v[242:243]
	v_mul_f32_e32 v236, v25, v25
	v_mul_f32_e32 v237, v27, v27
	v_mul_f32_e32 v238, v29, v29
	v_mul_f32_e32 v239, v31, v31
	v_fmac_f32_e32 v236, v24, v24
	v_fmac_f32_e32 v237, v26, v26
	v_fmac_f32_e32 v238, v28, v28
	v_fmac_f32_e32 v239, v30, v30
	v_cvt_pk_bf16_f32 v24, v24, v25
	v_cvt_pk_bf16_f32 v25, v26, v27
	v_cvt_pk_bf16_f32 v26, v28, v29
	v_cvt_pk_bf16_f32 v27, v30, v31
	v_add_f32_e32 v236, v236, v237
	v_add_f32_e32 v237, v238, v239
	v_add_f32_e32 v28, v236, v237
	v_add_u32_e32 v146, 0xa0000, v159
	global_store_dwordx4 v146, v[24:27], s[28:29]
	ds_write_b128 v156, v[12:15]
	ds_write_b128 v156, v[8:11] offset:64
	ds_read_b128 v[8:11], v157
	ds_read_b128 v[12:15], v157 offset:16
	s_waitcnt vmcnt(21) lgkmcnt(4)
	v_lshlrev_b32_e32 v236, 16, v216
	v_and_b32_e32 v237, 0xffff0000, v216
	v_lshlrev_b32_e32 v238, 16, v217
	v_and_b32_e32 v239, 0xffff0000, v217
	v_lshlrev_b32_e32 v240, 16, v218
	v_and_b32_e32 v241, 0xffff0000, v218
	v_lshlrev_b32_e32 v242, 16, v219
	v_and_b32_e32 v243, 0xffff0000, v219
	v_pk_add_f32 v[16:17], v[16:17], v[236:237]
	v_pk_add_f32 v[18:19], v[18:19], v[238:239]
	v_pk_add_f32 v[20:21], v[20:21], v[240:241]
	v_pk_add_f32 v[22:23], v[22:23], v[242:243]
	v_mul_f32_e32 v236, v17, v17
	v_mul_f32_e32 v237, v19, v19
	v_mul_f32_e32 v238, v21, v21
	v_mul_f32_e32 v239, v23, v23
	v_fmac_f32_e32 v236, v16, v16
	v_fmac_f32_e32 v237, v18, v18
	v_fmac_f32_e32 v238, v20, v20
	v_fmac_f32_e32 v239, v22, v22
	v_cvt_pk_bf16_f32 v16, v16, v17
	v_cvt_pk_bf16_f32 v17, v18, v19
	v_cvt_pk_bf16_f32 v18, v20, v21
	v_cvt_pk_bf16_f32 v19, v22, v23
	v_add_f32_e32 v236, v236, v237
	v_add_f32_e32 v237, v238, v239
	v_add_f32_e32 v20, v236, v237
	global_store_dwordx4 v146, v[16:19], s[28:29] offset:64
	v_add_f32_e32 v21, v28, v20
	s_nop 1
	v_add_f32_dpp v22, v21, v21 quad_perm:[1,0,3,2] row_mask:0xf bank_mask:0xf
	s_nop 1
	v_add_f32_dpp v23, v22, v22 quad_perm:[2,3,0,1] row_mask:0xf bank_mask:0xf
	v_mul_f32_e32 v30, 0x49800000, v23
	v_trunc_f32_e32 v30, v30
	v_mul_f32_e32 v31, 0x2f800000, v30
	v_floor_f32_e32 v31, v31
	v_fmac_f32_e32 v30, 0xcf800000, v31
	v_cvt_u32_f32_e32 v30, v30
	v_cvt_u32_f32_e32 v31, v31
	s_mov_b64 exec, s[8:9]
	global_atomic_add_x2 v208, v[30:31], s[44:45] offset:1280
	s_mov_b64 exec, -1
	ds_write_b128 v156, v[4:7]
	ds_write_b128 v156, v[0:3] offset:64
	ds_read_b128 v[0:3], v157
	ds_read_b128 v[4:7], v157 offset:16
	s_waitcnt vmcnt(22) lgkmcnt(4)
	v_lshlrev_b32_e32 v236, 16, v220
	v_and_b32_e32 v237, 0xffff0000, v220
	v_lshlrev_b32_e32 v238, 16, v221
	v_and_b32_e32 v239, 0xffff0000, v221
	v_lshlrev_b32_e32 v240, 16, v222
	v_and_b32_e32 v241, 0xffff0000, v222
	v_lshlrev_b32_e32 v242, 16, v223
	v_and_b32_e32 v243, 0xffff0000, v223
	v_pk_add_f32 v[8:9], v[8:9], v[236:237]
	v_pk_add_f32 v[10:11], v[10:11], v[238:239]
	v_pk_add_f32 v[12:13], v[12:13], v[240:241]
	v_pk_add_f32 v[14:15], v[14:15], v[242:243]
	v_mul_f32_e32 v236, v9, v9
	v_mul_f32_e32 v237, v11, v11
	v_mul_f32_e32 v238, v13, v13
	v_mul_f32_e32 v239, v15, v15
	v_fmac_f32_e32 v236, v8, v8
	v_fmac_f32_e32 v237, v10, v10
	v_fmac_f32_e32 v238, v12, v12
	v_fmac_f32_e32 v239, v14, v14
	v_cvt_pk_bf16_f32 v8, v8, v9
	v_cvt_pk_bf16_f32 v9, v10, v11
	v_cvt_pk_bf16_f32 v10, v12, v13
	v_cvt_pk_bf16_f32 v11, v14, v15
	v_add_f32_e32 v236, v236, v237
	v_add_f32_e32 v237, v238, v239
	v_add_f32_e32 v12, v236, v237
	v_add_u32_e32 v147, 0xb0000, v159
	global_store_dwordx4 v147, v[8:11], s[28:29]
	s_waitcnt vmcnt(22) lgkmcnt(0)
	v_lshlrev_b32_e32 v236, 16, v224
	v_and_b32_e32 v237, 0xffff0000, v224
	v_lshlrev_b32_e32 v238, 16, v225
	v_and_b32_e32 v239, 0xffff0000, v225
	v_lshlrev_b32_e32 v240, 16, v226
	v_and_b32_e32 v241, 0xffff0000, v226
	v_lshlrev_b32_e32 v242, 16, v227
	v_and_b32_e32 v243, 0xffff0000, v227
	v_pk_add_f32 v[0:1], v[0:1], v[236:237]
	v_pk_add_f32 v[2:3], v[2:3], v[238:239]
	v_pk_add_f32 v[4:5], v[4:5], v[240:241]
	v_pk_add_f32 v[6:7], v[6:7], v[242:243]
	v_mul_f32_e32 v236, v1, v1
	v_mul_f32_e32 v237, v3, v3
	v_mul_f32_e32 v238, v5, v5
	v_mul_f32_e32 v239, v7, v7
	v_fmac_f32_e32 v236, v0, v0
	v_fmac_f32_e32 v237, v2, v2
	v_fmac_f32_e32 v238, v4, v4
	v_fmac_f32_e32 v239, v6, v6
	v_cvt_pk_bf16_f32 v0, v0, v1
	v_cvt_pk_bf16_f32 v1, v2, v3
	v_cvt_pk_bf16_f32 v2, v4, v5
	v_cvt_pk_bf16_f32 v3, v6, v7
	v_add_f32_e32 v236, v236, v237
	v_add_f32_e32 v237, v238, v239
	v_add_f32_e32 v4, v236, v237
	global_store_dwordx4 v147, v[0:3], s[28:29] offset:64
	v_add_f32_e32 v5, v12, v4
	s_nop 1
	v_add_f32_dpp v6, v5, v5 quad_perm:[1,0,3,2] row_mask:0xf bank_mask:0xf
	s_nop 1
	v_add_f32_dpp v7, v6, v6 quad_perm:[2,3,0,1] row_mask:0xf bank_mask:0xf
	v_mul_f32_e32 v14, 0x49800000, v7
	v_trunc_f32_e32 v14, v14
	v_mul_f32_e32 v15, 0x2f800000, v14
	v_floor_f32_e32 v15, v15
	v_fmac_f32_e32 v14, 0xcf800000, v15
	v_cvt_u32_f32_e32 v14, v14
	v_cvt_u32_f32_e32 v15, v15
	s_mov_b64 exec, s[8:9]
	global_atomic_add_x2 v208, v[14:15], s[44:45] offset:1408
	s_mov_b64 exec, -1
	s_and_b64 vcc, exec, s[10:11]
	s_mov_b64 s[10:11], -1
	s_cbranch_vccnz .LBB0_464
	s_andn2_b64 vcc, exec, s[14:15]
	s_cbranch_vccnz .LBB0_463
	s_mov_b32 s98, 1
	s_branch .LBB0_463

; #define PG8_STAGE(bufoff, gbase, voff) do { _Pragma("unroll") for (int _i = 0; _i < 2; ++_i) \
;         __builtin_amdgcn_global_load_lds((const unsigned*)((const char*)(gbase) + (voff)[_i]), (PG8_LAS unsigned*)(lds + (bufoff) + ldsw + _i * 8192), 16, 0, 0); } while (0)
; #define PG8_LDA(dst, b, h) do { _Pragma("unroll") for (int m = 0; m < 4; ++m) _Pragma("unroll") for (int k = 0; k < 2; ++k) dst[m][k] = *(const PG8_LAS bf16x8*)(lds + PG8_SA(b, h) + aoff + m * 2048 + k * 1024); } while (0)
; #define PG8_LDB(dst, b, h) do { _Pragma("unroll") for (int n = 0; n < 2; ++n) _Pragma("unroll") for (int k = 0; k < 2; ++k) dst[n][k] = *(const PG8_LAS bf16x8*)(lds + PG8_SB(b, h) + boff + n * 2048 + k * 1024); } while (0)
; #define PG8_SCHED __builtin_amdgcn_sched_barrier(0)
; template <class Epi, class Sched, bool ALIGN_EPI = false, bool SP2 = false>
; __device__ __forceinline__ void gemm_phase(PG8_LAS unsigned char* lds, const Gemm g, const Sched& S, const Epi& E, int tid_in) {
;     ...
;         const bool has_next = S.next(ui + 1, nxt);
;         const char* nA = has_next ? (const char*)g.A + (size_t)nxt.pm * tstep : cA; const char* nB = has_next ? (const char*)g.Bt + (size_t)nxt.pn * tstepB : cB;
;         for (int t = 0; t < nt; t += 2) {
;             const bool last = (t == nt - 2);
;             const char* a1 = cA + (size_t)(t + 1) * kstep;
;             const char* a2 = last ? nA : cA + (size_t)(t + 2) * kstep; const char* b2 = last ? nB : cB + (size_t)(t + 2) * kstep;
;             const char* a3 = a2 + kstep; const char* b3 = b2 + kstep;
;             if (last && has_next) S.a_ready(nxt);
;             if constexpr (SP2) {
;             PG8_LDB(B0, 0, 0); PG8_LDB(B1, 0, 1); PG8_SCHED; PG8_LDA(At, 0, 0); PG8_STAGE(PG8_SA(1, 1), a1 + hstep, voffA);
;     ...
; #pragma unroll
;         for (int a = 0; a < 2; ++a)
; #pragma unroll
;             for (int b = 0; b < 2; ++b)
; #pragma unroll
;                 for (int m = 0; m < 4; ++m)
; #pragma unroll
;                     for (int n = 0; n < 2; ++n) acc[a][b][m][n] = (f32x4){0.f, 0.f, 0.f, 0.f};
;         cur = nxt; cA = nA; cB = nB; ++ui;
.LBB0_596:
	s_ashr_i32 s53, s52, 31
	s_lshl_b64 s[26:27], s[52:53], 20
	s_add_u32 s54, s28, s26
	s_addc_u32 s55, s29, s27
	s_and_b64 s[26:27], s[8:9], exec
	s_cselect_b32 s11, s55, s61
	s_cselect_b32 s53, s54, s60
	s_ashr_i32 s51, s50, 31
	s_lshl_b64 s[26:27], s[50:51], 20
	s_add_u32 s56, s66, s26
	s_addc_u32 s57, s67, s27
	s_and_b64 s[26:27], s[8:9], exec
	s_cselect_b32 s51, s57, s63
	s_cselect_b32 s85, s56, s62
	s_add_u32 s60, s60, 0x80080
	s_addc_u32 s61, s61, 0
	s_add_u32 s86, s62, 0x100
	v_mov_b32_e32 v0, 0
	s_addc_u32 s87, s63, 0
	s_mov_b32 s88, -2
	v_mov_b32_e32 v1, v0
	v_mov_b32_e32 v2, v0
	v_mov_b32_e32 v3, v0
	v_mov_b32_e32 v4, v0
	v_mov_b32_e32 v5, v0
	v_mov_b32_e32 v6, v0
	v_mov_b32_e32 v7, v0
	s_waitcnt vmcnt(0)
	v_mov_b32_e32 v16, v0
	v_mov_b32_e32 v17, v0
	v_mov_b32_e32 v18, v0
	v_mov_b32_e32 v19, v0
	v_mov_b32_e32 v20, v0
	v_mov_b32_e32 v21, v0
	v_mov_b32_e32 v22, v0
	v_mov_b32_e32 v23, v0
	v_mov_b32_e32 v32, v0
	v_mov_b32_e32 v33, v0
	v_mov_b32_e32 v34, v0
	v_mov_b32_e32 v35, v0
	v_mov_b32_e32 v36, v0
	v_mov_b32_e32 v37, v0
	v_mov_b32_e32 v38, v0
	v_mov_b32_e32 v39, v0
	v_mov_b32_e32 v48, v0
	v_mov_b32_e32 v49, v0
	v_mov_b32_e32 v50, v0
	v_mov_b32_e32 v51, v0
	v_mov_b32_e32 v52, v0
	v_mov_b32_e32 v53, v0
	v_mov_b32_e32 v54, v0
	v_mov_b32_e32 v55, v0
	v_mov_b32_e32 v8, v0
	v_mov_b32_e32 v9, v0
	v_mov_b32_e32 v10, v0
	v_mov_b32_e32 v11, v0
	v_mov_b32_e32 v12, v0
	v_mov_b32_e32 v13, v0
	v_mov_b32_e32 v14, v0
	v_mov_b32_e32 v15, v0
	v_mov_b32_e32 v24, v0
	v_mov_b32_e32 v25, v0
	v_mov_b32_e32 v26, v0
	v_mov_b32_e32 v27, v0
	v_mov_b32_e32 v28, v0
	v_mov_b32_e32 v29, v0
	v_mov_b32_e32 v30, v0
	v_mov_b32_e32 v31, v0
	v_mov_b32_e32 v40, v0
	v_mov_b32_e32 v41, v0
	v_mov_b32_e32 v42, v0
	v_mov_b32_e32 v43, v0
	v_mov_b32_e32 v44, v0
	v_mov_b32_e32 v45, v0
	v_mov_b32_e32 v46, v0
	v_mov_b32_e32 v47, v0
	v_mov_b32_e32 v56, v0
	v_mov_b32_e32 v57, v0
	v_mov_b32_e32 v58, v0
	v_mov_b32_e32 v59, v0
	v_mov_b32_e32 v60, v0
	v_mov_b32_e32 v61, v0
	v_mov_b32_e32 v62, v0
	v_mov_b32_e32 v63, v0
	v_mov_b32_e32 v64, v0
	v_mov_b32_e32 v65, v0
	v_mov_b32_e32 v66, v0
	v_mov_b32_e32 v67, v0
	v_mov_b32_e32 v68, v0
	v_mov_b32_e32 v69, v0
	v_mov_b32_e32 v70, v0
	v_mov_b32_e32 v71, v0
	v_mov_b32_e32 v80, v0
	v_mov_b32_e32 v81, v0
	v_mov_b32_e32 v82, v0
	v_mov_b32_e32 v83, v0
	v_mov_b32_e32 v84, v0
	v_mov_b32_e32 v85, v0
	v_mov_b32_e32 v86, v0
	v_mov_b32_e32 v87, v0
	v_mov_b32_e32 v96, v0
	v_mov_b32_e32 v97, v0
	v_mov_b32_e32 v98, v0
	v_mov_b32_e32 v99, v0
	v_mov_b32_e32 v100, v0
	v_mov_b32_e32 v101, v0
	v_mov_b32_e32 v102, v0
	v_mov_b32_e32 v103, v0
	v_mov_b32_e32 v112, v0
	v_mov_b32_e32 v113, v0
	v_mov_b32_e32 v114, v0
	v_mov_b32_e32 v115, v0
	v_mov_b32_e32 v116, v0
	v_mov_b32_e32 v117, v0
	v_mov_b32_e32 v118, v0
	v_mov_b32_e32 v119, v0
	v_mov_b32_e32 v72, v0
	v_mov_b32_e32 v73, v0
	v_mov_b32_e32 v74, v0
	v_mov_b32_e32 v75, v0
	v_mov_b32_e32 v76, v0
	v_mov_b32_e32 v77, v0
	v_mov_b32_e32 v78, v0
	v_mov_b32_e32 v79, v0
	v_mov_b32_e32 v88, v0
	v_mov_b32_e32 v89, v0
	v_mov_b32_e32 v90, v0
	v_mov_b32_e32 v91, v0
	v_mov_b32_e32 v92, v0
	v_mov_b32_e32 v93, v0
	v_mov_b32_e32 v94, v0
	v_mov_b32_e32 v95, v0
	v_mov_b32_e32 v104, v0
	v_mov_b32_e32 v105, v0
	v_mov_b32_e32 v106, v0
	v_mov_b32_e32 v107, v0
	v_mov_b32_e32 v108, v0
	v_mov_b32_e32 v109, v0
	v_mov_b32_e32 v110, v0
	v_mov_b32_e32 v111, v0
	v_mov_b32_e32 v120, v0
	v_mov_b32_e32 v121, v0
	v_mov_b32_e32 v122, v0
	v_mov_b32_e32 v123, v0
	v_mov_b32_e32 v124, v0
	v_mov_b32_e32 v125, v0
	v_mov_b32_e32 v126, v0
	v_mov_b32_e32 v127, v0
	s_cmp_eq_u32 s98, 1
	s_cbranch_scc0 .Lkb_skip_4
	s_mov_b32 s98, 0
	s_barrier
.Lkb_skip_4:
.LBB0_597:
	ds_read_b128 v[128:131], v171
	ds_read_b128 v[132:135], v171 offset:1024
	ds_read_b128 v[136:139], v171 offset:2048
	ds_read_b128 v[184:187], v171 offset:3072
	ds_read_b128 v[188:191], v172
	ds_read_b128 v[192:195], v172 offset:1024
	ds_read_b128 v[196:199], v172 offset:2048
	ds_read_b128 v[200:203], v172 offset:3072
	s_add_u32 s26, s60, 0xfff80080
	s_addc_u32 s27, s61, -1
	s_cmp_eq_u32 s88, 28
	s_cselect_b32 s65, s11, s27
	s_cselect_b32 s64, s53, s26
	s_cselect_b32 s63, s51, s87
	s_cselect_b32 s62, s85, s86
	v_lshl_add_u64 v[140:141], s[60:61], 0, v[158:159]
	s_add_i32 m0, s59, 0xc000
	ds_read_b128 v[204:207], v173
	ds_read_b128 v[212:215], v173 offset:1024
	ds_read_b128 v[216:219], v173 offset:2048
	ds_read_b128 v[220:223], v173 offset:3072
	ds_read_b128 v[224:227], v173 offset:4096
	ds_read_b128 v[228:231], v173 offset:5120
	ds_read_b128 v[232:235], v173 offset:6144
	ds_read_b128 v[236:239], v173 offset:7168
	global_load_lds_dwordx4 v[140:141], off
	v_lshl_add_u64 v[140:141], s[60:61], 0, v[160:161]
	s_add_i32 m0, s59, 0xe000
	s_nop 0
	global_load_lds_dwordx4 v[140:141], off
	s_waitcnt vmcnt(8)
	s_waitcnt lgkmcnt(0)
	s_barrier
; #define PG8_STAGE(bufoff, gbase, voff) do { _Pragma("unroll") for (int _i = 0; _i < 2; ++_i) \
;         __builtin_amdgcn_global_load_lds((const unsigned*)((const char*)(gbase) + (voff)[_i]), (PG8_LAS unsigned*)(lds + (bufoff) + ldsw + _i * 8192), 16, 0, 0); } while (0)
; #define PG8_LDA(dst, b, h) do { _Pragma("unroll") for (int m = 0; m < 4; ++m) _Pragma("unroll") for (int k = 0; k < 2; ++k) dst[m][k] = *(const PG8_LAS bf16x8*)(lds + PG8_SA(b, h) + aoff + m * 2048 + k * 1024); } while (0)
; #define PG8_MMA(ai, bj, At, Bt) do { __builtin_amdgcn_s_setprio(1); _Pragma("unroll") for (int m = 0; m < 4; ++m) _Pragma("unroll") for (int n = 0; n < 2; ++n) _Pragma("unroll") for (int k = 0; k < 2; ++k) \
;         acc[ai][bj][m][n] = __builtin_amdgcn_mfma_f32_16x16x32_bf16(Bt[n][k], At[m][k], acc[ai][bj][m][n], 0, 0, 0); __builtin_amdgcn_s_setprio(0); } while (0)
; #define PG8_WAIT_V(n) asm volatile("s_waitcnt vmcnt(" #n ")" ::: "memory")
; #define PG8_WAIT_L(n) asm volatile("s_waitcnt lgkmcnt(" #n ")" ::: "memory")
; #define PG8_BAR __builtin_amdgcn_s_barrier()
; #define PG8_SCHED __builtin_amdgcn_sched_barrier(0)
; template <class Epi, class Sched, bool ALIGN_EPI = false, bool SP2 = false>
; __device__ __forceinline__ void gemm_phase(PG8_LAS unsigned char* lds, const Gemm g, const Sched& S, const Epi& E, int tid_in) {
;     ...
;             PG8_WAIT_V(8); PG8_WAIT_L(0); PG8_BAR; PG8_MMA(0, 0, At, B0); PG8_MMA(0, 1, At, B1); PG8_BAR; PG8_SCHED;
;             PG8_LDA(At, 0, 1); PG8_STAGE(PG8_SB(0, 0), b2, voffB); PG8_STAGE(PG8_SB(0, 1), b2 + hstepB, voffB); PG8_STAGE(PG8_SA(0, 0), a2, voffA);
;             PG8_WAIT_V(8); PG8_WAIT_L(0); PG8_BAR; PG8_MMA(1, 0, At, B0); PG8_MMA(1, 1, At, B1); PG8_BAR; PG8_SCHED;
	s_setprio 1
	s_waitcnt lgkmcnt(0)
	v_mfma_f32_16x16x32_bf16 v[124:127], v[128:131], v[204:207], v[124:127]
	v_mfma_f32_16x16x32_bf16 v[120:123], v[136:139], v[204:207], v[120:123]
	v_mfma_f32_16x16x32_bf16 v[108:111], v[128:131], v[216:219], v[108:111]
	v_mfma_f32_16x16x32_bf16 v[104:107], v[136:139], v[216:219], v[104:107]
	v_mfma_f32_16x16x32_bf16 v[92:95], v[128:131], v[224:227], v[92:95]
	v_mfma_f32_16x16x32_bf16 v[88:91], v[136:139], v[224:227], v[88:91]
	v_mfma_f32_16x16x32_bf16 v[76:79], v[128:131], v[232:235], v[76:79]
	v_mfma_f32_16x16x32_bf16 v[72:75], v[136:139], v[232:235], v[72:75]
	v_mfma_f32_16x16x32_bf16 v[124:127], v[132:135], v[212:215], v[124:127]
	v_mfma_f32_16x16x32_bf16 v[120:123], v[184:187], v[212:215], v[120:123]
	v_mfma_f32_16x16x32_bf16 v[108:111], v[132:135], v[220:223], v[108:111]
	v_mfma_f32_16x16x32_bf16 v[104:107], v[184:187], v[220:223], v[104:107]
	v_mfma_f32_16x16x32_bf16 v[92:95], v[132:135], v[228:231], v[92:95]
	v_mfma_f32_16x16x32_bf16 v[88:91], v[184:187], v[228:231], v[88:91]
	v_mfma_f32_16x16x32_bf16 v[76:79], v[132:135], v[236:239], v[76:79]
	v_mfma_f32_16x16x32_bf16 v[72:75], v[184:187], v[236:239], v[72:75]
	s_setprio 0
	s_setprio 1
	v_mfma_f32_16x16x32_bf16 v[116:119], v[188:191], v[204:207], v[116:119]
	v_mfma_f32_16x16x32_bf16 v[112:115], v[196:199], v[204:207], v[112:115]
	v_mfma_f32_16x16x32_bf16 v[100:103], v[188:191], v[216:219], v[100:103]
	v_mfma_f32_16x16x32_bf16 v[96:99], v[196:199], v[216:219], v[96:99]
	v_mfma_f32_16x16x32_bf16 v[84:87], v[188:191], v[224:227], v[84:87]
	v_mfma_f32_16x16x32_bf16 v[80:83], v[196:199], v[224:227], v[80:83]
	v_mfma_f32_16x16x32_bf16 v[68:71], v[188:191], v[232:235], v[68:71]
	v_mfma_f32_16x16x32_bf16 v[64:67], v[196:199], v[232:235], v[64:67]
	v_mfma_f32_16x16x32_bf16 v[116:119], v[192:195], v[212:215], v[116:119]
	v_mfma_f32_16x16x32_bf16 v[112:115], v[200:203], v[212:215], v[112:115]
	v_mfma_f32_16x16x32_bf16 v[100:103], v[192:195], v[220:223], v[100:103]
	v_mfma_f32_16x16x32_bf16 v[96:99], v[200:203], v[220:223], v[96:99]
	v_mfma_f32_16x16x32_bf16 v[84:87], v[192:195], v[228:231], v[84:87]
	v_mfma_f32_16x16x32_bf16 v[80:83], v[200:203], v[228:231], v[80:83]
	v_mfma_f32_16x16x32_bf16 v[68:71], v[192:195], v[236:239], v[68:71]
	v_mfma_f32_16x16x32_bf16 v[64:67], v[200:203], v[236:239], v[64:67]
	s_setprio 0
	s_barrier
	s_add_i32 s26, s78, s68
	v_lshl_add_u64 v[140:141], s[62:63], 0, v[144:145]
	s_mov_b32 m0, s26
	ds_read_b128 v[204:207], v173 offset:16384
	ds_read_b128 v[212:215], v173 offset:17408
	ds_read_b128 v[216:219], v173 offset:18432
	ds_read_b128 v[220:223], v173 offset:19456
	ds_read_b128 v[224:227], v173 offset:20480
	ds_read_b128 v[228:231], v173 offset:21504
	ds_read_b128 v[232:235], v173 offset:22528
	ds_read_b128 v[236:239], v173 offset:23552
	global_load_lds_dwordx4 v[140:141], off
	s_add_i32 m0, s26, 0x2000
	s_add_u32 s26, s62, 0x20000
	v_lshl_add_u64 v[208:209], s[62:63], 0, v[148:149]
	s_addc_u32 s27, s63, 0
	s_add_i32 s33, s79, s68
	global_load_lds_dwordx4 v[208:209], off
	v_lshl_add_u64 v[240:241], s[26:27], 0, v[144:145]
	s_mov_b32 m0, s33
	v_lshl_add_u64 v[242:243], s[64:65], 0, v[146:147]
	global_load_lds_dwordx4 v[240:241], off
	v_lshl_add_u64 v[240:241], s[26:27], 0, v[148:149]
	s_add_i32 m0, s33, 0x2000
	s_nop 0
	global_load_lds_dwordx4 v[240:241], off
	v_lshl_add_u64 v[240:241], s[64:65], 0, v[142:143]
	s_mov_b32 m0, s59
	s_nop 0
	global_load_lds_dwordx4 v[240:241], off
	s_mov_b32 m0, s69
	s_nop 0
	global_load_lds_dwordx4 v[242:243], off
	s_waitcnt vmcnt(8)
	s_waitcnt lgkmcnt(0)
	s_barrier
	s_setprio 1
	s_waitcnt lgkmcnt(0)
	v_mfma_f32_16x16x32_bf16 v[60:63], v[128:131], v[204:207], v[60:63]
	v_mfma_f32_16x16x32_bf16 v[56:59], v[136:139], v[204:207], v[56:59]
	v_mfma_f32_16x16x32_bf16 v[44:47], v[128:131], v[216:219], v[44:47]
	v_mfma_f32_16x16x32_bf16 v[40:43], v[136:139], v[216:219], v[40:43]
	v_mfma_f32_16x16x32_bf16 v[28:31], v[128:131], v[224:227], v[28:31]
	v_mfma_f32_16x16x32_bf16 v[24:27], v[136:139], v[224:227], v[24:27]
	v_mfma_f32_16x16x32_bf16 v[12:15], v[128:131], v[232:235], v[12:15]
	v_mfma_f32_16x16x32_bf16 v[8:11], v[136:139], v[232:235], v[8:11]
	v_mfma_f32_16x16x32_bf16 v[60:63], v[132:135], v[212:215], v[60:63]
	v_mfma_f32_16x16x32_bf16 v[56:59], v[184:187], v[212:215], v[56:59]
	v_mfma_f32_16x16x32_bf16 v[44:47], v[132:135], v[220:223], v[44:47]
	v_mfma_f32_16x16x32_bf16 v[40:43], v[184:187], v[220:223], v[40:43]
	v_mfma_f32_16x16x32_bf16 v[28:31], v[132:135], v[228:231], v[28:31]
	v_mfma_f32_16x16x32_bf16 v[24:27], v[184:187], v[228:231], v[24:27]
	v_mfma_f32_16x16x32_bf16 v[12:15], v[132:135], v[236:239], v[12:15]
	v_mfma_f32_16x16x32_bf16 v[8:11], v[184:187], v[236:239], v[8:11]
	s_setprio 0
	s_setprio 1
	v_mfma_f32_16x16x32_bf16 v[52:55], v[188:191], v[204:207], v[52:55]
	v_mfma_f32_16x16x32_bf16 v[48:51], v[196:199], v[204:207], v[48:51]
	v_mfma_f32_16x16x32_bf16 v[36:39], v[188:191], v[216:219], v[36:39]
	v_mfma_f32_16x16x32_bf16 v[32:35], v[196:199], v[216:219], v[32:35]
	v_mfma_f32_16x16x32_bf16 v[20:23], v[188:191], v[224:227], v[20:23]
	v_mfma_f32_16x16x32_bf16 v[16:19], v[196:199], v[224:227], v[16:19]
	v_mfma_f32_16x16x32_bf16 v[4:7], v[188:191], v[232:235], v[4:7]
	v_mfma_f32_16x16x32_bf16 v[0:3], v[196:199], v[232:235], v[0:3]
	v_mfma_f32_16x16x32_bf16 v[52:55], v[192:195], v[212:215], v[52:55]
	v_mfma_f32_16x16x32_bf16 v[48:51], v[200:203], v[212:215], v[48:51]
	v_mfma_f32_16x16x32_bf16 v[36:39], v[192:195], v[220:223], v[36:39]
	v_mfma_f32_16x16x32_bf16 v[32:35], v[200:203], v[220:223], v[32:35]
	v_mfma_f32_16x16x32_bf16 v[20:23], v[192:195], v[228:231], v[20:23]
	v_mfma_f32_16x16x32_bf16 v[16:19], v[200:203], v[228:231], v[16:19]
	v_mfma_f32_16x16x32_bf16 v[4:7], v[192:195], v[236:239], v[4:7]
	v_mfma_f32_16x16x32_bf16 v[0:3], v[200:203], v[236:239], v[0:3]
	s_setprio 0
	s_barrier
; #define PG8_STAGE(bufoff, gbase, voff) do { _Pragma("unroll") for (int _i = 0; _i < 2; ++_i) \
;         __builtin_amdgcn_global_load_lds((const unsigned*)((const char*)(gbase) + (voff)[_i]), (PG8_LAS unsigned*)(lds + (bufoff) + ldsw + _i * 8192), 16, 0, 0); } while (0)
; #define PG8_LDA(dst, b, h) do { _Pragma("unroll") for (int m = 0; m < 4; ++m) _Pragma("unroll") for (int k = 0; k < 2; ++k) dst[m][k] = *(const PG8_LAS bf16x8*)(lds + PG8_SA(b, h) + aoff + m * 2048 + k * 1024); } while (0)
; #define PG8_LDB(dst, b, h) do { _Pragma("unroll") for (int n = 0; n < 2; ++n) _Pragma("unroll") for (int k = 0; k < 2; ++k) dst[n][k] = *(const PG8_LAS bf16x8*)(lds + PG8_SB(b, h) + boff + n * 2048 + k * 1024); } while (0)
; #define PG8_MMA(ai, bj, At, Bt) do { __builtin_amdgcn_s_setprio(1); _Pragma("unroll") for (int m = 0; m < 4; ++m) _Pragma("unroll") for (int n = 0; n < 2; ++n) _Pragma("unroll") for (int k = 0; k < 2; ++k) \
;         acc[ai][bj][m][n] = __builtin_amdgcn_mfma_f32_16x16x32_bf16(Bt[n][k], At[m][k], acc[ai][bj][m][n], 0, 0, 0); __builtin_amdgcn_s_setprio(0); } while (0)
; #define PG8_WAIT_V(n) asm volatile("s_waitcnt vmcnt(" #n ")" ::: "memory")
; #define PG8_WAIT_L(n) asm volatile("s_waitcnt lgkmcnt(" #n ")" ::: "memory")
; #define PG8_BAR __builtin_amdgcn_s_barrier()
; #define PG8_SCHED __builtin_amdgcn_sched_barrier(0)
; template <class Epi, class Sched, bool ALIGN_EPI = false, bool SP2 = false>
; __device__ __forceinline__ void gemm_phase(PG8_LAS unsigned char* lds, const Gemm g, const Sched& S, const Epi& E, int tid_in) {
;     ...
;             PG8_LDB(B0, 1, 0); PG8_LDB(B1, 1, 1); PG8_SCHED; PG8_LDA(At, 1, 0); PG8_STAGE(PG8_SA(0, 1), a2 + hstep, voffA);
;             PG8_WAIT_V(8); PG8_WAIT_L(0); PG8_BAR; PG8_MMA(0, 0, At, B0); PG8_MMA(0, 1, At, B1); PG8_BAR; PG8_SCHED;
	s_add_i32 s33, 0, 0x18000
	v_add_u32_e32 v150, s33, v167
	s_add_i32 s89, 0, 0x1c000
	ds_read_b128 v[128:131], v150
	ds_read_b128 v[132:135], v150 offset:1024
	ds_read_b128 v[136:139], v150 offset:2048
	ds_read_b128 v[184:187], v150 offset:3072
	v_add_u32_e32 v150, s89, v167
	ds_read_b128 v[188:191], v150
	ds_read_b128 v[192:195], v150 offset:1024
	ds_read_b128 v[196:199], v150 offset:2048
	ds_read_b128 v[200:203], v150 offset:3072
	s_add_u32 s26, s64, 0x80000
	s_addc_u32 s27, s65, 0
	s_mov_b32 m0, s70
	v_lshl_add_u64 v[244:245], s[26:27], 0, v[142:143]
	ds_read_b128 v[204:207], v173 offset:32768
	ds_read_b128 v[212:215], v173 offset:33792
	ds_read_b128 v[216:219], v173 offset:34816
	ds_read_b128 v[220:223], v173 offset:35840
	ds_read_b128 v[224:227], v173 offset:36864
	ds_read_b128 v[228:231], v173 offset:37888
	ds_read_b128 v[232:235], v173 offset:38912
	ds_read_b128 v[236:239], v173 offset:39936
	global_load_lds_dwordx4 v[244:245], off
	v_lshl_add_u64 v[244:245], s[26:27], 0, v[146:147]
	s_mov_b32 m0, s71
	s_nop 0
	global_load_lds_dwordx4 v[244:245], off
	s_waitcnt vmcnt(8)
	s_waitcnt lgkmcnt(0)
	s_barrier
	s_setprio 1
	s_waitcnt lgkmcnt(0)
	v_mfma_f32_16x16x32_bf16 v[124:127], v[128:131], v[204:207], v[124:127]
	v_mfma_f32_16x16x32_bf16 v[120:123], v[136:139], v[204:207], v[120:123]
	v_mfma_f32_16x16x32_bf16 v[108:111], v[128:131], v[216:219], v[108:111]
	v_mfma_f32_16x16x32_bf16 v[104:107], v[136:139], v[216:219], v[104:107]
	v_mfma_f32_16x16x32_bf16 v[92:95], v[128:131], v[224:227], v[92:95]
	v_mfma_f32_16x16x32_bf16 v[88:91], v[136:139], v[224:227], v[88:91]
	v_mfma_f32_16x16x32_bf16 v[76:79], v[128:131], v[232:235], v[76:79]
	v_mfma_f32_16x16x32_bf16 v[72:75], v[136:139], v[232:235], v[72:75]
	v_mfma_f32_16x16x32_bf16 v[124:127], v[132:135], v[212:215], v[124:127]
	v_mfma_f32_16x16x32_bf16 v[120:123], v[184:187], v[212:215], v[120:123]
	v_mfma_f32_16x16x32_bf16 v[108:111], v[132:135], v[220:223], v[108:111]
	v_mfma_f32_16x16x32_bf16 v[104:107], v[184:187], v[220:223], v[104:107]
	v_mfma_f32_16x16x32_bf16 v[92:95], v[132:135], v[228:231], v[92:95]
	v_mfma_f32_16x16x32_bf16 v[88:91], v[184:187], v[228:231], v[88:91]
	v_mfma_f32_16x16x32_bf16 v[76:79], v[132:135], v[236:239], v[76:79]
	v_mfma_f32_16x16x32_bf16 v[72:75], v[184:187], v[236:239], v[72:75]
	s_setprio 0
	s_setprio 1
	v_mfma_f32_16x16x32_bf16 v[116:119], v[188:191], v[204:207], v[116:119]
	v_mfma_f32_16x16x32_bf16 v[112:115], v[196:199], v[204:207], v[112:115]
	v_mfma_f32_16x16x32_bf16 v[100:103], v[188:191], v[216:219], v[100:103]
	v_mfma_f32_16x16x32_bf16 v[96:99], v[196:199], v[216:219], v[96:99]
	v_mfma_f32_16x16x32_bf16 v[84:87], v[188:191], v[224:227], v[84:87]
	v_mfma_f32_16x16x32_bf16 v[80:83], v[196:199], v[224:227], v[80:83]
	v_mfma_f32_16x16x32_bf16 v[68:71], v[188:191], v[232:235], v[68:71]
	v_mfma_f32_16x16x32_bf16 v[64:67], v[196:199], v[232:235], v[64:67]
	v_mfma_f32_16x16x32_bf16 v[116:119], v[192:195], v[212:215], v[116:119]
	v_mfma_f32_16x16x32_bf16 v[112:115], v[200:203], v[212:215], v[112:115]
	v_mfma_f32_16x16x32_bf16 v[100:103], v[192:195], v[220:223], v[100:103]
	v_mfma_f32_16x16x32_bf16 v[96:99], v[200:203], v[220:223], v[96:99]
	v_mfma_f32_16x16x32_bf16 v[84:87], v[192:195], v[228:231], v[84:87]
	v_mfma_f32_16x16x32_bf16 v[80:83], v[200:203], v[228:231], v[80:83]
	v_mfma_f32_16x16x32_bf16 v[68:71], v[192:195], v[236:239], v[68:71]
	v_mfma_f32_16x16x32_bf16 v[64:67], v[200:203], v[236:239], v[64:67]
	s_setprio 0
	s_barrier
; #define PG8_STAGE(bufoff, gbase, voff) do { _Pragma("unroll") for (int _i = 0; _i < 2; ++_i) \
;         __builtin_amdgcn_global_load_lds((const unsigned*)((const char*)(gbase) + (voff)[_i]), (PG8_LAS unsigned*)(lds + (bufoff) + ldsw + _i * 8192), 16, 0, 0); } while (0)
; #define PG8_LDA(dst, b, h) do { _Pragma("unroll") for (int m = 0; m < 4; ++m) _Pragma("unroll") for (int k = 0; k < 2; ++k) dst[m][k] = *(const PG8_LAS bf16x8*)(lds + PG8_SA(b, h) + aoff + m * 2048 + k * 1024); } while (0)
; #define PG8_MMA(ai, bj, At, Bt) do { __builtin_amdgcn_s_setprio(1); _Pragma("unroll") for (int m = 0; m < 4; ++m) _Pragma("unroll") for (int n = 0; n < 2; ++n) _Pragma("unroll") for (int k = 0; k < 2; ++k) \
;         acc[ai][bj][m][n] = __builtin_amdgcn_mfma_f32_16x16x32_bf16(Bt[n][k], At[m][k], acc[ai][bj][m][n], 0, 0, 0); __builtin_amdgcn_s_setprio(0); } while (0)
; #define PG8_WAIT_V(n) asm volatile("s_waitcnt vmcnt(" #n ")" ::: "memory")
; #define PG8_WAIT_L(n) asm volatile("s_waitcnt lgkmcnt(" #n ")" ::: "memory")
; #define PG8_BAR __builtin_amdgcn_s_barrier()
; #define PG8_SCHED __builtin_amdgcn_sched_barrier(0)
; template <class Epi, class Sched, bool ALIGN_EPI = false, bool SP2 = false>
; __device__ __forceinline__ void gemm_phase(PG8_LAS unsigned char* lds, const Gemm g, const Sched& S, const Epi& E, int tid_in) {
;     ...
;             PG8_LDA(At, 1, 1); PG8_STAGE(PG8_SB(1, 0), b3, voffB); PG8_STAGE(PG8_SB(1, 1), b3 + hstepB, voffB); PG8_STAGE(PG8_SA(1, 0), a3, voffA);
;             PG8_WAIT_V(8); PG8_WAIT_L(0); PG8_BAR; PG8_MMA(1, 0, At, B0); PG8_MMA(1, 1, At, B1); PG8_BAR; PG8_SCHED;
	s_add_i32 s26, s33, s68
	v_lshl_add_u64 v[140:141], v[140:141], 0, s[44:45]
	s_mov_b32 m0, s26
	ds_read_b128 v[204:207], v173 offset:49152
	ds_read_b128 v[212:215], v173 offset:50176
	ds_read_b128 v[216:219], v173 offset:51200
	ds_read_b128 v[220:223], v173 offset:52224
	ds_read_b128 v[224:227], v173 offset:53248
	ds_read_b128 v[228:231], v173 offset:54272
	ds_read_b128 v[232:235], v173 offset:55296
	ds_read_b128 v[236:239], v173 offset:56320
	global_load_lds_dwordx4 v[140:141], off
	s_add_i32 m0, s26, 0x2000
	s_add_u32 s26, s62, 0x20080
	v_lshl_add_u64 v[140:141], v[208:209], 0, s[44:45]
	s_addc_u32 s27, s63, 0
	s_add_i32 s33, s89, s68
	global_load_lds_dwordx4 v[140:141], off
	v_lshl_add_u64 v[140:141], s[26:27], 0, v[144:145]
	s_mov_b32 m0, s33
	s_nop 0
	global_load_lds_dwordx4 v[140:141], off
	v_lshl_add_u64 v[140:141], s[26:27], 0, v[148:149]
	s_add_i32 m0, s33, 0x2000
	s_nop 0
	global_load_lds_dwordx4 v[140:141], off
	v_lshl_add_u64 v[140:141], v[240:241], 0, s[44:45]
	s_mov_b32 m0, s74
	s_nop 0
	global_load_lds_dwordx4 v[140:141], off
	v_lshl_add_u64 v[140:141], v[242:243], 0, s[44:45]
	s_mov_b32 m0, s75
	s_nop 0
	global_load_lds_dwordx4 v[140:141], off
	s_waitcnt vmcnt(8)
	s_waitcnt lgkmcnt(0)
	s_barrier
	s_setprio 1
	s_waitcnt lgkmcnt(0)
	v_mfma_f32_16x16x32_bf16 v[60:63], v[128:131], v[204:207], v[60:63]
	v_mfma_f32_16x16x32_bf16 v[56:59], v[136:139], v[204:207], v[56:59]
	v_mfma_f32_16x16x32_bf16 v[44:47], v[128:131], v[216:219], v[44:47]
	v_mfma_f32_16x16x32_bf16 v[40:43], v[136:139], v[216:219], v[40:43]
	v_mfma_f32_16x16x32_bf16 v[28:31], v[128:131], v[224:227], v[28:31]
	v_mfma_f32_16x16x32_bf16 v[24:27], v[136:139], v[224:227], v[24:27]
	v_mfma_f32_16x16x32_bf16 v[12:15], v[128:131], v[232:235], v[12:15]
	v_mfma_f32_16x16x32_bf16 v[8:11], v[136:139], v[232:235], v[8:11]
	v_mfma_f32_16x16x32_bf16 v[60:63], v[132:135], v[212:215], v[60:63]
	v_mfma_f32_16x16x32_bf16 v[56:59], v[184:187], v[212:215], v[56:59]
	v_mfma_f32_16x16x32_bf16 v[44:47], v[132:135], v[220:223], v[44:47]
	v_mfma_f32_16x16x32_bf16 v[40:43], v[184:187], v[220:223], v[40:43]
	v_mfma_f32_16x16x32_bf16 v[28:31], v[132:135], v[228:231], v[28:31]
	v_mfma_f32_16x16x32_bf16 v[24:27], v[184:187], v[228:231], v[24:27]
	v_mfma_f32_16x16x32_bf16 v[12:15], v[132:135], v[236:239], v[12:15]
	v_mfma_f32_16x16x32_bf16 v[8:11], v[184:187], v[236:239], v[8:11]
	s_setprio 0
	s_setprio 1
	v_mfma_f32_16x16x32_bf16 v[52:55], v[188:191], v[204:207], v[52:55]
	v_mfma_f32_16x16x32_bf16 v[48:51], v[196:199], v[204:207], v[48:51]
	v_mfma_f32_16x16x32_bf16 v[36:39], v[188:191], v[216:219], v[36:39]
	v_mfma_f32_16x16x32_bf16 v[32:35], v[196:199], v[216:219], v[32:35]
	v_mfma_f32_16x16x32_bf16 v[20:23], v[188:191], v[224:227], v[20:23]
	v_mfma_f32_16x16x32_bf16 v[16:19], v[196:199], v[224:227], v[16:19]
	v_mfma_f32_16x16x32_bf16 v[4:7], v[188:191], v[232:235], v[4:7]
	v_mfma_f32_16x16x32_bf16 v[0:3], v[196:199], v[232:235], v[0:3]
	v_mfma_f32_16x16x32_bf16 v[52:55], v[192:195], v[212:215], v[52:55]
	v_mfma_f32_16x16x32_bf16 v[48:51], v[200:203], v[212:215], v[48:51]
	v_mfma_f32_16x16x32_bf16 v[36:39], v[192:195], v[220:223], v[36:39]
	v_mfma_f32_16x16x32_bf16 v[32:35], v[200:203], v[220:223], v[32:35]
	v_mfma_f32_16x16x32_bf16 v[20:23], v[192:195], v[228:231], v[20:23]
	v_mfma_f32_16x16x32_bf16 v[16:19], v[200:203], v[228:231], v[16:19]
	v_mfma_f32_16x16x32_bf16 v[4:7], v[192:195], v[236:239], v[4:7]
	v_mfma_f32_16x16x32_bf16 v[0:3], v[200:203], v[236:239], v[0:3]
	s_setprio 0
	s_barrier
	s_add_i32 s88, s88, 2
	s_add_u32 s60, s60, 0x100
	s_addc_u32 s61, s61, 0
	s_add_u32 s86, s86, 0x100
	s_addc_u32 s87, s87, 0
	s_cmp_gt_u32 s88, 29
	s_cbranch_scc0 .LBB0_597
	s_and_b64 vcc, exec, s[46:47]
	s_cbranch_vccz .LBB0_600
	s_barrier

; #define PG8_LAS __attribute__((address_space(3)))
; __device__ __forceinline__ unsigned cvt_pk_bf16(float lo, float hi) { unsigned r; asm volatile("v_cvt_pk_bf16_f32 %0, %1, %2" : "=v"(r) : "v"(lo), "v"(hi)); return r; }
; template <int LAYOUT> __device__ __forceinline__ void staged_store_bf16(PG8_LAS unsigned char* stg, bf16_t* O, size_t ldc, int rowg0, int pn, int wc, int lane) {
;     const int p = lane & 7;
; #pragma unroll
;     for (int hr = 0; hr < 2; ++hr) { const int r = 8 * hr + (lane >> 3), rowg = rowg0 + r; const u32x4 w = *(const PG8_LAS u32x4*)(stg + r * STG_ROW + p * 16);
;         if (LAYOUT == 0) __builtin_nontemporal_store(w, (u32x4*)(O + (size_t)rowg * ldc + pn * BM + wc * 64 + p * 8));
;         else { const int P = 2 * pn + (wc >> 1); int drow = rowg;
;             if (LAYOUT == 2) { const int sh = 2 * (P / 24), t = rowg & 16383; drow = (rowg & ~16383) + ((t & ((1 << sh) - 1)) << (14 - sh)) + (t >> sh); }
;             __builtin_nontemporal_store(w, (u32x4*)(O + (size_t)P * PLANE + (size_t)drow * 128 + (wc & 1) * 64 + p * 8)); } }
;     __device__ __forceinline__ void operator()(const f32x4 (&acc)[2][2][4][2], const Unit& u, int wr, int wc, int fr, int fq) const {
;     ...
;                 const int rowg0 = u.pm * BM + ai * HALF + wr * 64 + m * 16, row = rowg0 + fr; const float rs = rtab[ai * HALF + wr * 64 + m * 16 + fr];
;                 f32x4 c4 = {1.f, 1.f, 1.f, 1.f}, s4 = {0.f, 0.f, 0.f, 0.f};
;                 if (rot) { const int t = row & 16383; c4 = *(const f32x4*)(cst + t * 16 + 4 * fq); s4 = *(const f32x4*)(snt + t * 16 + 4 * fq); }
; #pragma unroll
;                 for (int bj = 0; bj < 2; ++bj) {
;                     const f32x4 a = acc[ai][bj][m][0] * rs, b = acc[ai][bj][m][1] * rs;
;                     const f32x4 a2 = (bj == 0) ? a * c4 - b * s4 : a, b2 = (bj == 0) ? b * c4 + a * s4 : b;
;                     u32x2 w0, w1; w0.x = cvt_pk_bf16(a2[0], a2[1]); w0.y = cvt_pk_bf16(a2[2], a2[3]); w1.x = cvt_pk_bf16(b2[0], b2[1]); w1.y = cvt_pk_bf16(b2[2], b2[3]);
;                     *(PG8_LAS u32x2*)(stg + fr * STG_ROW + bj * 64 + fq * 8) = w0; *(PG8_LAS u32x2*)(stg + fr * STG_ROW + bj * 64 + 32 + fq * 8) = w1; }
;                 staged_store_bf16<2>(stg, O, (size_t)ldc, rowg0, u.pn, wc, lane);
.LBB0_618:
	v_pk_mul_f32 v[8:9], v[8:9], v[16:17] op_sel_hi:[1,0]
	v_pk_mul_f32 v[12:13], v[12:13], v[16:17] op_sel_hi:[1,0]
	v_pk_mul_f32 v[10:11], v[10:11], v[16:17] op_sel_hi:[1,0]
	s_waitcnt vmcnt(0)
	v_pk_mul_f32 v[18:19], v[8:9], v[36:37]
	v_pk_mul_f32 v[8:9], v[8:9], v[32:33]
	v_pk_mul_f32 v[14:15], v[14:15], v[16:17] op_sel_hi:[1,0]
	v_pk_mul_f32 v[20:21], v[10:11], v[38:39]
	v_pk_mul_f32 v[10:11], v[10:11], v[34:35]
	v_pk_fma_f32 v[8:9], v[12:13], v[36:37], v[8:9]
	v_pk_mul_f32 v[4:5], v[4:5], v[16:17] op_sel_hi:[1,0]
	v_pk_fma_f32 v[20:21], v[14:15], v[34:35], v[20:21] neg_lo:[0,0,1] neg_hi:[0,0,1]
	v_pk_fma_f32 v[18:19], v[12:13], v[32:33], v[18:19] neg_lo:[0,0,1] neg_hi:[0,0,1]
	v_pk_fma_f32 v[10:11], v[14:15], v[38:39], v[10:11]
	v_cvt_pk_bf16_f32 v12, v18, v19
	v_cvt_pk_bf16_f32 v13, v20, v21
	v_cvt_pk_bf16_f32 v8, v8, v9
	v_pk_mul_f32 v[0:1], v[0:1], v[16:17] op_sel_hi:[1,0]
	v_cvt_pk_bf16_f32 v9, v10, v11
	ds_write2_b64 v174, v[12:13], v[8:9] offset1:4
	v_cvt_pk_bf16_f32 v4, v4, v5
	v_pk_mul_f32 v[6:7], v[6:7], v[16:17] op_sel_hi:[1,0]
	v_pk_mul_f32 v[2:3], v[2:3], v[16:17] op_sel_hi:[1,0]
	v_cvt_pk_bf16_f32 v5, v6, v7
	v_cvt_pk_bf16_f32 v0, v0, v1
	s_andn2_b64 vcc, exec, s[8:9]
	v_cvt_pk_bf16_f32 v1, v2, v3
	ds_write2_b64 v174, v[4:5], v[0:1] offset0:8 offset1:12
	v_or_b32_e32 v4, s26, v168
	v_lshlrev_b32_e32 v4, s53, v4
	v_bitop3_b32 v5, s26, v182, v168 bitop3:0xc8
	v_and_b32_e32 v4, 0x3fff, v4
	ds_read_b128 v[0:3], v175
	v_or_b32_e32 v4, s60, v4
	v_lshrrev_b32_e32 v5, s51, v5
	v_add_u32_e32 v4, v4, v5
	v_ashrrev_i32_e32 v5, 31, v4
	v_lshlrev_b64 v[4:5], 8, v[4:5]
	v_lshl_add_u64 v[8:9], v[112:113], 0, v[4:5]
	ds_read_b128 v[4:7], v175 offset:1152
	s_waitcnt lgkmcnt(1)
	global_store_dwordx4 v[8:9], v[0:3], off nt
	s_mov_b64 s[8:9], -1
	s_nop 0
	v_or_b32_e32 v0, s26, v169
	v_lshlrev_b32_e32 v0, s53, v0
	v_bitop3_b32 v1, s26, v183, v169 bitop3:0xc8
	v_and_b32_e32 v0, 0x3fff, v0
	v_or_b32_e32 v0, s60, v0
	v_lshrrev_b32_e32 v1, s51, v1
	v_add_u32_e32 v0, v0, v1
	v_ashrrev_i32_e32 v1, 31, v0
	v_lshlrev_b64 v[0:1], 8, v[0:1]
	v_lshl_add_u64 v[0:1], v[112:113], 0, v[0:1]
	s_waitcnt lgkmcnt(0)
	global_store_dwordx4 v[0:1], v[4:7], off nt
	s_cbranch_vccnz .LBB0_593
	s_andn2_b64 vcc, exec, s[12:13]
	s_cbranch_vccnz .LBB0_592
	s_mov_b32 s98, 1
	s_branch .LBB0_592

; #define PG8_STAGE(bufoff, gbase, voff) do { _Pragma("unroll") for (int _i = 0; _i < 2; ++_i) \
;         __builtin_amdgcn_global_load_lds((const unsigned*)((const char*)(gbase) + (voff)[_i]), (PG8_LAS unsigned*)(lds + (bufoff) + ldsw + _i * 8192), 16, 0, 0); } while (0)
; #define PG8_LDA(dst, b, h) do { _Pragma("unroll") for (int m = 0; m < 4; ++m) _Pragma("unroll") for (int k = 0; k < 2; ++k) dst[m][k] = *(const PG8_LAS bf16x8*)(lds + PG8_SA(b, h) + aoff + m * 2048 + k * 1024); } while (0)
; #define PG8_LDB(dst, b, h) do { _Pragma("unroll") for (int n = 0; n < 2; ++n) _Pragma("unroll") for (int k = 0; k < 2; ++k) dst[n][k] = *(const PG8_LAS bf16x8*)(lds + PG8_SB(b, h) + boff + n * 2048 + k * 1024); } while (0)
; #define PG8_SCHED __builtin_amdgcn_sched_barrier(0)
; template <class Epi, class Sched, bool ALIGN_EPI = false, bool SP2 = false>
; __device__ __forceinline__ void gemm_phase(PG8_LAS unsigned char* lds, const Gemm g, const Sched& S, const Epi& E, int tid_in) {
;     ...
;         const bool has_next = S.next(ui + 1, nxt);
;         const char* nA = has_next ? (const char*)g.A + (size_t)nxt.pm * tstep : cA; const char* nB = has_next ? (const char*)g.Bt + (size_t)nxt.pn * tstepB : cB;
;         for (int t = 0; t < nt; t += 2) {
;             const bool last = (t == nt - 2);
;             const char* a1 = cA + (size_t)(t + 1) * kstep;
;             const char* a2 = last ? nA : cA + (size_t)(t + 2) * kstep; const char* b2 = last ? nB : cB + (size_t)(t + 2) * kstep;
;             const char* a3 = a2 + kstep; const char* b3 = b2 + kstep;
;             if (last && has_next) S.a_ready(nxt);
;             if constexpr (SP2) {
;             PG8_LDB(B0, 0, 0); PG8_LDB(B1, 0, 1); PG8_SCHED; PG8_LDA(At, 0, 0); PG8_STAGE(PG8_SA(1, 1), a1 + hstep, voffA);
;     ...
; #pragma unroll
;         for (int a = 0; a < 2; ++a)
; #pragma unroll
;             for (int b = 0; b < 2; ++b)
; #pragma unroll
;                 for (int m = 0; m < 4; ++m)
; #pragma unroll
;                     for (int n = 0; n < 2; ++n) acc[a][b][m][n] = (f32x4){0.f, 0.f, 0.f, 0.f};
;         cur = nxt; cA = nA; cB = nB; ++ui;
.LBB0_766:
	s_ashr_i32 s53, s52, 31
	s_lshl_b64 s[26:27], s[52:53], 19
	s_add_u32 s54, s38, s26
	s_addc_u32 s55, s39, s27
	s_and_b64 s[26:27], s[10:11], exec
	s_cselect_b32 s53, s55, s63
	s_cselect_b32 s59, s54, s62
	s_ashr_i32 s51, s50, 31
	s_lshl_b64 s[26:27], s[50:51], 19
	s_add_u32 s56, s36, s26
	s_addc_u32 s57, s37, s27
	s_and_b64 s[26:27], s[10:11], exec
	s_cselect_b32 s51, s57, s65
	s_cselect_b32 s77, s56, s64
	s_add_u32 s62, s62, 0x40080
	s_addc_u32 s63, s63, 0
	s_add_u32 s78, s64, 0x100
	v_mov_b32_e32 v0, 0
	s_addc_u32 s79, s65, 0
	s_mov_b32 s83, -2
	s_waitcnt lgkmcnt(0)
	v_mov_b32_e32 v1, v0
	v_mov_b32_e32 v2, v0
	v_mov_b32_e32 v3, v0
	v_mov_b32_e32 v4, v0
	v_mov_b32_e32 v5, v0
	v_mov_b32_e32 v6, v0
	v_mov_b32_e32 v7, v0
	v_mov_b32_e32 v16, v0
	v_mov_b32_e32 v17, v0
	v_mov_b32_e32 v18, v0
	v_mov_b32_e32 v19, v0
	v_mov_b32_e32 v20, v0
	v_mov_b32_e32 v21, v0
	v_mov_b32_e32 v22, v0
	v_mov_b32_e32 v23, v0
	v_mov_b32_e32 v32, v0
	v_mov_b32_e32 v33, v0
	v_mov_b32_e32 v34, v0
	v_mov_b32_e32 v35, v0
	v_mov_b32_e32 v36, v0
	v_mov_b32_e32 v37, v0
	v_mov_b32_e32 v38, v0
	v_mov_b32_e32 v39, v0
	v_mov_b32_e32 v48, v0
	v_mov_b32_e32 v49, v0
	v_mov_b32_e32 v50, v0
	v_mov_b32_e32 v51, v0
	v_mov_b32_e32 v52, v0
	v_mov_b32_e32 v53, v0
	v_mov_b32_e32 v54, v0
	v_mov_b32_e32 v55, v0
	v_mov_b32_e32 v8, v0
	v_mov_b32_e32 v9, v0
	v_mov_b32_e32 v10, v0
	v_mov_b32_e32 v11, v0
	v_mov_b32_e32 v12, v0
	v_mov_b32_e32 v13, v0
	v_mov_b32_e32 v14, v0
	v_mov_b32_e32 v15, v0
	v_mov_b32_e32 v24, v0
	v_mov_b32_e32 v25, v0
	v_mov_b32_e32 v26, v0
	v_mov_b32_e32 v27, v0
	v_mov_b32_e32 v28, v0
	v_mov_b32_e32 v29, v0
	v_mov_b32_e32 v30, v0
	v_mov_b32_e32 v31, v0
	v_mov_b32_e32 v40, v0
	v_mov_b32_e32 v41, v0
	v_mov_b32_e32 v42, v0
	v_mov_b32_e32 v43, v0
	v_mov_b32_e32 v44, v0
	v_mov_b32_e32 v45, v0
	v_mov_b32_e32 v46, v0
	v_mov_b32_e32 v47, v0
	v_mov_b32_e32 v56, v0
	v_mov_b32_e32 v57, v0
	v_mov_b32_e32 v58, v0
	v_mov_b32_e32 v59, v0
	v_mov_b32_e32 v60, v0
	v_mov_b32_e32 v61, v0
	v_mov_b32_e32 v62, v0
	v_mov_b32_e32 v63, v0
	v_mov_b32_e32 v64, v0
	v_mov_b32_e32 v65, v0
	v_mov_b32_e32 v66, v0
	v_mov_b32_e32 v67, v0
	v_mov_b32_e32 v68, v0
	v_mov_b32_e32 v69, v0
	v_mov_b32_e32 v70, v0
	v_mov_b32_e32 v71, v0
	v_mov_b32_e32 v80, v0
	v_mov_b32_e32 v81, v0
	v_mov_b32_e32 v82, v0
	v_mov_b32_e32 v83, v0
	v_mov_b32_e32 v84, v0
	v_mov_b32_e32 v85, v0
	v_mov_b32_e32 v86, v0
	v_mov_b32_e32 v87, v0
	v_mov_b32_e32 v96, v0
	v_mov_b32_e32 v97, v0
	v_mov_b32_e32 v98, v0
	v_mov_b32_e32 v99, v0
	v_mov_b32_e32 v100, v0
	v_mov_b32_e32 v101, v0
	v_mov_b32_e32 v102, v0
	v_mov_b32_e32 v103, v0
	v_mov_b32_e32 v112, v0
	v_mov_b32_e32 v113, v0
	v_mov_b32_e32 v114, v0
	v_mov_b32_e32 v115, v0
	v_mov_b32_e32 v116, v0
	v_mov_b32_e32 v117, v0
	v_mov_b32_e32 v118, v0
	v_mov_b32_e32 v119, v0
	v_mov_b32_e32 v72, v0
	v_mov_b32_e32 v73, v0
	v_mov_b32_e32 v74, v0
	v_mov_b32_e32 v75, v0
	v_mov_b32_e32 v76, v0
	v_mov_b32_e32 v77, v0
	v_mov_b32_e32 v78, v0
	v_mov_b32_e32 v79, v0
	v_mov_b32_e32 v88, v0
	v_mov_b32_e32 v89, v0
	v_mov_b32_e32 v90, v0
	v_mov_b32_e32 v91, v0
	v_mov_b32_e32 v92, v0
	v_mov_b32_e32 v93, v0
	v_mov_b32_e32 v94, v0
	v_mov_b32_e32 v95, v0
	v_mov_b32_e32 v104, v0
	v_mov_b32_e32 v105, v0
	v_mov_b32_e32 v106, v0
	v_mov_b32_e32 v107, v0
	v_mov_b32_e32 v108, v0
	v_mov_b32_e32 v109, v0
	v_mov_b32_e32 v110, v0
	v_mov_b32_e32 v111, v0
	v_mov_b32_e32 v120, v0
	v_mov_b32_e32 v121, v0
	v_mov_b32_e32 v122, v0
	v_mov_b32_e32 v123, v0
	v_mov_b32_e32 v124, v0
	v_mov_b32_e32 v125, v0
	v_mov_b32_e32 v126, v0
	v_mov_b32_e32 v127, v0
	s_cmp_eq_u32 s98, 1
	s_cbranch_scc0 .Lkb_skip_5
	s_mov_b32 s98, 0
	s_barrier
.Lkb_skip_5:
.LBB0_767:
	ds_read_b128 v[146:149], v153
	ds_read_b128 v[158:161], v153 offset:1024
	ds_read_b128 v[162:165], v153 offset:2048
	ds_read_b128 v[166:169], v153 offset:3072
	ds_read_b128 v[170:173], v154
	ds_read_b128 v[174:177], v154 offset:1024
	ds_read_b128 v[178:181], v154 offset:2048
	ds_read_b128 v[182:185], v154 offset:3072
	s_add_u32 s26, s62, 0xfffc0080
	s_addc_u32 s27, s63, -1
	s_cmp_eq_u32 s83, 12
	s_cselect_b32 s67, s53, s27
	s_cselect_b32 s66, s59, s26
	s_cselect_b32 s65, s51, s79
	s_cselect_b32 s64, s77, s78
	v_lshl_add_u64 v[218:219], s[62:63], 0, v[138:139]
	s_add_i32 m0, s61, 0xc000
	ds_read_b128 v[186:189], v155
	ds_read_b128 v[190:193], v155 offset:1024
	ds_read_b128 v[194:197], v155 offset:2048
	ds_read_b128 v[198:201], v155 offset:3072
	ds_read_b128 v[202:205], v155 offset:4096
	ds_read_b128 v[206:209], v155 offset:5120
	ds_read_b128 v[210:213], v155 offset:6144
	ds_read_b128 v[214:217], v155 offset:7168
	global_load_lds_dwordx4 v[218:219], off
	v_lshl_add_u64 v[218:219], s[62:63], 0, v[140:141]
	s_add_i32 m0, s61, 0xe000
	s_nop 0
	global_load_lds_dwordx4 v[218:219], off
	s_waitcnt vmcnt(8)
	s_waitcnt lgkmcnt(0)
	s_barrier
; #define PG8_STAGE(bufoff, gbase, voff) do { _Pragma("unroll") for (int _i = 0; _i < 2; ++_i) \
;         __builtin_amdgcn_global_load_lds((const unsigned*)((const char*)(gbase) + (voff)[_i]), (PG8_LAS unsigned*)(lds + (bufoff) + ldsw + _i * 8192), 16, 0, 0); } while (0)
; #define PG8_LDA(dst, b, h) do { _Pragma("unroll") for (int m = 0; m < 4; ++m) _Pragma("unroll") for (int k = 0; k < 2; ++k) dst[m][k] = *(const PG8_LAS bf16x8*)(lds + PG8_SA(b, h) + aoff + m * 2048 + k * 1024); } while (0)
; #define PG8_MMA(ai, bj, At, Bt) do { __builtin_amdgcn_s_setprio(1); _Pragma("unroll") for (int m = 0; m < 4; ++m) _Pragma("unroll") for (int n = 0; n < 2; ++n) _Pragma("unroll") for (int k = 0; k < 2; ++k) \
;         acc[ai][bj][m][n] = __builtin_amdgcn_mfma_f32_16x16x32_bf16(Bt[n][k], At[m][k], acc[ai][bj][m][n], 0, 0, 0); __builtin_amdgcn_s_setprio(0); } while (0)
; #define PG8_WAIT_V(n) asm volatile("s_waitcnt vmcnt(" #n ")" ::: "memory")
; #define PG8_WAIT_L(n) asm volatile("s_waitcnt lgkmcnt(" #n ")" ::: "memory")
; #define PG8_BAR __builtin_amdgcn_s_barrier()
; #define PG8_SCHED __builtin_amdgcn_sched_barrier(0)
; template <class Epi, class Sched, bool ALIGN_EPI = false, bool SP2 = false>
; __device__ __forceinline__ void gemm_phase(PG8_LAS unsigned char* lds, const Gemm g, const Sched& S, const Epi& E, int tid_in) {
;     ...
;             PG8_WAIT_V(8); PG8_WAIT_L(0); PG8_BAR; PG8_MMA(0, 0, At, B0); PG8_MMA(0, 1, At, B1); PG8_BAR; PG8_SCHED;
;             PG8_LDA(At, 0, 1); PG8_STAGE(PG8_SB(0, 0), b2, voffB); PG8_STAGE(PG8_SB(0, 1), b2 + hstepB, voffB); PG8_STAGE(PG8_SA(0, 0), a2, voffA);
;             PG8_WAIT_V(8); PG8_WAIT_L(0); PG8_BAR; PG8_MMA(1, 0, At, B0); PG8_MMA(1, 1, At, B1); PG8_BAR; PG8_SCHED;
	s_setprio 1
	s_waitcnt lgkmcnt(0)
	v_mfma_f32_16x16x32_bf16 v[124:127], v[146:149], v[186:189], v[124:127]
	v_mfma_f32_16x16x32_bf16 v[120:123], v[162:165], v[186:189], v[120:123]
	v_mfma_f32_16x16x32_bf16 v[108:111], v[146:149], v[194:197], v[108:111]
	v_mfma_f32_16x16x32_bf16 v[104:107], v[162:165], v[194:197], v[104:107]
	v_mfma_f32_16x16x32_bf16 v[92:95], v[146:149], v[202:205], v[92:95]
	v_mfma_f32_16x16x32_bf16 v[88:91], v[162:165], v[202:205], v[88:91]
	v_mfma_f32_16x16x32_bf16 v[76:79], v[146:149], v[210:213], v[76:79]
	v_mfma_f32_16x16x32_bf16 v[72:75], v[162:165], v[210:213], v[72:75]
	v_mfma_f32_16x16x32_bf16 v[124:127], v[158:161], v[190:193], v[124:127]
	v_mfma_f32_16x16x32_bf16 v[120:123], v[166:169], v[190:193], v[120:123]
	v_mfma_f32_16x16x32_bf16 v[108:111], v[158:161], v[198:201], v[108:111]
	v_mfma_f32_16x16x32_bf16 v[104:107], v[166:169], v[198:201], v[104:107]
	v_mfma_f32_16x16x32_bf16 v[92:95], v[158:161], v[206:209], v[92:95]
	v_mfma_f32_16x16x32_bf16 v[88:91], v[166:169], v[206:209], v[88:91]
	v_mfma_f32_16x16x32_bf16 v[76:79], v[158:161], v[214:217], v[76:79]
	v_mfma_f32_16x16x32_bf16 v[72:75], v[166:169], v[214:217], v[72:75]
	s_setprio 0
	s_setprio 1
	v_mfma_f32_16x16x32_bf16 v[116:119], v[170:173], v[186:189], v[116:119]
	v_mfma_f32_16x16x32_bf16 v[112:115], v[178:181], v[186:189], v[112:115]
	v_mfma_f32_16x16x32_bf16 v[100:103], v[170:173], v[194:197], v[100:103]
	v_mfma_f32_16x16x32_bf16 v[96:99], v[178:181], v[194:197], v[96:99]
	v_mfma_f32_16x16x32_bf16 v[84:87], v[170:173], v[202:205], v[84:87]
	v_mfma_f32_16x16x32_bf16 v[80:83], v[178:181], v[202:205], v[80:83]
	v_mfma_f32_16x16x32_bf16 v[68:71], v[170:173], v[210:213], v[68:71]
	v_mfma_f32_16x16x32_bf16 v[64:67], v[178:181], v[210:213], v[64:67]
	v_mfma_f32_16x16x32_bf16 v[116:119], v[174:177], v[190:193], v[116:119]
	v_mfma_f32_16x16x32_bf16 v[112:115], v[182:185], v[190:193], v[112:115]
	v_mfma_f32_16x16x32_bf16 v[100:103], v[174:177], v[198:201], v[100:103]
	v_mfma_f32_16x16x32_bf16 v[96:99], v[182:185], v[198:201], v[96:99]
	v_mfma_f32_16x16x32_bf16 v[84:87], v[174:177], v[206:209], v[84:87]
	v_mfma_f32_16x16x32_bf16 v[80:83], v[182:185], v[206:209], v[80:83]
	v_mfma_f32_16x16x32_bf16 v[68:71], v[174:177], v[214:217], v[68:71]
	v_mfma_f32_16x16x32_bf16 v[64:67], v[182:185], v[214:217], v[64:67]
	s_setprio 0
	s_barrier
	s_add_i32 s26, s75, s68
	v_lshl_add_u64 v[218:219], s[64:65], 0, v[130:131]
	s_mov_b32 m0, s26
	ds_read_b128 v[186:189], v155 offset:16384
	ds_read_b128 v[190:193], v155 offset:17408
	ds_read_b128 v[194:197], v155 offset:18432
	ds_read_b128 v[198:201], v155 offset:19456
	ds_read_b128 v[202:205], v155 offset:20480
	ds_read_b128 v[206:209], v155 offset:21504
	ds_read_b128 v[210:213], v155 offset:22528
	ds_read_b128 v[214:217], v155 offset:23552
	global_load_lds_dwordx4 v[218:219], off
	s_add_i32 m0, s26, 0x2000
	s_add_u32 s26, s64, 0x10000
	v_lshl_add_u64 v[220:221], s[64:65], 0, v[134:135]
	s_addc_u32 s27, s65, 0
	s_add_i32 s33, s76, s68
	global_load_lds_dwordx4 v[220:221], off
	v_lshl_add_u64 v[222:223], s[26:27], 0, v[130:131]
	s_mov_b32 m0, s33
	v_lshl_add_u64 v[224:225], s[66:67], 0, v[132:133]
	global_load_lds_dwordx4 v[222:223], off
	v_lshl_add_u64 v[222:223], s[26:27], 0, v[134:135]
	s_add_i32 m0, s33, 0x2000
	s_nop 0
	global_load_lds_dwordx4 v[222:223], off
	v_lshl_add_u64 v[222:223], s[66:67], 0, v[128:129]
	s_mov_b32 m0, s61
	s_nop 0
	global_load_lds_dwordx4 v[222:223], off
	s_mov_b32 m0, s69
	s_nop 0
	global_load_lds_dwordx4 v[224:225], off
	s_waitcnt vmcnt(8)
	s_waitcnt lgkmcnt(0)
	s_barrier
	s_setprio 1
	s_waitcnt lgkmcnt(0)
	v_mfma_f32_16x16x32_bf16 v[60:63], v[146:149], v[186:189], v[60:63]
	v_mfma_f32_16x16x32_bf16 v[56:59], v[162:165], v[186:189], v[56:59]
	v_mfma_f32_16x16x32_bf16 v[44:47], v[146:149], v[194:197], v[44:47]
	v_mfma_f32_16x16x32_bf16 v[40:43], v[162:165], v[194:197], v[40:43]
	v_mfma_f32_16x16x32_bf16 v[28:31], v[146:149], v[202:205], v[28:31]
	v_mfma_f32_16x16x32_bf16 v[24:27], v[162:165], v[202:205], v[24:27]
	v_mfma_f32_16x16x32_bf16 v[12:15], v[146:149], v[210:213], v[12:15]
	v_mfma_f32_16x16x32_bf16 v[8:11], v[162:165], v[210:213], v[8:11]
	v_mfma_f32_16x16x32_bf16 v[60:63], v[158:161], v[190:193], v[60:63]
	v_mfma_f32_16x16x32_bf16 v[56:59], v[166:169], v[190:193], v[56:59]
	v_mfma_f32_16x16x32_bf16 v[44:47], v[158:161], v[198:201], v[44:47]
	v_mfma_f32_16x16x32_bf16 v[40:43], v[166:169], v[198:201], v[40:43]
	v_mfma_f32_16x16x32_bf16 v[28:31], v[158:161], v[206:209], v[28:31]
	v_mfma_f32_16x16x32_bf16 v[24:27], v[166:169], v[206:209], v[24:27]
	v_mfma_f32_16x16x32_bf16 v[12:15], v[158:161], v[214:217], v[12:15]
	v_mfma_f32_16x16x32_bf16 v[8:11], v[166:169], v[214:217], v[8:11]
	s_setprio 0
	s_setprio 1
	v_mfma_f32_16x16x32_bf16 v[52:55], v[170:173], v[186:189], v[52:55]
	v_mfma_f32_16x16x32_bf16 v[48:51], v[178:181], v[186:189], v[48:51]
	v_mfma_f32_16x16x32_bf16 v[36:39], v[170:173], v[194:197], v[36:39]
	v_mfma_f32_16x16x32_bf16 v[32:35], v[178:181], v[194:197], v[32:35]
	v_mfma_f32_16x16x32_bf16 v[20:23], v[170:173], v[202:205], v[20:23]
	v_mfma_f32_16x16x32_bf16 v[16:19], v[178:181], v[202:205], v[16:19]
	v_mfma_f32_16x16x32_bf16 v[4:7], v[170:173], v[210:213], v[4:7]
	v_mfma_f32_16x16x32_bf16 v[0:3], v[178:181], v[210:213], v[0:3]
	v_mfma_f32_16x16x32_bf16 v[52:55], v[174:177], v[190:193], v[52:55]
	v_mfma_f32_16x16x32_bf16 v[48:51], v[182:185], v[190:193], v[48:51]
	v_mfma_f32_16x16x32_bf16 v[36:39], v[174:177], v[198:201], v[36:39]
	v_mfma_f32_16x16x32_bf16 v[32:35], v[182:185], v[198:201], v[32:35]
	v_mfma_f32_16x16x32_bf16 v[20:23], v[174:177], v[206:209], v[20:23]
	v_mfma_f32_16x16x32_bf16 v[16:19], v[182:185], v[206:209], v[16:19]
	v_mfma_f32_16x16x32_bf16 v[4:7], v[174:177], v[214:217], v[4:7]
	v_mfma_f32_16x16x32_bf16 v[0:3], v[182:185], v[214:217], v[0:3]
	s_setprio 0
	s_barrier
; #define PG8_STAGE(bufoff, gbase, voff) do { _Pragma("unroll") for (int _i = 0; _i < 2; ++_i) \
;         __builtin_amdgcn_global_load_lds((const unsigned*)((const char*)(gbase) + (voff)[_i]), (PG8_LAS unsigned*)(lds + (bufoff) + ldsw + _i * 8192), 16, 0, 0); } while (0)
; #define PG8_LDA(dst, b, h) do { _Pragma("unroll") for (int m = 0; m < 4; ++m) _Pragma("unroll") for (int k = 0; k < 2; ++k) dst[m][k] = *(const PG8_LAS bf16x8*)(lds + PG8_SA(b, h) + aoff + m * 2048 + k * 1024); } while (0)
; #define PG8_LDB(dst, b, h) do { _Pragma("unroll") for (int n = 0; n < 2; ++n) _Pragma("unroll") for (int k = 0; k < 2; ++k) dst[n][k] = *(const PG8_LAS bf16x8*)(lds + PG8_SB(b, h) + boff + n * 2048 + k * 1024); } while (0)
; #define PG8_MMA(ai, bj, At, Bt) do { __builtin_amdgcn_s_setprio(1); _Pragma("unroll") for (int m = 0; m < 4; ++m) _Pragma("unroll") for (int n = 0; n < 2; ++n) _Pragma("unroll") for (int k = 0; k < 2; ++k) \
;         acc[ai][bj][m][n] = __builtin_amdgcn_mfma_f32_16x16x32_bf16(Bt[n][k], At[m][k], acc[ai][bj][m][n], 0, 0, 0); __builtin_amdgcn_s_setprio(0); } while (0)
; #define PG8_WAIT_V(n) asm volatile("s_waitcnt vmcnt(" #n ")" ::: "memory")
; #define PG8_WAIT_L(n) asm volatile("s_waitcnt lgkmcnt(" #n ")" ::: "memory")
; #define PG8_BAR __builtin_amdgcn_s_barrier()
; #define PG8_SCHED __builtin_amdgcn_sched_barrier(0)
; template <class Epi, class Sched, bool ALIGN_EPI = false, bool SP2 = false>
; __device__ __forceinline__ void gemm_phase(PG8_LAS unsigned char* lds, const Gemm g, const Sched& S, const Epi& E, int tid_in) {
;     ...
;             PG8_LDB(B0, 1, 0); PG8_LDB(B1, 1, 1); PG8_SCHED; PG8_LDA(At, 1, 0); PG8_STAGE(PG8_SA(0, 1), a2 + hstep, voffA);
;             PG8_WAIT_V(8); PG8_WAIT_L(0); PG8_BAR; PG8_MMA(0, 0, At, B0); PG8_MMA(0, 1, At, B1); PG8_BAR; PG8_SCHED;
;             PG8_LDA(At, 1, 1); PG8_STAGE(PG8_SB(1, 0), b3, voffB); PG8_STAGE(PG8_SB(1, 1), b3 + hstepB, voffB); PG8_STAGE(PG8_SA(1, 0), a3, voffA);
	s_add_i32 s33, 0, 0x18000
	s_add_i32 s84, 0, 0x1c000
	v_add_u32_e32 v166, s33, v137
	v_add_u32_e32 v182, s84, v137
	ds_read_b128 v[146:149], v166
	ds_read_b128 v[158:161], v166 offset:1024
	ds_read_b128 v[162:165], v166 offset:2048
	ds_read_b128 v[166:169], v166 offset:3072
	ds_read_b128 v[170:173], v182
	ds_read_b128 v[174:177], v182 offset:1024
	ds_read_b128 v[178:181], v182 offset:2048
	ds_read_b128 v[182:185], v182 offset:3072
	s_add_u32 s26, s66, 0x40000
	s_addc_u32 s27, s67, 0
	s_mov_b32 m0, s70
	v_lshl_add_u64 v[226:227], s[26:27], 0, v[128:129]
	ds_read_b128 v[186:189], v155 offset:32768
	ds_read_b128 v[190:193], v155 offset:33792
	ds_read_b128 v[194:197], v155 offset:34816
	ds_read_b128 v[198:201], v155 offset:35840
	ds_read_b128 v[202:205], v155 offset:36864
	ds_read_b128 v[206:209], v155 offset:37888
	ds_read_b128 v[210:213], v155 offset:38912
	ds_read_b128 v[214:217], v155 offset:39936
	global_load_lds_dwordx4 v[226:227], off
	v_lshl_add_u64 v[226:227], s[26:27], 0, v[132:133]
	s_mov_b32 m0, s71
	s_nop 0
	global_load_lds_dwordx4 v[226:227], off
	s_waitcnt vmcnt(8)
	s_waitcnt lgkmcnt(0)
	s_barrier
	s_setprio 1
	s_waitcnt lgkmcnt(0)
	v_mfma_f32_16x16x32_bf16 v[124:127], v[146:149], v[186:189], v[124:127]
	v_mfma_f32_16x16x32_bf16 v[120:123], v[162:165], v[186:189], v[120:123]
	v_mfma_f32_16x16x32_bf16 v[108:111], v[146:149], v[194:197], v[108:111]
	v_mfma_f32_16x16x32_bf16 v[104:107], v[162:165], v[194:197], v[104:107]
	v_mfma_f32_16x16x32_bf16 v[92:95], v[146:149], v[202:205], v[92:95]
	v_mfma_f32_16x16x32_bf16 v[88:91], v[162:165], v[202:205], v[88:91]
	v_mfma_f32_16x16x32_bf16 v[76:79], v[146:149], v[210:213], v[76:79]
	v_mfma_f32_16x16x32_bf16 v[72:75], v[162:165], v[210:213], v[72:75]
	v_mfma_f32_16x16x32_bf16 v[124:127], v[158:161], v[190:193], v[124:127]
	v_mfma_f32_16x16x32_bf16 v[120:123], v[166:169], v[190:193], v[120:123]
	v_mfma_f32_16x16x32_bf16 v[108:111], v[158:161], v[198:201], v[108:111]
	v_mfma_f32_16x16x32_bf16 v[104:107], v[166:169], v[198:201], v[104:107]
	v_mfma_f32_16x16x32_bf16 v[92:95], v[158:161], v[206:209], v[92:95]
	v_mfma_f32_16x16x32_bf16 v[88:91], v[166:169], v[206:209], v[88:91]
	v_mfma_f32_16x16x32_bf16 v[76:79], v[158:161], v[214:217], v[76:79]
	v_mfma_f32_16x16x32_bf16 v[72:75], v[166:169], v[214:217], v[72:75]
	s_setprio 0
	s_setprio 1
	v_mfma_f32_16x16x32_bf16 v[116:119], v[170:173], v[186:189], v[116:119]
	v_mfma_f32_16x16x32_bf16 v[112:115], v[178:181], v[186:189], v[112:115]
	v_mfma_f32_16x16x32_bf16 v[100:103], v[170:173], v[194:197], v[100:103]
	v_mfma_f32_16x16x32_bf16 v[96:99], v[178:181], v[194:197], v[96:99]
	v_mfma_f32_16x16x32_bf16 v[84:87], v[170:173], v[202:205], v[84:87]
	v_mfma_f32_16x16x32_bf16 v[80:83], v[178:181], v[202:205], v[80:83]
	v_mfma_f32_16x16x32_bf16 v[68:71], v[170:173], v[210:213], v[68:71]
	v_mfma_f32_16x16x32_bf16 v[64:67], v[178:181], v[210:213], v[64:67]
	v_mfma_f32_16x16x32_bf16 v[116:119], v[174:177], v[190:193], v[116:119]
	v_mfma_f32_16x16x32_bf16 v[112:115], v[182:185], v[190:193], v[112:115]
	v_mfma_f32_16x16x32_bf16 v[100:103], v[174:177], v[198:201], v[100:103]
	v_mfma_f32_16x16x32_bf16 v[96:99], v[182:185], v[198:201], v[96:99]
	v_mfma_f32_16x16x32_bf16 v[84:87], v[174:177], v[206:209], v[84:87]
	v_mfma_f32_16x16x32_bf16 v[80:83], v[182:185], v[206:209], v[80:83]
	v_mfma_f32_16x16x32_bf16 v[68:71], v[174:177], v[214:217], v[68:71]
	v_mfma_f32_16x16x32_bf16 v[64:67], v[182:185], v[214:217], v[64:67]
	s_setprio 0
	s_barrier
	s_add_i32 s26, s33, s68
	v_lshl_add_u64 v[218:219], v[218:219], 0, s[46:47]
	s_mov_b32 m0, s26
	ds_read_b128 v[186:189], v155 offset:49152
	ds_read_b128 v[190:193], v155 offset:50176
	ds_read_b128 v[194:197], v155 offset:51200
	ds_read_b128 v[198:201], v155 offset:52224
	ds_read_b128 v[202:205], v155 offset:53248
	ds_read_b128 v[206:209], v155 offset:54272
	ds_read_b128 v[210:213], v155 offset:55296
	ds_read_b128 v[214:217], v155 offset:56320
	global_load_lds_dwordx4 v[218:219], off
	s_add_i32 m0, s26, 0x2000
	s_add_u32 s26, s64, 0x10080
	v_lshl_add_u64 v[218:219], v[220:221], 0, s[46:47]
	s_addc_u32 s27, s65, 0
	s_add_i32 s33, s84, s68
	global_load_lds_dwordx4 v[218:219], off
	v_lshl_add_u64 v[218:219], s[26:27], 0, v[130:131]
	s_mov_b32 m0, s33
	s_nop 0
	global_load_lds_dwordx4 v[218:219], off
	v_lshl_add_u64 v[218:219], s[26:27], 0, v[134:135]
	s_add_i32 m0, s33, 0x2000
	s_nop 0
	global_load_lds_dwordx4 v[218:219], off
	v_lshl_add_u64 v[218:219], v[222:223], 0, s[46:47]
	s_mov_b32 m0, s73
	s_nop 0
	global_load_lds_dwordx4 v[218:219], off
	v_lshl_add_u64 v[218:219], v[224:225], 0, s[46:47]
	s_mov_b32 m0, s74
	s_nop 0
	global_load_lds_dwordx4 v[218:219], off
	s_waitcnt vmcnt(8)
	s_waitcnt lgkmcnt(0)
	s_barrier
; #define PG8_LAS __attribute__((address_space(3)))
; __device__ __forceinline__ unsigned cvt_pk_bf16(float lo, float hi) { unsigned r; asm volatile("v_cvt_pk_bf16_f32 %0, %1, %2" : "=v"(r) : "v"(lo), "v"(hi)); return r; }
; template <class Epi, class Sched, bool ALIGN_EPI = false, bool SP2 = false>
; __device__ __forceinline__ void gemm_phase(PG8_LAS unsigned char* lds, const Gemm g, const Sched& S, const Epi& E, int tid_in) {
;     ...
;             PG8_LDA(At, 1, 1); PG8_STAGE(PG8_SB(1, 0), b3, voffB); PG8_STAGE(PG8_SB(1, 1), b3 + hstepB, voffB); PG8_STAGE(PG8_SA(1, 0), a3, voffA);
;             PG8_WAIT_V(8); PG8_WAIT_L(0); PG8_BAR; PG8_MMA(1, 0, At, B0); PG8_MMA(1, 1, At, B1); PG8_BAR; PG8_SCHED;
;     __device__ __forceinline__ void operator()(const f32x4 (&acc)[2][2][4][2], const Unit& u, int wr, int wc, int fr, int fq) const {
;     ...
;                 const int row = u.pm * BM + ai * HALF + wr * 64 + m * 16 + r; float q = 0.f;
; #pragma unroll
;                 for (int bj = 0; bj < 2; ++bj) {
;                     const size_t off = (size_t)row * 2048 + u.pn * BM + wc * 64 + bj * 32 + 8 * p;
;                     f32x4 b0, b1;
;                     if (BASE_F32) { b0 = *(const f32x4*)((const float*)base + off); b1 = *(const f32x4*)((const float*)base + off + 4); }
;                     else { const u32x4 bb = *(const u32x4*)((const bf16_t*)base + off);
;                         b0 = (f32x4){__uint_as_float(bb.x << 16), __uint_as_float(bb.x & 0xffff0000u), __uint_as_float(bb.y << 16), __uint_as_float(bb.y & 0xffff0000u)};
;                         b1 = (f32x4){__uint_as_float(bb.z << 16), __uint_as_float(bb.z & 0xffff0000u), __uint_as_float(bb.w << 16), __uint_as_float(bb.w & 0xffff0000u)}; }
; #pragma unroll
;                     for (int n = 0; n < 2; ++n) *(PG8_LAS f32x4*)(stg + fr * STG_ROW + n * 64 + fq * 16) = acc[ai][bj][m][n];
;                     const f32x4 v0 = *(const PG8_LAS f32x4*)(stg + r * STG_ROW + p * 32) + b0, v1 = *(const PG8_LAS f32x4*)(stg + r * STG_ROW + p * 32 + 16) + b1;
;                     q += ((v0[0] * v0[0] + v0[1] * v0[1]) + (v0[2] * v0[2] + v0[3] * v0[3])) + ((v1[0] * v1[0] + v1[1] * v1[1]) + (v1[2] * v1[2] + v1[3] * v1[3]));
;                     u32x4 w; w.x = cvt_pk_bf16(v0[0], v0[1]); w.y = cvt_pk_bf16(v0[2], v0[3]); w.z = cvt_pk_bf16(v1[0], v1[1]); w.w = cvt_pk_bf16(v1[2], v1[3]);
;                     *(u32x4*)(out + off) = w;
	s_setprio 1
	s_waitcnt lgkmcnt(0)
	v_mfma_f32_16x16x32_bf16 v[60:63], v[146:149], v[186:189], v[60:63]
	v_mfma_f32_16x16x32_bf16 v[56:59], v[162:165], v[186:189], v[56:59]
	v_mfma_f32_16x16x32_bf16 v[44:47], v[146:149], v[194:197], v[44:47]
	v_mfma_f32_16x16x32_bf16 v[40:43], v[162:165], v[194:197], v[40:43]
	v_mfma_f32_16x16x32_bf16 v[28:31], v[146:149], v[202:205], v[28:31]
	v_mfma_f32_16x16x32_bf16 v[24:27], v[162:165], v[202:205], v[24:27]
	v_mfma_f32_16x16x32_bf16 v[12:15], v[146:149], v[210:213], v[12:15]
	v_mfma_f32_16x16x32_bf16 v[8:11], v[162:165], v[210:213], v[8:11]
	v_mfma_f32_16x16x32_bf16 v[60:63], v[158:161], v[190:193], v[60:63]
	v_mfma_f32_16x16x32_bf16 v[56:59], v[166:169], v[190:193], v[56:59]
	v_mfma_f32_16x16x32_bf16 v[44:47], v[158:161], v[198:201], v[44:47]
	v_mfma_f32_16x16x32_bf16 v[40:43], v[166:169], v[198:201], v[40:43]
	v_mfma_f32_16x16x32_bf16 v[28:31], v[158:161], v[206:209], v[28:31]
	v_mfma_f32_16x16x32_bf16 v[24:27], v[166:169], v[206:209], v[24:27]
	v_mfma_f32_16x16x32_bf16 v[12:15], v[158:161], v[214:217], v[12:15]
	v_mfma_f32_16x16x32_bf16 v[8:11], v[166:169], v[214:217], v[8:11]
	s_setprio 0
	s_setprio 1
	v_mfma_f32_16x16x32_bf16 v[52:55], v[170:173], v[186:189], v[52:55]
	v_mfma_f32_16x16x32_bf16 v[48:51], v[178:181], v[186:189], v[48:51]
	v_mfma_f32_16x16x32_bf16 v[36:39], v[170:173], v[194:197], v[36:39]
	v_mfma_f32_16x16x32_bf16 v[32:35], v[178:181], v[194:197], v[32:35]
	v_mfma_f32_16x16x32_bf16 v[20:23], v[170:173], v[202:205], v[20:23]
	v_mfma_f32_16x16x32_bf16 v[16:19], v[178:181], v[202:205], v[16:19]
	v_mfma_f32_16x16x32_bf16 v[4:7], v[170:173], v[210:213], v[4:7]
	v_mfma_f32_16x16x32_bf16 v[0:3], v[178:181], v[210:213], v[0:3]
	v_mfma_f32_16x16x32_bf16 v[52:55], v[174:177], v[190:193], v[52:55]
	v_mfma_f32_16x16x32_bf16 v[48:51], v[182:185], v[190:193], v[48:51]
	v_mfma_f32_16x16x32_bf16 v[36:39], v[174:177], v[198:201], v[36:39]
	v_mfma_f32_16x16x32_bf16 v[32:35], v[182:185], v[198:201], v[32:35]
	v_mfma_f32_16x16x32_bf16 v[20:23], v[174:177], v[206:209], v[20:23]
	v_mfma_f32_16x16x32_bf16 v[16:19], v[182:185], v[206:209], v[16:19]
	v_mfma_f32_16x16x32_bf16 v[4:7], v[174:177], v[214:217], v[4:7]
	v_mfma_f32_16x16x32_bf16 v[0:3], v[182:185], v[214:217], v[0:3]
	s_setprio 0
	s_barrier
	s_add_i32 s83, s83, 2
	s_add_u32 s62, s62, 0x100
	s_addc_u32 s63, s63, 0
	s_add_u32 s78, s78, 0x100
	s_addc_u32 s79, s79, 0
	s_cmp_gt_u32 s83, 13
	s_cbranch_scc0 .LBB0_767
	v_lshl_add_u32 v148, s58, 8, v150
	v_lshl_or_b32 v146, s60, 8, v136
	v_lshl_add_u32 v147, v148, 11, v146
	v_lshlrev_b32_e32 v159, 1, v147
	v_lshlrev_b32_e32 v208, 3, v148
	global_load_dwordx4 v[160:163], v159, s[28:29]
	global_load_dwordx4 v[164:167], v159, s[28:29] offset:64
	v_add_u32_e32 v149, 0x10000, v159
	global_load_dwordx4 v[168:171], v149, s[28:29]
	global_load_dwordx4 v[172:175], v149, s[28:29] offset:64
	v_add_u32_e32 v209, 0x20000, v159
	global_load_dwordx4 v[176:179], v209, s[28:29]
	global_load_dwordx4 v[180:183], v209, s[28:29] offset:64
	v_add_u32_e32 v149, 0x30000, v159
	global_load_dwordx4 v[184:187], v149, s[28:29]
	global_load_dwordx4 v[188:191], v149, s[28:29] offset:64
	v_add_u32_e32 v209, 0x80000, v159
	global_load_dwordx4 v[192:195], v209, s[28:29]
	global_load_dwordx4 v[196:199], v209, s[28:29] offset:64
	v_add_u32_e32 v149, 0x90000, v159
	global_load_dwordx4 v[200:203], v149, s[28:29]
	global_load_dwordx4 v[204:207], v149, s[28:29] offset:64
	v_add_u32_e32 v209, 0xa0000, v159
	global_load_dwordx4 v[212:215], v209, s[28:29]
	global_load_dwordx4 v[216:219], v209, s[28:29] offset:64
	v_add_u32_e32 v149, 0xb0000, v159
	global_load_dwordx4 v[220:223], v149, s[28:29]
	global_load_dwordx4 v[224:227], v149, s[28:29] offset:64
	s_and_b64 vcc, exec, s[48:49]
	s_cbranch_vccz .LBB0_770
	s_barrier
.LBB0_770:
	ds_write_b128 v156, v[124:127]
	ds_write_b128 v156, v[120:123] offset:64
	ds_read_b128 v[120:123], v157
	ds_read_b128 v[124:127], v157 offset:16
	ds_write_b128 v156, v[116:119]
	ds_write_b128 v156, v[112:115] offset:64
	ds_read_b128 v[112:115], v157
	ds_read_b128 v[116:119], v157 offset:16
	s_waitcnt vmcnt(15) lgkmcnt(4)
	v_lshlrev_b32_e32 v236, 16, v160
	v_and_b32_e32 v237, 0xffff0000, v160
	v_lshlrev_b32_e32 v238, 16, v161
	v_and_b32_e32 v239, 0xffff0000, v161
	v_lshlrev_b32_e32 v240, 16, v162
	v_and_b32_e32 v241, 0xffff0000, v162
	v_lshlrev_b32_e32 v242, 16, v163
	v_and_b32_e32 v243, 0xffff0000, v163
	v_pk_add_f32 v[120:121], v[120:121], v[236:237]
	v_pk_add_f32 v[122:123], v[122:123], v[238:239]
	v_pk_add_f32 v[124:125], v[124:125], v[240:241]
	v_pk_add_f32 v[126:127], v[126:127], v[242:243]
	v_mul_f32_e32 v236, v121, v121
	v_mul_f32_e32 v237, v123, v123
	v_mul_f32_e32 v238, v125, v125
	v_mul_f32_e32 v239, v127, v127
	v_fmac_f32_e32 v236, v120, v120
	v_fmac_f32_e32 v237, v122, v122
	v_fmac_f32_e32 v238, v124, v124
	v_fmac_f32_e32 v239, v126, v126
	v_cvt_pk_bf16_f32 v120, v120, v121
	v_cvt_pk_bf16_f32 v121, v122, v123
	v_cvt_pk_bf16_f32 v122, v124, v125
	v_cvt_pk_bf16_f32 v123, v126, v127
	v_add_f32_e32 v236, v236, v237
	v_add_f32_e32 v237, v238, v239
	v_add_f32_e32 v124, v236, v237
	global_store_dwordx4 v159, v[120:123], s[28:29]
	ds_write_b128 v156, v[108:111]
	ds_write_b128 v156, v[104:107] offset:64
	ds_read_b128 v[104:107], v157
	ds_read_b128 v[108:111], v157 offset:16
	s_waitcnt vmcnt(15) lgkmcnt(4)
; #define PG8_LAS __attribute__((address_space(3)))
; __device__ __forceinline__ unsigned cvt_pk_bf16(float lo, float hi) { unsigned r; asm volatile("v_cvt_pk_bf16_f32 %0, %1, %2" : "=v"(r) : "v"(lo), "v"(hi)); return r; }
;     __device__ __forceinline__ void operator()(const f32x4 (&acc)[2][2][4][2], const Unit& u, int wr, int wc, int fr, int fq) const {
;     ...
;                 const int row = u.pm * BM + ai * HALF + wr * 64 + m * 16 + r; float q = 0.f;
; #pragma unroll
;                 for (int bj = 0; bj < 2; ++bj) {
;                     const size_t off = (size_t)row * 2048 + u.pn * BM + wc * 64 + bj * 32 + 8 * p;
;                     f32x4 b0, b1;
;                     if (BASE_F32) { b0 = *(const f32x4*)((const float*)base + off); b1 = *(const f32x4*)((const float*)base + off + 4); }
;                     else { const u32x4 bb = *(const u32x4*)((const bf16_t*)base + off);
;                         b0 = (f32x4){__uint_as_float(bb.x << 16), __uint_as_float(bb.x & 0xffff0000u), __uint_as_float(bb.y << 16), __uint_as_float(bb.y & 0xffff0000u)};
;                         b1 = (f32x4){__uint_as_float(bb.z << 16), __uint_as_float(bb.z & 0xffff0000u), __uint_as_float(bb.w << 16), __uint_as_float(bb.w & 0xffff0000u)}; }
; #pragma unroll
;                     for (int n = 0; n < 2; ++n) *(PG8_LAS f32x4*)(stg + fr * STG_ROW + n * 64 + fq * 16) = acc[ai][bj][m][n];
;                     const f32x4 v0 = *(const PG8_LAS f32x4*)(stg + r * STG_ROW + p * 32) + b0, v1 = *(const PG8_LAS f32x4*)(stg + r * STG_ROW + p * 32 + 16) + b1;
;                     q += ((v0[0] * v0[0] + v0[1] * v0[1]) + (v0[2] * v0[2] + v0[3] * v0[3])) + ((v1[0] * v1[0] + v1[1] * v1[1]) + (v1[2] * v1[2] + v1[3] * v1[3]));
;                     u32x4 w; w.x = cvt_pk_bf16(v0[0], v0[1]); w.y = cvt_pk_bf16(v0[2], v0[3]); w.z = cvt_pk_bf16(v1[0], v1[1]); w.w = cvt_pk_bf16(v1[2], v1[3]);
;                     *(u32x4*)(out + off) = w;
;                 }
;                 q += __shfl_xor(q, 1); q += __shfl_xor(q, 2);
;                 if (p == 0) atomicAdd(ssn + row, (u64)(q * SS_SCALE));
	v_lshlrev_b32_e32 v236, 16, v164
	v_and_b32_e32 v237, 0xffff0000, v164
	v_lshlrev_b32_e32 v238, 16, v165
	v_and_b32_e32 v239, 0xffff0000, v165
	v_lshlrev_b32_e32 v240, 16, v166
	v_and_b32_e32 v241, 0xffff0000, v166
	v_lshlrev_b32_e32 v242, 16, v167
	v_and_b32_e32 v243, 0xffff0000, v167
	v_pk_add_f32 v[112:113], v[112:113], v[236:237]
	v_pk_add_f32 v[114:115], v[114:115], v[238:239]
	v_pk_add_f32 v[116:117], v[116:117], v[240:241]
	v_pk_add_f32 v[118:119], v[118:119], v[242:243]
	v_mul_f32_e32 v236, v113, v113
	v_mul_f32_e32 v237, v115, v115
	v_mul_f32_e32 v238, v117, v117
	v_mul_f32_e32 v239, v119, v119
	v_fmac_f32_e32 v236, v112, v112
	v_fmac_f32_e32 v237, v114, v114
	v_fmac_f32_e32 v238, v116, v116
	v_fmac_f32_e32 v239, v118, v118
	v_cvt_pk_bf16_f32 v112, v112, v113
	v_cvt_pk_bf16_f32 v113, v114, v115
	v_cvt_pk_bf16_f32 v114, v116, v117
	v_cvt_pk_bf16_f32 v115, v118, v119
	v_add_f32_e32 v236, v236, v237
	v_add_f32_e32 v237, v238, v239
	v_add_f32_e32 v116, v236, v237
	global_store_dwordx4 v159, v[112:115], s[28:29] offset:64
	v_add_f32_e32 v117, v124, v116
	s_nop 1
	v_add_f32_dpp v118, v117, v117 quad_perm:[1,0,3,2] row_mask:0xf bank_mask:0xf
	s_nop 1
	v_add_f32_dpp v119, v118, v118 quad_perm:[2,3,0,1] row_mask:0xf bank_mask:0xf
	v_mul_f32_e32 v126, 0x49800000, v119
	v_trunc_f32_e32 v126, v126
	v_mul_f32_e32 v127, 0x2f800000, v126
	v_floor_f32_e32 v127, v127
	v_fmac_f32_e32 v126, 0xcf800000, v127
	v_cvt_u32_f32_e32 v126, v126
	v_cvt_u32_f32_e32 v127, v127
	s_mov_b64 exec, s[8:9]
	global_atomic_add_x2 v208, v[126:127], s[12:13]
	s_mov_b64 exec, -1
	ds_write_b128 v156, v[100:103]
	ds_write_b128 v156, v[96:99] offset:64
	ds_read_b128 v[96:99], v157
	ds_read_b128 v[100:103], v157 offset:16
	s_waitcnt vmcnt(16) lgkmcnt(4)
	v_lshlrev_b32_e32 v236, 16, v168
	v_and_b32_e32 v237, 0xffff0000, v168
	v_lshlrev_b32_e32 v238, 16, v169
	v_and_b32_e32 v239, 0xffff0000, v169
	v_lshlrev_b32_e32 v240, 16, v170
	v_and_b32_e32 v241, 0xffff0000, v170
	v_lshlrev_b32_e32 v242, 16, v171
	v_and_b32_e32 v243, 0xffff0000, v171
	v_pk_add_f32 v[104:105], v[104:105], v[236:237]
	v_pk_add_f32 v[106:107], v[106:107], v[238:239]
	v_pk_add_f32 v[108:109], v[108:109], v[240:241]
	v_pk_add_f32 v[110:111], v[110:111], v[242:243]
	v_mul_f32_e32 v236, v105, v105
	v_mul_f32_e32 v237, v107, v107
	v_mul_f32_e32 v238, v109, v109
	v_mul_f32_e32 v239, v111, v111
	v_fmac_f32_e32 v236, v104, v104
	v_fmac_f32_e32 v237, v106, v106
	v_fmac_f32_e32 v238, v108, v108
	v_fmac_f32_e32 v239, v110, v110
	v_cvt_pk_bf16_f32 v104, v104, v105
	v_cvt_pk_bf16_f32 v105, v106, v107
	v_cvt_pk_bf16_f32 v106, v108, v109
	v_cvt_pk_bf16_f32 v107, v110, v111
	v_add_f32_e32 v236, v236, v237
	v_add_f32_e32 v237, v238, v239
	v_add_f32_e32 v108, v236, v237
	v_add_u32_e32 v147, 0x10000, v159
	global_store_dwordx4 v147, v[104:107], s[28:29]
	ds_write_b128 v156, v[92:95]
	ds_write_b128 v156, v[88:91] offset:64
	ds_read_b128 v[88:91], v157
	ds_read_b128 v[92:95], v157 offset:16
	s_waitcnt vmcnt(16) lgkmcnt(4)
	v_lshlrev_b32_e32 v236, 16, v172
	v_and_b32_e32 v237, 0xffff0000, v172
	v_lshlrev_b32_e32 v238, 16, v173
	v_and_b32_e32 v239, 0xffff0000, v173
	v_lshlrev_b32_e32 v240, 16, v174
	v_and_b32_e32 v241, 0xffff0000, v174
	v_lshlrev_b32_e32 v242, 16, v175
	v_and_b32_e32 v243, 0xffff0000, v175
	v_pk_add_f32 v[96:97], v[96:97], v[236:237]
	v_pk_add_f32 v[98:99], v[98:99], v[238:239]
	v_pk_add_f32 v[100:101], v[100:101], v[240:241]
	v_pk_add_f32 v[102:103], v[102:103], v[242:243]
	v_mul_f32_e32 v236, v97, v97
	v_mul_f32_e32 v237, v99, v99
	v_mul_f32_e32 v238, v101, v101
	v_mul_f32_e32 v239, v103, v103
	v_fmac_f32_e32 v236, v96, v96
	v_fmac_f32_e32 v237, v98, v98
	v_fmac_f32_e32 v238, v100, v100
	v_fmac_f32_e32 v239, v102, v102
	v_cvt_pk_bf16_f32 v96, v96, v97
	v_cvt_pk_bf16_f32 v97, v98, v99
	v_cvt_pk_bf16_f32 v98, v100, v101
	v_cvt_pk_bf16_f32 v99, v102, v103
	v_add_f32_e32 v236, v236, v237
	v_add_f32_e32 v237, v238, v239
	v_add_f32_e32 v100, v236, v237
	global_store_dwordx4 v147, v[96:99], s[28:29] offset:64
	v_add_f32_e32 v101, v108, v100
	s_nop 1
	v_add_f32_dpp v102, v101, v101 quad_perm:[1,0,3,2] row_mask:0xf bank_mask:0xf
	s_nop 1
	v_add_f32_dpp v103, v102, v102 quad_perm:[2,3,0,1] row_mask:0xf bank_mask:0xf
	v_mul_f32_e32 v110, 0x49800000, v103
	v_trunc_f32_e32 v110, v110
	v_mul_f32_e32 v111, 0x2f800000, v110
	v_floor_f32_e32 v111, v111
	v_fmac_f32_e32 v110, 0xcf800000, v111
	v_cvt_u32_f32_e32 v110, v110
	v_cvt_u32_f32_e32 v111, v111
	s_mov_b64 exec, s[8:9]
	global_atomic_add_x2 v208, v[110:111], s[12:13] offset:128
	s_mov_b64 exec, -1
	ds_write_b128 v156, v[84:87]
	ds_write_b128 v156, v[80:83] offset:64
	ds_read_b128 v[80:83], v157
	ds_read_b128 v[84:87], v157 offset:16
	s_waitcnt vmcnt(17) lgkmcnt(4)
	v_lshlrev_b32_e32 v236, 16, v176
	v_and_b32_e32 v237, 0xffff0000, v176
	v_lshlrev_b32_e32 v238, 16, v177
	v_and_b32_e32 v239, 0xffff0000, v177
	v_lshlrev_b32_e32 v240, 16, v178
	v_and_b32_e32 v241, 0xffff0000, v178
	v_lshlrev_b32_e32 v242, 16, v179
	v_and_b32_e32 v243, 0xffff0000, v179
	v_pk_add_f32 v[88:89], v[88:89], v[236:237]
	v_pk_add_f32 v[90:91], v[90:91], v[238:239]
	v_pk_add_f32 v[92:93], v[92:93], v[240:241]
	v_pk_add_f32 v[94:95], v[94:95], v[242:243]
	v_mul_f32_e32 v236, v89, v89
	v_mul_f32_e32 v237, v91, v91
	v_mul_f32_e32 v238, v93, v93
	v_mul_f32_e32 v239, v95, v95
	v_fmac_f32_e32 v236, v88, v88
	v_fmac_f32_e32 v237, v90, v90
	v_fmac_f32_e32 v238, v92, v92
	v_fmac_f32_e32 v239, v94, v94
	v_cvt_pk_bf16_f32 v88, v88, v89
	v_cvt_pk_bf16_f32 v89, v90, v91
	v_cvt_pk_bf16_f32 v90, v92, v93
	v_cvt_pk_bf16_f32 v91, v94, v95
	v_add_f32_e32 v236, v236, v237
	v_add_f32_e32 v237, v238, v239
	v_add_f32_e32 v92, v236, v237
	v_add_u32_e32 v146, 0x20000, v159
	global_store_dwordx4 v146, v[88:91], s[28:29]
	ds_write_b128 v156, v[76:79]
	ds_write_b128 v156, v[72:75] offset:64
	ds_read_b128 v[72:75], v157
	ds_read_b128 v[76:79], v157 offset:16
	s_waitcnt vmcnt(17) lgkmcnt(4)
; #define PG8_LAS __attribute__((address_space(3)))
; __device__ __forceinline__ unsigned cvt_pk_bf16(float lo, float hi) { unsigned r; asm volatile("v_cvt_pk_bf16_f32 %0, %1, %2" : "=v"(r) : "v"(lo), "v"(hi)); return r; }
;     __device__ __forceinline__ void operator()(const f32x4 (&acc)[2][2][4][2], const Unit& u, int wr, int wc, int fr, int fq) const {
;     ...
;                 const int row = u.pm * BM + ai * HALF + wr * 64 + m * 16 + r; float q = 0.f;
; #pragma unroll
;                 for (int bj = 0; bj < 2; ++bj) {
;                     const size_t off = (size_t)row * 2048 + u.pn * BM + wc * 64 + bj * 32 + 8 * p;
;                     f32x4 b0, b1;
;                     if (BASE_F32) { b0 = *(const f32x4*)((const float*)base + off); b1 = *(const f32x4*)((const float*)base + off + 4); }
;                     else { const u32x4 bb = *(const u32x4*)((const bf16_t*)base + off);
;                         b0 = (f32x4){__uint_as_float(bb.x << 16), __uint_as_float(bb.x & 0xffff0000u), __uint_as_float(bb.y << 16), __uint_as_float(bb.y & 0xffff0000u)};
;                         b1 = (f32x4){__uint_as_float(bb.z << 16), __uint_as_float(bb.z & 0xffff0000u), __uint_as_float(bb.w << 16), __uint_as_float(bb.w & 0xffff0000u)}; }
; #pragma unroll
;                     for (int n = 0; n < 2; ++n) *(PG8_LAS f32x4*)(stg + fr * STG_ROW + n * 64 + fq * 16) = acc[ai][bj][m][n];
;                     const f32x4 v0 = *(const PG8_LAS f32x4*)(stg + r * STG_ROW + p * 32) + b0, v1 = *(const PG8_LAS f32x4*)(stg + r * STG_ROW + p * 32 + 16) + b1;
;                     q += ((v0[0] * v0[0] + v0[1] * v0[1]) + (v0[2] * v0[2] + v0[3] * v0[3])) + ((v1[0] * v1[0] + v1[1] * v1[1]) + (v1[2] * v1[2] + v1[3] * v1[3]));
;                     u32x4 w; w.x = cvt_pk_bf16(v0[0], v0[1]); w.y = cvt_pk_bf16(v0[2], v0[3]); w.z = cvt_pk_bf16(v1[0], v1[1]); w.w = cvt_pk_bf16(v1[2], v1[3]);
;                     *(u32x4*)(out + off) = w;
;                 }
;                 q += __shfl_xor(q, 1); q += __shfl_xor(q, 2);
;                 if (p == 0) atomicAdd(ssn + row, (u64)(q * SS_SCALE));
	v_lshlrev_b32_e32 v236, 16, v180
	v_and_b32_e32 v237, 0xffff0000, v180
	v_lshlrev_b32_e32 v238, 16, v181
	v_and_b32_e32 v239, 0xffff0000, v181
	v_lshlrev_b32_e32 v240, 16, v182
	v_and_b32_e32 v241, 0xffff0000, v182
	v_lshlrev_b32_e32 v242, 16, v183
	v_and_b32_e32 v243, 0xffff0000, v183
	v_pk_add_f32 v[80:81], v[80:81], v[236:237]
	v_pk_add_f32 v[82:83], v[82:83], v[238:239]
	v_pk_add_f32 v[84:85], v[84:85], v[240:241]
	v_pk_add_f32 v[86:87], v[86:87], v[242:243]
	v_mul_f32_e32 v236, v81, v81
	v_mul_f32_e32 v237, v83, v83
	v_mul_f32_e32 v238, v85, v85
	v_mul_f32_e32 v239, v87, v87
	v_fmac_f32_e32 v236, v80, v80
	v_fmac_f32_e32 v237, v82, v82
	v_fmac_f32_e32 v238, v84, v84
	v_fmac_f32_e32 v239, v86, v86
	v_cvt_pk_bf16_f32 v80, v80, v81
	v_cvt_pk_bf16_f32 v81, v82, v83
	v_cvt_pk_bf16_f32 v82, v84, v85
	v_cvt_pk_bf16_f32 v83, v86, v87
	v_add_f32_e32 v236, v236, v237
	v_add_f32_e32 v237, v238, v239
	v_add_f32_e32 v84, v236, v237
	global_store_dwordx4 v146, v[80:83], s[28:29] offset:64
	v_add_f32_e32 v85, v92, v84
	s_nop 1
	v_add_f32_dpp v86, v85, v85 quad_perm:[1,0,3,2] row_mask:0xf bank_mask:0xf
	s_nop 1
	v_add_f32_dpp v87, v86, v86 quad_perm:[2,3,0,1] row_mask:0xf bank_mask:0xf
	v_mul_f32_e32 v94, 0x49800000, v87
	v_trunc_f32_e32 v94, v94
	v_mul_f32_e32 v95, 0x2f800000, v94
	v_floor_f32_e32 v95, v95
	v_fmac_f32_e32 v94, 0xcf800000, v95
	v_cvt_u32_f32_e32 v94, v94
	v_cvt_u32_f32_e32 v95, v95
	s_mov_b64 exec, s[8:9]
	global_atomic_add_x2 v208, v[94:95], s[12:13] offset:256
	s_mov_b64 exec, -1
	ds_write_b128 v156, v[68:71]
	ds_write_b128 v156, v[64:67] offset:64
	ds_read_b128 v[64:67], v157
	ds_read_b128 v[68:71], v157 offset:16
	s_waitcnt vmcnt(18) lgkmcnt(4)
	v_lshlrev_b32_e32 v236, 16, v184
	v_and_b32_e32 v237, 0xffff0000, v184
	v_lshlrev_b32_e32 v238, 16, v185
	v_and_b32_e32 v239, 0xffff0000, v185
	v_lshlrev_b32_e32 v240, 16, v186
	v_and_b32_e32 v241, 0xffff0000, v186
	v_lshlrev_b32_e32 v242, 16, v187
	v_and_b32_e32 v243, 0xffff0000, v187
	v_pk_add_f32 v[72:73], v[72:73], v[236:237]
	v_pk_add_f32 v[74:75], v[74:75], v[238:239]
	v_pk_add_f32 v[76:77], v[76:77], v[240:241]
	v_pk_add_f32 v[78:79], v[78:79], v[242:243]
	v_mul_f32_e32 v236, v73, v73
	v_mul_f32_e32 v237, v75, v75
	v_mul_f32_e32 v238, v77, v77
	v_mul_f32_e32 v239, v79, v79
	v_fmac_f32_e32 v236, v72, v72
	v_fmac_f32_e32 v237, v74, v74
	v_fmac_f32_e32 v238, v76, v76
	v_fmac_f32_e32 v239, v78, v78
	v_cvt_pk_bf16_f32 v72, v72, v73
	v_cvt_pk_bf16_f32 v73, v74, v75
	v_cvt_pk_bf16_f32 v74, v76, v77
	v_cvt_pk_bf16_f32 v75, v78, v79
	v_add_f32_e32 v236, v236, v237
	v_add_f32_e32 v237, v238, v239
	v_add_f32_e32 v76, v236, v237
	v_add_u32_e32 v147, 0x30000, v159
	global_store_dwordx4 v147, v[72:75], s[28:29]
	ds_write_b128 v156, v[60:63]
	ds_write_b128 v156, v[56:59] offset:64
	ds_read_b128 v[56:59], v157
	ds_read_b128 v[60:63], v157 offset:16
	s_waitcnt vmcnt(18) lgkmcnt(4)
	v_lshlrev_b32_e32 v236, 16, v188
	v_and_b32_e32 v237, 0xffff0000, v188
	v_lshlrev_b32_e32 v238, 16, v189
	v_and_b32_e32 v239, 0xffff0000, v189
	v_lshlrev_b32_e32 v240, 16, v190
	v_and_b32_e32 v241, 0xffff0000, v190
	v_lshlrev_b32_e32 v242, 16, v191
	v_and_b32_e32 v243, 0xffff0000, v191
	v_pk_add_f32 v[64:65], v[64:65], v[236:237]
	v_pk_add_f32 v[66:67], v[66:67], v[238:239]
	v_pk_add_f32 v[68:69], v[68:69], v[240:241]
	v_pk_add_f32 v[70:71], v[70:71], v[242:243]
	v_mul_f32_e32 v236, v65, v65
	v_mul_f32_e32 v237, v67, v67
	v_mul_f32_e32 v238, v69, v69
	v_mul_f32_e32 v239, v71, v71
	v_fmac_f32_e32 v236, v64, v64
	v_fmac_f32_e32 v237, v66, v66
	v_fmac_f32_e32 v238, v68, v68
	v_fmac_f32_e32 v239, v70, v70
	v_cvt_pk_bf16_f32 v64, v64, v65
	v_cvt_pk_bf16_f32 v65, v66, v67
	v_cvt_pk_bf16_f32 v66, v68, v69
	v_cvt_pk_bf16_f32 v67, v70, v71
	v_add_f32_e32 v236, v236, v237
	v_add_f32_e32 v237, v238, v239
	v_add_f32_e32 v68, v236, v237
	global_store_dwordx4 v147, v[64:67], s[28:29] offset:64
	v_add_f32_e32 v69, v76, v68
	s_nop 1
	v_add_f32_dpp v70, v69, v69 quad_perm:[1,0,3,2] row_mask:0xf bank_mask:0xf
	s_nop 1
	v_add_f32_dpp v71, v70, v70 quad_perm:[2,3,0,1] row_mask:0xf bank_mask:0xf
	v_mul_f32_e32 v78, 0x49800000, v71
	v_trunc_f32_e32 v78, v78
	v_mul_f32_e32 v79, 0x2f800000, v78
	v_floor_f32_e32 v79, v79
	v_fmac_f32_e32 v78, 0xcf800000, v79
	v_cvt_u32_f32_e32 v78, v78
	v_cvt_u32_f32_e32 v79, v79
	s_mov_b64 exec, s[8:9]
	global_atomic_add_x2 v208, v[78:79], s[12:13] offset:384
	s_mov_b64 exec, -1
	ds_write_b128 v156, v[52:55]
	ds_write_b128 v156, v[48:51] offset:64
	ds_read_b128 v[48:51], v157
	ds_read_b128 v[52:55], v157 offset:16
	s_waitcnt vmcnt(19) lgkmcnt(4)
	v_lshlrev_b32_e32 v236, 16, v192
	v_and_b32_e32 v237, 0xffff0000, v192
	v_lshlrev_b32_e32 v238, 16, v193
	v_and_b32_e32 v239, 0xffff0000, v193
	v_lshlrev_b32_e32 v240, 16, v194
	v_and_b32_e32 v241, 0xffff0000, v194
	v_lshlrev_b32_e32 v242, 16, v195
	v_and_b32_e32 v243, 0xffff0000, v195
	v_pk_add_f32 v[56:57], v[56:57], v[236:237]
	v_pk_add_f32 v[58:59], v[58:59], v[238:239]
	v_pk_add_f32 v[60:61], v[60:61], v[240:241]
	v_pk_add_f32 v[62:63], v[62:63], v[242:243]
	v_mul_f32_e32 v236, v57, v57
	v_mul_f32_e32 v237, v59, v59
	v_mul_f32_e32 v238, v61, v61
	v_mul_f32_e32 v239, v63, v63
	v_fmac_f32_e32 v236, v56, v56
	v_fmac_f32_e32 v237, v58, v58
	v_fmac_f32_e32 v238, v60, v60
	v_fmac_f32_e32 v239, v62, v62
	v_cvt_pk_bf16_f32 v56, v56, v57
	v_cvt_pk_bf16_f32 v57, v58, v59
	v_cvt_pk_bf16_f32 v58, v60, v61
	v_cvt_pk_bf16_f32 v59, v62, v63
	v_add_f32_e32 v236, v236, v237
	v_add_f32_e32 v237, v238, v239
	v_add_f32_e32 v60, v236, v237
	v_add_u32_e32 v146, 0x80000, v159
	global_store_dwordx4 v146, v[56:59], s[28:29]
	ds_write_b128 v156, v[44:47]
	ds_write_b128 v156, v[40:43] offset:64
	ds_read_b128 v[40:43], v157
	ds_read_b128 v[44:47], v157 offset:16
	s_waitcnt vmcnt(19) lgkmcnt(4)
; #define PG8_LAS __attribute__((address_space(3)))
; __device__ __forceinline__ unsigned cvt_pk_bf16(float lo, float hi) { unsigned r; asm volatile("v_cvt_pk_bf16_f32 %0, %1, %2" : "=v"(r) : "v"(lo), "v"(hi)); return r; }
;     __device__ __forceinline__ void operator()(const f32x4 (&acc)[2][2][4][2], const Unit& u, int wr, int wc, int fr, int fq) const {
;     ...
;                 const int row = u.pm * BM + ai * HALF + wr * 64 + m * 16 + r; float q = 0.f;
; #pragma unroll
;                 for (int bj = 0; bj < 2; ++bj) {
;                     const size_t off = (size_t)row * 2048 + u.pn * BM + wc * 64 + bj * 32 + 8 * p;
;                     f32x4 b0, b1;
;                     if (BASE_F32) { b0 = *(const f32x4*)((const float*)base + off); b1 = *(const f32x4*)((const float*)base + off + 4); }
;                     else { const u32x4 bb = *(const u32x4*)((const bf16_t*)base + off);
;                         b0 = (f32x4){__uint_as_float(bb.x << 16), __uint_as_float(bb.x & 0xffff0000u), __uint_as_float(bb.y << 16), __uint_as_float(bb.y & 0xffff0000u)};
;                         b1 = (f32x4){__uint_as_float(bb.z << 16), __uint_as_float(bb.z & 0xffff0000u), __uint_as_float(bb.w << 16), __uint_as_float(bb.w & 0xffff0000u)}; }
; #pragma unroll
;                     for (int n = 0; n < 2; ++n) *(PG8_LAS f32x4*)(stg + fr * STG_ROW + n * 64 + fq * 16) = acc[ai][bj][m][n];
;                     const f32x4 v0 = *(const PG8_LAS f32x4*)(stg + r * STG_ROW + p * 32) + b0, v1 = *(const PG8_LAS f32x4*)(stg + r * STG_ROW + p * 32 + 16) + b1;
;                     q += ((v0[0] * v0[0] + v0[1] * v0[1]) + (v0[2] * v0[2] + v0[3] * v0[3])) + ((v1[0] * v1[0] + v1[1] * v1[1]) + (v1[2] * v1[2] + v1[3] * v1[3]));
;                     u32x4 w; w.x = cvt_pk_bf16(v0[0], v0[1]); w.y = cvt_pk_bf16(v0[2], v0[3]); w.z = cvt_pk_bf16(v1[0], v1[1]); w.w = cvt_pk_bf16(v1[2], v1[3]);
;                     *(u32x4*)(out + off) = w;
;                 }
;                 q += __shfl_xor(q, 1); q += __shfl_xor(q, 2);
;                 if (p == 0) atomicAdd(ssn + row, (u64)(q * SS_SCALE));
	v_lshlrev_b32_e32 v236, 16, v196
	v_and_b32_e32 v237, 0xffff0000, v196
	v_lshlrev_b32_e32 v238, 16, v197
	v_and_b32_e32 v239, 0xffff0000, v197
	v_lshlrev_b32_e32 v240, 16, v198
	v_and_b32_e32 v241, 0xffff0000, v198
	v_lshlrev_b32_e32 v242, 16, v199
	v_and_b32_e32 v243, 0xffff0000, v199
	v_pk_add_f32 v[48:49], v[48:49], v[236:237]
	v_pk_add_f32 v[50:51], v[50:51], v[238:239]
	v_pk_add_f32 v[52:53], v[52:53], v[240:241]
	v_pk_add_f32 v[54:55], v[54:55], v[242:243]
	v_mul_f32_e32 v236, v49, v49
	v_mul_f32_e32 v237, v51, v51
	v_mul_f32_e32 v238, v53, v53
	v_mul_f32_e32 v239, v55, v55
	v_fmac_f32_e32 v236, v48, v48
	v_fmac_f32_e32 v237, v50, v50
	v_fmac_f32_e32 v238, v52, v52
	v_fmac_f32_e32 v239, v54, v54
	v_cvt_pk_bf16_f32 v48, v48, v49
	v_cvt_pk_bf16_f32 v49, v50, v51
	v_cvt_pk_bf16_f32 v50, v52, v53
	v_cvt_pk_bf16_f32 v51, v54, v55
	v_add_f32_e32 v236, v236, v237
	v_add_f32_e32 v237, v238, v239
	v_add_f32_e32 v52, v236, v237
	global_store_dwordx4 v146, v[48:51], s[28:29] offset:64
	v_add_f32_e32 v53, v60, v52
	s_nop 1
	v_add_f32_dpp v54, v53, v53 quad_perm:[1,0,3,2] row_mask:0xf bank_mask:0xf
	s_nop 1
	v_add_f32_dpp v55, v54, v54 quad_perm:[2,3,0,1] row_mask:0xf bank_mask:0xf
	v_mul_f32_e32 v62, 0x49800000, v55
	v_trunc_f32_e32 v62, v62
	v_mul_f32_e32 v63, 0x2f800000, v62
	v_floor_f32_e32 v63, v63
	v_fmac_f32_e32 v62, 0xcf800000, v63
	v_cvt_u32_f32_e32 v62, v62
	v_cvt_u32_f32_e32 v63, v63
	s_mov_b64 exec, s[8:9]
	global_atomic_add_x2 v208, v[62:63], s[12:13] offset:1024
	s_mov_b64 exec, -1
	ds_write_b128 v156, v[36:39]
	ds_write_b128 v156, v[32:35] offset:64
	ds_read_b128 v[32:35], v157
	ds_read_b128 v[36:39], v157 offset:16
	s_waitcnt vmcnt(20) lgkmcnt(4)
	v_lshlrev_b32_e32 v236, 16, v200
	v_and_b32_e32 v237, 0xffff0000, v200
	v_lshlrev_b32_e32 v238, 16, v201
	v_and_b32_e32 v239, 0xffff0000, v201
	v_lshlrev_b32_e32 v240, 16, v202
	v_and_b32_e32 v241, 0xffff0000, v202
	v_lshlrev_b32_e32 v242, 16, v203
	v_and_b32_e32 v243, 0xffff0000, v203
	v_pk_add_f32 v[40:41], v[40:41], v[236:237]
	v_pk_add_f32 v[42:43], v[42:43], v[238:239]
	v_pk_add_f32 v[44:45], v[44:45], v[240:241]
	v_pk_add_f32 v[46:47], v[46:47], v[242:243]
	v_mul_f32_e32 v236, v41, v41
	v_mul_f32_e32 v237, v43, v43
	v_mul_f32_e32 v238, v45, v45
	v_mul_f32_e32 v239, v47, v47
	v_fmac_f32_e32 v236, v40, v40
	v_fmac_f32_e32 v237, v42, v42
	v_fmac_f32_e32 v238, v44, v44
	v_fmac_f32_e32 v239, v46, v46
	v_cvt_pk_bf16_f32 v40, v40, v41
	v_cvt_pk_bf16_f32 v41, v42, v43
	v_cvt_pk_bf16_f32 v42, v44, v45
	v_cvt_pk_bf16_f32 v43, v46, v47
	v_add_f32_e32 v236, v236, v237
	v_add_f32_e32 v237, v238, v239
	v_add_f32_e32 v44, v236, v237
	v_add_u32_e32 v147, 0x90000, v159
	global_store_dwordx4 v147, v[40:43], s[28:29]
	ds_write_b128 v156, v[28:31]
	ds_write_b128 v156, v[24:27] offset:64
	ds_read_b128 v[24:27], v157
	ds_read_b128 v[28:31], v157 offset:16
	s_waitcnt vmcnt(20) lgkmcnt(4)
	v_lshlrev_b32_e32 v236, 16, v204
	v_and_b32_e32 v237, 0xffff0000, v204
	v_lshlrev_b32_e32 v238, 16, v205
	v_and_b32_e32 v239, 0xffff0000, v205
	v_lshlrev_b32_e32 v240, 16, v206
	v_and_b32_e32 v241, 0xffff0000, v206
	v_lshlrev_b32_e32 v242, 16, v207
	v_and_b32_e32 v243, 0xffff0000, v207
	v_pk_add_f32 v[32:33], v[32:33], v[236:237]
	v_pk_add_f32 v[34:35], v[34:35], v[238:239]
	v_pk_add_f32 v[36:37], v[36:37], v[240:241]
	v_pk_add_f32 v[38:39], v[38:39], v[242:243]
	v_mul_f32_e32 v236, v33, v33
	v_mul_f32_e32 v237, v35, v35
	v_mul_f32_e32 v238, v37, v37
	v_mul_f32_e32 v239, v39, v39
	v_fmac_f32_e32 v236, v32, v32
	v_fmac_f32_e32 v237, v34, v34
	v_fmac_f32_e32 v238, v36, v36
	v_fmac_f32_e32 v239, v38, v38
	v_cvt_pk_bf16_f32 v32, v32, v33
	v_cvt_pk_bf16_f32 v33, v34, v35
	v_cvt_pk_bf16_f32 v34, v36, v37
	v_cvt_pk_bf16_f32 v35, v38, v39
	v_add_f32_e32 v236, v236, v237
	v_add_f32_e32 v237, v238, v239
	v_add_f32_e32 v36, v236, v237
	global_store_dwordx4 v147, v[32:35], s[28:29] offset:64
	v_add_f32_e32 v37, v44, v36
	s_nop 1
	v_add_f32_dpp v38, v37, v37 quad_perm:[1,0,3,2] row_mask:0xf bank_mask:0xf
	s_nop 1
	v_add_f32_dpp v39, v38, v38 quad_perm:[2,3,0,1] row_mask:0xf bank_mask:0xf
	v_mul_f32_e32 v46, 0x49800000, v39
	v_trunc_f32_e32 v46, v46
	v_mul_f32_e32 v47, 0x2f800000, v46
	v_floor_f32_e32 v47, v47
	v_fmac_f32_e32 v46, 0xcf800000, v47
	v_cvt_u32_f32_e32 v46, v46
	v_cvt_u32_f32_e32 v47, v47
	s_mov_b64 exec, s[8:9]
	global_atomic_add_x2 v208, v[46:47], s[12:13] offset:1152
	s_mov_b64 exec, -1
	ds_write_b128 v156, v[20:23]
	ds_write_b128 v156, v[16:19] offset:64
	ds_read_b128 v[16:19], v157
	ds_read_b128 v[20:23], v157 offset:16
	s_waitcnt vmcnt(21) lgkmcnt(4)
; template <class Epi, class Sched, bool ALIGN_EPI = false, bool SP2 = false>
; __device__ __forceinline__ void gemm_phase(PG8_LAS unsigned char* lds, const Gemm g, const Sched& S, const Epi& E, int tid_in) {
;     ...
;         if (!has_next) break;
; #pragma unroll
;         for (int a = 0; a < 2; ++a)
; #pragma unroll
;             for (int b = 0; b < 2; ++b)
; #pragma unroll
;                 for (int m = 0; m < 4; ++m)
; #pragma unroll
;                     for (int n = 0; n < 2; ++n) acc[a][b][m][n] = (f32x4){0.f, 0.f, 0.f, 0.f};
;     __device__ __forceinline__ void operator()(const f32x4 (&acc)[2][2][4][2], const Unit& u, int wr, int wc, int fr, int fq) const {
;     ...
;                 const int row = u.pm * BM + ai * HALF + wr * 64 + m * 16 + r; float q = 0.f;
; #pragma unroll
;                 for (int bj = 0; bj < 2; ++bj) {
;                     const size_t off = (size_t)row * 2048 + u.pn * BM + wc * 64 + bj * 32 + 8 * p;
;                     f32x4 b0, b1;
;                     if (BASE_F32) { b0 = *(const f32x4*)((const float*)base + off); b1 = *(const f32x4*)((const float*)base + off + 4); }
;                     else { const u32x4 bb = *(const u32x4*)((const bf16_t*)base + off);
;                         b0 = (f32x4){__uint_as_float(bb.x << 16), __uint_as_float(bb.x & 0xffff0000u), __uint_as_float(bb.y << 16), __uint_as_float(bb.y & 0xffff0000u)};
;                         b1 = (f32x4){__uint_as_float(bb.z << 16), __uint_as_float(bb.z & 0xffff0000u), __uint_as_float(bb.w << 16), __uint_as_float(bb.w & 0xffff0000u)}; }
; #pragma unroll
;                     for (int n = 0; n < 2; ++n) *(PG8_LAS f32x4*)(stg + fr * STG_ROW + n * 64 + fq * 16) = acc[ai][bj][m][n];
;                     const f32x4 v0 = *(const PG8_LAS f32x4*)(stg + r * STG_ROW + p * 32) + b0, v1 = *(const PG8_LAS f32x4*)(stg + r * STG_ROW + p * 32 + 16) + b1;
;                     q += ((v0[0] * v0[0] + v0[1] * v0[1]) + (v0[2] * v0[2] + v0[3] * v0[3])) + ((v1[0] * v1[0] + v1[1] * v1[1]) + (v1[2] * v1[2] + v1[3] * v1[3]));
;                     u32x4 w; w.x = cvt_pk_bf16(v0[0], v0[1]); w.y = cvt_pk_bf16(v0[2], v0[3]); w.z = cvt_pk_bf16(v1[0], v1[1]); w.w = cvt_pk_bf16(v1[2], v1[3]);
;                     *(u32x4*)(out + off) = w;
;                 }
;                 q += __shfl_xor(q, 1); q += __shfl_xor(q, 2);
;                 if (p == 0) atomicAdd(ssn + row, (u64)(q * SS_SCALE));
	v_lshlrev_b32_e32 v236, 16, v212
	v_and_b32_e32 v237, 0xffff0000, v212
	v_lshlrev_b32_e32 v238, 16, v213
	v_and_b32_e32 v239, 0xffff0000, v213
	v_lshlrev_b32_e32 v240, 16, v214
	v_and_b32_e32 v241, 0xffff0000, v214
	v_lshlrev_b32_e32 v242, 16, v215
	v_and_b32_e32 v243, 0xffff0000, v215
	v_pk_add_f32 v[24:25], v[24:25], v[236:237]
	v_pk_add_f32 v[26:27], v[26:27], v[238:239]
	v_pk_add_f32 v[28:29], v[28:29], v[240:241]
	v_pk_add_f32 v[30:31], v[30:31], v[242:243]
	v_mul_f32_e32 v236, v25, v25
	v_mul_f32_e32 v237, v27, v27
	v_mul_f32_e32 v238, v29, v29
	v_mul_f32_e32 v239, v31, v31
	v_fmac_f32_e32 v236, v24, v24
	v_fmac_f32_e32 v237, v26, v26
	v_fmac_f32_e32 v238, v28, v28
	v_fmac_f32_e32 v239, v30, v30
	v_cvt_pk_bf16_f32 v24, v24, v25
	v_cvt_pk_bf16_f32 v25, v26, v27
	v_cvt_pk_bf16_f32 v26, v28, v29
	v_cvt_pk_bf16_f32 v27, v30, v31
	v_add_f32_e32 v236, v236, v237
	v_add_f32_e32 v237, v238, v239
	v_add_f32_e32 v28, v236, v237
	v_add_u32_e32 v146, 0xa0000, v159
	global_store_dwordx4 v146, v[24:27], s[28:29]
	ds_write_b128 v156, v[12:15]
	ds_write_b128 v156, v[8:11] offset:64
	ds_read_b128 v[8:11], v157
	ds_read_b128 v[12:15], v157 offset:16
	s_waitcnt vmcnt(21) lgkmcnt(4)
	v_lshlrev_b32_e32 v236, 16, v216
	v_and_b32_e32 v237, 0xffff0000, v216
	v_lshlrev_b32_e32 v238, 16, v217
	v_and_b32_e32 v239, 0xffff0000, v217
	v_lshlrev_b32_e32 v240, 16, v218
	v_and_b32_e32 v241, 0xffff0000, v218
	v_lshlrev_b32_e32 v242, 16, v219
	v_and_b32_e32 v243, 0xffff0000, v219
	v_pk_add_f32 v[16:17], v[16:17], v[236:237]
	v_pk_add_f32 v[18:19], v[18:19], v[238:239]
	v_pk_add_f32 v[20:21], v[20:21], v[240:241]
	v_pk_add_f32 v[22:23], v[22:23], v[242:243]
	v_mul_f32_e32 v236, v17, v17
	v_mul_f32_e32 v237, v19, v19
	v_mul_f32_e32 v238, v21, v21
	v_mul_f32_e32 v239, v23, v23
	v_fmac_f32_e32 v236, v16, v16
	v_fmac_f32_e32 v237, v18, v18
	v_fmac_f32_e32 v238, v20, v20
	v_fmac_f32_e32 v239, v22, v22
	v_cvt_pk_bf16_f32 v16, v16, v17
	v_cvt_pk_bf16_f32 v17, v18, v19
	v_cvt_pk_bf16_f32 v18, v20, v21
	v_cvt_pk_bf16_f32 v19, v22, v23
	v_add_f32_e32 v236, v236, v237
	v_add_f32_e32 v237, v238, v239
	v_add_f32_e32 v20, v236, v237
	global_store_dwordx4 v146, v[16:19], s[28:29] offset:64
	v_add_f32_e32 v21, v28, v20
	s_nop 1
	v_add_f32_dpp v22, v21, v21 quad_perm:[1,0,3,2] row_mask:0xf bank_mask:0xf
	s_nop 1
	v_add_f32_dpp v23, v22, v22 quad_perm:[2,3,0,1] row_mask:0xf bank_mask:0xf
	v_mul_f32_e32 v30, 0x49800000, v23
	v_trunc_f32_e32 v30, v30
	v_mul_f32_e32 v31, 0x2f800000, v30
	v_floor_f32_e32 v31, v31
	v_fmac_f32_e32 v30, 0xcf800000, v31
	v_cvt_u32_f32_e32 v30, v30
	v_cvt_u32_f32_e32 v31, v31
	s_mov_b64 exec, s[8:9]
	global_atomic_add_x2 v208, v[30:31], s[12:13] offset:1280
	s_mov_b64 exec, -1
	ds_write_b128 v156, v[4:7]
	ds_write_b128 v156, v[0:3] offset:64
	ds_read_b128 v[0:3], v157
	ds_read_b128 v[4:7], v157 offset:16
	s_waitcnt vmcnt(22) lgkmcnt(4)
	v_lshlrev_b32_e32 v236, 16, v220
	v_and_b32_e32 v237, 0xffff0000, v220
	v_lshlrev_b32_e32 v238, 16, v221
	v_and_b32_e32 v239, 0xffff0000, v221
	v_lshlrev_b32_e32 v240, 16, v222
	v_and_b32_e32 v241, 0xffff0000, v222
	v_lshlrev_b32_e32 v242, 16, v223
	v_and_b32_e32 v243, 0xffff0000, v223
	v_pk_add_f32 v[8:9], v[8:9], v[236:237]
	v_pk_add_f32 v[10:11], v[10:11], v[238:239]
	v_pk_add_f32 v[12:13], v[12:13], v[240:241]
	v_pk_add_f32 v[14:15], v[14:15], v[242:243]
	v_mul_f32_e32 v236, v9, v9
	v_mul_f32_e32 v237, v11, v11
	v_mul_f32_e32 v238, v13, v13
	v_mul_f32_e32 v239, v15, v15
	v_fmac_f32_e32 v236, v8, v8
	v_fmac_f32_e32 v237, v10, v10
	v_fmac_f32_e32 v238, v12, v12
	v_fmac_f32_e32 v239, v14, v14
	v_cvt_pk_bf16_f32 v8, v8, v9
	v_cvt_pk_bf16_f32 v9, v10, v11
	v_cvt_pk_bf16_f32 v10, v12, v13
	v_cvt_pk_bf16_f32 v11, v14, v15
	v_add_f32_e32 v236, v236, v237
	v_add_f32_e32 v237, v238, v239
	v_add_f32_e32 v12, v236, v237
	v_add_u32_e32 v147, 0xb0000, v159
	global_store_dwordx4 v147, v[8:11], s[28:29]
	s_waitcnt vmcnt(22) lgkmcnt(0)
	v_lshlrev_b32_e32 v236, 16, v224
	v_and_b32_e32 v237, 0xffff0000, v224
	v_lshlrev_b32_e32 v238, 16, v225
	v_and_b32_e32 v239, 0xffff0000, v225
	v_lshlrev_b32_e32 v240, 16, v226
	v_and_b32_e32 v241, 0xffff0000, v226
	v_lshlrev_b32_e32 v242, 16, v227
	v_and_b32_e32 v243, 0xffff0000, v227
	v_pk_add_f32 v[0:1], v[0:1], v[236:237]
	v_pk_add_f32 v[2:3], v[2:3], v[238:239]
	v_pk_add_f32 v[4:5], v[4:5], v[240:241]
	v_pk_add_f32 v[6:7], v[6:7], v[242:243]
	v_mul_f32_e32 v236, v1, v1
	v_mul_f32_e32 v237, v3, v3
	v_mul_f32_e32 v238, v5, v5
	v_mul_f32_e32 v239, v7, v7
	v_fmac_f32_e32 v236, v0, v0
	v_fmac_f32_e32 v237, v2, v2
	v_fmac_f32_e32 v238, v4, v4
	v_fmac_f32_e32 v239, v6, v6
	v_cvt_pk_bf16_f32 v0, v0, v1
	v_cvt_pk_bf16_f32 v1, v2, v3
	v_cvt_pk_bf16_f32 v2, v4, v5
	v_cvt_pk_bf16_f32 v3, v6, v7
	v_add_f32_e32 v236, v236, v237
	v_add_f32_e32 v237, v238, v239
	v_add_f32_e32 v4, v236, v237
	global_store_dwordx4 v147, v[0:3], s[28:29] offset:64
	v_add_f32_e32 v5, v12, v4
	s_nop 1
	v_add_f32_dpp v6, v5, v5 quad_perm:[1,0,3,2] row_mask:0xf bank_mask:0xf
	s_nop 1
	v_add_f32_dpp v7, v6, v6 quad_perm:[2,3,0,1] row_mask:0xf bank_mask:0xf
	v_mul_f32_e32 v14, 0x49800000, v7
	v_trunc_f32_e32 v14, v14
	v_mul_f32_e32 v15, 0x2f800000, v14
	v_floor_f32_e32 v15, v15
	v_fmac_f32_e32 v14, 0xcf800000, v15
	v_cvt_u32_f32_e32 v14, v14
	v_cvt_u32_f32_e32 v15, v15
	s_mov_b64 exec, s[8:9]
	global_atomic_add_x2 v208, v[14:15], s[12:13] offset:1408
	s_mov_b64 exec, -1
	s_andn2_b64 vcc, exec, s[10:11]
	s_mov_b64 s[10:11], -1
	s_cbranch_vccnz .LBB0_759
	s_andn2_b64 vcc, exec, s[44:45]
	s_cbranch_vccnz .LBB0_758
	s_mov_b32 s98, 1
	s_branch .LBB0_758

; #define PG8_STAGE(bufoff, gbase, voff) do { _Pragma("unroll") for (int _i = 0; _i < 2; ++_i) \
;         __builtin_amdgcn_global_load_lds((const unsigned*)((const char*)(gbase) + (voff)[_i]), (PG8_LAS unsigned*)(lds + (bufoff) + ldsw + _i * 8192), 16, 0, 0); } while (0)
; #define PG8_LDA(dst, b, h) do { _Pragma("unroll") for (int m = 0; m < 4; ++m) _Pragma("unroll") for (int k = 0; k < 2; ++k) dst[m][k] = *(const PG8_LAS bf16x8*)(lds + PG8_SA(b, h) + aoff + m * 2048 + k * 1024); } while (0)
; #define PG8_LDB(dst, b, h) do { _Pragma("unroll") for (int n = 0; n < 2; ++n) _Pragma("unroll") for (int k = 0; k < 2; ++k) dst[n][k] = *(const PG8_LAS bf16x8*)(lds + PG8_SB(b, h) + boff + n * 2048 + k * 1024); } while (0)
; #define PG8_SCHED __builtin_amdgcn_sched_barrier(0)
; template <class Epi, class Sched, bool ALIGN_EPI = false, bool SP2 = false>
; __device__ __forceinline__ void gemm_phase(PG8_LAS unsigned char* lds, const Gemm g, const Sched& S, const Epi& E, int tid_in) {
;     ...
;         const bool has_next = S.next(ui + 1, nxt);
;         const char* nA = has_next ? (const char*)g.A + (size_t)nxt.pm * tstep : cA; const char* nB = has_next ? (const char*)g.Bt + (size_t)nxt.pn * tstepB : cB;
;         for (int t = 0; t < nt; t += 2) {
;             const bool last = (t == nt - 2);
;             const char* a1 = cA + (size_t)(t + 1) * kstep;
;             const char* a2 = last ? nA : cA + (size_t)(t + 2) * kstep; const char* b2 = last ? nB : cB + (size_t)(t + 2) * kstep;
;             const char* a3 = a2 + kstep; const char* b3 = b2 + kstep;
;             if (last && has_next) S.a_ready(nxt);
;             if constexpr (SP2) {
;             PG8_LDB(B0, 0, 0); PG8_LDB(B1, 0, 1); PG8_SCHED; PG8_LDA(At, 0, 0); PG8_STAGE(PG8_SA(1, 1), a1 + hstep, voffA);
;     ...
; #pragma unroll
;         for (int a = 0; a < 2; ++a)
; #pragma unroll
;             for (int b = 0; b < 2; ++b)
; #pragma unroll
;                 for (int m = 0; m < 4; ++m)
; #pragma unroll
;                     for (int n = 0; n < 2; ++n) acc[a][b][m][n] = (f32x4){0.f, 0.f, 0.f, 0.f};
;         cur = nxt; cA = nA; cB = nB; ++ui;
.LBB0_868:
	s_ashr_i32 s41, s40, 31
	s_lshl_b64 s[26:27], s[40:41], 20
	s_add_u32 s44, s28, s26
	s_addc_u32 s45, s29, s27
	s_and_b64 s[26:27], s[8:9], exec
	s_cselect_b32 s41, s45, s51
	s_cselect_b32 s68, s44, s50
	s_ashr_i32 s39, s38, 31
	s_lshl_b64 s[26:27], s[38:39], 20
	s_add_u32 s46, s42, s26
	s_addc_u32 s47, s43, s27
	s_and_b64 s[26:27], s[8:9], exec
	s_cselect_b32 s39, s47, s53
	s_cselect_b32 s69, s46, s52
	s_add_u32 s50, s50, 0x80080
	s_addc_u32 s51, s51, 0
	s_add_u32 s70, s52, 0x100
	v_mov_b32_e32 v0, 0
	s_addc_u32 s71, s53, 0
	s_mov_b32 s72, -2
	v_mov_b32_e32 v1, v0
	v_mov_b32_e32 v2, v0
	v_mov_b32_e32 v3, v0
	v_mov_b32_e32 v4, v0
	v_mov_b32_e32 v5, v0
	v_mov_b32_e32 v6, v0
	v_mov_b32_e32 v7, v0
	v_mov_b32_e32 v16, v0
	v_mov_b32_e32 v17, v0
	v_mov_b32_e32 v18, v0
	v_mov_b32_e32 v19, v0
	v_mov_b32_e32 v20, v0
	v_mov_b32_e32 v21, v0
	v_mov_b32_e32 v22, v0
	v_mov_b32_e32 v23, v0
	v_mov_b32_e32 v32, v0
	v_mov_b32_e32 v33, v0
	v_mov_b32_e32 v34, v0
	v_mov_b32_e32 v35, v0
	v_mov_b32_e32 v36, v0
	v_mov_b32_e32 v37, v0
	v_mov_b32_e32 v38, v0
	v_mov_b32_e32 v39, v0
	v_mov_b32_e32 v48, v0
	v_mov_b32_e32 v49, v0
	v_mov_b32_e32 v50, v0
	v_mov_b32_e32 v51, v0
	v_mov_b32_e32 v52, v0
	v_mov_b32_e32 v53, v0
	v_mov_b32_e32 v54, v0
	v_mov_b32_e32 v55, v0
	v_mov_b32_e32 v8, v0
	v_mov_b32_e32 v9, v0
	v_mov_b32_e32 v10, v0
	v_mov_b32_e32 v11, v0
	v_mov_b32_e32 v12, v0
	v_mov_b32_e32 v13, v0
	v_mov_b32_e32 v14, v0
	v_mov_b32_e32 v15, v0
	v_mov_b32_e32 v24, v0
	v_mov_b32_e32 v25, v0
	v_mov_b32_e32 v26, v0
	v_mov_b32_e32 v27, v0
	v_mov_b32_e32 v28, v0
	v_mov_b32_e32 v29, v0
	v_mov_b32_e32 v30, v0
	v_mov_b32_e32 v31, v0
	v_mov_b32_e32 v40, v0
	v_mov_b32_e32 v41, v0
	v_mov_b32_e32 v42, v0
	v_mov_b32_e32 v43, v0
	v_mov_b32_e32 v44, v0
	v_mov_b32_e32 v45, v0
	v_mov_b32_e32 v46, v0
	v_mov_b32_e32 v47, v0
	v_mov_b32_e32 v56, v0
	v_mov_b32_e32 v57, v0
	v_mov_b32_e32 v58, v0
	v_mov_b32_e32 v59, v0
	v_mov_b32_e32 v60, v0
	v_mov_b32_e32 v61, v0
	v_mov_b32_e32 v62, v0
	v_mov_b32_e32 v63, v0
	v_mov_b32_e32 v64, v0
	v_mov_b32_e32 v65, v0
	v_mov_b32_e32 v66, v0
	v_mov_b32_e32 v67, v0
	v_mov_b32_e32 v68, v0
	v_mov_b32_e32 v69, v0
	v_mov_b32_e32 v70, v0
	v_mov_b32_e32 v71, v0
	v_mov_b32_e32 v80, v0
	v_mov_b32_e32 v81, v0
	v_mov_b32_e32 v82, v0
	v_mov_b32_e32 v83, v0
	v_mov_b32_e32 v84, v0
	v_mov_b32_e32 v85, v0
	v_mov_b32_e32 v86, v0
	v_mov_b32_e32 v87, v0
	v_mov_b32_e32 v96, v0
	v_mov_b32_e32 v97, v0
	v_mov_b32_e32 v98, v0
	v_mov_b32_e32 v99, v0
	v_mov_b32_e32 v100, v0
	v_mov_b32_e32 v101, v0
	v_mov_b32_e32 v102, v0
	v_mov_b32_e32 v103, v0
	v_mov_b32_e32 v112, v0
	v_mov_b32_e32 v113, v0
	v_mov_b32_e32 v114, v0
	v_mov_b32_e32 v115, v0
	v_mov_b32_e32 v116, v0
	v_mov_b32_e32 v117, v0
	v_mov_b32_e32 v118, v0
	v_mov_b32_e32 v119, v0
	v_mov_b32_e32 v72, v0
	v_mov_b32_e32 v73, v0
	v_mov_b32_e32 v74, v0
	v_mov_b32_e32 v75, v0
	v_mov_b32_e32 v76, v0
	v_mov_b32_e32 v77, v0
	v_mov_b32_e32 v78, v0
	v_mov_b32_e32 v79, v0
	v_mov_b32_e32 v88, v0
	v_mov_b32_e32 v89, v0
	v_mov_b32_e32 v90, v0
	v_mov_b32_e32 v91, v0
	v_mov_b32_e32 v92, v0
	v_mov_b32_e32 v93, v0
	v_mov_b32_e32 v94, v0
	v_mov_b32_e32 v95, v0
	v_mov_b32_e32 v104, v0
	v_mov_b32_e32 v105, v0
	v_mov_b32_e32 v106, v0
	v_mov_b32_e32 v107, v0
	v_mov_b32_e32 v108, v0
	v_mov_b32_e32 v109, v0
	v_mov_b32_e32 v110, v0
	v_mov_b32_e32 v111, v0
	v_mov_b32_e32 v120, v0
	v_mov_b32_e32 v121, v0
	v_mov_b32_e32 v122, v0
	v_mov_b32_e32 v123, v0
	v_mov_b32_e32 v124, v0
	v_mov_b32_e32 v125, v0
	v_mov_b32_e32 v126, v0
	v_mov_b32_e32 v127, v0
	s_cmp_eq_u32 s98, 1
	s_cbranch_scc0 .Lkb_skip_6
	s_mov_b32 s98, 0
	s_barrier
.Lkb_skip_6:
.LBB0_869:
	ds_read_b128 v[156:159], v150
	ds_read_b128 v[160:163], v150 offset:1024
	ds_read_b128 v[164:167], v150 offset:2048
	ds_read_b128 v[168:171], v150 offset:3072
	ds_read_b128 v[172:175], v151
	ds_read_b128 v[176:179], v151 offset:1024
	ds_read_b128 v[180:183], v151 offset:2048
	ds_read_b128 v[184:187], v151 offset:3072
	s_add_u32 s26, s50, 0xfff80080
	s_addc_u32 s27, s51, -1
	s_cmp_eq_u32 s72, 28
	s_cselect_b32 s55, s41, s27
	s_cselect_b32 s54, s68, s26
	s_cselect_b32 s53, s39, s71
	s_cselect_b32 s52, s69, s70
	v_lshl_add_u64 v[220:221], s[50:51], 0, v[138:139]
	s_add_i32 m0, s49, 0xc000
	ds_read_b128 v[188:191], v152
	ds_read_b128 v[192:195], v152 offset:1024
	ds_read_b128 v[196:199], v152 offset:2048
	ds_read_b128 v[200:203], v152 offset:3072
	ds_read_b128 v[204:207], v152 offset:4096
	ds_read_b128 v[208:211], v152 offset:5120
	ds_read_b128 v[212:215], v152 offset:6144
	ds_read_b128 v[216:219], v152 offset:7168
	global_load_lds_dwordx4 v[220:221], off
	v_lshl_add_u64 v[220:221], s[50:51], 0, v[140:141]
	s_add_i32 m0, s49, 0xe000
	s_nop 0
	global_load_lds_dwordx4 v[220:221], off
	s_waitcnt vmcnt(8)
	s_waitcnt lgkmcnt(0)
	s_barrier
; #define PG8_STAGE(bufoff, gbase, voff) do { _Pragma("unroll") for (int _i = 0; _i < 2; ++_i) \
;         __builtin_amdgcn_global_load_lds((const unsigned*)((const char*)(gbase) + (voff)[_i]), (PG8_LAS unsigned*)(lds + (bufoff) + ldsw + _i * 8192), 16, 0, 0); } while (0)
; #define PG8_LDA(dst, b, h) do { _Pragma("unroll") for (int m = 0; m < 4; ++m) _Pragma("unroll") for (int k = 0; k < 2; ++k) dst[m][k] = *(const PG8_LAS bf16x8*)(lds + PG8_SA(b, h) + aoff + m * 2048 + k * 1024); } while (0)
; #define PG8_MMA(ai, bj, At, Bt) do { __builtin_amdgcn_s_setprio(1); _Pragma("unroll") for (int m = 0; m < 4; ++m) _Pragma("unroll") for (int n = 0; n < 2; ++n) _Pragma("unroll") for (int k = 0; k < 2; ++k) \
;         acc[ai][bj][m][n] = __builtin_amdgcn_mfma_f32_16x16x32_bf16(Bt[n][k], At[m][k], acc[ai][bj][m][n], 0, 0, 0); __builtin_amdgcn_s_setprio(0); } while (0)
; #define PG8_WAIT_V(n) asm volatile("s_waitcnt vmcnt(" #n ")" ::: "memory")
; #define PG8_WAIT_L(n) asm volatile("s_waitcnt lgkmcnt(" #n ")" ::: "memory")
; #define PG8_BAR __builtin_amdgcn_s_barrier()
; #define PG8_SCHED __builtin_amdgcn_sched_barrier(0)
; template <class Epi, class Sched, bool ALIGN_EPI = false, bool SP2 = false>
; __device__ __forceinline__ void gemm_phase(PG8_LAS unsigned char* lds, const Gemm g, const Sched& S, const Epi& E, int tid_in) {
;     ...
;             PG8_WAIT_V(8); PG8_WAIT_L(0); PG8_BAR; PG8_MMA(0, 0, At, B0); PG8_MMA(0, 1, At, B1); PG8_BAR; PG8_SCHED;
;             PG8_LDA(At, 0, 1); PG8_STAGE(PG8_SB(0, 0), b2, voffB); PG8_STAGE(PG8_SB(0, 1), b2 + hstepB, voffB); PG8_STAGE(PG8_SA(0, 0), a2, voffA);
;             PG8_WAIT_V(8); PG8_WAIT_L(0); PG8_BAR; PG8_MMA(1, 0, At, B0); PG8_MMA(1, 1, At, B1); PG8_BAR; PG8_SCHED;
	s_setprio 1
	s_waitcnt lgkmcnt(0)
	v_mfma_f32_16x16x32_bf16 v[124:127], v[156:159], v[188:191], v[124:127]
	v_mfma_f32_16x16x32_bf16 v[120:123], v[164:167], v[188:191], v[120:123]
	v_mfma_f32_16x16x32_bf16 v[108:111], v[156:159], v[196:199], v[108:111]
	v_mfma_f32_16x16x32_bf16 v[104:107], v[164:167], v[196:199], v[104:107]
	v_mfma_f32_16x16x32_bf16 v[92:95], v[156:159], v[204:207], v[92:95]
	v_mfma_f32_16x16x32_bf16 v[88:91], v[164:167], v[204:207], v[88:91]
	v_mfma_f32_16x16x32_bf16 v[76:79], v[156:159], v[212:215], v[76:79]
	v_mfma_f32_16x16x32_bf16 v[72:75], v[164:167], v[212:215], v[72:75]
	v_mfma_f32_16x16x32_bf16 v[124:127], v[160:163], v[192:195], v[124:127]
	v_mfma_f32_16x16x32_bf16 v[120:123], v[168:171], v[192:195], v[120:123]
	v_mfma_f32_16x16x32_bf16 v[108:111], v[160:163], v[200:203], v[108:111]
	v_mfma_f32_16x16x32_bf16 v[104:107], v[168:171], v[200:203], v[104:107]
	v_mfma_f32_16x16x32_bf16 v[92:95], v[160:163], v[208:211], v[92:95]
	v_mfma_f32_16x16x32_bf16 v[88:91], v[168:171], v[208:211], v[88:91]
	v_mfma_f32_16x16x32_bf16 v[76:79], v[160:163], v[216:219], v[76:79]
	v_mfma_f32_16x16x32_bf16 v[72:75], v[168:171], v[216:219], v[72:75]
	s_setprio 0
	s_setprio 1
	v_mfma_f32_16x16x32_bf16 v[116:119], v[172:175], v[188:191], v[116:119]
	v_mfma_f32_16x16x32_bf16 v[112:115], v[180:183], v[188:191], v[112:115]
	v_mfma_f32_16x16x32_bf16 v[100:103], v[172:175], v[196:199], v[100:103]
	v_mfma_f32_16x16x32_bf16 v[96:99], v[180:183], v[196:199], v[96:99]
	v_mfma_f32_16x16x32_bf16 v[84:87], v[172:175], v[204:207], v[84:87]
	v_mfma_f32_16x16x32_bf16 v[80:83], v[180:183], v[204:207], v[80:83]
	v_mfma_f32_16x16x32_bf16 v[68:71], v[172:175], v[212:215], v[68:71]
	v_mfma_f32_16x16x32_bf16 v[64:67], v[180:183], v[212:215], v[64:67]
	v_mfma_f32_16x16x32_bf16 v[116:119], v[176:179], v[192:195], v[116:119]
	v_mfma_f32_16x16x32_bf16 v[112:115], v[184:187], v[192:195], v[112:115]
	v_mfma_f32_16x16x32_bf16 v[100:103], v[176:179], v[200:203], v[100:103]
	v_mfma_f32_16x16x32_bf16 v[96:99], v[184:187], v[200:203], v[96:99]
	v_mfma_f32_16x16x32_bf16 v[84:87], v[176:179], v[208:211], v[84:87]
	v_mfma_f32_16x16x32_bf16 v[80:83], v[184:187], v[208:211], v[80:83]
	v_mfma_f32_16x16x32_bf16 v[68:71], v[176:179], v[216:219], v[68:71]
	v_mfma_f32_16x16x32_bf16 v[64:67], v[184:187], v[216:219], v[64:67]
	s_setprio 0
	s_barrier
	s_add_i32 s26, s64, s56
	v_lshl_add_u64 v[220:221], s[52:53], 0, v[130:131]
	s_mov_b32 m0, s26
	ds_read_b128 v[188:191], v152 offset:16384
	ds_read_b128 v[192:195], v152 offset:17408
	ds_read_b128 v[196:199], v152 offset:18432
	ds_read_b128 v[200:203], v152 offset:19456
	ds_read_b128 v[204:207], v152 offset:20480
	ds_read_b128 v[208:211], v152 offset:21504
	ds_read_b128 v[212:215], v152 offset:22528
	ds_read_b128 v[216:219], v152 offset:23552
	global_load_lds_dwordx4 v[220:221], off
	s_add_i32 m0, s26, 0x2000
	s_add_u32 s26, s52, 0x20000
	v_lshl_add_u64 v[222:223], s[52:53], 0, v[134:135]
	s_addc_u32 s27, s53, 0
	s_add_i32 s33, s65, s56
	global_load_lds_dwordx4 v[222:223], off
	v_lshl_add_u64 v[224:225], s[26:27], 0, v[130:131]
	s_mov_b32 m0, s33
	v_lshl_add_u64 v[226:227], s[54:55], 0, v[132:133]
	global_load_lds_dwordx4 v[224:225], off
	v_lshl_add_u64 v[224:225], s[26:27], 0, v[134:135]
	s_add_i32 m0, s33, 0x2000
	s_nop 0
	global_load_lds_dwordx4 v[224:225], off
	v_lshl_add_u64 v[224:225], s[54:55], 0, v[128:129]
	s_mov_b32 m0, s49
	s_nop 0
	global_load_lds_dwordx4 v[224:225], off
	s_mov_b32 m0, s57
	s_nop 0
	global_load_lds_dwordx4 v[226:227], off
	s_waitcnt vmcnt(8)
	s_waitcnt lgkmcnt(0)
	s_barrier
	s_setprio 1
	s_waitcnt lgkmcnt(0)
	v_mfma_f32_16x16x32_bf16 v[60:63], v[156:159], v[188:191], v[60:63]
	v_mfma_f32_16x16x32_bf16 v[56:59], v[164:167], v[188:191], v[56:59]
	v_mfma_f32_16x16x32_bf16 v[44:47], v[156:159], v[196:199], v[44:47]
	v_mfma_f32_16x16x32_bf16 v[40:43], v[164:167], v[196:199], v[40:43]
	v_mfma_f32_16x16x32_bf16 v[28:31], v[156:159], v[204:207], v[28:31]
	v_mfma_f32_16x16x32_bf16 v[24:27], v[164:167], v[204:207], v[24:27]
	v_mfma_f32_16x16x32_bf16 v[12:15], v[156:159], v[212:215], v[12:15]
	v_mfma_f32_16x16x32_bf16 v[8:11], v[164:167], v[212:215], v[8:11]
	v_mfma_f32_16x16x32_bf16 v[60:63], v[160:163], v[192:195], v[60:63]
	v_mfma_f32_16x16x32_bf16 v[56:59], v[168:171], v[192:195], v[56:59]
	v_mfma_f32_16x16x32_bf16 v[44:47], v[160:163], v[200:203], v[44:47]
	v_mfma_f32_16x16x32_bf16 v[40:43], v[168:171], v[200:203], v[40:43]
	v_mfma_f32_16x16x32_bf16 v[28:31], v[160:163], v[208:211], v[28:31]
	v_mfma_f32_16x16x32_bf16 v[24:27], v[168:171], v[208:211], v[24:27]
	v_mfma_f32_16x16x32_bf16 v[12:15], v[160:163], v[216:219], v[12:15]
	v_mfma_f32_16x16x32_bf16 v[8:11], v[168:171], v[216:219], v[8:11]
	s_setprio 0
	s_setprio 1
	v_mfma_f32_16x16x32_bf16 v[52:55], v[172:175], v[188:191], v[52:55]
	v_mfma_f32_16x16x32_bf16 v[48:51], v[180:183], v[188:191], v[48:51]
	v_mfma_f32_16x16x32_bf16 v[36:39], v[172:175], v[196:199], v[36:39]
	v_mfma_f32_16x16x32_bf16 v[32:35], v[180:183], v[196:199], v[32:35]
	v_mfma_f32_16x16x32_bf16 v[20:23], v[172:175], v[204:207], v[20:23]
	v_mfma_f32_16x16x32_bf16 v[16:19], v[180:183], v[204:207], v[16:19]
	v_mfma_f32_16x16x32_bf16 v[4:7], v[172:175], v[212:215], v[4:7]
	v_mfma_f32_16x16x32_bf16 v[0:3], v[180:183], v[212:215], v[0:3]
	v_mfma_f32_16x16x32_bf16 v[52:55], v[176:179], v[192:195], v[52:55]
	v_mfma_f32_16x16x32_bf16 v[48:51], v[184:187], v[192:195], v[48:51]
	v_mfma_f32_16x16x32_bf16 v[36:39], v[176:179], v[200:203], v[36:39]
	v_mfma_f32_16x16x32_bf16 v[32:35], v[184:187], v[200:203], v[32:35]
	v_mfma_f32_16x16x32_bf16 v[20:23], v[176:179], v[208:211], v[20:23]
	v_mfma_f32_16x16x32_bf16 v[16:19], v[184:187], v[208:211], v[16:19]
	v_mfma_f32_16x16x32_bf16 v[4:7], v[176:179], v[216:219], v[4:7]
	v_mfma_f32_16x16x32_bf16 v[0:3], v[184:187], v[216:219], v[0:3]
	s_setprio 0
	s_barrier
; #define PG8_STAGE(bufoff, gbase, voff) do { _Pragma("unroll") for (int _i = 0; _i < 2; ++_i) \
;         __builtin_amdgcn_global_load_lds((const unsigned*)((const char*)(gbase) + (voff)[_i]), (PG8_LAS unsigned*)(lds + (bufoff) + ldsw + _i * 8192), 16, 0, 0); } while (0)
; #define PG8_LDA(dst, b, h) do { _Pragma("unroll") for (int m = 0; m < 4; ++m) _Pragma("unroll") for (int k = 0; k < 2; ++k) dst[m][k] = *(const PG8_LAS bf16x8*)(lds + PG8_SA(b, h) + aoff + m * 2048 + k * 1024); } while (0)
; #define PG8_LDB(dst, b, h) do { _Pragma("unroll") for (int n = 0; n < 2; ++n) _Pragma("unroll") for (int k = 0; k < 2; ++k) dst[n][k] = *(const PG8_LAS bf16x8*)(lds + PG8_SB(b, h) + boff + n * 2048 + k * 1024); } while (0)
; #define PG8_MMA(ai, bj, At, Bt) do { __builtin_amdgcn_s_setprio(1); _Pragma("unroll") for (int m = 0; m < 4; ++m) _Pragma("unroll") for (int n = 0; n < 2; ++n) _Pragma("unroll") for (int k = 0; k < 2; ++k) \
;         acc[ai][bj][m][n] = __builtin_amdgcn_mfma_f32_16x16x32_bf16(Bt[n][k], At[m][k], acc[ai][bj][m][n], 0, 0, 0); __builtin_amdgcn_s_setprio(0); } while (0)
; #define PG8_WAIT_V(n) asm volatile("s_waitcnt vmcnt(" #n ")" ::: "memory")
; #define PG8_WAIT_L(n) asm volatile("s_waitcnt lgkmcnt(" #n ")" ::: "memory")
; #define PG8_BAR __builtin_amdgcn_s_barrier()
; #define PG8_SCHED __builtin_amdgcn_sched_barrier(0)
; template <class Epi, class Sched, bool ALIGN_EPI = false, bool SP2 = false>
; __device__ __forceinline__ void gemm_phase(PG8_LAS unsigned char* lds, const Gemm g, const Sched& S, const Epi& E, int tid_in) {
;     ...
;             PG8_LDB(B0, 1, 0); PG8_LDB(B1, 1, 1); PG8_SCHED; PG8_LDA(At, 1, 0); PG8_STAGE(PG8_SA(0, 1), a2 + hstep, voffA);
;             PG8_WAIT_V(8); PG8_WAIT_L(0); PG8_BAR; PG8_MMA(0, 0, At, B0); PG8_MMA(0, 1, At, B1); PG8_BAR; PG8_SCHED;
;             PG8_LDA(At, 1, 1); PG8_STAGE(PG8_SB(1, 0), b3, voffB); PG8_STAGE(PG8_SB(1, 1), b3 + hstepB, voffB); PG8_STAGE(PG8_SA(1, 0), a3, voffA);
	s_add_i32 s33, 0, 0x18000
	v_add_u32_e32 v155, s33, v146
	s_add_i32 s73, 0, 0x1c000
	ds_read_b128 v[156:159], v155
	ds_read_b128 v[160:163], v155 offset:1024
	ds_read_b128 v[164:167], v155 offset:2048
	ds_read_b128 v[168:171], v155 offset:3072
	v_add_u32_e32 v155, s73, v146
	ds_read_b128 v[172:175], v155
	ds_read_b128 v[176:179], v155 offset:1024
	ds_read_b128 v[180:183], v155 offset:2048
	ds_read_b128 v[184:187], v155 offset:3072
	s_add_u32 s26, s54, 0x80000
	s_addc_u32 s27, s55, 0
	s_mov_b32 m0, s58
	v_lshl_add_u64 v[228:229], s[26:27], 0, v[128:129]
	ds_read_b128 v[188:191], v152 offset:32768
	ds_read_b128 v[192:195], v152 offset:33792
	ds_read_b128 v[196:199], v152 offset:34816
	ds_read_b128 v[200:203], v152 offset:35840
	ds_read_b128 v[204:207], v152 offset:36864
	ds_read_b128 v[208:211], v152 offset:37888
	ds_read_b128 v[212:215], v152 offset:38912
	ds_read_b128 v[216:219], v152 offset:39936
	global_load_lds_dwordx4 v[228:229], off
	v_lshl_add_u64 v[228:229], s[26:27], 0, v[132:133]
	s_mov_b32 m0, s59
	s_nop 0
	global_load_lds_dwordx4 v[228:229], off
	s_waitcnt vmcnt(8)
	s_waitcnt lgkmcnt(0)
	s_barrier
	s_setprio 1
	s_waitcnt lgkmcnt(0)
	v_mfma_f32_16x16x32_bf16 v[124:127], v[156:159], v[188:191], v[124:127]
	v_mfma_f32_16x16x32_bf16 v[120:123], v[164:167], v[188:191], v[120:123]
	v_mfma_f32_16x16x32_bf16 v[108:111], v[156:159], v[196:199], v[108:111]
	v_mfma_f32_16x16x32_bf16 v[104:107], v[164:167], v[196:199], v[104:107]
	v_mfma_f32_16x16x32_bf16 v[92:95], v[156:159], v[204:207], v[92:95]
	v_mfma_f32_16x16x32_bf16 v[88:91], v[164:167], v[204:207], v[88:91]
	v_mfma_f32_16x16x32_bf16 v[76:79], v[156:159], v[212:215], v[76:79]
	v_mfma_f32_16x16x32_bf16 v[72:75], v[164:167], v[212:215], v[72:75]
	v_mfma_f32_16x16x32_bf16 v[124:127], v[160:163], v[192:195], v[124:127]
	v_mfma_f32_16x16x32_bf16 v[120:123], v[168:171], v[192:195], v[120:123]
	v_mfma_f32_16x16x32_bf16 v[108:111], v[160:163], v[200:203], v[108:111]
	v_mfma_f32_16x16x32_bf16 v[104:107], v[168:171], v[200:203], v[104:107]
	v_mfma_f32_16x16x32_bf16 v[92:95], v[160:163], v[208:211], v[92:95]
	v_mfma_f32_16x16x32_bf16 v[88:91], v[168:171], v[208:211], v[88:91]
	v_mfma_f32_16x16x32_bf16 v[76:79], v[160:163], v[216:219], v[76:79]
	v_mfma_f32_16x16x32_bf16 v[72:75], v[168:171], v[216:219], v[72:75]
	s_setprio 0
	s_setprio 1
	v_mfma_f32_16x16x32_bf16 v[116:119], v[172:175], v[188:191], v[116:119]
	v_mfma_f32_16x16x32_bf16 v[112:115], v[180:183], v[188:191], v[112:115]
	v_mfma_f32_16x16x32_bf16 v[100:103], v[172:175], v[196:199], v[100:103]
	v_mfma_f32_16x16x32_bf16 v[96:99], v[180:183], v[196:199], v[96:99]
	v_mfma_f32_16x16x32_bf16 v[84:87], v[172:175], v[204:207], v[84:87]
	v_mfma_f32_16x16x32_bf16 v[80:83], v[180:183], v[204:207], v[80:83]
	v_mfma_f32_16x16x32_bf16 v[68:71], v[172:175], v[212:215], v[68:71]
	v_mfma_f32_16x16x32_bf16 v[64:67], v[180:183], v[212:215], v[64:67]
	v_mfma_f32_16x16x32_bf16 v[116:119], v[176:179], v[192:195], v[116:119]
	v_mfma_f32_16x16x32_bf16 v[112:115], v[184:187], v[192:195], v[112:115]
	v_mfma_f32_16x16x32_bf16 v[100:103], v[176:179], v[200:203], v[100:103]
	v_mfma_f32_16x16x32_bf16 v[96:99], v[184:187], v[200:203], v[96:99]
	v_mfma_f32_16x16x32_bf16 v[84:87], v[176:179], v[208:211], v[84:87]
	v_mfma_f32_16x16x32_bf16 v[80:83], v[184:187], v[208:211], v[80:83]
	v_mfma_f32_16x16x32_bf16 v[68:71], v[176:179], v[216:219], v[68:71]
	v_mfma_f32_16x16x32_bf16 v[64:67], v[184:187], v[216:219], v[64:67]
	s_setprio 0
	s_barrier
	s_add_i32 s26, s33, s56
	v_lshl_add_u64 v[220:221], v[220:221], 0, s[12:13]
	s_mov_b32 m0, s26
	ds_read_b128 v[188:191], v152 offset:49152
	ds_read_b128 v[192:195], v152 offset:50176
	ds_read_b128 v[196:199], v152 offset:51200
	ds_read_b128 v[200:203], v152 offset:52224
	ds_read_b128 v[204:207], v152 offset:53248
	ds_read_b128 v[208:211], v152 offset:54272
	ds_read_b128 v[212:215], v152 offset:55296
	ds_read_b128 v[216:219], v152 offset:56320
	global_load_lds_dwordx4 v[220:221], off
	s_add_i32 m0, s26, 0x2000
	s_add_u32 s26, s52, 0x20080
	v_lshl_add_u64 v[220:221], v[222:223], 0, s[12:13]
	s_addc_u32 s27, s53, 0
	s_add_i32 s33, s73, s56
	global_load_lds_dwordx4 v[220:221], off
	v_lshl_add_u64 v[220:221], s[26:27], 0, v[130:131]
	s_mov_b32 m0, s33
	s_nop 0
	global_load_lds_dwordx4 v[220:221], off
	v_lshl_add_u64 v[220:221], s[26:27], 0, v[134:135]
	s_add_i32 m0, s33, 0x2000
	s_nop 0
	global_load_lds_dwordx4 v[220:221], off
	v_lshl_add_u64 v[220:221], v[224:225], 0, s[12:13]
	s_mov_b32 m0, s62
	s_nop 0
	global_load_lds_dwordx4 v[220:221], off
	v_lshl_add_u64 v[220:221], v[226:227], 0, s[12:13]
	s_mov_b32 m0, s63
	s_nop 0
	global_load_lds_dwordx4 v[220:221], off
	s_waitcnt vmcnt(8)
	s_waitcnt lgkmcnt(0)
	s_barrier
; #define PG8_LAS __attribute__((address_space(3)))
; __device__ __forceinline__ unsigned cvt_pk_bf16(float lo, float hi) { unsigned r; asm volatile("v_cvt_pk_bf16_f32 %0, %1, %2" : "=v"(r) : "v"(lo), "v"(hi)); return r; }
; #define PG8_STAGE(bufoff, gbase, voff) do { _Pragma("unroll") for (int _i = 0; _i < 2; ++_i) \
;         __builtin_amdgcn_global_load_lds((const unsigned*)((const char*)(gbase) + (voff)[_i]), (PG8_LAS unsigned*)(lds + (bufoff) + ldsw + _i * 8192), 16, 0, 0); } while (0)
; #define PG8_LDA(dst, b, h) do { _Pragma("unroll") for (int m = 0; m < 4; ++m) _Pragma("unroll") for (int k = 0; k < 2; ++k) dst[m][k] = *(const PG8_LAS bf16x8*)(lds + PG8_SA(b, h) + aoff + m * 2048 + k * 1024); } while (0)
; #define PG8_WAIT_V(n) asm volatile("s_waitcnt vmcnt(" #n ")" ::: "memory")
; #define PG8_WAIT_L(n) asm volatile("s_waitcnt lgkmcnt(" #n ")" ::: "memory")
; #define PG8_BAR __builtin_amdgcn_s_barrier()
; template <class Epi, class Sched, bool ALIGN_EPI = false, bool SP2 = false>
; __device__ __forceinline__ void gemm_phase(PG8_LAS unsigned char* lds, const Gemm g, const Sched& S, const Epi& E, int tid_in) {
;     ...
;             PG8_WAIT_V(8); PG8_WAIT_L(0); PG8_BAR; PG8_MMA(0, 0, At, B0); PG8_MMA(0, 1, At, B1); PG8_BAR; PG8_SCHED;
;             PG8_LDA(At, 1, 1); PG8_STAGE(PG8_SB(1, 0), b3, voffB); PG8_STAGE(PG8_SB(1, 1), b3 + hstepB, voffB); PG8_STAGE(PG8_SA(1, 0), a3, voffA);
;             PG8_WAIT_V(8); PG8_WAIT_L(0); PG8_BAR; PG8_MMA(1, 0, At, B0); PG8_MMA(1, 1, At, B1); PG8_BAR; PG8_SCHED;
;     __device__ __forceinline__ void operator()(const f32x4 (&acc)[2][2][4][2], const Unit& u, int wr, int wc, int fr, int fq) const {
;     ...
;                 const int rowg0 = u.pm * BM + ai * HALF + wr * 64 + m * 16; const float rs = rtab[ai * HALF + wr * 64 + m * 16 + fr];
; #pragma unroll
;                 for (int bj = 0; bj < 2; ++bj) {
;                     f32x4 v0 = acc[ai][bj][m][0] * rs, v1 = acc[ai][bj][m][1] * rs;
;                     if (ACT == 1) { const f32x4 z = {0.f, 0.f, 0.f, 0.f}; v0 = __builtin_elementwise_max(v0, z); v1 = __builtin_elementwise_max(v1, z); v0 = v0 * v0; v1 = v1 * v1; }
;                     u32x4 w; w.x = cvt_pk_bf16(v0[0], v0[1]); w.y = cvt_pk_bf16(v0[2], v0[3]); w.z = cvt_pk_bf16(v1[0], v1[1]); w.w = cvt_pk_bf16(v1[2], v1[3]);
;                     *(PG8_LAS u32x4*)(stg + fr * STG_ROW + bj * 64 + fq * 16) = w; }
	s_setprio 1
	s_waitcnt lgkmcnt(0)
	v_mfma_f32_16x16x32_bf16 v[60:63], v[156:159], v[188:191], v[60:63]
	v_mfma_f32_16x16x32_bf16 v[56:59], v[164:167], v[188:191], v[56:59]
	v_mfma_f32_16x16x32_bf16 v[44:47], v[156:159], v[196:199], v[44:47]
	v_mfma_f32_16x16x32_bf16 v[40:43], v[164:167], v[196:199], v[40:43]
	v_mfma_f32_16x16x32_bf16 v[28:31], v[156:159], v[204:207], v[28:31]
	v_mfma_f32_16x16x32_bf16 v[24:27], v[164:167], v[204:207], v[24:27]
	v_mfma_f32_16x16x32_bf16 v[12:15], v[156:159], v[212:215], v[12:15]
	v_mfma_f32_16x16x32_bf16 v[8:11], v[164:167], v[212:215], v[8:11]
	v_mfma_f32_16x16x32_bf16 v[60:63], v[160:163], v[192:195], v[60:63]
	v_mfma_f32_16x16x32_bf16 v[56:59], v[168:171], v[192:195], v[56:59]
	v_mfma_f32_16x16x32_bf16 v[44:47], v[160:163], v[200:203], v[44:47]
	v_mfma_f32_16x16x32_bf16 v[40:43], v[168:171], v[200:203], v[40:43]
	v_mfma_f32_16x16x32_bf16 v[28:31], v[160:163], v[208:211], v[28:31]
	v_mfma_f32_16x16x32_bf16 v[24:27], v[168:171], v[208:211], v[24:27]
	v_mfma_f32_16x16x32_bf16 v[12:15], v[160:163], v[216:219], v[12:15]
	v_mfma_f32_16x16x32_bf16 v[8:11], v[168:171], v[216:219], v[8:11]
	s_setprio 0
	s_setprio 1
	v_mfma_f32_16x16x32_bf16 v[52:55], v[172:175], v[188:191], v[52:55]
	v_mfma_f32_16x16x32_bf16 v[48:51], v[180:183], v[188:191], v[48:51]
	v_mfma_f32_16x16x32_bf16 v[36:39], v[172:175], v[196:199], v[36:39]
	v_mfma_f32_16x16x32_bf16 v[32:35], v[180:183], v[196:199], v[32:35]
	v_mfma_f32_16x16x32_bf16 v[20:23], v[172:175], v[204:207], v[20:23]
	v_mfma_f32_16x16x32_bf16 v[16:19], v[180:183], v[204:207], v[16:19]
	v_mfma_f32_16x16x32_bf16 v[4:7], v[172:175], v[212:215], v[4:7]
	v_mfma_f32_16x16x32_bf16 v[0:3], v[180:183], v[212:215], v[0:3]
	v_mfma_f32_16x16x32_bf16 v[52:55], v[176:179], v[192:195], v[52:55]
	v_mfma_f32_16x16x32_bf16 v[48:51], v[184:187], v[192:195], v[48:51]
	v_mfma_f32_16x16x32_bf16 v[36:39], v[176:179], v[200:203], v[36:39]
	v_mfma_f32_16x16x32_bf16 v[32:35], v[184:187], v[200:203], v[32:35]
	v_mfma_f32_16x16x32_bf16 v[20:23], v[176:179], v[208:211], v[20:23]
	v_mfma_f32_16x16x32_bf16 v[16:19], v[184:187], v[208:211], v[16:19]
	v_mfma_f32_16x16x32_bf16 v[4:7], v[176:179], v[216:219], v[4:7]
	v_mfma_f32_16x16x32_bf16 v[0:3], v[184:187], v[216:219], v[0:3]
	s_setprio 0
	s_barrier
	s_add_i32 s72, s72, 2
	s_add_u32 s50, s50, 0x100
	s_addc_u32 s51, s51, 0
	s_add_u32 s70, s70, 0x100
	s_addc_u32 s71, s71, 0
	s_cmp_gt_u32 s72, 29
	s_cbranch_scc0 .LBB0_869
	s_and_b64 vcc, exec, s[36:37]
	s_cbranch_vccz .LBB0_872
	s_barrier
.LBB0_872:
	s_lshl_b32 s26, s48, 7
	s_and_b32 s26, s26, 0xc00
	v_add_u32_e32 v155, s26, v149
	ds_read_b32 v156, v155
	s_lshl_b32 s39, s48, 8
	s_lshl_b32 s26, s67, 8
	s_add_i32 s39, s39, s61
	s_ashr_i32 s27, s26, 31
	s_waitcnt lgkmcnt(0)
	v_pk_mul_f32 v[126:127], v[126:127], v[156:157] op_sel_hi:[1,0]
	v_pk_mul_f32 v[124:125], v[124:125], v[156:157] op_sel_hi:[1,0]
	v_pk_mul_f32 v[122:123], v[122:123], v[156:157] op_sel_hi:[1,0]
	v_pk_mul_f32 v[120:121], v[120:121], v[156:157] op_sel_hi:[1,0]
	v_max_f32_e32 v127, 0, v127
	v_max_f32_e32 v126, 0, v126
	v_max_f32_e32 v125, 0, v125
	v_max_f32_e32 v124, 0, v124
	v_max_f32_e32 v123, 0, v123
	v_max_f32_e32 v122, 0, v122
	v_max_f32_e32 v121, 0, v121
	v_max_f32_e32 v120, 0, v120
	v_pk_mul_f32 v[118:119], v[118:119], v[156:157] op_sel_hi:[1,0]
	v_pk_mul_f32 v[116:117], v[116:117], v[156:157] op_sel_hi:[1,0]
	v_pk_mul_f32 v[114:115], v[114:115], v[156:157] op_sel_hi:[1,0]
	v_pk_mul_f32 v[112:113], v[112:113], v[156:157] op_sel_hi:[1,0]
	v_pk_mul_f32 v[126:127], v[126:127], v[126:127]
	v_pk_mul_f32 v[124:125], v[124:125], v[124:125]
	v_pk_mul_f32 v[158:159], v[122:123], v[122:123]
	v_pk_mul_f32 v[122:123], v[120:121], v[120:121]
	v_cvt_pk_bf16_f32 v120, v124, v125
	v_cvt_pk_bf16_f32 v121, v126, v127
	v_max_f32_e32 v119, 0, v119
	v_max_f32_e32 v118, 0, v118
	v_max_f32_e32 v117, 0, v117
	v_max_f32_e32 v116, 0, v116
	v_max_f32_e32 v115, 0, v115
	v_max_f32_e32 v114, 0, v114
	v_max_f32_e32 v113, 0, v113
	v_max_f32_e32 v112, 0, v112
	v_cvt_pk_bf16_f32 v122, v122, v123
	v_cvt_pk_bf16_f32 v123, v158, v159
	ds_write_b128 v153, v[120:123]
	v_pk_mul_f32 v[118:119], v[118:119], v[118:119]
	v_pk_mul_f32 v[116:117], v[116:117], v[116:117]
	v_pk_mul_f32 v[120:121], v[114:115], v[114:115]
	v_pk_mul_f32 v[114:115], v[112:113], v[112:113]
	v_cvt_pk_bf16_f32 v112, v116, v117
	v_cvt_pk_bf16_f32 v113, v118, v119
	v_or_b32_e32 v118, s39, v147
	v_cvt_pk_bf16_f32 v114, v114, v115
	v_cvt_pk_bf16_f32 v115, v120, v121
	ds_write_b128 v153, v[112:115] offset:64
	v_lshl_add_u64 v[112:113], s[26:27], 1, v[136:137]
	ds_read_b128 v[114:117], v154
	v_mad_i64_i32 v[122:123], s[26:27], v118, s66, v[112:113]
	ds_read_b128 v[118:121], v154 offset:1152
	ds_read_b32 v124, v155 offset:64
	s_or_b32 s33, s39, 16
	s_waitcnt lgkmcnt(0)
; #define PG8_LAS __attribute__((address_space(3)))
; __device__ __forceinline__ unsigned cvt_pk_bf16(float lo, float hi) { unsigned r; asm volatile("v_cvt_pk_bf16_f32 %0, %1, %2" : "=v"(r) : "v"(lo), "v"(hi)); return r; }
; template <int LAYOUT> __device__ __forceinline__ void staged_store_bf16(PG8_LAS unsigned char* stg, bf16_t* O, size_t ldc, int rowg0, int pn, int wc, int lane) {
;     const int p = lane & 7;
; #pragma unroll
;     for (int hr = 0; hr < 2; ++hr) { const int r = 8 * hr + (lane >> 3), rowg = rowg0 + r; const u32x4 w = *(const PG8_LAS u32x4*)(stg + r * STG_ROW + p * 16);
;         if (LAYOUT == 0) __builtin_nontemporal_store(w, (u32x4*)(O + (size_t)rowg * ldc + pn * BM + wc * 64 + p * 8));
;     __device__ __forceinline__ void operator()(const f32x4 (&acc)[2][2][4][2], const Unit& u, int wr, int wc, int fr, int fq) const {
;     ...
;             for (int m = 0; m < 4; ++m) {
;                 const int rowg0 = u.pm * BM + ai * HALF + wr * 64 + m * 16; const float rs = rtab[ai * HALF + wr * 64 + m * 16 + fr];
; #pragma unroll
;                 for (int bj = 0; bj < 2; ++bj) {
;                     f32x4 v0 = acc[ai][bj][m][0] * rs, v1 = acc[ai][bj][m][1] * rs;
;                     if (ACT == 1) { const f32x4 z = {0.f, 0.f, 0.f, 0.f}; v0 = __builtin_elementwise_max(v0, z); v1 = __builtin_elementwise_max(v1, z); v0 = v0 * v0; v1 = v1 * v1; }
;                     u32x4 w; w.x = cvt_pk_bf16(v0[0], v0[1]); w.y = cvt_pk_bf16(v0[2], v0[3]); w.z = cvt_pk_bf16(v1[0], v1[1]); w.w = cvt_pk_bf16(v1[2], v1[3]);
;                     *(PG8_LAS u32x4*)(stg + fr * STG_ROW + bj * 64 + fq * 16) = w; }
;                 staged_store_bf16<LAYOUT>(stg, O, (size_t)ldc, rowg0, u.pn, wc, lane);
	global_store_dwordx4 v[122:123], v[114:117], off nt
	s_andn2_b64 vcc, exec, s[8:9]
	s_mov_b64 s[8:9], -1
	v_or_b32_e32 v114, s39, v148
	v_pk_mul_f32 v[110:111], v[110:111], v[124:125] op_sel_hi:[1,0]
	v_pk_mul_f32 v[108:109], v[108:109], v[124:125] op_sel_hi:[1,0]
	v_pk_mul_f32 v[106:107], v[106:107], v[124:125] op_sel_hi:[1,0]
	v_pk_mul_f32 v[104:105], v[104:105], v[124:125] op_sel_hi:[1,0]
	v_mad_i64_i32 v[114:115], s[26:27], v114, s66, v[112:113]
	v_max_f32_e32 v111, 0, v111
	v_max_f32_e32 v110, 0, v110
	v_max_f32_e32 v109, 0, v109
	v_max_f32_e32 v108, 0, v108
	v_max_f32_e32 v107, 0, v107
	v_max_f32_e32 v106, 0, v106
	v_max_f32_e32 v105, 0, v105
	v_max_f32_e32 v104, 0, v104
	v_pk_mul_f32 v[100:101], v[100:101], v[124:125] op_sel_hi:[1,0]
	v_pk_mul_f32 v[98:99], v[98:99], v[124:125] op_sel_hi:[1,0]
	v_pk_mul_f32 v[96:97], v[96:97], v[124:125] op_sel_hi:[1,0]
	global_store_dwordx4 v[114:115], v[118:121], off nt
	v_pk_mul_f32 v[110:111], v[110:111], v[110:111]
	v_pk_mul_f32 v[108:109], v[108:109], v[108:109]
	v_pk_mul_f32 v[114:115], v[106:107], v[106:107]
	v_pk_mul_f32 v[106:107], v[104:105], v[104:105]
	v_cvt_pk_bf16_f32 v104, v108, v109
	v_cvt_pk_bf16_f32 v105, v110, v111
	v_pk_mul_f32 v[102:103], v[102:103], v[124:125] op_sel_hi:[1,0]
	v_max_f32_e32 v101, 0, v101
	v_max_f32_e32 v100, 0, v100
	v_max_f32_e32 v99, 0, v99
	v_max_f32_e32 v98, 0, v98
	v_max_f32_e32 v97, 0, v97
	v_max_f32_e32 v96, 0, v96
	v_cvt_pk_bf16_f32 v106, v106, v107
	v_cvt_pk_bf16_f32 v107, v114, v115
	ds_write_b128 v153, v[104:107]
	v_max_f32_e32 v103, 0, v103
	v_max_f32_e32 v102, 0, v102
	v_pk_mul_f32 v[100:101], v[100:101], v[100:101]
	v_pk_mul_f32 v[104:105], v[98:99], v[98:99]
	v_pk_mul_f32 v[98:99], v[96:97], v[96:97]
	v_pk_mul_f32 v[102:103], v[102:103], v[102:103]
	v_cvt_pk_bf16_f32 v96, v100, v101
	v_or_b32_e32 v100, s33, v147
	v_cvt_pk_bf16_f32 v97, v102, v103
	v_cvt_pk_bf16_f32 v98, v98, v99
	v_cvt_pk_bf16_f32 v99, v104, v105
	ds_write_b128 v153, v[96:99] offset:64
	ds_read_b128 v[96:99], v154
	v_mad_i64_i32 v[104:105], s[26:27], v100, s66, v[112:113]
	ds_read_b128 v[100:103], v154 offset:1152
	ds_read_b32 v106, v155 offset:128
	s_waitcnt lgkmcnt(0)
	global_store_dwordx4 v[104:105], v[96:99], off nt
	v_pk_mul_f32 v[94:95], v[94:95], v[106:107] op_sel_hi:[1,0]
	s_nop 0
	v_or_b32_e32 v96, s33, v148
	v_pk_mul_f32 v[92:93], v[92:93], v[106:107] op_sel_hi:[1,0]
	v_pk_mul_f32 v[90:91], v[90:91], v[106:107] op_sel_hi:[1,0]
	v_pk_mul_f32 v[88:89], v[88:89], v[106:107] op_sel_hi:[1,0]
	v_mad_i64_i32 v[96:97], s[26:27], v96, s66, v[112:113]
	v_max_f32_e32 v95, 0, v95
	v_max_f32_e32 v94, 0, v94
	v_max_f32_e32 v93, 0, v93
	v_max_f32_e32 v92, 0, v92
	v_max_f32_e32 v91, 0, v91
	v_max_f32_e32 v90, 0, v90
	v_max_f32_e32 v89, 0, v89
	v_max_f32_e32 v88, 0, v88
	v_pk_mul_f32 v[84:85], v[84:85], v[106:107] op_sel_hi:[1,0]
	v_pk_mul_f32 v[82:83], v[82:83], v[106:107] op_sel_hi:[1,0]
	v_pk_mul_f32 v[80:81], v[80:81], v[106:107] op_sel_hi:[1,0]
	global_store_dwordx4 v[96:97], v[100:103], off nt
	v_pk_mul_f32 v[94:95], v[94:95], v[94:95]
	v_pk_mul_f32 v[92:93], v[92:93], v[92:93]
	v_pk_mul_f32 v[96:97], v[90:91], v[90:91]
	v_pk_mul_f32 v[90:91], v[88:89], v[88:89]
	v_cvt_pk_bf16_f32 v88, v92, v93
	v_cvt_pk_bf16_f32 v89, v94, v95
	v_pk_mul_f32 v[86:87], v[86:87], v[106:107] op_sel_hi:[1,0]
	v_max_f32_e32 v85, 0, v85
	v_max_f32_e32 v84, 0, v84
	v_max_f32_e32 v83, 0, v83
	v_max_f32_e32 v82, 0, v82
	v_max_f32_e32 v81, 0, v81
	v_max_f32_e32 v80, 0, v80
	v_cvt_pk_bf16_f32 v90, v90, v91
	v_cvt_pk_bf16_f32 v91, v96, v97
	ds_write_b128 v153, v[88:91]
	v_max_f32_e32 v87, 0, v87
	v_max_f32_e32 v86, 0, v86
	v_pk_mul_f32 v[84:85], v[84:85], v[84:85]
	v_pk_mul_f32 v[88:89], v[82:83], v[82:83]
	v_pk_mul_f32 v[82:83], v[80:81], v[80:81]
	s_or_b32 s33, s39, 32
	v_pk_mul_f32 v[86:87], v[86:87], v[86:87]
	v_cvt_pk_bf16_f32 v80, v84, v85
	v_or_b32_e32 v84, s33, v147
	v_cvt_pk_bf16_f32 v81, v86, v87
	v_cvt_pk_bf16_f32 v82, v82, v83
	v_cvt_pk_bf16_f32 v83, v88, v89
	ds_write_b128 v153, v[80:83] offset:64
	ds_read_b128 v[80:83], v154
	v_mad_i64_i32 v[88:89], s[26:27], v84, s66, v[112:113]
	ds_read_b128 v[84:87], v154 offset:1152
	ds_read_b32 v90, v155 offset:192
	s_waitcnt lgkmcnt(0)
	global_store_dwordx4 v[88:89], v[80:83], off nt
	v_pk_mul_f32 v[78:79], v[78:79], v[90:91] op_sel_hi:[1,0]
	s_nop 0
	v_or_b32_e32 v80, s33, v148
	v_pk_mul_f32 v[76:77], v[76:77], v[90:91] op_sel_hi:[1,0]
	v_pk_mul_f32 v[74:75], v[74:75], v[90:91] op_sel_hi:[1,0]
	v_pk_mul_f32 v[72:73], v[72:73], v[90:91] op_sel_hi:[1,0]
	v_mad_i64_i32 v[80:81], s[26:27], v80, s66, v[112:113]
	v_max_f32_e32 v79, 0, v79
	v_max_f32_e32 v78, 0, v78
	v_max_f32_e32 v77, 0, v77
	v_max_f32_e32 v76, 0, v76
	v_max_f32_e32 v75, 0, v75
	v_max_f32_e32 v74, 0, v74
	v_max_f32_e32 v73, 0, v73
	v_max_f32_e32 v72, 0, v72
	v_pk_mul_f32 v[68:69], v[68:69], v[90:91] op_sel_hi:[1,0]
	v_pk_mul_f32 v[66:67], v[66:67], v[90:91] op_sel_hi:[1,0]
	v_pk_mul_f32 v[64:65], v[64:65], v[90:91] op_sel_hi:[1,0]
	global_store_dwordx4 v[80:81], v[84:87], off nt
	v_pk_mul_f32 v[78:79], v[78:79], v[78:79]
	v_pk_mul_f32 v[76:77], v[76:77], v[76:77]
	v_pk_mul_f32 v[80:81], v[74:75], v[74:75]
	v_pk_mul_f32 v[74:75], v[72:73], v[72:73]
	v_cvt_pk_bf16_f32 v72, v76, v77
	v_cvt_pk_bf16_f32 v73, v78, v79
	v_pk_mul_f32 v[70:71], v[70:71], v[90:91] op_sel_hi:[1,0]
	v_max_f32_e32 v69, 0, v69
	v_max_f32_e32 v68, 0, v68
	v_max_f32_e32 v67, 0, v67
	v_max_f32_e32 v66, 0, v66
	v_max_f32_e32 v65, 0, v65
	v_max_f32_e32 v64, 0, v64
	v_cvt_pk_bf16_f32 v74, v74, v75
	v_cvt_pk_bf16_f32 v75, v80, v81
	ds_write_b128 v153, v[72:75]
	v_max_f32_e32 v71, 0, v71
	v_max_f32_e32 v70, 0, v70
	v_pk_mul_f32 v[68:69], v[68:69], v[68:69]
	v_pk_mul_f32 v[72:73], v[66:67], v[66:67]
	v_pk_mul_f32 v[66:67], v[64:65], v[64:65]
	s_or_b32 s33, s39, 48
	v_pk_mul_f32 v[70:71], v[70:71], v[70:71]
	v_cvt_pk_bf16_f32 v64, v68, v69
	v_or_b32_e32 v68, s33, v147
	v_cvt_pk_bf16_f32 v65, v70, v71
	v_cvt_pk_bf16_f32 v66, v66, v67
	v_cvt_pk_bf16_f32 v67, v72, v73
	ds_write_b128 v153, v[64:67] offset:64
	ds_read_b128 v[64:67], v154
	v_mad_i64_i32 v[72:73], s[26:27], v68, s66, v[112:113]
	ds_read_b128 v[68:71], v154 offset:1152
	ds_read_b32 v74, v155 offset:512
	s_waitcnt lgkmcnt(0)
; #define PG8_LAS __attribute__((address_space(3)))
; __device__ __forceinline__ unsigned cvt_pk_bf16(float lo, float hi) { unsigned r; asm volatile("v_cvt_pk_bf16_f32 %0, %1, %2" : "=v"(r) : "v"(lo), "v"(hi)); return r; }
; template <int LAYOUT> __device__ __forceinline__ void staged_store_bf16(PG8_LAS unsigned char* stg, bf16_t* O, size_t ldc, int rowg0, int pn, int wc, int lane) {
;     const int p = lane & 7;
; #pragma unroll
;     for (int hr = 0; hr < 2; ++hr) { const int r = 8 * hr + (lane >> 3), rowg = rowg0 + r; const u32x4 w = *(const PG8_LAS u32x4*)(stg + r * STG_ROW + p * 16);
;         if (LAYOUT == 0) __builtin_nontemporal_store(w, (u32x4*)(O + (size_t)rowg * ldc + pn * BM + wc * 64 + p * 8));
;     __device__ __forceinline__ void operator()(const f32x4 (&acc)[2][2][4][2], const Unit& u, int wr, int wc, int fr, int fq) const {
;     ...
;             for (int m = 0; m < 4; ++m) {
;                 const int rowg0 = u.pm * BM + ai * HALF + wr * 64 + m * 16; const float rs = rtab[ai * HALF + wr * 64 + m * 16 + fr];
; #pragma unroll
;                 for (int bj = 0; bj < 2; ++bj) {
;                     f32x4 v0 = acc[ai][bj][m][0] * rs, v1 = acc[ai][bj][m][1] * rs;
;                     if (ACT == 1) { const f32x4 z = {0.f, 0.f, 0.f, 0.f}; v0 = __builtin_elementwise_max(v0, z); v1 = __builtin_elementwise_max(v1, z); v0 = v0 * v0; v1 = v1 * v1; }
;                     u32x4 w; w.x = cvt_pk_bf16(v0[0], v0[1]); w.y = cvt_pk_bf16(v0[2], v0[3]); w.z = cvt_pk_bf16(v1[0], v1[1]); w.w = cvt_pk_bf16(v1[2], v1[3]);
;                     *(PG8_LAS u32x4*)(stg + fr * STG_ROW + bj * 64 + fq * 16) = w; }
;                 staged_store_bf16<LAYOUT>(stg, O, (size_t)ldc, rowg0, u.pn, wc, lane);
	global_store_dwordx4 v[72:73], v[64:67], off nt
	v_pk_mul_f32 v[62:63], v[62:63], v[74:75] op_sel_hi:[1,0]
	s_nop 0
	v_or_b32_e32 v64, s33, v148
	v_pk_mul_f32 v[60:61], v[60:61], v[74:75] op_sel_hi:[1,0]
	v_pk_mul_f32 v[58:59], v[58:59], v[74:75] op_sel_hi:[1,0]
	v_pk_mul_f32 v[56:57], v[56:57], v[74:75] op_sel_hi:[1,0]
	v_mad_i64_i32 v[64:65], s[26:27], v64, s66, v[112:113]
	v_max_f32_e32 v63, 0, v63
	v_max_f32_e32 v62, 0, v62
	v_max_f32_e32 v61, 0, v61
	v_max_f32_e32 v60, 0, v60
	v_max_f32_e32 v59, 0, v59
	v_max_f32_e32 v58, 0, v58
	v_max_f32_e32 v57, 0, v57
	v_max_f32_e32 v56, 0, v56
	v_pk_mul_f32 v[52:53], v[52:53], v[74:75] op_sel_hi:[1,0]
	v_pk_mul_f32 v[50:51], v[50:51], v[74:75] op_sel_hi:[1,0]
	v_pk_mul_f32 v[48:49], v[48:49], v[74:75] op_sel_hi:[1,0]
	global_store_dwordx4 v[64:65], v[68:71], off nt
	v_pk_mul_f32 v[62:63], v[62:63], v[62:63]
	v_pk_mul_f32 v[60:61], v[60:61], v[60:61]
	v_pk_mul_f32 v[64:65], v[58:59], v[58:59]
	v_pk_mul_f32 v[58:59], v[56:57], v[56:57]
	v_cvt_pk_bf16_f32 v56, v60, v61
	v_cvt_pk_bf16_f32 v57, v62, v63
	v_pk_mul_f32 v[54:55], v[54:55], v[74:75] op_sel_hi:[1,0]
	v_max_f32_e32 v53, 0, v53
	v_max_f32_e32 v52, 0, v52
	v_max_f32_e32 v51, 0, v51
	v_max_f32_e32 v50, 0, v50
	v_max_f32_e32 v49, 0, v49
	v_max_f32_e32 v48, 0, v48
	s_add_i32 s33, s39, 0x80
	v_cvt_pk_bf16_f32 v58, v58, v59
	v_cvt_pk_bf16_f32 v59, v64, v65
	ds_write_b128 v153, v[56:59]
	v_max_f32_e32 v55, 0, v55
	v_max_f32_e32 v54, 0, v54
	v_pk_mul_f32 v[52:53], v[52:53], v[52:53]
	v_pk_mul_f32 v[56:57], v[50:51], v[50:51]
	v_pk_mul_f32 v[50:51], v[48:49], v[48:49]
	v_pk_mul_f32 v[54:55], v[54:55], v[54:55]
	v_cvt_pk_bf16_f32 v48, v52, v53
	v_or_b32_e32 v52, s33, v147
	v_cvt_pk_bf16_f32 v49, v54, v55
	v_cvt_pk_bf16_f32 v50, v50, v51
	v_cvt_pk_bf16_f32 v51, v56, v57
	ds_write_b128 v153, v[48:51] offset:64
	ds_read_b128 v[48:51], v154
	v_mad_i64_i32 v[56:57], s[26:27], v52, s66, v[112:113]
	ds_read_b128 v[52:55], v154 offset:1152
	ds_read_b32 v58, v155 offset:576
	s_waitcnt lgkmcnt(0)
	global_store_dwordx4 v[56:57], v[48:51], off nt
	v_pk_mul_f32 v[46:47], v[46:47], v[58:59] op_sel_hi:[1,0]
	s_nop 0
	v_or_b32_e32 v48, s33, v148
	v_pk_mul_f32 v[44:45], v[44:45], v[58:59] op_sel_hi:[1,0]
	v_pk_mul_f32 v[42:43], v[42:43], v[58:59] op_sel_hi:[1,0]
	v_pk_mul_f32 v[40:41], v[40:41], v[58:59] op_sel_hi:[1,0]
	v_mad_i64_i32 v[48:49], s[26:27], v48, s66, v[112:113]
	v_max_f32_e32 v47, 0, v47
	v_max_f32_e32 v46, 0, v46
	v_max_f32_e32 v45, 0, v45
	v_max_f32_e32 v44, 0, v44
	v_max_f32_e32 v43, 0, v43
	v_max_f32_e32 v42, 0, v42
	v_max_f32_e32 v41, 0, v41
	v_max_f32_e32 v40, 0, v40
	v_pk_mul_f32 v[36:37], v[36:37], v[58:59] op_sel_hi:[1,0]
	v_pk_mul_f32 v[34:35], v[34:35], v[58:59] op_sel_hi:[1,0]
	v_pk_mul_f32 v[32:33], v[32:33], v[58:59] op_sel_hi:[1,0]
	global_store_dwordx4 v[48:49], v[52:55], off nt
	v_pk_mul_f32 v[46:47], v[46:47], v[46:47]
	v_pk_mul_f32 v[44:45], v[44:45], v[44:45]
	v_pk_mul_f32 v[48:49], v[42:43], v[42:43]
	v_pk_mul_f32 v[42:43], v[40:41], v[40:41]
	v_cvt_pk_bf16_f32 v40, v44, v45
	v_cvt_pk_bf16_f32 v41, v46, v47
	v_pk_mul_f32 v[38:39], v[38:39], v[58:59] op_sel_hi:[1,0]
	v_max_f32_e32 v37, 0, v37
	v_max_f32_e32 v36, 0, v36
	v_max_f32_e32 v35, 0, v35
	v_max_f32_e32 v34, 0, v34
	v_max_f32_e32 v33, 0, v33
	v_max_f32_e32 v32, 0, v32
	v_cvt_pk_bf16_f32 v42, v42, v43
	v_cvt_pk_bf16_f32 v43, v48, v49
	ds_write_b128 v153, v[40:43]
	v_max_f32_e32 v39, 0, v39
	v_max_f32_e32 v38, 0, v38
	v_pk_mul_f32 v[36:37], v[36:37], v[36:37]
	v_pk_mul_f32 v[40:41], v[34:35], v[34:35]
	v_pk_mul_f32 v[34:35], v[32:33], v[32:33]
	s_add_i32 s33, s39, 0x90
	v_pk_mul_f32 v[38:39], v[38:39], v[38:39]
	v_cvt_pk_bf16_f32 v32, v36, v37
	v_or_b32_e32 v36, s33, v147
	v_cvt_pk_bf16_f32 v33, v38, v39
	v_cvt_pk_bf16_f32 v34, v34, v35
	v_cvt_pk_bf16_f32 v35, v40, v41
	ds_write_b128 v153, v[32:35] offset:64
	ds_read_b128 v[32:35], v154
	v_mad_i64_i32 v[40:41], s[26:27], v36, s66, v[112:113]
	ds_read_b128 v[36:39], v154 offset:1152
	ds_read_b32 v42, v155 offset:640
	s_waitcnt lgkmcnt(0)
; #define PG8_LAS __attribute__((address_space(3)))
; __device__ __forceinline__ unsigned cvt_pk_bf16(float lo, float hi) { unsigned r; asm volatile("v_cvt_pk_bf16_f32 %0, %1, %2" : "=v"(r) : "v"(lo), "v"(hi)); return r; }
; template <int LAYOUT> __device__ __forceinline__ void staged_store_bf16(PG8_LAS unsigned char* stg, bf16_t* O, size_t ldc, int rowg0, int pn, int wc, int lane) {
;     const int p = lane & 7;
; #pragma unroll
;     for (int hr = 0; hr < 2; ++hr) { const int r = 8 * hr + (lane >> 3), rowg = rowg0 + r; const u32x4 w = *(const PG8_LAS u32x4*)(stg + r * STG_ROW + p * 16);
;         if (LAYOUT == 0) __builtin_nontemporal_store(w, (u32x4*)(O + (size_t)rowg * ldc + pn * BM + wc * 64 + p * 8));
;     __device__ __forceinline__ void operator()(const f32x4 (&acc)[2][2][4][2], const Unit& u, int wr, int wc, int fr, int fq) const {
;     ...
;             for (int m = 0; m < 4; ++m) {
;                 const int rowg0 = u.pm * BM + ai * HALF + wr * 64 + m * 16; const float rs = rtab[ai * HALF + wr * 64 + m * 16 + fr];
; #pragma unroll
;                 for (int bj = 0; bj < 2; ++bj) {
;                     f32x4 v0 = acc[ai][bj][m][0] * rs, v1 = acc[ai][bj][m][1] * rs;
;                     if (ACT == 1) { const f32x4 z = {0.f, 0.f, 0.f, 0.f}; v0 = __builtin_elementwise_max(v0, z); v1 = __builtin_elementwise_max(v1, z); v0 = v0 * v0; v1 = v1 * v1; }
;                     u32x4 w; w.x = cvt_pk_bf16(v0[0], v0[1]); w.y = cvt_pk_bf16(v0[2], v0[3]); w.z = cvt_pk_bf16(v1[0], v1[1]); w.w = cvt_pk_bf16(v1[2], v1[3]);
;                     *(PG8_LAS u32x4*)(stg + fr * STG_ROW + bj * 64 + fq * 16) = w; }
;                 staged_store_bf16<LAYOUT>(stg, O, (size_t)ldc, rowg0, u.pn, wc, lane);
	global_store_dwordx4 v[40:41], v[32:35], off nt
	v_pk_mul_f32 v[30:31], v[30:31], v[42:43] op_sel_hi:[1,0]
	s_nop 0
	v_or_b32_e32 v32, s33, v148
	v_pk_mul_f32 v[28:29], v[28:29], v[42:43] op_sel_hi:[1,0]
	v_pk_mul_f32 v[26:27], v[26:27], v[42:43] op_sel_hi:[1,0]
	v_pk_mul_f32 v[24:25], v[24:25], v[42:43] op_sel_hi:[1,0]
	v_mad_i64_i32 v[32:33], s[26:27], v32, s66, v[112:113]
	v_max_f32_e32 v31, 0, v31
	v_max_f32_e32 v30, 0, v30
	v_max_f32_e32 v29, 0, v29
	v_max_f32_e32 v28, 0, v28
	v_max_f32_e32 v27, 0, v27
	v_max_f32_e32 v26, 0, v26
	v_max_f32_e32 v25, 0, v25
	v_max_f32_e32 v24, 0, v24
	v_pk_mul_f32 v[20:21], v[20:21], v[42:43] op_sel_hi:[1,0]
	v_pk_mul_f32 v[18:19], v[18:19], v[42:43] op_sel_hi:[1,0]
	v_pk_mul_f32 v[16:17], v[16:17], v[42:43] op_sel_hi:[1,0]
	global_store_dwordx4 v[32:33], v[36:39], off nt
	v_pk_mul_f32 v[30:31], v[30:31], v[30:31]
	v_pk_mul_f32 v[28:29], v[28:29], v[28:29]
	v_pk_mul_f32 v[32:33], v[26:27], v[26:27]
	v_pk_mul_f32 v[26:27], v[24:25], v[24:25]
	v_cvt_pk_bf16_f32 v24, v28, v29
	v_cvt_pk_bf16_f32 v25, v30, v31
	v_pk_mul_f32 v[22:23], v[22:23], v[42:43] op_sel_hi:[1,0]
	v_max_f32_e32 v21, 0, v21
	v_max_f32_e32 v20, 0, v20
	v_max_f32_e32 v19, 0, v19
	v_max_f32_e32 v18, 0, v18
	v_max_f32_e32 v17, 0, v17
	v_max_f32_e32 v16, 0, v16
	v_cvt_pk_bf16_f32 v26, v26, v27
	v_cvt_pk_bf16_f32 v27, v32, v33
	ds_write_b128 v153, v[24:27]
	v_max_f32_e32 v23, 0, v23
	v_max_f32_e32 v22, 0, v22
	v_pk_mul_f32 v[20:21], v[20:21], v[20:21]
	v_pk_mul_f32 v[24:25], v[18:19], v[18:19]
	v_pk_mul_f32 v[18:19], v[16:17], v[16:17]
	s_add_i32 s33, s39, 0xa0
	v_pk_mul_f32 v[22:23], v[22:23], v[22:23]
	v_cvt_pk_bf16_f32 v16, v20, v21
	v_or_b32_e32 v20, s33, v147
	v_cvt_pk_bf16_f32 v17, v22, v23
	v_cvt_pk_bf16_f32 v18, v18, v19
	v_cvt_pk_bf16_f32 v19, v24, v25
	ds_write_b128 v153, v[16:19] offset:64
	ds_read_b128 v[16:19], v154
	v_mad_i64_i32 v[24:25], s[26:27], v20, s66, v[112:113]
	ds_read_b128 v[20:23], v154 offset:1152
	ds_read_b32 v26, v155 offset:704
	s_addk_i32 s39, 0xb0
	s_waitcnt lgkmcnt(0)
	global_store_dwordx4 v[24:25], v[16:19], off nt
	v_pk_mul_f32 v[14:15], v[14:15], v[26:27] op_sel_hi:[1,0]
	s_nop 0
	v_or_b32_e32 v16, s33, v148
	v_pk_mul_f32 v[12:13], v[12:13], v[26:27] op_sel_hi:[1,0]
	v_pk_mul_f32 v[10:11], v[10:11], v[26:27] op_sel_hi:[1,0]
	v_pk_mul_f32 v[8:9], v[8:9], v[26:27] op_sel_hi:[1,0]
	v_mad_i64_i32 v[16:17], s[26:27], v16, s66, v[112:113]
	v_max_f32_e32 v15, 0, v15
	v_max_f32_e32 v14, 0, v14
	v_max_f32_e32 v13, 0, v13
	v_max_f32_e32 v12, 0, v12
	v_max_f32_e32 v11, 0, v11
	v_max_f32_e32 v10, 0, v10
	v_max_f32_e32 v9, 0, v9
	v_max_f32_e32 v8, 0, v8
	v_pk_mul_f32 v[2:3], v[2:3], v[26:27] op_sel_hi:[1,0]
	v_pk_mul_f32 v[0:1], v[0:1], v[26:27] op_sel_hi:[1,0]
	global_store_dwordx4 v[16:17], v[20:23], off nt
	v_pk_mul_f32 v[14:15], v[14:15], v[14:15]
	v_pk_mul_f32 v[12:13], v[12:13], v[12:13]
	v_pk_mul_f32 v[16:17], v[10:11], v[10:11]
	v_pk_mul_f32 v[10:11], v[8:9], v[8:9]
	v_cvt_pk_bf16_f32 v8, v12, v13
	v_cvt_pk_bf16_f32 v9, v14, v15
	v_pk_mul_f32 v[6:7], v[6:7], v[26:27] op_sel_hi:[1,0]
	v_pk_mul_f32 v[4:5], v[4:5], v[26:27] op_sel_hi:[1,0]
	v_max_f32_e32 v3, 0, v3
	v_max_f32_e32 v2, 0, v2
	v_max_f32_e32 v1, 0, v1
	v_max_f32_e32 v0, 0, v0
	v_cvt_pk_bf16_f32 v10, v10, v11
	v_cvt_pk_bf16_f32 v11, v16, v17
	ds_write_b128 v153, v[8:11]
	v_max_f32_e32 v7, 0, v7
	v_max_f32_e32 v6, 0, v6
	v_max_f32_e32 v5, 0, v5
	v_max_f32_e32 v4, 0, v4
	v_pk_mul_f32 v[8:9], v[2:3], v[2:3]
	v_pk_mul_f32 v[2:3], v[0:1], v[0:1]
	v_pk_mul_f32 v[6:7], v[6:7], v[6:7]
	v_pk_mul_f32 v[4:5], v[4:5], v[4:5]
	s_nop 0
	v_cvt_pk_bf16_f32 v0, v4, v5
	v_cvt_pk_bf16_f32 v1, v6, v7
	v_cvt_pk_bf16_f32 v2, v2, v3
	v_cvt_pk_bf16_f32 v3, v8, v9
	ds_write_b128 v153, v[0:3] offset:64
	ds_read_b128 v[0:3], v154
	v_or_b32_e32 v4, s39, v147
	v_mad_i64_i32 v[8:9], s[26:27], v4, s66, v[112:113]
	ds_read_b128 v[4:7], v154 offset:1152
	s_waitcnt lgkmcnt(0)
	global_store_dwordx4 v[8:9], v[0:3], off nt
	s_nop 1
	v_or_b32_e32 v0, s39, v148
	v_mad_i64_i32 v[0:1], s[26:27], v0, s66, v[112:113]
	global_store_dwordx4 v[0:1], v[4:7], off nt
	s_cbranch_vccnz .LBB0_861
	s_andn2_b64 vcc, exec, s[10:11]
	s_cbranch_vccnz .LBB0_860
	s_mov_b32 s98, 1
	s_branch .LBB0_860

; #define PG8_STAGE(bufoff, gbase, voff) do { _Pragma("unroll") for (int _i = 0; _i < 2; ++_i) \
;         __builtin_amdgcn_global_load_lds((const unsigned*)((const char*)(gbase) + (voff)[_i]), (PG8_LAS unsigned*)(lds + (bufoff) + ldsw + _i * 8192), 16, 0, 0); } while (0)
; #define PG8_LDA(dst, b, h) do { _Pragma("unroll") for (int m = 0; m < 4; ++m) _Pragma("unroll") for (int k = 0; k < 2; ++k) dst[m][k] = *(const PG8_LAS bf16x8*)(lds + PG8_SA(b, h) + aoff + m * 2048 + k * 1024); } while (0)
; #define PG8_LDB(dst, b, h) do { _Pragma("unroll") for (int n = 0; n < 2; ++n) _Pragma("unroll") for (int k = 0; k < 2; ++k) dst[n][k] = *(const PG8_LAS bf16x8*)(lds + PG8_SB(b, h) + boff + n * 2048 + k * 1024); } while (0)
; #define PG8_SCHED __builtin_amdgcn_sched_barrier(0)
; template <class Epi, class Sched, bool ALIGN_EPI = false, bool SP2 = false>
; __device__ __forceinline__ void gemm_phase(PG8_LAS unsigned char* lds, const Gemm g, const Sched& S, const Epi& E, int tid_in) {
;     ...
;         const bool has_next = S.next(ui + 1, nxt);
;         const char* nA = has_next ? (const char*)g.A + (size_t)nxt.pm * tstep : cA; const char* nB = has_next ? (const char*)g.Bt + (size_t)nxt.pn * tstepB : cB;
;         for (int t = 0; t < nt; t += 2) {
;             const bool last = (t == nt - 2);
;             const char* a1 = cA + (size_t)(t + 1) * kstep;
;             const char* a2 = last ? nA : cA + (size_t)(t + 2) * kstep; const char* b2 = last ? nB : cB + (size_t)(t + 2) * kstep;
;             const char* a3 = a2 + kstep; const char* b3 = b2 + kstep;
;             if (last && has_next) S.a_ready(nxt);
;             if constexpr (SP2) {
;             PG8_LDB(B0, 0, 0); PG8_LDB(B1, 0, 1); PG8_SCHED; PG8_LDA(At, 0, 0); PG8_STAGE(PG8_SA(1, 1), a1 + hstep, voffA);
;     ...
; #pragma unroll
;         for (int a = 0; a < 2; ++a)
; #pragma unroll
;             for (int b = 0; b < 2; ++b)
; #pragma unroll
;                 for (int m = 0; m < 4; ++m)
; #pragma unroll
;                     for (int n = 0; n < 2; ++n) acc[a][b][m][n] = (f32x4){0.f, 0.f, 0.f, 0.f};
;         cur = nxt; cA = nA; cB = nB; ++ui;
.LBB0_948:
	s_ashr_i32 s43, s42, 31
	s_lshl_b64 s[26:27], s[42:43], 22
	s_add_u32 s46, s14, s26
	s_addc_u32 s47, s15, s27
	s_and_b64 s[10:11], s[10:11], exec
	s_cselect_b32 s43, s47, s53
	s_cselect_b32 s67, s46, s52
	s_add_u32 s68, s52, 0x100
	v_mov_b32_e32 v0, 0
	s_addc_u32 s69, s53, 0
	s_mov_b32 s70, -2
	s_waitcnt lgkmcnt(0)
	v_mov_b32_e32 v1, v0
	v_mov_b32_e32 v2, v0
	v_mov_b32_e32 v3, v0
	v_mov_b32_e32 v4, v0
	v_mov_b32_e32 v5, v0
	v_mov_b32_e32 v6, v0
	v_mov_b32_e32 v7, v0
	v_mov_b32_e32 v16, v0
	v_mov_b32_e32 v17, v0
	v_mov_b32_e32 v18, v0
	v_mov_b32_e32 v19, v0
	v_mov_b32_e32 v20, v0
	v_mov_b32_e32 v21, v0
	v_mov_b32_e32 v22, v0
	v_mov_b32_e32 v23, v0
	v_mov_b32_e32 v32, v0
	v_mov_b32_e32 v33, v0
	v_mov_b32_e32 v34, v0
	v_mov_b32_e32 v35, v0
	v_mov_b32_e32 v36, v0
	v_mov_b32_e32 v37, v0
	v_mov_b32_e32 v38, v0
	v_mov_b32_e32 v39, v0
	v_mov_b32_e32 v48, v0
	v_mov_b32_e32 v49, v0
	v_mov_b32_e32 v50, v0
	v_mov_b32_e32 v51, v0
	v_mov_b32_e32 v52, v0
	v_mov_b32_e32 v53, v0
	v_mov_b32_e32 v54, v0
	v_mov_b32_e32 v55, v0
	v_mov_b32_e32 v8, v0
	v_mov_b32_e32 v9, v0
	v_mov_b32_e32 v10, v0
	v_mov_b32_e32 v11, v0
	v_mov_b32_e32 v12, v0
	v_mov_b32_e32 v13, v0
	v_mov_b32_e32 v14, v0
	v_mov_b32_e32 v15, v0
	v_mov_b32_e32 v24, v0
	v_mov_b32_e32 v25, v0
	v_mov_b32_e32 v26, v0
	v_mov_b32_e32 v27, v0
	v_mov_b32_e32 v28, v0
	v_mov_b32_e32 v29, v0
	v_mov_b32_e32 v30, v0
	v_mov_b32_e32 v31, v0
	v_mov_b32_e32 v40, v0
	v_mov_b32_e32 v41, v0
	v_mov_b32_e32 v42, v0
	v_mov_b32_e32 v43, v0
	v_mov_b32_e32 v44, v0
	v_mov_b32_e32 v45, v0
	v_mov_b32_e32 v46, v0
	v_mov_b32_e32 v47, v0
	v_mov_b32_e32 v56, v0
	v_mov_b32_e32 v57, v0
	v_mov_b32_e32 v58, v0
	v_mov_b32_e32 v59, v0
	v_mov_b32_e32 v60, v0
	v_mov_b32_e32 v61, v0
	v_mov_b32_e32 v62, v0
	v_mov_b32_e32 v63, v0
	v_mov_b32_e32 v64, v0
	v_mov_b32_e32 v65, v0
	v_mov_b32_e32 v66, v0
	v_mov_b32_e32 v67, v0
	v_mov_b32_e32 v68, v0
	v_mov_b32_e32 v69, v0
	v_mov_b32_e32 v70, v0
	v_mov_b32_e32 v71, v0
	v_mov_b32_e32 v80, v0
	v_mov_b32_e32 v81, v0
	v_mov_b32_e32 v82, v0
	v_mov_b32_e32 v83, v0
	v_mov_b32_e32 v84, v0
	v_mov_b32_e32 v85, v0
	v_mov_b32_e32 v86, v0
	v_mov_b32_e32 v87, v0
	v_mov_b32_e32 v96, v0
	v_mov_b32_e32 v97, v0
	v_mov_b32_e32 v98, v0
	v_mov_b32_e32 v99, v0
	v_mov_b32_e32 v100, v0
	v_mov_b32_e32 v101, v0
	v_mov_b32_e32 v102, v0
	v_mov_b32_e32 v103, v0
	v_mov_b32_e32 v112, v0
	v_mov_b32_e32 v113, v0
	v_mov_b32_e32 v114, v0
	v_mov_b32_e32 v115, v0
	v_mov_b32_e32 v116, v0
	v_mov_b32_e32 v117, v0
	v_mov_b32_e32 v118, v0
	v_mov_b32_e32 v119, v0
	v_mov_b32_e32 v72, v0
	v_mov_b32_e32 v73, v0
	v_mov_b32_e32 v74, v0
	v_mov_b32_e32 v75, v0
	v_mov_b32_e32 v76, v0
	v_mov_b32_e32 v77, v0
	v_mov_b32_e32 v78, v0
	v_mov_b32_e32 v79, v0
	v_mov_b32_e32 v88, v0
	v_mov_b32_e32 v89, v0
	v_mov_b32_e32 v90, v0
	v_mov_b32_e32 v91, v0
	v_mov_b32_e32 v92, v0
	v_mov_b32_e32 v93, v0
	v_mov_b32_e32 v94, v0
	v_mov_b32_e32 v95, v0
	v_mov_b32_e32 v104, v0
	v_mov_b32_e32 v105, v0
	v_mov_b32_e32 v106, v0
	v_mov_b32_e32 v107, v0
	v_mov_b32_e32 v108, v0
	v_mov_b32_e32 v109, v0
	v_mov_b32_e32 v110, v0
	v_mov_b32_e32 v111, v0
	v_mov_b32_e32 v120, v0
	v_mov_b32_e32 v121, v0
	v_mov_b32_e32 v122, v0
	v_mov_b32_e32 v123, v0
	v_mov_b32_e32 v124, v0
	v_mov_b32_e32 v125, v0
	v_mov_b32_e32 v126, v0
	v_mov_b32_e32 v127, v0
	s_cmp_eq_u32 s98, 1
	s_cbranch_scc0 .Lkb_skip_7
	s_mov_b32 s98, 0
	s_barrier
.Lkb_skip_7:
.LBB0_949:
	ds_read_b128 v[146:149], v153
	ds_read_b128 v[158:161], v153 offset:1024
	ds_read_b128 v[162:165], v153 offset:2048
	ds_read_b128 v[166:169], v153 offset:3072
	ds_read_b128 v[170:173], v154
	ds_read_b128 v[174:177], v154 offset:1024
	ds_read_b128 v[178:181], v154 offset:2048
	ds_read_b128 v[182:185], v154 offset:3072
	s_add_u32 s10, s50, 0x100
	s_addc_u32 s11, s51, 0
	s_cmpk_eq_i32 s70, 0x7c
	s_cselect_b32 s55, s45, s11
	s_cselect_b32 s54, s44, s10
	s_cselect_b32 s53, s43, s69
	s_cselect_b32 s52, s67, s68
	v_lshl_add_u64 v[218:219], s[50:51], 0, v[138:139]
	s_add_i32 m0, s49, 0xc000
	ds_read_b128 v[186:189], v155
	ds_read_b128 v[190:193], v155 offset:1024
	ds_read_b128 v[194:197], v155 offset:2048
	ds_read_b128 v[198:201], v155 offset:3072
	ds_read_b128 v[202:205], v155 offset:4096
	ds_read_b128 v[206:209], v155 offset:5120
	ds_read_b128 v[210:213], v155 offset:6144
	ds_read_b128 v[214:217], v155 offset:7168
	global_load_lds_dwordx4 v[218:219], off
	v_lshl_add_u64 v[218:219], s[50:51], 0, v[140:141]
	s_add_i32 m0, s49, 0xe000
	s_nop 0
	global_load_lds_dwordx4 v[218:219], off
	s_waitcnt vmcnt(8)
	s_waitcnt lgkmcnt(0)
	s_barrier
; #define PG8_STAGE(bufoff, gbase, voff) do { _Pragma("unroll") for (int _i = 0; _i < 2; ++_i) \
;         __builtin_amdgcn_global_load_lds((const unsigned*)((const char*)(gbase) + (voff)[_i]), (PG8_LAS unsigned*)(lds + (bufoff) + ldsw + _i * 8192), 16, 0, 0); } while (0)
; #define PG8_LDA(dst, b, h) do { _Pragma("unroll") for (int m = 0; m < 4; ++m) _Pragma("unroll") for (int k = 0; k < 2; ++k) dst[m][k] = *(const PG8_LAS bf16x8*)(lds + PG8_SA(b, h) + aoff + m * 2048 + k * 1024); } while (0)
; #define PG8_MMA(ai, bj, At, Bt) do { __builtin_amdgcn_s_setprio(1); _Pragma("unroll") for (int m = 0; m < 4; ++m) _Pragma("unroll") for (int n = 0; n < 2; ++n) _Pragma("unroll") for (int k = 0; k < 2; ++k) \
;         acc[ai][bj][m][n] = __builtin_amdgcn_mfma_f32_16x16x32_bf16(Bt[n][k], At[m][k], acc[ai][bj][m][n], 0, 0, 0); __builtin_amdgcn_s_setprio(0); } while (0)
; #define PG8_WAIT_V(n) asm volatile("s_waitcnt vmcnt(" #n ")" ::: "memory")
; #define PG8_WAIT_L(n) asm volatile("s_waitcnt lgkmcnt(" #n ")" ::: "memory")
; #define PG8_BAR __builtin_amdgcn_s_barrier()
; #define PG8_SCHED __builtin_amdgcn_sched_barrier(0)
; template <class Epi, class Sched, bool ALIGN_EPI = false, bool SP2 = false>
; __device__ __forceinline__ void gemm_phase(PG8_LAS unsigned char* lds, const Gemm g, const Sched& S, const Epi& E, int tid_in) {
;     ...
;             PG8_WAIT_V(8); PG8_WAIT_L(0); PG8_BAR; PG8_MMA(0, 0, At, B0); PG8_MMA(0, 1, At, B1); PG8_BAR; PG8_SCHED;
;             PG8_LDA(At, 0, 1); PG8_STAGE(PG8_SB(0, 0), b2, voffB); PG8_STAGE(PG8_SB(0, 1), b2 + hstepB, voffB); PG8_STAGE(PG8_SA(0, 0), a2, voffA);
;             PG8_WAIT_V(8); PG8_WAIT_L(0); PG8_BAR; PG8_MMA(1, 0, At, B0); PG8_MMA(1, 1, At, B1); PG8_BAR; PG8_SCHED;
	s_setprio 1
	s_waitcnt lgkmcnt(0)
	v_mfma_f32_16x16x32_bf16 v[124:127], v[146:149], v[186:189], v[124:127]
	v_mfma_f32_16x16x32_bf16 v[120:123], v[162:165], v[186:189], v[120:123]
	v_mfma_f32_16x16x32_bf16 v[108:111], v[146:149], v[194:197], v[108:111]
	v_mfma_f32_16x16x32_bf16 v[104:107], v[162:165], v[194:197], v[104:107]
	v_mfma_f32_16x16x32_bf16 v[92:95], v[146:149], v[202:205], v[92:95]
	v_mfma_f32_16x16x32_bf16 v[88:91], v[162:165], v[202:205], v[88:91]
	v_mfma_f32_16x16x32_bf16 v[76:79], v[146:149], v[210:213], v[76:79]
	v_mfma_f32_16x16x32_bf16 v[72:75], v[162:165], v[210:213], v[72:75]
	v_mfma_f32_16x16x32_bf16 v[124:127], v[158:161], v[190:193], v[124:127]
	v_mfma_f32_16x16x32_bf16 v[120:123], v[166:169], v[190:193], v[120:123]
	v_mfma_f32_16x16x32_bf16 v[108:111], v[158:161], v[198:201], v[108:111]
	v_mfma_f32_16x16x32_bf16 v[104:107], v[166:169], v[198:201], v[104:107]
	v_mfma_f32_16x16x32_bf16 v[92:95], v[158:161], v[206:209], v[92:95]
	v_mfma_f32_16x16x32_bf16 v[88:91], v[166:169], v[206:209], v[88:91]
	v_mfma_f32_16x16x32_bf16 v[76:79], v[158:161], v[214:217], v[76:79]
	v_mfma_f32_16x16x32_bf16 v[72:75], v[166:169], v[214:217], v[72:75]
	s_setprio 0
	s_setprio 1
	v_mfma_f32_16x16x32_bf16 v[116:119], v[170:173], v[186:189], v[116:119]
	v_mfma_f32_16x16x32_bf16 v[112:115], v[178:181], v[186:189], v[112:115]
	v_mfma_f32_16x16x32_bf16 v[100:103], v[170:173], v[194:197], v[100:103]
	v_mfma_f32_16x16x32_bf16 v[96:99], v[178:181], v[194:197], v[96:99]
	v_mfma_f32_16x16x32_bf16 v[84:87], v[170:173], v[202:205], v[84:87]
	v_mfma_f32_16x16x32_bf16 v[80:83], v[178:181], v[202:205], v[80:83]
	v_mfma_f32_16x16x32_bf16 v[68:71], v[170:173], v[210:213], v[68:71]
	v_mfma_f32_16x16x32_bf16 v[64:67], v[178:181], v[210:213], v[64:67]
	v_mfma_f32_16x16x32_bf16 v[116:119], v[174:177], v[190:193], v[116:119]
	v_mfma_f32_16x16x32_bf16 v[112:115], v[182:185], v[190:193], v[112:115]
	v_mfma_f32_16x16x32_bf16 v[100:103], v[174:177], v[198:201], v[100:103]
	v_mfma_f32_16x16x32_bf16 v[96:99], v[182:185], v[198:201], v[96:99]
	v_mfma_f32_16x16x32_bf16 v[84:87], v[174:177], v[206:209], v[84:87]
	v_mfma_f32_16x16x32_bf16 v[80:83], v[182:185], v[206:209], v[80:83]
	v_mfma_f32_16x16x32_bf16 v[68:71], v[174:177], v[214:217], v[68:71]
	v_mfma_f32_16x16x32_bf16 v[64:67], v[182:185], v[214:217], v[64:67]
	s_setprio 0
	s_barrier
	s_add_i32 s26, s63, s56
	v_lshl_add_u64 v[218:219], s[52:53], 0, v[130:131]
	s_mov_b32 m0, s26
	ds_read_b128 v[186:189], v155 offset:16384
	ds_read_b128 v[190:193], v155 offset:17408
	ds_read_b128 v[194:197], v155 offset:18432
	ds_read_b128 v[198:201], v155 offset:19456
	ds_read_b128 v[202:205], v155 offset:20480
	ds_read_b128 v[206:209], v155 offset:21504
	ds_read_b128 v[210:213], v155 offset:22528
	ds_read_b128 v[214:217], v155 offset:23552
	global_load_lds_dwordx4 v[218:219], off
	s_add_i32 m0, s26, 0x2000
	s_add_u32 s26, s52, 0x80000
	v_lshl_add_u64 v[220:221], s[52:53], 0, v[134:135]
	s_addc_u32 s27, s53, 0
	s_add_i32 s33, s64, s56
	global_load_lds_dwordx4 v[220:221], off
	v_lshl_add_u64 v[222:223], s[26:27], 0, v[130:131]
	s_mov_b32 m0, s33
	v_lshl_add_u64 v[224:225], s[54:55], 0, v[132:133]
	global_load_lds_dwordx4 v[222:223], off
	v_lshl_add_u64 v[222:223], s[26:27], 0, v[134:135]
	s_add_i32 m0, s33, 0x2000
	s_nop 0
	global_load_lds_dwordx4 v[222:223], off
	v_lshl_add_u64 v[222:223], s[54:55], 0, v[128:129]
	s_mov_b32 m0, s49
	s_nop 0
	global_load_lds_dwordx4 v[222:223], off
	s_mov_b32 m0, s57
	s_nop 0
	global_load_lds_dwordx4 v[224:225], off
	s_waitcnt vmcnt(8)
	s_waitcnt lgkmcnt(0)
	s_barrier
	s_setprio 1
	s_waitcnt lgkmcnt(0)
	v_mfma_f32_16x16x32_bf16 v[60:63], v[146:149], v[186:189], v[60:63]
	v_mfma_f32_16x16x32_bf16 v[56:59], v[162:165], v[186:189], v[56:59]
	v_mfma_f32_16x16x32_bf16 v[44:47], v[146:149], v[194:197], v[44:47]
	v_mfma_f32_16x16x32_bf16 v[40:43], v[162:165], v[194:197], v[40:43]
	v_mfma_f32_16x16x32_bf16 v[28:31], v[146:149], v[202:205], v[28:31]
	v_mfma_f32_16x16x32_bf16 v[24:27], v[162:165], v[202:205], v[24:27]
	v_mfma_f32_16x16x32_bf16 v[12:15], v[146:149], v[210:213], v[12:15]
	v_mfma_f32_16x16x32_bf16 v[8:11], v[162:165], v[210:213], v[8:11]
	v_mfma_f32_16x16x32_bf16 v[60:63], v[158:161], v[190:193], v[60:63]
	v_mfma_f32_16x16x32_bf16 v[56:59], v[166:169], v[190:193], v[56:59]
	v_mfma_f32_16x16x32_bf16 v[44:47], v[158:161], v[198:201], v[44:47]
	v_mfma_f32_16x16x32_bf16 v[40:43], v[166:169], v[198:201], v[40:43]
	v_mfma_f32_16x16x32_bf16 v[28:31], v[158:161], v[206:209], v[28:31]
	v_mfma_f32_16x16x32_bf16 v[24:27], v[166:169], v[206:209], v[24:27]
	v_mfma_f32_16x16x32_bf16 v[12:15], v[158:161], v[214:217], v[12:15]
	v_mfma_f32_16x16x32_bf16 v[8:11], v[166:169], v[214:217], v[8:11]
	s_setprio 0
	s_setprio 1
	v_mfma_f32_16x16x32_bf16 v[52:55], v[170:173], v[186:189], v[52:55]
	v_mfma_f32_16x16x32_bf16 v[48:51], v[178:181], v[186:189], v[48:51]
	v_mfma_f32_16x16x32_bf16 v[36:39], v[170:173], v[194:197], v[36:39]
	v_mfma_f32_16x16x32_bf16 v[32:35], v[178:181], v[194:197], v[32:35]
	v_mfma_f32_16x16x32_bf16 v[20:23], v[170:173], v[202:205], v[20:23]
	v_mfma_f32_16x16x32_bf16 v[16:19], v[178:181], v[202:205], v[16:19]
	v_mfma_f32_16x16x32_bf16 v[4:7], v[170:173], v[210:213], v[4:7]
	v_mfma_f32_16x16x32_bf16 v[0:3], v[178:181], v[210:213], v[0:3]
	v_mfma_f32_16x16x32_bf16 v[52:55], v[174:177], v[190:193], v[52:55]
	v_mfma_f32_16x16x32_bf16 v[48:51], v[182:185], v[190:193], v[48:51]
	v_mfma_f32_16x16x32_bf16 v[36:39], v[174:177], v[198:201], v[36:39]
	v_mfma_f32_16x16x32_bf16 v[32:35], v[182:185], v[198:201], v[32:35]
	v_mfma_f32_16x16x32_bf16 v[20:23], v[174:177], v[206:209], v[20:23]
	v_mfma_f32_16x16x32_bf16 v[16:19], v[182:185], v[206:209], v[16:19]
	v_mfma_f32_16x16x32_bf16 v[4:7], v[174:177], v[214:217], v[4:7]
	v_mfma_f32_16x16x32_bf16 v[0:3], v[182:185], v[214:217], v[0:3]
	s_setprio 0
	s_barrier
; #define PG8_STAGE(bufoff, gbase, voff) do { _Pragma("unroll") for (int _i = 0; _i < 2; ++_i) \
;         __builtin_amdgcn_global_load_lds((const unsigned*)((const char*)(gbase) + (voff)[_i]), (PG8_LAS unsigned*)(lds + (bufoff) + ldsw + _i * 8192), 16, 0, 0); } while (0)
; #define PG8_LDA(dst, b, h) do { _Pragma("unroll") for (int m = 0; m < 4; ++m) _Pragma("unroll") for (int k = 0; k < 2; ++k) dst[m][k] = *(const PG8_LAS bf16x8*)(lds + PG8_SA(b, h) + aoff + m * 2048 + k * 1024); } while (0)
; #define PG8_LDB(dst, b, h) do { _Pragma("unroll") for (int n = 0; n < 2; ++n) _Pragma("unroll") for (int k = 0; k < 2; ++k) dst[n][k] = *(const PG8_LAS bf16x8*)(lds + PG8_SB(b, h) + boff + n * 2048 + k * 1024); } while (0)
; #define PG8_MMA(ai, bj, At, Bt) do { __builtin_amdgcn_s_setprio(1); _Pragma("unroll") for (int m = 0; m < 4; ++m) _Pragma("unroll") for (int n = 0; n < 2; ++n) _Pragma("unroll") for (int k = 0; k < 2; ++k) \
;         acc[ai][bj][m][n] = __builtin_amdgcn_mfma_f32_16x16x32_bf16(Bt[n][k], At[m][k], acc[ai][bj][m][n], 0, 0, 0); __builtin_amdgcn_s_setprio(0); } while (0)
; #define PG8_WAIT_V(n) asm volatile("s_waitcnt vmcnt(" #n ")" ::: "memory")
; #define PG8_WAIT_L(n) asm volatile("s_waitcnt lgkmcnt(" #n ")" ::: "memory")
; #define PG8_BAR __builtin_amdgcn_s_barrier()
; #define PG8_SCHED __builtin_amdgcn_sched_barrier(0)
; template <class Epi, class Sched, bool ALIGN_EPI = false, bool SP2 = false>
; __device__ __forceinline__ void gemm_phase(PG8_LAS unsigned char* lds, const Gemm g, const Sched& S, const Epi& E, int tid_in) {
;     ...
;             PG8_LDB(B0, 1, 0); PG8_LDB(B1, 1, 1); PG8_SCHED; PG8_LDA(At, 1, 0); PG8_STAGE(PG8_SA(0, 1), a2 + hstep, voffA);
;             PG8_WAIT_V(8); PG8_WAIT_L(0); PG8_BAR; PG8_MMA(0, 0, At, B0); PG8_MMA(0, 1, At, B1); PG8_BAR; PG8_SCHED;
;             PG8_LDA(At, 1, 1); PG8_STAGE(PG8_SB(1, 0), b3, voffB); PG8_STAGE(PG8_SB(1, 1), b3 + hstepB, voffB); PG8_STAGE(PG8_SA(1, 0), a3, voffA);
;             PG8_WAIT_V(8); PG8_WAIT_L(0); PG8_BAR; PG8_MMA(1, 0, At, B0); PG8_MMA(1, 1, At, B1); PG8_BAR; PG8_SCHED;
	s_add_i32 s33, 0, 0x18000
	s_add_i32 s50, 0, 0x1c000
	v_add_u32_e32 v166, s33, v137
	v_add_u32_e32 v182, s50, v137
	ds_read_b128 v[146:149], v166
	ds_read_b128 v[158:161], v166 offset:1024
	ds_read_b128 v[162:165], v166 offset:2048
	ds_read_b128 v[166:169], v166 offset:3072
	ds_read_b128 v[170:173], v182
	ds_read_b128 v[174:177], v182 offset:1024
	ds_read_b128 v[178:181], v182 offset:2048
	ds_read_b128 v[182:185], v182 offset:3072
	s_add_u32 s26, s54, 0x204000
	s_addc_u32 s27, s55, 0
	s_mov_b32 m0, s58
	v_lshl_add_u64 v[226:227], s[26:27], 0, v[128:129]
	ds_read_b128 v[186:189], v155 offset:32768
	ds_read_b128 v[190:193], v155 offset:33792
	ds_read_b128 v[194:197], v155 offset:34816
	ds_read_b128 v[198:201], v155 offset:35840
	ds_read_b128 v[202:205], v155 offset:36864
	ds_read_b128 v[206:209], v155 offset:37888
	ds_read_b128 v[210:213], v155 offset:38912
	ds_read_b128 v[214:217], v155 offset:39936
	global_load_lds_dwordx4 v[226:227], off
	v_lshl_add_u64 v[226:227], s[26:27], 0, v[132:133]
	s_mov_b32 m0, s59
	s_nop 0
	global_load_lds_dwordx4 v[226:227], off
	s_waitcnt vmcnt(8)
	s_waitcnt lgkmcnt(0)
	s_barrier
	s_setprio 1
	s_waitcnt lgkmcnt(0)
	v_mfma_f32_16x16x32_bf16 v[124:127], v[146:149], v[186:189], v[124:127]
	v_mfma_f32_16x16x32_bf16 v[120:123], v[162:165], v[186:189], v[120:123]
	v_mfma_f32_16x16x32_bf16 v[108:111], v[146:149], v[194:197], v[108:111]
	v_mfma_f32_16x16x32_bf16 v[104:107], v[162:165], v[194:197], v[104:107]
	v_mfma_f32_16x16x32_bf16 v[92:95], v[146:149], v[202:205], v[92:95]
	v_mfma_f32_16x16x32_bf16 v[88:91], v[162:165], v[202:205], v[88:91]
	v_mfma_f32_16x16x32_bf16 v[76:79], v[146:149], v[210:213], v[76:79]
	v_mfma_f32_16x16x32_bf16 v[72:75], v[162:165], v[210:213], v[72:75]
	v_mfma_f32_16x16x32_bf16 v[124:127], v[158:161], v[190:193], v[124:127]
	v_mfma_f32_16x16x32_bf16 v[120:123], v[166:169], v[190:193], v[120:123]
	v_mfma_f32_16x16x32_bf16 v[108:111], v[158:161], v[198:201], v[108:111]
	v_mfma_f32_16x16x32_bf16 v[104:107], v[166:169], v[198:201], v[104:107]
	v_mfma_f32_16x16x32_bf16 v[92:95], v[158:161], v[206:209], v[92:95]
	v_mfma_f32_16x16x32_bf16 v[88:91], v[166:169], v[206:209], v[88:91]
	v_mfma_f32_16x16x32_bf16 v[76:79], v[158:161], v[214:217], v[76:79]
	v_mfma_f32_16x16x32_bf16 v[72:75], v[166:169], v[214:217], v[72:75]
	s_setprio 0
	s_setprio 1
	v_mfma_f32_16x16x32_bf16 v[116:119], v[170:173], v[186:189], v[116:119]
	v_mfma_f32_16x16x32_bf16 v[112:115], v[178:181], v[186:189], v[112:115]
	v_mfma_f32_16x16x32_bf16 v[100:103], v[170:173], v[194:197], v[100:103]
	v_mfma_f32_16x16x32_bf16 v[96:99], v[178:181], v[194:197], v[96:99]
	v_mfma_f32_16x16x32_bf16 v[84:87], v[170:173], v[202:205], v[84:87]
	v_mfma_f32_16x16x32_bf16 v[80:83], v[178:181], v[202:205], v[80:83]
	v_mfma_f32_16x16x32_bf16 v[68:71], v[170:173], v[210:213], v[68:71]
	v_mfma_f32_16x16x32_bf16 v[64:67], v[178:181], v[210:213], v[64:67]
	v_mfma_f32_16x16x32_bf16 v[116:119], v[174:177], v[190:193], v[116:119]
	v_mfma_f32_16x16x32_bf16 v[112:115], v[182:185], v[190:193], v[112:115]
	v_mfma_f32_16x16x32_bf16 v[100:103], v[174:177], v[198:201], v[100:103]
	v_mfma_f32_16x16x32_bf16 v[96:99], v[182:185], v[198:201], v[96:99]
	v_mfma_f32_16x16x32_bf16 v[84:87], v[174:177], v[206:209], v[84:87]
	v_mfma_f32_16x16x32_bf16 v[80:83], v[182:185], v[206:209], v[80:83]
	v_mfma_f32_16x16x32_bf16 v[68:71], v[174:177], v[214:217], v[68:71]
	v_mfma_f32_16x16x32_bf16 v[64:67], v[182:185], v[214:217], v[64:67]
	s_setprio 0
	s_barrier
	s_add_i32 s26, s33, s56
	v_lshl_add_u64 v[218:219], v[218:219], 0, s[38:39]
	s_mov_b32 m0, s26
	ds_read_b128 v[186:189], v155 offset:49152
	ds_read_b128 v[190:193], v155 offset:50176
	ds_read_b128 v[194:197], v155 offset:51200
	ds_read_b128 v[198:201], v155 offset:52224
	ds_read_b128 v[202:205], v155 offset:53248
	ds_read_b128 v[206:209], v155 offset:54272
	ds_read_b128 v[210:213], v155 offset:55296
	ds_read_b128 v[214:217], v155 offset:56320
	global_load_lds_dwordx4 v[218:219], off
	s_add_i32 m0, s26, 0x2000
	s_add_u32 s26, s52, 0x80080
	v_lshl_add_u64 v[218:219], v[220:221], 0, s[38:39]
	s_addc_u32 s27, s53, 0
	s_add_i32 s33, s50, s56
	global_load_lds_dwordx4 v[218:219], off
	v_lshl_add_u64 v[218:219], s[26:27], 0, v[130:131]
	s_mov_b32 m0, s33
	s_nop 0
	global_load_lds_dwordx4 v[218:219], off
	v_lshl_add_u64 v[218:219], s[26:27], 0, v[134:135]
	s_add_i32 m0, s33, 0x2000
	s_nop 0
	global_load_lds_dwordx4 v[218:219], off
	v_lshl_add_u64 v[218:219], v[222:223], 0, s[38:39]
	s_mov_b32 m0, s61
	s_nop 0
	global_load_lds_dwordx4 v[218:219], off
	v_lshl_add_u64 v[218:219], v[224:225], 0, s[38:39]
	s_mov_b32 m0, s62
	s_nop 0
	global_load_lds_dwordx4 v[218:219], off
	s_waitcnt vmcnt(8)
	s_waitcnt lgkmcnt(0)
	s_barrier
; #define PG8_LAS __attribute__((address_space(3)))
; #define PG8_BAR __builtin_amdgcn_s_barrier()
; template <class Epi, class Sched, bool ALIGN_EPI = false, bool SP2 = false>
; __device__ __forceinline__ void gemm_phase(PG8_LAS unsigned char* lds, const Gemm g, const Sched& S, const Epi& E, int tid_in) {
;     ...
;             PG8_WAIT_V(8); PG8_WAIT_L(0); PG8_BAR; PG8_MMA(1, 0, At, B0); PG8_MMA(1, 1, At, B1); PG8_BAR; PG8_SCHED;
;     __device__ __forceinline__ void operator()(const f32x4 (&acc)[2][2][4][2], const Unit& u, int wr, int wc, int fr, int fq) const {
;         const int lane = fr + 16 * fq, r = lane >> 2, p = lane & 3; PG8_LAS unsigned char* stg = lds + STG_OFF + (wr * 4 + wc) * STG_WAVE;
; #pragma unroll
;         for (int ai = 0; ai < 2; ++ai)
; #pragma unroll
;             for (int m = 0; m < 4; ++m) {
;                 const int row = u.pm * BM + ai * HALF + wr * 64 + m * 16 + r; float q = 0.f;
; #pragma unroll
;                 for (int bj = 0; bj < 2; ++bj) {
;                     const size_t off = (size_t)row * 2048 + u.pn * BM + wc * 64 + bj * 32 + 8 * p;
;                     f32x4 b0, b1;
;                     if (BASE_F32) { b0 = *(const f32x4*)((const float*)base + off); b1 = *(const f32x4*)((const float*)base + off + 4); }
;                     else { const u32x4 bb = *(const u32x4*)((const bf16_t*)base + off);
;                         b0 = (f32x4){__uint_as_float(bb.x << 16), __uint_as_float(bb.x & 0xffff0000u), __uint_as_float(bb.y << 16), __uint_as_float(bb.y & 0xffff0000u)};
;                         b1 = (f32x4){__uint_as_float(bb.z << 16), __uint_as_float(bb.z & 0xffff0000u), __uint_as_float(bb.w << 16), __uint_as_float(bb.w & 0xffff0000u)}; }
; #pragma unroll
;                     for (int n = 0; n < 2; ++n) *(PG8_LAS f32x4*)(stg + fr * STG_ROW + n * 64 + fq * 16) = acc[ai][bj][m][n];
;                     const f32x4 v0 = *(const PG8_LAS f32x4*)(stg + r * STG_ROW + p * 32) + b0, v1 = *(const PG8_LAS f32x4*)(stg + r * STG_ROW + p * 32 + 16) + b1;
;                     q += ((v0[0] * v0[0] + v0[1] * v0[1]) + (v0[2] * v0[2] + v0[3] * v0[3])) + ((v1[0] * v1[0] + v1[1] * v1[1]) + (v1[2] * v1[2] + v1[3] * v1[3]));
;                     u32x4 w; w.x = cvt_pk_bf16(v0[0], v0[1]); w.y = cvt_pk_bf16(v0[2], v0[3]); w.z = cvt_pk_bf16(v1[0], v1[1]); w.w = cvt_pk_bf16(v1[2], v1[3]);
;                     *(u32x4*)(out + off) = w;
	s_setprio 1
	s_waitcnt lgkmcnt(0)
	v_mfma_f32_16x16x32_bf16 v[60:63], v[146:149], v[186:189], v[60:63]
	v_mfma_f32_16x16x32_bf16 v[56:59], v[162:165], v[186:189], v[56:59]
	v_mfma_f32_16x16x32_bf16 v[44:47], v[146:149], v[194:197], v[44:47]
	v_mfma_f32_16x16x32_bf16 v[40:43], v[162:165], v[194:197], v[40:43]
	v_mfma_f32_16x16x32_bf16 v[28:31], v[146:149], v[202:205], v[28:31]
	v_mfma_f32_16x16x32_bf16 v[24:27], v[162:165], v[202:205], v[24:27]
	v_mfma_f32_16x16x32_bf16 v[12:15], v[146:149], v[210:213], v[12:15]
	v_mfma_f32_16x16x32_bf16 v[8:11], v[162:165], v[210:213], v[8:11]
	v_mfma_f32_16x16x32_bf16 v[60:63], v[158:161], v[190:193], v[60:63]
	v_mfma_f32_16x16x32_bf16 v[56:59], v[166:169], v[190:193], v[56:59]
	v_mfma_f32_16x16x32_bf16 v[44:47], v[158:161], v[198:201], v[44:47]
	v_mfma_f32_16x16x32_bf16 v[40:43], v[166:169], v[198:201], v[40:43]
	v_mfma_f32_16x16x32_bf16 v[28:31], v[158:161], v[206:209], v[28:31]
	v_mfma_f32_16x16x32_bf16 v[24:27], v[166:169], v[206:209], v[24:27]
	v_mfma_f32_16x16x32_bf16 v[12:15], v[158:161], v[214:217], v[12:15]
	v_mfma_f32_16x16x32_bf16 v[8:11], v[166:169], v[214:217], v[8:11]
	s_setprio 0
	s_setprio 1
	v_mfma_f32_16x16x32_bf16 v[52:55], v[170:173], v[186:189], v[52:55]
	v_mfma_f32_16x16x32_bf16 v[48:51], v[178:181], v[186:189], v[48:51]
	v_mfma_f32_16x16x32_bf16 v[36:39], v[170:173], v[194:197], v[36:39]
	v_mfma_f32_16x16x32_bf16 v[32:35], v[178:181], v[194:197], v[32:35]
	v_mfma_f32_16x16x32_bf16 v[20:23], v[170:173], v[202:205], v[20:23]
	v_mfma_f32_16x16x32_bf16 v[16:19], v[178:181], v[202:205], v[16:19]
	v_mfma_f32_16x16x32_bf16 v[4:7], v[170:173], v[210:213], v[4:7]
	v_mfma_f32_16x16x32_bf16 v[0:3], v[178:181], v[210:213], v[0:3]
	v_mfma_f32_16x16x32_bf16 v[52:55], v[174:177], v[190:193], v[52:55]
	v_mfma_f32_16x16x32_bf16 v[48:51], v[182:185], v[190:193], v[48:51]
	v_mfma_f32_16x16x32_bf16 v[36:39], v[174:177], v[198:201], v[36:39]
	v_mfma_f32_16x16x32_bf16 v[32:35], v[182:185], v[198:201], v[32:35]
	v_mfma_f32_16x16x32_bf16 v[20:23], v[174:177], v[206:209], v[20:23]
	v_mfma_f32_16x16x32_bf16 v[16:19], v[182:185], v[206:209], v[16:19]
	v_mfma_f32_16x16x32_bf16 v[4:7], v[174:177], v[214:217], v[4:7]
	v_mfma_f32_16x16x32_bf16 v[0:3], v[182:185], v[214:217], v[0:3]
	s_setprio 0
	s_barrier
	s_add_i32 s70, s70, 2
	s_add_u32 s68, s68, 0x100
	s_addc_u32 s69, s69, 0
	s_cmpk_gt_u32 s70, 0x7d
	s_mov_b64 s[50:51], s[10:11]
	s_cbranch_scc0 .LBB0_949
	v_lshl_add_u32 v148, s66, 8, v150
	v_lshl_or_b32 v146, s48, 8, v136
	v_lshl_add_u32 v147, v148, 11, v146
	v_lshlrev_b32_e32 v159, 1, v147
	v_lshlrev_b32_e32 v208, 3, v148
	global_load_dwordx4 v[160:163], v159, s[28:29]
	global_load_dwordx4 v[164:167], v159, s[28:29] offset:64
	v_add_u32_e32 v149, 0x10000, v159
	global_load_dwordx4 v[168:171], v149, s[28:29]
	global_load_dwordx4 v[172:175], v149, s[28:29] offset:64
	v_add_u32_e32 v209, 0x20000, v159
	global_load_dwordx4 v[176:179], v209, s[28:29]
	global_load_dwordx4 v[180:183], v209, s[28:29] offset:64
	v_add_u32_e32 v149, 0x30000, v159
	global_load_dwordx4 v[184:187], v149, s[28:29]
	global_load_dwordx4 v[188:191], v149, s[28:29] offset:64
	v_add_u32_e32 v209, 0x80000, v159
	global_load_dwordx4 v[192:195], v209, s[28:29]
	global_load_dwordx4 v[196:199], v209, s[28:29] offset:64
	v_add_u32_e32 v149, 0x90000, v159
	global_load_dwordx4 v[200:203], v149, s[28:29]
	global_load_dwordx4 v[204:207], v149, s[28:29] offset:64
	v_add_u32_e32 v209, 0xa0000, v159
	global_load_dwordx4 v[212:215], v209, s[28:29]
	global_load_dwordx4 v[216:219], v209, s[28:29] offset:64
	v_add_u32_e32 v149, 0xb0000, v159
	global_load_dwordx4 v[220:223], v149, s[28:29]
	global_load_dwordx4 v[224:227], v149, s[28:29] offset:64
	s_and_b64 vcc, exec, s[40:41]
	s_cbranch_vccz .LBB0_952
	s_barrier
.LBB0_952:
	ds_write_b128 v156, v[124:127]
	ds_write_b128 v156, v[120:123] offset:64
	ds_read_b128 v[120:123], v157
	ds_read_b128 v[124:127], v157 offset:16
	ds_write_b128 v156, v[116:119]
	ds_write_b128 v156, v[112:115] offset:64
	ds_read_b128 v[112:115], v157
	ds_read_b128 v[116:119], v157 offset:16
	s_waitcnt vmcnt(15) lgkmcnt(4)
	v_lshlrev_b32_e32 v236, 16, v160
	v_and_b32_e32 v237, 0xffff0000, v160
	v_lshlrev_b32_e32 v238, 16, v161
	v_and_b32_e32 v239, 0xffff0000, v161
	v_lshlrev_b32_e32 v240, 16, v162
	v_and_b32_e32 v241, 0xffff0000, v162
	v_lshlrev_b32_e32 v242, 16, v163
	v_and_b32_e32 v243, 0xffff0000, v163
	v_pk_add_f32 v[120:121], v[120:121], v[236:237]
	v_pk_add_f32 v[122:123], v[122:123], v[238:239]
	v_pk_add_f32 v[124:125], v[124:125], v[240:241]
	v_pk_add_f32 v[126:127], v[126:127], v[242:243]
	v_mul_f32_e32 v236, v121, v121
	v_mul_f32_e32 v237, v123, v123
	v_mul_f32_e32 v238, v125, v125
	v_mul_f32_e32 v239, v127, v127
	v_fmac_f32_e32 v236, v120, v120
	v_fmac_f32_e32 v237, v122, v122
	v_fmac_f32_e32 v238, v124, v124
	v_fmac_f32_e32 v239, v126, v126
	v_cvt_pk_bf16_f32 v120, v120, v121
	v_cvt_pk_bf16_f32 v121, v122, v123
	v_cvt_pk_bf16_f32 v122, v124, v125
	v_cvt_pk_bf16_f32 v123, v126, v127
	v_add_f32_e32 v236, v236, v237
	v_add_f32_e32 v237, v238, v239
	v_add_f32_e32 v124, v236, v237
	global_store_dwordx4 v159, v[120:123], s[28:29]
	ds_write_b128 v156, v[108:111]
	ds_write_b128 v156, v[104:107] offset:64
	ds_read_b128 v[104:107], v157
	ds_read_b128 v[108:111], v157 offset:16
	s_waitcnt vmcnt(15) lgkmcnt(4)
; #define PG8_LAS __attribute__((address_space(3)))
; __device__ __forceinline__ unsigned cvt_pk_bf16(float lo, float hi) { unsigned r; asm volatile("v_cvt_pk_bf16_f32 %0, %1, %2" : "=v"(r) : "v"(lo), "v"(hi)); return r; }
;     __device__ __forceinline__ void operator()(const f32x4 (&acc)[2][2][4][2], const Unit& u, int wr, int wc, int fr, int fq) const {
;     ...
;                 for (int bj = 0; bj < 2; ++bj) {
;                     const size_t off = (size_t)row * 2048 + u.pn * BM + wc * 64 + bj * 32 + 8 * p;
;                     f32x4 b0, b1;
;                     if (BASE_F32) { b0 = *(const f32x4*)((const float*)base + off); b1 = *(const f32x4*)((const float*)base + off + 4); }
;                     else { const u32x4 bb = *(const u32x4*)((const bf16_t*)base + off);
;                         b0 = (f32x4){__uint_as_float(bb.x << 16), __uint_as_float(bb.x & 0xffff0000u), __uint_as_float(bb.y << 16), __uint_as_float(bb.y & 0xffff0000u)};
;                         b1 = (f32x4){__uint_as_float(bb.z << 16), __uint_as_float(bb.z & 0xffff0000u), __uint_as_float(bb.w << 16), __uint_as_float(bb.w & 0xffff0000u)}; }
; #pragma unroll
;                     for (int n = 0; n < 2; ++n) *(PG8_LAS f32x4*)(stg + fr * STG_ROW + n * 64 + fq * 16) = acc[ai][bj][m][n];
;                     const f32x4 v0 = *(const PG8_LAS f32x4*)(stg + r * STG_ROW + p * 32) + b0, v1 = *(const PG8_LAS f32x4*)(stg + r * STG_ROW + p * 32 + 16) + b1;
;                     q += ((v0[0] * v0[0] + v0[1] * v0[1]) + (v0[2] * v0[2] + v0[3] * v0[3])) + ((v1[0] * v1[0] + v1[1] * v1[1]) + (v1[2] * v1[2] + v1[3] * v1[3]));
;                     u32x4 w; w.x = cvt_pk_bf16(v0[0], v0[1]); w.y = cvt_pk_bf16(v0[2], v0[3]); w.z = cvt_pk_bf16(v1[0], v1[1]); w.w = cvt_pk_bf16(v1[2], v1[3]);
;                     *(u32x4*)(out + off) = w;
;                 }
;                 q += __shfl_xor(q, 1); q += __shfl_xor(q, 2);
;                 if (p == 0) atomicAdd(ssn + row, (u64)(q * SS_SCALE));
	v_lshlrev_b32_e32 v236, 16, v164
	v_and_b32_e32 v237, 0xffff0000, v164
	v_lshlrev_b32_e32 v238, 16, v165
	v_and_b32_e32 v239, 0xffff0000, v165
	v_lshlrev_b32_e32 v240, 16, v166
	v_and_b32_e32 v241, 0xffff0000, v166
	v_lshlrev_b32_e32 v242, 16, v167
	v_and_b32_e32 v243, 0xffff0000, v167
	v_pk_add_f32 v[112:113], v[112:113], v[236:237]
	v_pk_add_f32 v[114:115], v[114:115], v[238:239]
	v_pk_add_f32 v[116:117], v[116:117], v[240:241]
	v_pk_add_f32 v[118:119], v[118:119], v[242:243]
	v_mul_f32_e32 v236, v113, v113
	v_mul_f32_e32 v237, v115, v115
	v_mul_f32_e32 v238, v117, v117
	v_mul_f32_e32 v239, v119, v119
	v_fmac_f32_e32 v236, v112, v112
	v_fmac_f32_e32 v237, v114, v114
	v_fmac_f32_e32 v238, v116, v116
	v_fmac_f32_e32 v239, v118, v118
	v_cvt_pk_bf16_f32 v112, v112, v113
	v_cvt_pk_bf16_f32 v113, v114, v115
	v_cvt_pk_bf16_f32 v114, v116, v117
	v_cvt_pk_bf16_f32 v115, v118, v119
	v_add_f32_e32 v236, v236, v237
	v_add_f32_e32 v237, v238, v239
	v_add_f32_e32 v116, v236, v237
	global_store_dwordx4 v159, v[112:115], s[28:29] offset:64
	v_add_f32_e32 v117, v124, v116
	s_nop 1
	v_add_f32_dpp v118, v117, v117 quad_perm:[1,0,3,2] row_mask:0xf bank_mask:0xf
	s_nop 1
	v_add_f32_dpp v119, v118, v118 quad_perm:[2,3,0,1] row_mask:0xf bank_mask:0xf
	v_mul_f32_e32 v126, 0x49800000, v119
	v_trunc_f32_e32 v126, v126
	v_mul_f32_e32 v127, 0x2f800000, v126
	v_floor_f32_e32 v127, v127
	v_fmac_f32_e32 v126, 0xcf800000, v127
	v_cvt_u32_f32_e32 v126, v126
	v_cvt_u32_f32_e32 v127, v127
	s_mov_b64 exec, s[6:7]
	global_atomic_add_x2 v208, v[126:127], s[12:13]
	s_mov_b64 exec, -1
	ds_write_b128 v156, v[100:103]
	ds_write_b128 v156, v[96:99] offset:64
	ds_read_b128 v[96:99], v157
	ds_read_b128 v[100:103], v157 offset:16
	s_waitcnt vmcnt(16) lgkmcnt(4)
	v_lshlrev_b32_e32 v236, 16, v168
	v_and_b32_e32 v237, 0xffff0000, v168
	v_lshlrev_b32_e32 v238, 16, v169
	v_and_b32_e32 v239, 0xffff0000, v169
	v_lshlrev_b32_e32 v240, 16, v170
	v_and_b32_e32 v241, 0xffff0000, v170
	v_lshlrev_b32_e32 v242, 16, v171
	v_and_b32_e32 v243, 0xffff0000, v171
	v_pk_add_f32 v[104:105], v[104:105], v[236:237]
	v_pk_add_f32 v[106:107], v[106:107], v[238:239]
	v_pk_add_f32 v[108:109], v[108:109], v[240:241]
	v_pk_add_f32 v[110:111], v[110:111], v[242:243]
	v_mul_f32_e32 v236, v105, v105
	v_mul_f32_e32 v237, v107, v107
	v_mul_f32_e32 v238, v109, v109
	v_mul_f32_e32 v239, v111, v111
	v_fmac_f32_e32 v236, v104, v104
	v_fmac_f32_e32 v237, v106, v106
	v_fmac_f32_e32 v238, v108, v108
	v_fmac_f32_e32 v239, v110, v110
	v_cvt_pk_bf16_f32 v104, v104, v105
	v_cvt_pk_bf16_f32 v105, v106, v107
	v_cvt_pk_bf16_f32 v106, v108, v109
	v_cvt_pk_bf16_f32 v107, v110, v111
	v_add_f32_e32 v236, v236, v237
	v_add_f32_e32 v237, v238, v239
	v_add_f32_e32 v108, v236, v237
	v_add_u32_e32 v147, 0x10000, v159
	global_store_dwordx4 v147, v[104:107], s[28:29]
	ds_write_b128 v156, v[92:95]
	ds_write_b128 v156, v[88:91] offset:64
	ds_read_b128 v[88:91], v157
	ds_read_b128 v[92:95], v157 offset:16
	s_waitcnt vmcnt(16) lgkmcnt(4)
	v_lshlrev_b32_e32 v236, 16, v172
	v_and_b32_e32 v237, 0xffff0000, v172
	v_lshlrev_b32_e32 v238, 16, v173
	v_and_b32_e32 v239, 0xffff0000, v173
	v_lshlrev_b32_e32 v240, 16, v174
	v_and_b32_e32 v241, 0xffff0000, v174
	v_lshlrev_b32_e32 v242, 16, v175
	v_and_b32_e32 v243, 0xffff0000, v175
	v_pk_add_f32 v[96:97], v[96:97], v[236:237]
	v_pk_add_f32 v[98:99], v[98:99], v[238:239]
	v_pk_add_f32 v[100:101], v[100:101], v[240:241]
	v_pk_add_f32 v[102:103], v[102:103], v[242:243]
	v_mul_f32_e32 v236, v97, v97
	v_mul_f32_e32 v237, v99, v99
	v_mul_f32_e32 v238, v101, v101
	v_mul_f32_e32 v239, v103, v103
	v_fmac_f32_e32 v236, v96, v96
	v_fmac_f32_e32 v237, v98, v98
	v_fmac_f32_e32 v238, v100, v100
	v_fmac_f32_e32 v239, v102, v102
	v_cvt_pk_bf16_f32 v96, v96, v97
	v_cvt_pk_bf16_f32 v97, v98, v99
	v_cvt_pk_bf16_f32 v98, v100, v101
	v_cvt_pk_bf16_f32 v99, v102, v103
	v_add_f32_e32 v236, v236, v237
	v_add_f32_e32 v237, v238, v239
	v_add_f32_e32 v100, v236, v237
	global_store_dwordx4 v147, v[96:99], s[28:29] offset:64
	v_add_f32_e32 v101, v108, v100
	s_nop 1
	v_add_f32_dpp v102, v101, v101 quad_perm:[1,0,3,2] row_mask:0xf bank_mask:0xf
	s_nop 1
	v_add_f32_dpp v103, v102, v102 quad_perm:[2,3,0,1] row_mask:0xf bank_mask:0xf
	v_mul_f32_e32 v110, 0x49800000, v103
	v_trunc_f32_e32 v110, v110
	v_mul_f32_e32 v111, 0x2f800000, v110
	v_floor_f32_e32 v111, v111
	v_fmac_f32_e32 v110, 0xcf800000, v111
	v_cvt_u32_f32_e32 v110, v110
	v_cvt_u32_f32_e32 v111, v111
	s_mov_b64 exec, s[6:7]
	global_atomic_add_x2 v208, v[110:111], s[12:13] offset:128
	s_mov_b64 exec, -1
	ds_write_b128 v156, v[84:87]
	ds_write_b128 v156, v[80:83] offset:64
	ds_read_b128 v[80:83], v157
	ds_read_b128 v[84:87], v157 offset:16
	s_waitcnt vmcnt(17) lgkmcnt(4)
	v_lshlrev_b32_e32 v236, 16, v176
	v_and_b32_e32 v237, 0xffff0000, v176
	v_lshlrev_b32_e32 v238, 16, v177
	v_and_b32_e32 v239, 0xffff0000, v177
	v_lshlrev_b32_e32 v240, 16, v178
	v_and_b32_e32 v241, 0xffff0000, v178
	v_lshlrev_b32_e32 v242, 16, v179
	v_and_b32_e32 v243, 0xffff0000, v179
	v_pk_add_f32 v[88:89], v[88:89], v[236:237]
	v_pk_add_f32 v[90:91], v[90:91], v[238:239]
	v_pk_add_f32 v[92:93], v[92:93], v[240:241]
	v_pk_add_f32 v[94:95], v[94:95], v[242:243]
	v_mul_f32_e32 v236, v89, v89
	v_mul_f32_e32 v237, v91, v91
	v_mul_f32_e32 v238, v93, v93
	v_mul_f32_e32 v239, v95, v95
	v_fmac_f32_e32 v236, v88, v88
	v_fmac_f32_e32 v237, v90, v90
	v_fmac_f32_e32 v238, v92, v92
	v_fmac_f32_e32 v239, v94, v94
	v_cvt_pk_bf16_f32 v88, v88, v89
	v_cvt_pk_bf16_f32 v89, v90, v91
	v_cvt_pk_bf16_f32 v90, v92, v93
	v_cvt_pk_bf16_f32 v91, v94, v95
	v_add_f32_e32 v236, v236, v237
	v_add_f32_e32 v237, v238, v239
	v_add_f32_e32 v92, v236, v237
	v_add_u32_e32 v146, 0x20000, v159
	global_store_dwordx4 v146, v[88:91], s[28:29]
	ds_write_b128 v156, v[76:79]
	ds_write_b128 v156, v[72:75] offset:64
	ds_read_b128 v[72:75], v157
	ds_read_b128 v[76:79], v157 offset:16
	s_waitcnt vmcnt(17) lgkmcnt(4)
; #define PG8_LAS __attribute__((address_space(3)))
; __device__ __forceinline__ unsigned cvt_pk_bf16(float lo, float hi) { unsigned r; asm volatile("v_cvt_pk_bf16_f32 %0, %1, %2" : "=v"(r) : "v"(lo), "v"(hi)); return r; }
;     __device__ __forceinline__ void operator()(const f32x4 (&acc)[2][2][4][2], const Unit& u, int wr, int wc, int fr, int fq) const {
;     ...
;                 for (int bj = 0; bj < 2; ++bj) {
;                     const size_t off = (size_t)row * 2048 + u.pn * BM + wc * 64 + bj * 32 + 8 * p;
;                     f32x4 b0, b1;
;                     if (BASE_F32) { b0 = *(const f32x4*)((const float*)base + off); b1 = *(const f32x4*)((const float*)base + off + 4); }
;                     else { const u32x4 bb = *(const u32x4*)((const bf16_t*)base + off);
;                         b0 = (f32x4){__uint_as_float(bb.x << 16), __uint_as_float(bb.x & 0xffff0000u), __uint_as_float(bb.y << 16), __uint_as_float(bb.y & 0xffff0000u)};
;                         b1 = (f32x4){__uint_as_float(bb.z << 16), __uint_as_float(bb.z & 0xffff0000u), __uint_as_float(bb.w << 16), __uint_as_float(bb.w & 0xffff0000u)}; }
; #pragma unroll
;                     for (int n = 0; n < 2; ++n) *(PG8_LAS f32x4*)(stg + fr * STG_ROW + n * 64 + fq * 16) = acc[ai][bj][m][n];
;                     const f32x4 v0 = *(const PG8_LAS f32x4*)(stg + r * STG_ROW + p * 32) + b0, v1 = *(const PG8_LAS f32x4*)(stg + r * STG_ROW + p * 32 + 16) + b1;
;                     q += ((v0[0] * v0[0] + v0[1] * v0[1]) + (v0[2] * v0[2] + v0[3] * v0[3])) + ((v1[0] * v1[0] + v1[1] * v1[1]) + (v1[2] * v1[2] + v1[3] * v1[3]));
;                     u32x4 w; w.x = cvt_pk_bf16(v0[0], v0[1]); w.y = cvt_pk_bf16(v0[2], v0[3]); w.z = cvt_pk_bf16(v1[0], v1[1]); w.w = cvt_pk_bf16(v1[2], v1[3]);
;                     *(u32x4*)(out + off) = w;
;                 }
;                 q += __shfl_xor(q, 1); q += __shfl_xor(q, 2);
;                 if (p == 0) atomicAdd(ssn + row, (u64)(q * SS_SCALE));
	v_lshlrev_b32_e32 v236, 16, v180
	v_and_b32_e32 v237, 0xffff0000, v180
	v_lshlrev_b32_e32 v238, 16, v181
	v_and_b32_e32 v239, 0xffff0000, v181
	v_lshlrev_b32_e32 v240, 16, v182
	v_and_b32_e32 v241, 0xffff0000, v182
	v_lshlrev_b32_e32 v242, 16, v183
	v_and_b32_e32 v243, 0xffff0000, v183
	v_pk_add_f32 v[80:81], v[80:81], v[236:237]
	v_pk_add_f32 v[82:83], v[82:83], v[238:239]
	v_pk_add_f32 v[84:85], v[84:85], v[240:241]
	v_pk_add_f32 v[86:87], v[86:87], v[242:243]
	v_mul_f32_e32 v236, v81, v81
	v_mul_f32_e32 v237, v83, v83
	v_mul_f32_e32 v238, v85, v85
	v_mul_f32_e32 v239, v87, v87
	v_fmac_f32_e32 v236, v80, v80
	v_fmac_f32_e32 v237, v82, v82
	v_fmac_f32_e32 v238, v84, v84
	v_fmac_f32_e32 v239, v86, v86
	v_cvt_pk_bf16_f32 v80, v80, v81
	v_cvt_pk_bf16_f32 v81, v82, v83
	v_cvt_pk_bf16_f32 v82, v84, v85
	v_cvt_pk_bf16_f32 v83, v86, v87
	v_add_f32_e32 v236, v236, v237
	v_add_f32_e32 v237, v238, v239
	v_add_f32_e32 v84, v236, v237
	global_store_dwordx4 v146, v[80:83], s[28:29] offset:64
	v_add_f32_e32 v85, v92, v84
	s_nop 1
	v_add_f32_dpp v86, v85, v85 quad_perm:[1,0,3,2] row_mask:0xf bank_mask:0xf
	s_nop 1
	v_add_f32_dpp v87, v86, v86 quad_perm:[2,3,0,1] row_mask:0xf bank_mask:0xf
	v_mul_f32_e32 v94, 0x49800000, v87
	v_trunc_f32_e32 v94, v94
	v_mul_f32_e32 v95, 0x2f800000, v94
	v_floor_f32_e32 v95, v95
	v_fmac_f32_e32 v94, 0xcf800000, v95
	v_cvt_u32_f32_e32 v94, v94
	v_cvt_u32_f32_e32 v95, v95
	s_mov_b64 exec, s[6:7]
	global_atomic_add_x2 v208, v[94:95], s[12:13] offset:256
	s_mov_b64 exec, -1
	ds_write_b128 v156, v[68:71]
	ds_write_b128 v156, v[64:67] offset:64
	ds_read_b128 v[64:67], v157
	ds_read_b128 v[68:71], v157 offset:16
	s_waitcnt vmcnt(18) lgkmcnt(4)
	v_lshlrev_b32_e32 v236, 16, v184
	v_and_b32_e32 v237, 0xffff0000, v184
	v_lshlrev_b32_e32 v238, 16, v185
	v_and_b32_e32 v239, 0xffff0000, v185
	v_lshlrev_b32_e32 v240, 16, v186
	v_and_b32_e32 v241, 0xffff0000, v186
	v_lshlrev_b32_e32 v242, 16, v187
	v_and_b32_e32 v243, 0xffff0000, v187
	v_pk_add_f32 v[72:73], v[72:73], v[236:237]
	v_pk_add_f32 v[74:75], v[74:75], v[238:239]
	v_pk_add_f32 v[76:77], v[76:77], v[240:241]
	v_pk_add_f32 v[78:79], v[78:79], v[242:243]
	v_mul_f32_e32 v236, v73, v73
	v_mul_f32_e32 v237, v75, v75
	v_mul_f32_e32 v238, v77, v77
	v_mul_f32_e32 v239, v79, v79
	v_fmac_f32_e32 v236, v72, v72
	v_fmac_f32_e32 v237, v74, v74
	v_fmac_f32_e32 v238, v76, v76
	v_fmac_f32_e32 v239, v78, v78
	v_cvt_pk_bf16_f32 v72, v72, v73
	v_cvt_pk_bf16_f32 v73, v74, v75
	v_cvt_pk_bf16_f32 v74, v76, v77
	v_cvt_pk_bf16_f32 v75, v78, v79
	v_add_f32_e32 v236, v236, v237
	v_add_f32_e32 v237, v238, v239
	v_add_f32_e32 v76, v236, v237
	v_add_u32_e32 v147, 0x30000, v159
	global_store_dwordx4 v147, v[72:75], s[28:29]
	ds_write_b128 v156, v[60:63]
	ds_write_b128 v156, v[56:59] offset:64
	ds_read_b128 v[56:59], v157
	ds_read_b128 v[60:63], v157 offset:16
	s_waitcnt vmcnt(18) lgkmcnt(4)
	v_lshlrev_b32_e32 v236, 16, v188
	v_and_b32_e32 v237, 0xffff0000, v188
	v_lshlrev_b32_e32 v238, 16, v189
	v_and_b32_e32 v239, 0xffff0000, v189
	v_lshlrev_b32_e32 v240, 16, v190
	v_and_b32_e32 v241, 0xffff0000, v190
	v_lshlrev_b32_e32 v242, 16, v191
	v_and_b32_e32 v243, 0xffff0000, v191
	v_pk_add_f32 v[64:65], v[64:65], v[236:237]
	v_pk_add_f32 v[66:67], v[66:67], v[238:239]
	v_pk_add_f32 v[68:69], v[68:69], v[240:241]
	v_pk_add_f32 v[70:71], v[70:71], v[242:243]
	v_mul_f32_e32 v236, v65, v65
	v_mul_f32_e32 v237, v67, v67
	v_mul_f32_e32 v238, v69, v69
	v_mul_f32_e32 v239, v71, v71
	v_fmac_f32_e32 v236, v64, v64
	v_fmac_f32_e32 v237, v66, v66
	v_fmac_f32_e32 v238, v68, v68
	v_fmac_f32_e32 v239, v70, v70
	v_cvt_pk_bf16_f32 v64, v64, v65
	v_cvt_pk_bf16_f32 v65, v66, v67
	v_cvt_pk_bf16_f32 v66, v68, v69
	v_cvt_pk_bf16_f32 v67, v70, v71
	v_add_f32_e32 v236, v236, v237
	v_add_f32_e32 v237, v238, v239
	v_add_f32_e32 v68, v236, v237
	global_store_dwordx4 v147, v[64:67], s[28:29] offset:64
	v_add_f32_e32 v69, v76, v68
	s_nop 1
	v_add_f32_dpp v70, v69, v69 quad_perm:[1,0,3,2] row_mask:0xf bank_mask:0xf
	s_nop 1
	v_add_f32_dpp v71, v70, v70 quad_perm:[2,3,0,1] row_mask:0xf bank_mask:0xf
	v_mul_f32_e32 v78, 0x49800000, v71
	v_trunc_f32_e32 v78, v78
	v_mul_f32_e32 v79, 0x2f800000, v78
	v_floor_f32_e32 v79, v79
	v_fmac_f32_e32 v78, 0xcf800000, v79
	v_cvt_u32_f32_e32 v78, v78
	v_cvt_u32_f32_e32 v79, v79
	s_mov_b64 exec, s[6:7]
	global_atomic_add_x2 v208, v[78:79], s[12:13] offset:384
	s_mov_b64 exec, -1
	ds_write_b128 v156, v[52:55]
	ds_write_b128 v156, v[48:51] offset:64
	ds_read_b128 v[48:51], v157
	ds_read_b128 v[52:55], v157 offset:16
	s_waitcnt vmcnt(19) lgkmcnt(4)
	v_lshlrev_b32_e32 v236, 16, v192
	v_and_b32_e32 v237, 0xffff0000, v192
	v_lshlrev_b32_e32 v238, 16, v193
	v_and_b32_e32 v239, 0xffff0000, v193
	v_lshlrev_b32_e32 v240, 16, v194
	v_and_b32_e32 v241, 0xffff0000, v194
	v_lshlrev_b32_e32 v242, 16, v195
	v_and_b32_e32 v243, 0xffff0000, v195
	v_pk_add_f32 v[56:57], v[56:57], v[236:237]
	v_pk_add_f32 v[58:59], v[58:59], v[238:239]
	v_pk_add_f32 v[60:61], v[60:61], v[240:241]
	v_pk_add_f32 v[62:63], v[62:63], v[242:243]
	v_mul_f32_e32 v236, v57, v57
	v_mul_f32_e32 v237, v59, v59
	v_mul_f32_e32 v238, v61, v61
	v_mul_f32_e32 v239, v63, v63
	v_fmac_f32_e32 v236, v56, v56
	v_fmac_f32_e32 v237, v58, v58
	v_fmac_f32_e32 v238, v60, v60
	v_fmac_f32_e32 v239, v62, v62
	v_cvt_pk_bf16_f32 v56, v56, v57
	v_cvt_pk_bf16_f32 v57, v58, v59
	v_cvt_pk_bf16_f32 v58, v60, v61
	v_cvt_pk_bf16_f32 v59, v62, v63
	v_add_f32_e32 v236, v236, v237
	v_add_f32_e32 v237, v238, v239
	v_add_f32_e32 v60, v236, v237
	v_add_u32_e32 v146, 0x80000, v159
	global_store_dwordx4 v146, v[56:59], s[28:29]
	ds_write_b128 v156, v[44:47]
	ds_write_b128 v156, v[40:43] offset:64
	ds_read_b128 v[40:43], v157
	ds_read_b128 v[44:47], v157 offset:16
	s_waitcnt vmcnt(19) lgkmcnt(4)
; #define PG8_LAS __attribute__((address_space(3)))
; __device__ __forceinline__ unsigned cvt_pk_bf16(float lo, float hi) { unsigned r; asm volatile("v_cvt_pk_bf16_f32 %0, %1, %2" : "=v"(r) : "v"(lo), "v"(hi)); return r; }
;     __device__ __forceinline__ void operator()(const f32x4 (&acc)[2][2][4][2], const Unit& u, int wr, int wc, int fr, int fq) const {
;     ...
;                 for (int bj = 0; bj < 2; ++bj) {
;                     const size_t off = (size_t)row * 2048 + u.pn * BM + wc * 64 + bj * 32 + 8 * p;
;                     f32x4 b0, b1;
;                     if (BASE_F32) { b0 = *(const f32x4*)((const float*)base + off); b1 = *(const f32x4*)((const float*)base + off + 4); }
;                     else { const u32x4 bb = *(const u32x4*)((const bf16_t*)base + off);
;                         b0 = (f32x4){__uint_as_float(bb.x << 16), __uint_as_float(bb.x & 0xffff0000u), __uint_as_float(bb.y << 16), __uint_as_float(bb.y & 0xffff0000u)};
;                         b1 = (f32x4){__uint_as_float(bb.z << 16), __uint_as_float(bb.z & 0xffff0000u), __uint_as_float(bb.w << 16), __uint_as_float(bb.w & 0xffff0000u)}; }
; #pragma unroll
;                     for (int n = 0; n < 2; ++n) *(PG8_LAS f32x4*)(stg + fr * STG_ROW + n * 64 + fq * 16) = acc[ai][bj][m][n];
;                     const f32x4 v0 = *(const PG8_LAS f32x4*)(stg + r * STG_ROW + p * 32) + b0, v1 = *(const PG8_LAS f32x4*)(stg + r * STG_ROW + p * 32 + 16) + b1;
;                     q += ((v0[0] * v0[0] + v0[1] * v0[1]) + (v0[2] * v0[2] + v0[3] * v0[3])) + ((v1[0] * v1[0] + v1[1] * v1[1]) + (v1[2] * v1[2] + v1[3] * v1[3]));
;                     u32x4 w; w.x = cvt_pk_bf16(v0[0], v0[1]); w.y = cvt_pk_bf16(v0[2], v0[3]); w.z = cvt_pk_bf16(v1[0], v1[1]); w.w = cvt_pk_bf16(v1[2], v1[3]);
;                     *(u32x4*)(out + off) = w;
;                 }
;                 q += __shfl_xor(q, 1); q += __shfl_xor(q, 2);
;                 if (p == 0) atomicAdd(ssn + row, (u64)(q * SS_SCALE));
	v_lshlrev_b32_e32 v236, 16, v196
	v_and_b32_e32 v237, 0xffff0000, v196
	v_lshlrev_b32_e32 v238, 16, v197
	v_and_b32_e32 v239, 0xffff0000, v197
	v_lshlrev_b32_e32 v240, 16, v198
	v_and_b32_e32 v241, 0xffff0000, v198
	v_lshlrev_b32_e32 v242, 16, v199
	v_and_b32_e32 v243, 0xffff0000, v199
	v_pk_add_f32 v[48:49], v[48:49], v[236:237]
	v_pk_add_f32 v[50:51], v[50:51], v[238:239]
	v_pk_add_f32 v[52:53], v[52:53], v[240:241]
	v_pk_add_f32 v[54:55], v[54:55], v[242:243]
	v_mul_f32_e32 v236, v49, v49
	v_mul_f32_e32 v237, v51, v51
	v_mul_f32_e32 v238, v53, v53
	v_mul_f32_e32 v239, v55, v55
	v_fmac_f32_e32 v236, v48, v48
	v_fmac_f32_e32 v237, v50, v50
	v_fmac_f32_e32 v238, v52, v52
	v_fmac_f32_e32 v239, v54, v54
	v_cvt_pk_bf16_f32 v48, v48, v49
	v_cvt_pk_bf16_f32 v49, v50, v51
	v_cvt_pk_bf16_f32 v50, v52, v53
	v_cvt_pk_bf16_f32 v51, v54, v55
	v_add_f32_e32 v236, v236, v237
	v_add_f32_e32 v237, v238, v239
	v_add_f32_e32 v52, v236, v237
	global_store_dwordx4 v146, v[48:51], s[28:29] offset:64
	v_add_f32_e32 v53, v60, v52
	s_nop 1
	v_add_f32_dpp v54, v53, v53 quad_perm:[1,0,3,2] row_mask:0xf bank_mask:0xf
	s_nop 1
	v_add_f32_dpp v55, v54, v54 quad_perm:[2,3,0,1] row_mask:0xf bank_mask:0xf
	v_mul_f32_e32 v62, 0x49800000, v55
	v_trunc_f32_e32 v62, v62
	v_mul_f32_e32 v63, 0x2f800000, v62
	v_floor_f32_e32 v63, v63
	v_fmac_f32_e32 v62, 0xcf800000, v63
	v_cvt_u32_f32_e32 v62, v62
	v_cvt_u32_f32_e32 v63, v63
	s_mov_b64 exec, s[6:7]
	global_atomic_add_x2 v208, v[62:63], s[12:13] offset:1024
	s_mov_b64 exec, -1
	ds_write_b128 v156, v[36:39]
	ds_write_b128 v156, v[32:35] offset:64
	ds_read_b128 v[32:35], v157
	ds_read_b128 v[36:39], v157 offset:16
	s_waitcnt vmcnt(20) lgkmcnt(4)
	v_lshlrev_b32_e32 v236, 16, v200
	v_and_b32_e32 v237, 0xffff0000, v200
	v_lshlrev_b32_e32 v238, 16, v201
	v_and_b32_e32 v239, 0xffff0000, v201
	v_lshlrev_b32_e32 v240, 16, v202
	v_and_b32_e32 v241, 0xffff0000, v202
	v_lshlrev_b32_e32 v242, 16, v203
	v_and_b32_e32 v243, 0xffff0000, v203
	v_pk_add_f32 v[40:41], v[40:41], v[236:237]
	v_pk_add_f32 v[42:43], v[42:43], v[238:239]
	v_pk_add_f32 v[44:45], v[44:45], v[240:241]
	v_pk_add_f32 v[46:47], v[46:47], v[242:243]
	v_mul_f32_e32 v236, v41, v41
	v_mul_f32_e32 v237, v43, v43
	v_mul_f32_e32 v238, v45, v45
	v_mul_f32_e32 v239, v47, v47
	v_fmac_f32_e32 v236, v40, v40
	v_fmac_f32_e32 v237, v42, v42
	v_fmac_f32_e32 v238, v44, v44
	v_fmac_f32_e32 v239, v46, v46
	v_cvt_pk_bf16_f32 v40, v40, v41
	v_cvt_pk_bf16_f32 v41, v42, v43
	v_cvt_pk_bf16_f32 v42, v44, v45
	v_cvt_pk_bf16_f32 v43, v46, v47
	v_add_f32_e32 v236, v236, v237
	v_add_f32_e32 v237, v238, v239
	v_add_f32_e32 v44, v236, v237
	v_add_u32_e32 v147, 0x90000, v159
	global_store_dwordx4 v147, v[40:43], s[28:29]
	ds_write_b128 v156, v[28:31]
	ds_write_b128 v156, v[24:27] offset:64
	ds_read_b128 v[24:27], v157
	ds_read_b128 v[28:31], v157 offset:16
	s_waitcnt vmcnt(20) lgkmcnt(4)
	v_lshlrev_b32_e32 v236, 16, v204
	v_and_b32_e32 v237, 0xffff0000, v204
	v_lshlrev_b32_e32 v238, 16, v205
	v_and_b32_e32 v239, 0xffff0000, v205
	v_lshlrev_b32_e32 v240, 16, v206
	v_and_b32_e32 v241, 0xffff0000, v206
	v_lshlrev_b32_e32 v242, 16, v207
	v_and_b32_e32 v243, 0xffff0000, v207
	v_pk_add_f32 v[32:33], v[32:33], v[236:237]
	v_pk_add_f32 v[34:35], v[34:35], v[238:239]
	v_pk_add_f32 v[36:37], v[36:37], v[240:241]
	v_pk_add_f32 v[38:39], v[38:39], v[242:243]
	v_mul_f32_e32 v236, v33, v33
	v_mul_f32_e32 v237, v35, v35
	v_mul_f32_e32 v238, v37, v37
	v_mul_f32_e32 v239, v39, v39
	v_fmac_f32_e32 v236, v32, v32
	v_fmac_f32_e32 v237, v34, v34
	v_fmac_f32_e32 v238, v36, v36
	v_fmac_f32_e32 v239, v38, v38
	v_cvt_pk_bf16_f32 v32, v32, v33
	v_cvt_pk_bf16_f32 v33, v34, v35
	v_cvt_pk_bf16_f32 v34, v36, v37
	v_cvt_pk_bf16_f32 v35, v38, v39
	v_add_f32_e32 v236, v236, v237
	v_add_f32_e32 v237, v238, v239
	v_add_f32_e32 v36, v236, v237
	global_store_dwordx4 v147, v[32:35], s[28:29] offset:64
	v_add_f32_e32 v37, v44, v36
	s_nop 1
	v_add_f32_dpp v38, v37, v37 quad_perm:[1,0,3,2] row_mask:0xf bank_mask:0xf
	s_nop 1
	v_add_f32_dpp v39, v38, v38 quad_perm:[2,3,0,1] row_mask:0xf bank_mask:0xf
	v_mul_f32_e32 v46, 0x49800000, v39
	v_trunc_f32_e32 v46, v46
	v_mul_f32_e32 v47, 0x2f800000, v46
	v_floor_f32_e32 v47, v47
	v_fmac_f32_e32 v46, 0xcf800000, v47
	v_cvt_u32_f32_e32 v46, v46
	v_cvt_u32_f32_e32 v47, v47
	s_mov_b64 exec, s[6:7]
	global_atomic_add_x2 v208, v[46:47], s[12:13] offset:1152
	s_mov_b64 exec, -1
	ds_write_b128 v156, v[20:23]
	ds_write_b128 v156, v[16:19] offset:64
	ds_read_b128 v[16:19], v157
	ds_read_b128 v[20:23], v157 offset:16
	s_waitcnt vmcnt(21) lgkmcnt(4)
; template <class Epi, class Sched, bool ALIGN_EPI = false, bool SP2 = false>
; __device__ __forceinline__ void gemm_phase(PG8_LAS unsigned char* lds, const Gemm g, const Sched& S, const Epi& E, int tid_in) {
;     ...
;         if (!has_next) break;
; #pragma unroll
;         for (int a = 0; a < 2; ++a)
; #pragma unroll
;             for (int b = 0; b < 2; ++b)
; #pragma unroll
;                 for (int m = 0; m < 4; ++m)
; #pragma unroll
;                     for (int n = 0; n < 2; ++n) acc[a][b][m][n] = (f32x4){0.f, 0.f, 0.f, 0.f};
;         cur = nxt; cA = nA; cB = nB; ++ui;
;         if constexpr (ALIGN_EPI) { if (wr == 1) PG8_BAR; }
;     __device__ __forceinline__ void operator()(const f32x4 (&acc)[2][2][4][2], const Unit& u, int wr, int wc, int fr, int fq) const {
;     ...
;                 for (int bj = 0; bj < 2; ++bj) {
;                     const size_t off = (size_t)row * 2048 + u.pn * BM + wc * 64 + bj * 32 + 8 * p;
;                     f32x4 b0, b1;
;                     if (BASE_F32) { b0 = *(const f32x4*)((const float*)base + off); b1 = *(const f32x4*)((const float*)base + off + 4); }
;                     else { const u32x4 bb = *(const u32x4*)((const bf16_t*)base + off);
;                         b0 = (f32x4){__uint_as_float(bb.x << 16), __uint_as_float(bb.x & 0xffff0000u), __uint_as_float(bb.y << 16), __uint_as_float(bb.y & 0xffff0000u)};
;                         b1 = (f32x4){__uint_as_float(bb.z << 16), __uint_as_float(bb.z & 0xffff0000u), __uint_as_float(bb.w << 16), __uint_as_float(bb.w & 0xffff0000u)}; }
; #pragma unroll
;                     for (int n = 0; n < 2; ++n) *(PG8_LAS f32x4*)(stg + fr * STG_ROW + n * 64 + fq * 16) = acc[ai][bj][m][n];
;                     const f32x4 v0 = *(const PG8_LAS f32x4*)(stg + r * STG_ROW + p * 32) + b0, v1 = *(const PG8_LAS f32x4*)(stg + r * STG_ROW + p * 32 + 16) + b1;
;                     q += ((v0[0] * v0[0] + v0[1] * v0[1]) + (v0[2] * v0[2] + v0[3] * v0[3])) + ((v1[0] * v1[0] + v1[1] * v1[1]) + (v1[2] * v1[2] + v1[3] * v1[3]));
;                     u32x4 w; w.x = cvt_pk_bf16(v0[0], v0[1]); w.y = cvt_pk_bf16(v0[2], v0[3]); w.z = cvt_pk_bf16(v1[0], v1[1]); w.w = cvt_pk_bf16(v1[2], v1[3]);
;                     *(u32x4*)(out + off) = w;
;                 }
;                 q += __shfl_xor(q, 1); q += __shfl_xor(q, 2);
;                 if (p == 0) atomicAdd(ssn + row, (u64)(q * SS_SCALE));
	v_lshlrev_b32_e32 v236, 16, v212
	v_and_b32_e32 v237, 0xffff0000, v212
	v_lshlrev_b32_e32 v238, 16, v213
	v_and_b32_e32 v239, 0xffff0000, v213
	v_lshlrev_b32_e32 v240, 16, v214
	v_and_b32_e32 v241, 0xffff0000, v214
	v_lshlrev_b32_e32 v242, 16, v215
	v_and_b32_e32 v243, 0xffff0000, v215
	v_pk_add_f32 v[24:25], v[24:25], v[236:237]
	v_pk_add_f32 v[26:27], v[26:27], v[238:239]
	v_pk_add_f32 v[28:29], v[28:29], v[240:241]
	v_pk_add_f32 v[30:31], v[30:31], v[242:243]
	v_mul_f32_e32 v236, v25, v25
	v_mul_f32_e32 v237, v27, v27
	v_mul_f32_e32 v238, v29, v29
	v_mul_f32_e32 v239, v31, v31
	v_fmac_f32_e32 v236, v24, v24
	v_fmac_f32_e32 v237, v26, v26
	v_fmac_f32_e32 v238, v28, v28
	v_fmac_f32_e32 v239, v30, v30
	v_cvt_pk_bf16_f32 v24, v24, v25
	v_cvt_pk_bf16_f32 v25, v26, v27
	v_cvt_pk_bf16_f32 v26, v28, v29
	v_cvt_pk_bf16_f32 v27, v30, v31
	v_add_f32_e32 v236, v236, v237
	v_add_f32_e32 v237, v238, v239
	v_add_f32_e32 v28, v236, v237
	v_add_u32_e32 v146, 0xa0000, v159
	global_store_dwordx4 v146, v[24:27], s[28:29]
	ds_write_b128 v156, v[12:15]
	ds_write_b128 v156, v[8:11] offset:64
	ds_read_b128 v[8:11], v157
	ds_read_b128 v[12:15], v157 offset:16
	s_waitcnt vmcnt(21) lgkmcnt(4)
	v_lshlrev_b32_e32 v236, 16, v216
	v_and_b32_e32 v237, 0xffff0000, v216
	v_lshlrev_b32_e32 v238, 16, v217
	v_and_b32_e32 v239, 0xffff0000, v217
	v_lshlrev_b32_e32 v240, 16, v218
	v_and_b32_e32 v241, 0xffff0000, v218
	v_lshlrev_b32_e32 v242, 16, v219
	v_and_b32_e32 v243, 0xffff0000, v219
	v_pk_add_f32 v[16:17], v[16:17], v[236:237]
	v_pk_add_f32 v[18:19], v[18:19], v[238:239]
	v_pk_add_f32 v[20:21], v[20:21], v[240:241]
	v_pk_add_f32 v[22:23], v[22:23], v[242:243]
	v_mul_f32_e32 v236, v17, v17
	v_mul_f32_e32 v237, v19, v19
	v_mul_f32_e32 v238, v21, v21
	v_mul_f32_e32 v239, v23, v23
	v_fmac_f32_e32 v236, v16, v16
	v_fmac_f32_e32 v237, v18, v18
	v_fmac_f32_e32 v238, v20, v20
	v_fmac_f32_e32 v239, v22, v22
	v_cvt_pk_bf16_f32 v16, v16, v17
	v_cvt_pk_bf16_f32 v17, v18, v19
	v_cvt_pk_bf16_f32 v18, v20, v21
	v_cvt_pk_bf16_f32 v19, v22, v23
	v_add_f32_e32 v236, v236, v237
	v_add_f32_e32 v237, v238, v239
	v_add_f32_e32 v20, v236, v237
	global_store_dwordx4 v146, v[16:19], s[28:29] offset:64
	v_add_f32_e32 v21, v28, v20
	s_nop 1
	v_add_f32_dpp v22, v21, v21 quad_perm:[1,0,3,2] row_mask:0xf bank_mask:0xf
	s_nop 1
	v_add_f32_dpp v23, v22, v22 quad_perm:[2,3,0,1] row_mask:0xf bank_mask:0xf
	v_mul_f32_e32 v30, 0x49800000, v23
	v_trunc_f32_e32 v30, v30
	v_mul_f32_e32 v31, 0x2f800000, v30
	v_floor_f32_e32 v31, v31
	v_fmac_f32_e32 v30, 0xcf800000, v31
	v_cvt_u32_f32_e32 v30, v30
	v_cvt_u32_f32_e32 v31, v31
	s_mov_b64 exec, s[6:7]
	global_atomic_add_x2 v208, v[30:31], s[12:13] offset:1280
	s_mov_b64 exec, -1
	ds_write_b128 v156, v[4:7]
	ds_write_b128 v156, v[0:3] offset:64
	ds_read_b128 v[0:3], v157
	ds_read_b128 v[4:7], v157 offset:16
	s_waitcnt vmcnt(22) lgkmcnt(4)
	v_lshlrev_b32_e32 v236, 16, v220
	v_and_b32_e32 v237, 0xffff0000, v220
	v_lshlrev_b32_e32 v238, 16, v221
	v_and_b32_e32 v239, 0xffff0000, v221
	v_lshlrev_b32_e32 v240, 16, v222
	v_and_b32_e32 v241, 0xffff0000, v222
	v_lshlrev_b32_e32 v242, 16, v223
	v_and_b32_e32 v243, 0xffff0000, v223
	v_pk_add_f32 v[8:9], v[8:9], v[236:237]
	v_pk_add_f32 v[10:11], v[10:11], v[238:239]
	v_pk_add_f32 v[12:13], v[12:13], v[240:241]
	v_pk_add_f32 v[14:15], v[14:15], v[242:243]
	v_mul_f32_e32 v236, v9, v9
	v_mul_f32_e32 v237, v11, v11
	v_mul_f32_e32 v238, v13, v13
	v_mul_f32_e32 v239, v15, v15
	v_fmac_f32_e32 v236, v8, v8
	v_fmac_f32_e32 v237, v10, v10
	v_fmac_f32_e32 v238, v12, v12
	v_fmac_f32_e32 v239, v14, v14
	v_cvt_pk_bf16_f32 v8, v8, v9
	v_cvt_pk_bf16_f32 v9, v10, v11
	v_cvt_pk_bf16_f32 v10, v12, v13
	v_cvt_pk_bf16_f32 v11, v14, v15
	v_add_f32_e32 v236, v236, v237
	v_add_f32_e32 v237, v238, v239
	v_add_f32_e32 v12, v236, v237
	v_add_u32_e32 v147, 0xb0000, v159
	global_store_dwordx4 v147, v[8:11], s[28:29]
	s_waitcnt vmcnt(22) lgkmcnt(0)
	v_lshlrev_b32_e32 v236, 16, v224
	v_and_b32_e32 v237, 0xffff0000, v224
	v_lshlrev_b32_e32 v238, 16, v225
	v_and_b32_e32 v239, 0xffff0000, v225
	v_lshlrev_b32_e32 v240, 16, v226
	v_and_b32_e32 v241, 0xffff0000, v226
	v_lshlrev_b32_e32 v242, 16, v227
	v_and_b32_e32 v243, 0xffff0000, v227
	v_pk_add_f32 v[0:1], v[0:1], v[236:237]
	v_pk_add_f32 v[2:3], v[2:3], v[238:239]
	v_pk_add_f32 v[4:5], v[4:5], v[240:241]
	v_pk_add_f32 v[6:7], v[6:7], v[242:243]
	v_mul_f32_e32 v236, v1, v1
	v_mul_f32_e32 v237, v3, v3
	v_mul_f32_e32 v238, v5, v5
	v_mul_f32_e32 v239, v7, v7
	v_fmac_f32_e32 v236, v0, v0
	v_fmac_f32_e32 v237, v2, v2
	v_fmac_f32_e32 v238, v4, v4
	v_fmac_f32_e32 v239, v6, v6
	v_cvt_pk_bf16_f32 v0, v0, v1
	v_cvt_pk_bf16_f32 v1, v2, v3
	v_cvt_pk_bf16_f32 v2, v4, v5
	v_cvt_pk_bf16_f32 v3, v6, v7
	v_add_f32_e32 v236, v236, v237
	v_add_f32_e32 v237, v238, v239
	v_add_f32_e32 v4, v236, v237
	global_store_dwordx4 v147, v[0:3], s[28:29] offset:64
	v_add_f32_e32 v5, v12, v4
	s_nop 1
	v_add_f32_dpp v6, v5, v5 quad_perm:[1,0,3,2] row_mask:0xf bank_mask:0xf
	s_nop 1
	v_add_f32_dpp v7, v6, v6 quad_perm:[2,3,0,1] row_mask:0xf bank_mask:0xf
	v_mul_f32_e32 v14, 0x49800000, v7
	v_trunc_f32_e32 v14, v14
	v_mul_f32_e32 v15, 0x2f800000, v14
	v_floor_f32_e32 v15, v15
	v_fmac_f32_e32 v14, 0xcf800000, v15
	v_cvt_u32_f32_e32 v14, v14
	v_cvt_u32_f32_e32 v15, v15
	s_mov_b64 exec, s[6:7]
	global_atomic_add_x2 v208, v[14:15], s[12:13] offset:1408
	s_mov_b64 exec, -1
	s_and_b64 vcc, exec, s[8:9]
	s_mov_b64 s[8:9], -1
	s_cbranch_vccnz .LBB0_939
	s_andn2_b64 vcc, exec, s[36:37]
	s_cbranch_vccnz .LBB0_938
	s_mov_b32 s98, 1
	s_branch .LBB0_938

; __global__ void __launch_bounds__(NWAVES * 64, 2) mk_fwd(Args args) {
	.amdhsa_kernel _Z6mk_fwd4Args
		.amdhsa_group_segment_fixed_size 0
		.amdhsa_private_segment_fixed_size 0
		.amdhsa_kernarg_size 456
		.amdhsa_user_sgpr_count 2
		.amdhsa_user_sgpr_dispatch_ptr 0
		.amdhsa_user_sgpr_queue_ptr 0
		.amdhsa_user_sgpr_kernarg_segment_ptr 1
		.amdhsa_user_sgpr_dispatch_id 0
		.amdhsa_user_sgpr_kernarg_preload_length 0
		.amdhsa_user_sgpr_kernarg_preload_offset 0
		.amdhsa_user_sgpr_private_segment_size 0
		.amdhsa_uses_dynamic_stack 0
		.amdhsa_enable_private_segment 0
		.amdhsa_system_sgpr_workgroup_id_x 1
		.amdhsa_system_sgpr_workgroup_id_y 0
		.amdhsa_system_sgpr_workgroup_id_z 0
		.amdhsa_system_sgpr_workgroup_info 0
		.amdhsa_system_vgpr_workitem_id 2
		.amdhsa_next_free_vgpr 256
		.amdhsa_next_free_sgpr 102
		.amdhsa_accum_offset 256
		.amdhsa_reserve_vcc 1
		.amdhsa_float_round_mode_32 0
		.amdhsa_float_round_mode_16_64 0
		.amdhsa_float_denorm_mode_32 3
		.amdhsa_float_denorm_mode_16_64 3
		.amdhsa_dx10_clamp 1
		.amdhsa_ieee_mode 1
		.amdhsa_fp16_overflow 0
		.amdhsa_tg_split 0
		.amdhsa_exception_fp_ieee_invalid_op 0
		.amdhsa_exception_fp_denorm_src 0
		.amdhsa_exception_fp_ieee_div_zero 0
		.amdhsa_exception_fp_ieee_overflow 0
		.amdhsa_exception_fp_ieee_underflow 0
		.amdhsa_exception_fp_ieee_inexact 0
		.amdhsa_exception_int_div_zero 0
	.end_amdhsa_kernel

; __global__ void __launch_bounds__(NWAVES * 64, 2) mk_fwd(Args args) {
amdhsa.kernels:
  - .agpr_count:     0
    .args:
      - .offset:         0
        .size:           200
        .value_kind:     by_value
      - .offset:         200
        .size:           4
        .value_kind:     hidden_block_count_x
      - .offset:         204
        .size:           4
        .value_kind:     hidden_block_count_y
      - .offset:         208
        .size:           4
        .value_kind:     hidden_block_count_z
      - .offset:         212
        .size:           2
        .value_kind:     hidden_group_size_x
      - .offset:         214
        .size:           2
        .value_kind:     hidden_group_size_y
      - .offset:         216
        .size:           2
        .value_kind:     hidden_group_size_z
      - .offset:         218
        .size:           2
        .value_kind:     hidden_remainder_x
      - .offset:         220
        .size:           2
        .value_kind:     hidden_remainder_y
      - .offset:         222
        .size:           2
        .value_kind:     hidden_remainder_z
      - .offset:         240
        .size:           8
        .value_kind:     hidden_global_offset_x
      - .offset:         248
        .size:           8
        .value_kind:     hidden_global_offset_y
      - .offset:         256
        .size:           8
        .value_kind:     hidden_global_offset_z
      - .offset:         264
        .size:           2
        .value_kind:     hidden_grid_dims
      - .offset:         288
        .size:           8
        .value_kind:     hidden_multigrid_sync_arg
      - .offset:         320
        .size:           4
        .value_kind:     hidden_dynamic_lds_size
    .group_segment_fixed_size: 0
    .kernarg_segment_align: 8
    .kernarg_segment_size: 456
    .language:       OpenCL C
    .language_version:
      - 2
      - 0
    .max_flat_workgroup_size: 512
    .name:           _Z6mk_fwd4Args
    .private_segment_fixed_size: 0
    .sgpr_count:     108
    .sgpr_spill_count: 2
    .symbol:         _Z6mk_fwd4Args.kd
    .uniform_work_group_size: 1
    .uses_dynamic_stack: false
    .vgpr_count:     256
    .vgpr_spill_count: 0
    .wavefront_size: 64
